# GEMM compute segments: redundant s_waitcnt lgkmcnt(0) after the barrier (already drained before it) removed at 84 MFMA-segment heads
# baseline (speedup 1.0000x reference)
.LBB0_161:
	ds_read_b128 v[152:155], v143
	ds_read_b128 v[162:165], v143 offset:1024
	ds_read_b128 v[166:169], v143 offset:2048
	ds_read_b128 v[170:173], v143 offset:3072
	ds_read_b128 v[174:177], v158
	ds_read_b128 v[178:181], v158 offset:1024
	ds_read_b128 v[182:185], v158 offset:2048
	ds_read_b128 v[186:189], v158 offset:3072
	s_add_u32 s30, s28, 0xfffc0080
	s_addc_u32 s31, s29, -1
	s_cmp_eq_u32 s55, 12
	s_cselect_b32 s35, s19, s31
	s_cselect_b32 s34, s25, s30
	s_cselect_b32 s31, s17, s54
	s_cselect_b32 s30, s27, s53
	s_waitcnt lgkmcnt(0)
	v_lshl_add_u64 v[156:157], s[28:29], 0, v[144:145]
	s_add_i32 m0, s39, 0xc000
	ds_read_b128 v[190:193], v159
	ds_read_b128 v[194:197], v159 offset:1024
	ds_read_b128 v[198:201], v159 offset:2048
	ds_read_b128 v[202:205], v159 offset:3072
	ds_read_b128 v[206:209], v159 offset:4096
	ds_read_b128 v[210:213], v159 offset:5120
	ds_read_b128 v[214:217], v159 offset:6144
	ds_read_b128 v[218:221], v159 offset:7168
	global_load_lds_dwordx4 v[156:157], off
	v_lshl_add_u64 v[156:157], s[28:29], 0, v[146:147]
	s_add_i32 m0, s39, 0xe000
	s_nop 0
	global_load_lds_dwordx4 v[156:157], off
	s_waitcnt vmcnt(8)
	s_waitcnt lgkmcnt(0)
	s_barrier
	s_setprio 1
	v_mfma_f32_16x16x32_bf16 v[116:119], v[152:155], v[190:193], v[116:119]
	v_mfma_f32_16x16x32_bf16 v[112:115], v[166:169], v[190:193], v[112:115]
	v_mfma_f32_16x16x32_bf16 v[100:103], v[152:155], v[198:201], v[100:103]
	v_mfma_f32_16x16x32_bf16 v[96:99], v[166:169], v[198:201], v[96:99]
	v_mfma_f32_16x16x32_bf16 v[88:91], v[152:155], v[206:209], v[88:91]
	v_mfma_f32_16x16x32_bf16 v[84:87], v[166:169], v[206:209], v[84:87]
	v_mfma_f32_16x16x32_bf16 v[72:75], v[152:155], v[214:217], v[72:75]
	v_mfma_f32_16x16x32_bf16 v[68:71], v[166:169], v[214:217], v[68:71]
	v_mfma_f32_16x16x32_bf16 v[116:119], v[162:165], v[194:197], v[116:119]
	v_mfma_f32_16x16x32_bf16 v[112:115], v[170:173], v[194:197], v[112:115]
	v_mfma_f32_16x16x32_bf16 v[100:103], v[162:165], v[202:205], v[100:103]
	v_mfma_f32_16x16x32_bf16 v[96:99], v[170:173], v[202:205], v[96:99]
	v_mfma_f32_16x16x32_bf16 v[88:91], v[162:165], v[210:213], v[88:91]
	v_mfma_f32_16x16x32_bf16 v[84:87], v[170:173], v[210:213], v[84:87]
	v_mfma_f32_16x16x32_bf16 v[72:75], v[162:165], v[218:221], v[72:75]
	v_mfma_f32_16x16x32_bf16 v[68:71], v[170:173], v[218:221], v[68:71]
	s_setprio 0
	s_setprio 1
	v_mfma_f32_16x16x32_bf16 v[124:127], v[174:177], v[190:193], v[124:127]
	v_mfma_f32_16x16x32_bf16 v[120:123], v[182:185], v[190:193], v[120:123]
	v_mfma_f32_16x16x32_bf16 v[108:111], v[174:177], v[198:201], v[108:111]
	v_mfma_f32_16x16x32_bf16 v[104:107], v[182:185], v[198:201], v[104:107]
	v_mfma_f32_16x16x32_bf16 v[92:95], v[174:177], v[206:209], v[92:95]
	v_mfma_f32_16x16x32_bf16 v[80:83], v[182:185], v[206:209], v[80:83]
	v_mfma_f32_16x16x32_bf16 v[76:79], v[174:177], v[214:217], v[76:79]
	v_mfma_f32_16x16x32_bf16 v[64:67], v[182:185], v[214:217], v[64:67]
	v_mfma_f32_16x16x32_bf16 v[124:127], v[178:181], v[194:197], v[124:127]
	v_mfma_f32_16x16x32_bf16 v[120:123], v[186:189], v[194:197], v[120:123]
	v_mfma_f32_16x16x32_bf16 v[108:111], v[178:181], v[202:205], v[108:111]
	v_mfma_f32_16x16x32_bf16 v[104:107], v[186:189], v[202:205], v[104:107]
	v_mfma_f32_16x16x32_bf16 v[92:95], v[178:181], v[210:213], v[92:95]
	v_mfma_f32_16x16x32_bf16 v[80:83], v[186:189], v[210:213], v[80:83]
	v_mfma_f32_16x16x32_bf16 v[76:79], v[178:181], v[218:221], v[76:79]
	v_mfma_f32_16x16x32_bf16 v[64:67], v[186:189], v[218:221], v[64:67]
	s_setprio 0
	s_barrier
	s_add_i32 s56, s49, s36
	v_lshl_add_u64 v[156:157], s[30:31], 0, v[130:131]
	s_mov_b32 m0, s56
	ds_read_b128 v[190:193], v159 offset:16384
	ds_read_b128 v[194:197], v159 offset:17408
	ds_read_b128 v[198:201], v159 offset:18432
	ds_read_b128 v[202:205], v159 offset:19456
	ds_read_b128 v[206:209], v159 offset:20480
	ds_read_b128 v[210:213], v159 offset:21504
	ds_read_b128 v[214:217], v159 offset:22528
	ds_read_b128 v[218:221], v159 offset:23552
	global_load_lds_dwordx4 v[156:157], off
	s_add_i32 m0, s56, 0x2000
	s_add_u32 s56, s30, 0x40000
	v_lshl_add_u64 v[222:223], s[30:31], 0, v[134:135]
	s_addc_u32 s57, s31, 0
	s_add_i32 s58, s50, s36
	global_load_lds_dwordx4 v[222:223], off
	v_lshl_add_u64 v[224:225], s[56:57], 0, v[130:131]
	s_mov_b32 m0, s58
	v_lshl_add_u64 v[226:227], s[34:35], 0, v[132:133]
	global_load_lds_dwordx4 v[224:225], off
	v_lshl_add_u64 v[224:225], s[56:57], 0, v[134:135]
	s_add_i32 m0, s58, 0x2000
	s_nop 0
	global_load_lds_dwordx4 v[224:225], off
	v_lshl_add_u64 v[224:225], s[34:35], 0, v[128:129]
	s_mov_b32 m0, s39
	s_nop 0
	global_load_lds_dwordx4 v[224:225], off
	s_mov_b32 m0, s40
	s_nop 0
	global_load_lds_dwordx4 v[226:227], off
	s_waitcnt vmcnt(8)
	s_waitcnt lgkmcnt(0)
	s_barrier
	s_setprio 1
	v_mfma_f32_16x16x32_bf16 v[56:59], v[152:155], v[190:193], v[56:59]
	v_mfma_f32_16x16x32_bf16 v[52:55], v[166:169], v[190:193], v[52:55]
	v_mfma_f32_16x16x32_bf16 v[40:43], v[152:155], v[198:201], v[40:43]
	v_mfma_f32_16x16x32_bf16 v[36:39], v[166:169], v[198:201], v[36:39]
	v_mfma_f32_16x16x32_bf16 v[24:27], v[152:155], v[206:209], v[24:27]
	v_mfma_f32_16x16x32_bf16 v[20:23], v[166:169], v[206:209], v[20:23]
	v_mfma_f32_16x16x32_bf16 v[8:11], v[152:155], v[214:217], v[8:11]
	v_mfma_f32_16x16x32_bf16 v[4:7], v[166:169], v[214:217], v[4:7]
	v_mfma_f32_16x16x32_bf16 v[56:59], v[162:165], v[194:197], v[56:59]
	v_mfma_f32_16x16x32_bf16 v[52:55], v[170:173], v[194:197], v[52:55]
	v_mfma_f32_16x16x32_bf16 v[40:43], v[162:165], v[202:205], v[40:43]
	v_mfma_f32_16x16x32_bf16 v[36:39], v[170:173], v[202:205], v[36:39]
	v_mfma_f32_16x16x32_bf16 v[24:27], v[162:165], v[210:213], v[24:27]
	v_mfma_f32_16x16x32_bf16 v[20:23], v[170:173], v[210:213], v[20:23]
	v_mfma_f32_16x16x32_bf16 v[8:11], v[162:165], v[218:221], v[8:11]
	v_mfma_f32_16x16x32_bf16 v[4:7], v[170:173], v[218:221], v[4:7]
	s_setprio 0
	s_setprio 1
	v_mfma_f32_16x16x32_bf16 v[60:63], v[174:177], v[190:193], v[60:63]
	v_mfma_f32_16x16x32_bf16 v[48:51], v[182:185], v[190:193], v[48:51]
	v_mfma_f32_16x16x32_bf16 v[44:47], v[174:177], v[198:201], v[44:47]
	v_mfma_f32_16x16x32_bf16 v[32:35], v[182:185], v[198:201], v[32:35]
	v_mfma_f32_16x16x32_bf16 v[28:31], v[174:177], v[206:209], v[28:31]
	v_mfma_f32_16x16x32_bf16 v[16:19], v[182:185], v[206:209], v[16:19]
	v_mfma_f32_16x16x32_bf16 v[12:15], v[174:177], v[214:217], v[12:15]
	v_mfma_f32_16x16x32_bf16 v[0:3], v[182:185], v[214:217], v[0:3]
	v_mfma_f32_16x16x32_bf16 v[60:63], v[178:181], v[194:197], v[60:63]
	v_mfma_f32_16x16x32_bf16 v[48:51], v[186:189], v[194:197], v[48:51]
	v_mfma_f32_16x16x32_bf16 v[44:47], v[178:181], v[202:205], v[44:47]
	v_mfma_f32_16x16x32_bf16 v[32:35], v[186:189], v[202:205], v[32:35]
	v_mfma_f32_16x16x32_bf16 v[28:31], v[178:181], v[210:213], v[28:31]
	v_mfma_f32_16x16x32_bf16 v[16:19], v[186:189], v[210:213], v[16:19]
	v_mfma_f32_16x16x32_bf16 v[12:15], v[178:181], v[218:221], v[12:15]
	v_mfma_f32_16x16x32_bf16 v[0:3], v[186:189], v[218:221], v[0:3]
	s_setprio 0
	s_barrier
	s_add_i32 s56, 0, 0x18000
	s_add_i32 s57, 0, 0x1c000
	v_add_u32_e32 v170, s56, v141
	v_add_u32_e32 v186, s57, v141
	ds_read_b128 v[152:155], v170
	ds_read_b128 v[162:165], v170 offset:1024
	ds_read_b128 v[166:169], v170 offset:2048
	ds_read_b128 v[170:173], v170 offset:3072
	ds_read_b128 v[174:177], v186
	ds_read_b128 v[178:181], v186 offset:1024
	ds_read_b128 v[182:185], v186 offset:2048
	ds_read_b128 v[186:189], v186 offset:3072
	s_add_u32 s34, s34, 0x40000
	s_addc_u32 s35, s35, 0
	s_mov_b32 m0, s41
	v_lshl_add_u64 v[228:229], s[34:35], 0, v[128:129]
	ds_read_b128 v[190:193], v159 offset:32768
	ds_read_b128 v[194:197], v159 offset:33792
	ds_read_b128 v[198:201], v159 offset:34816
	ds_read_b128 v[202:205], v159 offset:35840
	ds_read_b128 v[206:209], v159 offset:36864
	ds_read_b128 v[210:213], v159 offset:37888
	ds_read_b128 v[214:217], v159 offset:38912
	ds_read_b128 v[218:221], v159 offset:39936
	global_load_lds_dwordx4 v[228:229], off
	v_lshl_add_u64 v[228:229], s[34:35], 0, v[132:133]
	s_mov_b32 m0, s42
	s_nop 0
	global_load_lds_dwordx4 v[228:229], off
	s_waitcnt vmcnt(8)
	s_waitcnt lgkmcnt(0)
	s_barrier
	s_setprio 1
	v_mfma_f32_16x16x32_bf16 v[116:119], v[152:155], v[190:193], v[116:119]
	v_mfma_f32_16x16x32_bf16 v[112:115], v[166:169], v[190:193], v[112:115]
	v_mfma_f32_16x16x32_bf16 v[100:103], v[152:155], v[198:201], v[100:103]
	v_mfma_f32_16x16x32_bf16 v[96:99], v[166:169], v[198:201], v[96:99]
	v_mfma_f32_16x16x32_bf16 v[88:91], v[152:155], v[206:209], v[88:91]
	v_mfma_f32_16x16x32_bf16 v[84:87], v[166:169], v[206:209], v[84:87]
	v_mfma_f32_16x16x32_bf16 v[72:75], v[152:155], v[214:217], v[72:75]
	v_mfma_f32_16x16x32_bf16 v[68:71], v[166:169], v[214:217], v[68:71]
	v_mfma_f32_16x16x32_bf16 v[116:119], v[162:165], v[194:197], v[116:119]
	v_mfma_f32_16x16x32_bf16 v[112:115], v[170:173], v[194:197], v[112:115]
	v_mfma_f32_16x16x32_bf16 v[100:103], v[162:165], v[202:205], v[100:103]
	v_mfma_f32_16x16x32_bf16 v[96:99], v[170:173], v[202:205], v[96:99]
	v_mfma_f32_16x16x32_bf16 v[88:91], v[162:165], v[210:213], v[88:91]
	v_mfma_f32_16x16x32_bf16 v[84:87], v[170:173], v[210:213], v[84:87]
	v_mfma_f32_16x16x32_bf16 v[72:75], v[162:165], v[218:221], v[72:75]
	v_mfma_f32_16x16x32_bf16 v[68:71], v[170:173], v[218:221], v[68:71]
	s_setprio 0
	s_setprio 1
	v_mfma_f32_16x16x32_bf16 v[124:127], v[174:177], v[190:193], v[124:127]
	v_mfma_f32_16x16x32_bf16 v[120:123], v[182:185], v[190:193], v[120:123]
	v_mfma_f32_16x16x32_bf16 v[108:111], v[174:177], v[198:201], v[108:111]
	v_mfma_f32_16x16x32_bf16 v[104:107], v[182:185], v[198:201], v[104:107]
	v_mfma_f32_16x16x32_bf16 v[92:95], v[174:177], v[206:209], v[92:95]
	v_mfma_f32_16x16x32_bf16 v[80:83], v[182:185], v[206:209], v[80:83]
	v_mfma_f32_16x16x32_bf16 v[76:79], v[174:177], v[214:217], v[76:79]
	v_mfma_f32_16x16x32_bf16 v[64:67], v[182:185], v[214:217], v[64:67]
	v_mfma_f32_16x16x32_bf16 v[124:127], v[178:181], v[194:197], v[124:127]
	v_mfma_f32_16x16x32_bf16 v[120:123], v[186:189], v[194:197], v[120:123]
	v_mfma_f32_16x16x32_bf16 v[108:111], v[178:181], v[202:205], v[108:111]
	v_mfma_f32_16x16x32_bf16 v[104:107], v[186:189], v[202:205], v[104:107]
	v_mfma_f32_16x16x32_bf16 v[92:95], v[178:181], v[210:213], v[92:95]
	v_mfma_f32_16x16x32_bf16 v[80:83], v[186:189], v[210:213], v[80:83]
	v_mfma_f32_16x16x32_bf16 v[76:79], v[178:181], v[218:221], v[76:79]
	v_mfma_f32_16x16x32_bf16 v[64:67], v[186:189], v[218:221], v[64:67]
	s_setprio 0
	s_barrier
	s_add_i32 s34, s56, s36
	v_lshl_add_u64 v[156:157], v[156:157], 0, s[10:11]
	s_mov_b32 m0, s34
	ds_read_b128 v[190:193], v159 offset:49152
	ds_read_b128 v[194:197], v159 offset:50176
	ds_read_b128 v[198:201], v159 offset:51200
	ds_read_b128 v[202:205], v159 offset:52224
	ds_read_b128 v[206:209], v159 offset:53248
	ds_read_b128 v[210:213], v159 offset:54272
	ds_read_b128 v[214:217], v159 offset:55296
	ds_read_b128 v[218:221], v159 offset:56320
	global_load_lds_dwordx4 v[156:157], off
	s_add_i32 m0, s34, 0x2000
	s_add_u32 s30, s30, 0x40080
	v_lshl_add_u64 v[156:157], v[222:223], 0, s[10:11]
	s_addc_u32 s31, s31, 0
	s_add_i32 s34, s57, s36
	global_load_lds_dwordx4 v[156:157], off
	v_lshl_add_u64 v[156:157], s[30:31], 0, v[130:131]
	s_mov_b32 m0, s34
	s_nop 0
	global_load_lds_dwordx4 v[156:157], off
	v_lshl_add_u64 v[156:157], s[30:31], 0, v[134:135]
	s_add_i32 m0, s34, 0x2000
	s_nop 0
	global_load_lds_dwordx4 v[156:157], off
	v_lshl_add_u64 v[156:157], v[224:225], 0, s[10:11]
	s_mov_b32 m0, s43
	s_nop 0
	global_load_lds_dwordx4 v[156:157], off
	v_lshl_add_u64 v[156:157], v[226:227], 0, s[10:11]
	s_mov_b32 m0, s44
	s_nop 0
	global_load_lds_dwordx4 v[156:157], off
	s_waitcnt vmcnt(8)
	s_waitcnt lgkmcnt(0)
	s_barrier
	s_setprio 1
	v_mfma_f32_16x16x32_bf16 v[56:59], v[152:155], v[190:193], v[56:59]
	v_mfma_f32_16x16x32_bf16 v[52:55], v[166:169], v[190:193], v[52:55]
	v_mfma_f32_16x16x32_bf16 v[40:43], v[152:155], v[198:201], v[40:43]
	v_mfma_f32_16x16x32_bf16 v[36:39], v[166:169], v[198:201], v[36:39]
	v_mfma_f32_16x16x32_bf16 v[24:27], v[152:155], v[206:209], v[24:27]
	v_mfma_f32_16x16x32_bf16 v[20:23], v[166:169], v[206:209], v[20:23]
	v_mfma_f32_16x16x32_bf16 v[8:11], v[152:155], v[214:217], v[8:11]
	v_mfma_f32_16x16x32_bf16 v[4:7], v[166:169], v[214:217], v[4:7]
	v_mfma_f32_16x16x32_bf16 v[56:59], v[162:165], v[194:197], v[56:59]
	v_mfma_f32_16x16x32_bf16 v[52:55], v[170:173], v[194:197], v[52:55]
	v_mfma_f32_16x16x32_bf16 v[40:43], v[162:165], v[202:205], v[40:43]
	v_mfma_f32_16x16x32_bf16 v[36:39], v[170:173], v[202:205], v[36:39]
	v_mfma_f32_16x16x32_bf16 v[24:27], v[162:165], v[210:213], v[24:27]
	v_mfma_f32_16x16x32_bf16 v[20:23], v[170:173], v[210:213], v[20:23]
	v_mfma_f32_16x16x32_bf16 v[8:11], v[162:165], v[218:221], v[8:11]
	v_mfma_f32_16x16x32_bf16 v[4:7], v[170:173], v[218:221], v[4:7]
	s_setprio 0
	s_setprio 1
	v_mfma_f32_16x16x32_bf16 v[60:63], v[174:177], v[190:193], v[60:63]
	v_mfma_f32_16x16x32_bf16 v[48:51], v[182:185], v[190:193], v[48:51]
	v_mfma_f32_16x16x32_bf16 v[44:47], v[174:177], v[198:201], v[44:47]
	v_mfma_f32_16x16x32_bf16 v[32:35], v[182:185], v[198:201], v[32:35]
	v_mfma_f32_16x16x32_bf16 v[28:31], v[174:177], v[206:209], v[28:31]
	v_mfma_f32_16x16x32_bf16 v[16:19], v[182:185], v[206:209], v[16:19]
	v_mfma_f32_16x16x32_bf16 v[12:15], v[174:177], v[214:217], v[12:15]
	v_mfma_f32_16x16x32_bf16 v[0:3], v[182:185], v[214:217], v[0:3]
	v_mfma_f32_16x16x32_bf16 v[60:63], v[178:181], v[194:197], v[60:63]
	v_mfma_f32_16x16x32_bf16 v[48:51], v[186:189], v[194:197], v[48:51]
	v_mfma_f32_16x16x32_bf16 v[44:47], v[178:181], v[202:205], v[44:47]
	v_mfma_f32_16x16x32_bf16 v[32:35], v[186:189], v[202:205], v[32:35]
	v_mfma_f32_16x16x32_bf16 v[28:31], v[178:181], v[210:213], v[28:31]
	v_mfma_f32_16x16x32_bf16 v[16:19], v[186:189], v[210:213], v[16:19]
	v_mfma_f32_16x16x32_bf16 v[12:15], v[178:181], v[218:221], v[12:15]
	v_mfma_f32_16x16x32_bf16 v[0:3], v[186:189], v[218:221], v[0:3]
	s_setprio 0
	s_barrier
	s_add_i32 s55, s55, 2
	s_add_u32 s28, s28, 0x100
	s_addc_u32 s29, s29, 0
	s_add_u32 s53, s53, 0x100
	s_addc_u32 s54, s54, 0
	s_cmp_gt_u32 s55, 13
	s_cbranch_scc0 .LBB0_161
	s_and_b64 vcc, exec, s[12:13]
	s_cbranch_vccz .LBB0_166
	s_barrier
	v_lshl_add_u32 v152, s26, 8, v139
	s_cmp_gt_i32 s24, 21
	s_mov_b64 s[26:27], -1
	s_cbranch_scc1 .LBB0_167

.LBB0_247:
	ds_read_b128 v[148:151], v145
	ds_read_b128 v[152:155], v145 offset:1024
	ds_read_b128 v[156:159], v145 offset:2048
	ds_read_b128 v[160:163], v145 offset:3072
	ds_read_b128 v[164:167], v146
	ds_read_b128 v[168:171], v146 offset:1024
	ds_read_b128 v[172:175], v146 offset:2048
	ds_read_b128 v[176:179], v146 offset:3072
	s_add_u32 s28, s26, 0x100
	s_addc_u32 s29, s27, 0
	s_cmp_eq_u32 s56, 40
	s_cselect_b32 s35, s5, s29
	s_cselect_b32 s34, s4, s28
	s_cselect_b32 s31, s25, s55
	s_cselect_b32 s30, s24, s54
	v_lshl_add_u64 v[140:141], s[26:27], 0, v[132:133]
	s_add_i32 m0, s40, 0xc000
	ds_read_b128 v[180:183], v147
	ds_read_b128 v[184:187], v147 offset:1024
	ds_read_b128 v[188:191], v147 offset:2048
	ds_read_b128 v[192:195], v147 offset:3072
	ds_read_b128 v[196:199], v147 offset:4096
	ds_read_b128 v[200:203], v147 offset:5120
	ds_read_b128 v[204:207], v147 offset:6144
	ds_read_b128 v[208:211], v147 offset:7168
	global_load_lds_dwordx4 v[140:141], off
	v_lshl_add_u64 v[140:141], s[26:27], 0, v[134:135]
	s_add_i32 m0, s40, 0xe000
	s_nop 0
	global_load_lds_dwordx4 v[140:141], off
	s_waitcnt vmcnt(8)
	s_waitcnt lgkmcnt(0)
	s_barrier
	s_setprio 1
	v_mfma_f32_16x16x32_bf16 v[124:127], v[148:151], v[180:183], v[124:127]
	v_mfma_f32_16x16x32_bf16 v[120:123], v[156:159], v[180:183], v[120:123]
	v_mfma_f32_16x16x32_bf16 v[112:115], v[148:151], v[188:191], v[112:115]
	v_mfma_f32_16x16x32_bf16 v[108:111], v[156:159], v[188:191], v[108:111]
	v_mfma_f32_16x16x32_bf16 v[96:99], v[148:151], v[196:199], v[96:99]
	v_mfma_f32_16x16x32_bf16 v[92:95], v[156:159], v[196:199], v[92:95]
	v_mfma_f32_16x16x32_bf16 v[80:83], v[148:151], v[204:207], v[80:83]
	v_mfma_f32_16x16x32_bf16 v[76:79], v[156:159], v[204:207], v[76:79]
	v_mfma_f32_16x16x32_bf16 v[124:127], v[152:155], v[184:187], v[124:127]
	v_mfma_f32_16x16x32_bf16 v[120:123], v[160:163], v[184:187], v[120:123]
	v_mfma_f32_16x16x32_bf16 v[112:115], v[152:155], v[192:195], v[112:115]
	v_mfma_f32_16x16x32_bf16 v[108:111], v[160:163], v[192:195], v[108:111]
	v_mfma_f32_16x16x32_bf16 v[96:99], v[152:155], v[200:203], v[96:99]
	v_mfma_f32_16x16x32_bf16 v[92:95], v[160:163], v[200:203], v[92:95]
	v_mfma_f32_16x16x32_bf16 v[80:83], v[152:155], v[208:211], v[80:83]
	v_mfma_f32_16x16x32_bf16 v[76:79], v[160:163], v[208:211], v[76:79]
	s_setprio 0
	s_setprio 1
	v_mfma_f32_16x16x32_bf16 v[116:119], v[164:167], v[180:183], v[116:119]
	v_mfma_f32_16x16x32_bf16 v[104:107], v[172:175], v[180:183], v[104:107]
	v_mfma_f32_16x16x32_bf16 v[100:103], v[164:167], v[188:191], v[100:103]
	v_mfma_f32_16x16x32_bf16 v[88:91], v[172:175], v[188:191], v[88:91]
	v_mfma_f32_16x16x32_bf16 v[84:87], v[164:167], v[196:199], v[84:87]
	v_mfma_f32_16x16x32_bf16 v[72:75], v[172:175], v[196:199], v[72:75]
	v_mfma_f32_16x16x32_bf16 v[68:71], v[164:167], v[204:207], v[68:71]
	v_mfma_f32_16x16x32_bf16 v[64:67], v[172:175], v[204:207], v[64:67]
	v_mfma_f32_16x16x32_bf16 v[116:119], v[168:171], v[184:187], v[116:119]
	v_mfma_f32_16x16x32_bf16 v[104:107], v[176:179], v[184:187], v[104:107]
	v_mfma_f32_16x16x32_bf16 v[100:103], v[168:171], v[192:195], v[100:103]
	v_mfma_f32_16x16x32_bf16 v[88:91], v[176:179], v[192:195], v[88:91]
	v_mfma_f32_16x16x32_bf16 v[84:87], v[168:171], v[200:203], v[84:87]
	v_mfma_f32_16x16x32_bf16 v[72:75], v[176:179], v[200:203], v[72:75]
	v_mfma_f32_16x16x32_bf16 v[68:71], v[168:171], v[208:211], v[68:71]
	v_mfma_f32_16x16x32_bf16 v[64:67], v[176:179], v[208:211], v[64:67]
	s_setprio 0
	s_barrier
	s_add_i32 s26, s48, s37
	v_lshl_add_u64 v[140:141], s[30:31], 0, v[128:129]
	s_mov_b32 m0, s26
	ds_read_b128 v[180:183], v147 offset:16384
	ds_read_b128 v[184:187], v147 offset:17408
	ds_read_b128 v[188:191], v147 offset:18432
	ds_read_b128 v[192:195], v147 offset:19456
	ds_read_b128 v[196:199], v147 offset:20480
	ds_read_b128 v[200:203], v147 offset:21504
	ds_read_b128 v[204:207], v147 offset:22528
	ds_read_b128 v[208:211], v147 offset:23552
	global_load_lds_dwordx4 v[140:141], off
	s_add_i32 m0, s26, 0x2000
	s_add_u32 s26, s30, 0xb0000
	v_lshl_add_u64 v[212:213], s[30:31], 0, v[130:131]
	s_addc_u32 s27, s31, 0
	s_add_i32 s57, s49, s37
	global_load_lds_dwordx4 v[212:213], off
	v_lshl_add_u64 v[214:215], s[26:27], 0, v[128:129]
	s_mov_b32 m0, s57
	v_lshl_add_u64 v[216:217], s[34:35], 0, v[130:131]
	global_load_lds_dwordx4 v[214:215], off
	v_lshl_add_u64 v[214:215], s[26:27], 0, v[130:131]
	s_add_i32 m0, s57, 0x2000
	s_nop 0
	global_load_lds_dwordx4 v[214:215], off
	v_lshl_add_u64 v[214:215], s[34:35], 0, v[128:129]
	s_mov_b32 m0, s40
	s_nop 0
	global_load_lds_dwordx4 v[214:215], off
	s_mov_b32 m0, s41
	s_nop 0
	global_load_lds_dwordx4 v[216:217], off
	s_waitcnt vmcnt(8)
	s_waitcnt lgkmcnt(0)
	s_barrier
	s_setprio 1
	v_mfma_f32_16x16x32_bf16 v[60:63], v[148:151], v[180:183], v[60:63]
	v_mfma_f32_16x16x32_bf16 v[56:59], v[156:159], v[180:183], v[56:59]
	v_mfma_f32_16x16x32_bf16 v[48:51], v[148:151], v[188:191], v[48:51]
	v_mfma_f32_16x16x32_bf16 v[44:47], v[156:159], v[188:191], v[44:47]
	v_mfma_f32_16x16x32_bf16 v[32:35], v[148:151], v[196:199], v[32:35]
	v_mfma_f32_16x16x32_bf16 v[28:31], v[156:159], v[196:199], v[28:31]
	v_mfma_f32_16x16x32_bf16 v[16:19], v[148:151], v[204:207], v[16:19]
	v_mfma_f32_16x16x32_bf16 v[12:15], v[156:159], v[204:207], v[12:15]
	v_mfma_f32_16x16x32_bf16 v[60:63], v[152:155], v[184:187], v[60:63]
	v_mfma_f32_16x16x32_bf16 v[56:59], v[160:163], v[184:187], v[56:59]
	v_mfma_f32_16x16x32_bf16 v[48:51], v[152:155], v[192:195], v[48:51]
	v_mfma_f32_16x16x32_bf16 v[44:47], v[160:163], v[192:195], v[44:47]
	v_mfma_f32_16x16x32_bf16 v[32:35], v[152:155], v[200:203], v[32:35]
	v_mfma_f32_16x16x32_bf16 v[28:31], v[160:163], v[200:203], v[28:31]
	v_mfma_f32_16x16x32_bf16 v[16:19], v[152:155], v[208:211], v[16:19]
	v_mfma_f32_16x16x32_bf16 v[12:15], v[160:163], v[208:211], v[12:15]
	s_setprio 0
	s_setprio 1
	v_mfma_f32_16x16x32_bf16 v[52:55], v[164:167], v[180:183], v[52:55]
	v_mfma_f32_16x16x32_bf16 v[40:43], v[172:175], v[180:183], v[40:43]
	v_mfma_f32_16x16x32_bf16 v[36:39], v[164:167], v[188:191], v[36:39]
	v_mfma_f32_16x16x32_bf16 v[24:27], v[172:175], v[188:191], v[24:27]
	v_mfma_f32_16x16x32_bf16 v[20:23], v[164:167], v[196:199], v[20:23]
	v_mfma_f32_16x16x32_bf16 v[8:11], v[172:175], v[196:199], v[8:11]
	v_mfma_f32_16x16x32_bf16 v[4:7], v[164:167], v[204:207], v[4:7]
	v_mfma_f32_16x16x32_bf16 v[0:3], v[172:175], v[204:207], v[0:3]
	v_mfma_f32_16x16x32_bf16 v[52:55], v[168:171], v[184:187], v[52:55]
	v_mfma_f32_16x16x32_bf16 v[40:43], v[176:179], v[184:187], v[40:43]
	v_mfma_f32_16x16x32_bf16 v[36:39], v[168:171], v[192:195], v[36:39]
	v_mfma_f32_16x16x32_bf16 v[24:27], v[176:179], v[192:195], v[24:27]
	v_mfma_f32_16x16x32_bf16 v[20:23], v[168:171], v[200:203], v[20:23]
	v_mfma_f32_16x16x32_bf16 v[8:11], v[176:179], v[200:203], v[8:11]
	v_mfma_f32_16x16x32_bf16 v[4:7], v[168:171], v[208:211], v[4:7]
	v_mfma_f32_16x16x32_bf16 v[0:3], v[176:179], v[208:211], v[0:3]
	s_setprio 0
	s_barrier
	s_add_i32 s57, 0, 0x18000
	s_add_i32 s58, 0, 0x1c000
	v_add_u32_e32 v160, s57, v143
	v_add_u32_e32 v176, s58, v143
	ds_read_b128 v[148:151], v160
	ds_read_b128 v[152:155], v160 offset:1024
	ds_read_b128 v[156:159], v160 offset:2048
	ds_read_b128 v[160:163], v160 offset:3072
	ds_read_b128 v[164:167], v176
	ds_read_b128 v[168:171], v176 offset:1024
	ds_read_b128 v[172:175], v176 offset:2048
	ds_read_b128 v[176:179], v176 offset:3072
	s_add_u32 s26, s34, 0xb0000
	s_addc_u32 s27, s35, 0
	s_mov_b32 m0, s42
	v_lshl_add_u64 v[218:219], s[26:27], 0, v[128:129]
	ds_read_b128 v[180:183], v147 offset:32768
	ds_read_b128 v[184:187], v147 offset:33792
	ds_read_b128 v[188:191], v147 offset:34816
	ds_read_b128 v[192:195], v147 offset:35840
	ds_read_b128 v[196:199], v147 offset:36864
	ds_read_b128 v[200:203], v147 offset:37888
	ds_read_b128 v[204:207], v147 offset:38912
	ds_read_b128 v[208:211], v147 offset:39936
	global_load_lds_dwordx4 v[218:219], off
	v_lshl_add_u64 v[218:219], s[26:27], 0, v[130:131]
	s_mov_b32 m0, s43
	s_nop 0
	global_load_lds_dwordx4 v[218:219], off
	s_waitcnt vmcnt(8)
	s_waitcnt lgkmcnt(0)
	s_barrier
	s_setprio 1
	v_mfma_f32_16x16x32_bf16 v[124:127], v[148:151], v[180:183], v[124:127]
	v_mfma_f32_16x16x32_bf16 v[120:123], v[156:159], v[180:183], v[120:123]
	v_mfma_f32_16x16x32_bf16 v[112:115], v[148:151], v[188:191], v[112:115]
	v_mfma_f32_16x16x32_bf16 v[108:111], v[156:159], v[188:191], v[108:111]
	v_mfma_f32_16x16x32_bf16 v[96:99], v[148:151], v[196:199], v[96:99]
	v_mfma_f32_16x16x32_bf16 v[92:95], v[156:159], v[196:199], v[92:95]
	v_mfma_f32_16x16x32_bf16 v[80:83], v[148:151], v[204:207], v[80:83]
	v_mfma_f32_16x16x32_bf16 v[76:79], v[156:159], v[204:207], v[76:79]
	v_mfma_f32_16x16x32_bf16 v[124:127], v[152:155], v[184:187], v[124:127]
	v_mfma_f32_16x16x32_bf16 v[120:123], v[160:163], v[184:187], v[120:123]
	v_mfma_f32_16x16x32_bf16 v[112:115], v[152:155], v[192:195], v[112:115]
	v_mfma_f32_16x16x32_bf16 v[108:111], v[160:163], v[192:195], v[108:111]
	v_mfma_f32_16x16x32_bf16 v[96:99], v[152:155], v[200:203], v[96:99]
	v_mfma_f32_16x16x32_bf16 v[92:95], v[160:163], v[200:203], v[92:95]
	v_mfma_f32_16x16x32_bf16 v[80:83], v[152:155], v[208:211], v[80:83]
	v_mfma_f32_16x16x32_bf16 v[76:79], v[160:163], v[208:211], v[76:79]
	s_setprio 0
	s_setprio 1
	v_mfma_f32_16x16x32_bf16 v[116:119], v[164:167], v[180:183], v[116:119]
	v_mfma_f32_16x16x32_bf16 v[104:107], v[172:175], v[180:183], v[104:107]
	v_mfma_f32_16x16x32_bf16 v[100:103], v[164:167], v[188:191], v[100:103]
	v_mfma_f32_16x16x32_bf16 v[88:91], v[172:175], v[188:191], v[88:91]
	v_mfma_f32_16x16x32_bf16 v[84:87], v[164:167], v[196:199], v[84:87]
	v_mfma_f32_16x16x32_bf16 v[72:75], v[172:175], v[196:199], v[72:75]
	v_mfma_f32_16x16x32_bf16 v[68:71], v[164:167], v[204:207], v[68:71]
	v_mfma_f32_16x16x32_bf16 v[64:67], v[172:175], v[204:207], v[64:67]
	v_mfma_f32_16x16x32_bf16 v[116:119], v[168:171], v[184:187], v[116:119]
	v_mfma_f32_16x16x32_bf16 v[104:107], v[176:179], v[184:187], v[104:107]
	v_mfma_f32_16x16x32_bf16 v[100:103], v[168:171], v[192:195], v[100:103]
	v_mfma_f32_16x16x32_bf16 v[88:91], v[176:179], v[192:195], v[88:91]
	v_mfma_f32_16x16x32_bf16 v[84:87], v[168:171], v[200:203], v[84:87]
	v_mfma_f32_16x16x32_bf16 v[72:75], v[176:179], v[200:203], v[72:75]
	v_mfma_f32_16x16x32_bf16 v[68:71], v[168:171], v[208:211], v[68:71]
	v_mfma_f32_16x16x32_bf16 v[64:67], v[176:179], v[208:211], v[64:67]
	s_setprio 0
	s_barrier
	s_add_i32 s26, s57, s37
	v_lshl_add_u64 v[140:141], v[140:141], 0, s[14:15]
	s_mov_b32 m0, s26
	ds_read_b128 v[180:183], v147 offset:49152
	ds_read_b128 v[184:187], v147 offset:50176
	ds_read_b128 v[188:191], v147 offset:51200
	ds_read_b128 v[192:195], v147 offset:52224
	ds_read_b128 v[196:199], v147 offset:53248
	ds_read_b128 v[200:203], v147 offset:54272
	ds_read_b128 v[204:207], v147 offset:55296
	ds_read_b128 v[208:211], v147 offset:56320
	global_load_lds_dwordx4 v[140:141], off
	s_add_i32 m0, s26, 0x2000
	s_add_u32 s26, s30, 0xb0080
	v_lshl_add_u64 v[140:141], v[212:213], 0, s[14:15]
	s_addc_u32 s27, s31, 0
	s_add_i32 s30, s58, s37
	global_load_lds_dwordx4 v[140:141], off
	v_lshl_add_u64 v[140:141], s[26:27], 0, v[128:129]
	s_mov_b32 m0, s30
	s_nop 0
	global_load_lds_dwordx4 v[140:141], off
	v_lshl_add_u64 v[140:141], s[26:27], 0, v[130:131]
	s_add_i32 m0, s30, 0x2000
	s_nop 0
	global_load_lds_dwordx4 v[140:141], off
	v_lshl_add_u64 v[140:141], v[214:215], 0, s[14:15]
	s_mov_b32 m0, s45
	s_nop 0
	global_load_lds_dwordx4 v[140:141], off
	v_lshl_add_u64 v[140:141], v[216:217], 0, s[14:15]
	s_mov_b32 m0, s46
	s_nop 0
	global_load_lds_dwordx4 v[140:141], off
	s_waitcnt vmcnt(8)
	s_waitcnt lgkmcnt(0)
	s_barrier
	s_setprio 1
	v_mfma_f32_16x16x32_bf16 v[60:63], v[148:151], v[180:183], v[60:63]
	v_mfma_f32_16x16x32_bf16 v[56:59], v[156:159], v[180:183], v[56:59]
	v_mfma_f32_16x16x32_bf16 v[48:51], v[148:151], v[188:191], v[48:51]
	v_mfma_f32_16x16x32_bf16 v[44:47], v[156:159], v[188:191], v[44:47]
	v_mfma_f32_16x16x32_bf16 v[32:35], v[148:151], v[196:199], v[32:35]
	v_mfma_f32_16x16x32_bf16 v[28:31], v[156:159], v[196:199], v[28:31]
	v_mfma_f32_16x16x32_bf16 v[16:19], v[148:151], v[204:207], v[16:19]
	v_mfma_f32_16x16x32_bf16 v[12:15], v[156:159], v[204:207], v[12:15]
	v_mfma_f32_16x16x32_bf16 v[60:63], v[152:155], v[184:187], v[60:63]
	v_mfma_f32_16x16x32_bf16 v[56:59], v[160:163], v[184:187], v[56:59]
	v_mfma_f32_16x16x32_bf16 v[48:51], v[152:155], v[192:195], v[48:51]
	v_mfma_f32_16x16x32_bf16 v[44:47], v[160:163], v[192:195], v[44:47]
	v_mfma_f32_16x16x32_bf16 v[32:35], v[152:155], v[200:203], v[32:35]
	v_mfma_f32_16x16x32_bf16 v[28:31], v[160:163], v[200:203], v[28:31]
	v_mfma_f32_16x16x32_bf16 v[16:19], v[152:155], v[208:211], v[16:19]
	v_mfma_f32_16x16x32_bf16 v[12:15], v[160:163], v[208:211], v[12:15]
	s_setprio 0
	s_setprio 1
	v_mfma_f32_16x16x32_bf16 v[52:55], v[164:167], v[180:183], v[52:55]
	v_mfma_f32_16x16x32_bf16 v[40:43], v[172:175], v[180:183], v[40:43]
	v_mfma_f32_16x16x32_bf16 v[36:39], v[164:167], v[188:191], v[36:39]
	v_mfma_f32_16x16x32_bf16 v[24:27], v[172:175], v[188:191], v[24:27]
	v_mfma_f32_16x16x32_bf16 v[20:23], v[164:167], v[196:199], v[20:23]
	v_mfma_f32_16x16x32_bf16 v[8:11], v[172:175], v[196:199], v[8:11]
	v_mfma_f32_16x16x32_bf16 v[4:7], v[164:167], v[204:207], v[4:7]
	v_mfma_f32_16x16x32_bf16 v[0:3], v[172:175], v[204:207], v[0:3]
	v_mfma_f32_16x16x32_bf16 v[52:55], v[168:171], v[184:187], v[52:55]
	v_mfma_f32_16x16x32_bf16 v[40:43], v[176:179], v[184:187], v[40:43]
	v_mfma_f32_16x16x32_bf16 v[36:39], v[168:171], v[192:195], v[36:39]
	v_mfma_f32_16x16x32_bf16 v[24:27], v[176:179], v[192:195], v[24:27]
	v_mfma_f32_16x16x32_bf16 v[20:23], v[168:171], v[200:203], v[20:23]
	v_mfma_f32_16x16x32_bf16 v[8:11], v[176:179], v[200:203], v[8:11]
	v_mfma_f32_16x16x32_bf16 v[4:7], v[168:171], v[208:211], v[4:7]
	v_mfma_f32_16x16x32_bf16 v[0:3], v[176:179], v[208:211], v[0:3]
	s_setprio 0
	s_barrier
	s_add_i32 s56, s56, 2
	s_add_u32 s54, s54, 0x100
	s_addc_u32 s55, s55, 0
	s_cmp_gt_u32 s56, 41
	s_mov_b64 s[26:27], s[28:29]
	s_cbranch_scc0 .LBB0_247
	s_and_b64 vcc, exec, s[16:17]
	s_cbranch_vccz .LBB0_250
	s_barrier

.LBB0_340:
	ds_read_b128 v[128:131], v143
	ds_read_b128 v[150:153], v143 offset:1024
	ds_read_b128 v[154:157], v143 offset:2048
	ds_read_b128 v[164:167], v143 offset:3072
	ds_read_b128 v[168:171], v162
	ds_read_b128 v[172:175], v162 offset:1024
	ds_read_b128 v[176:179], v162 offset:2048
	ds_read_b128 v[180:183], v162 offset:3072
	s_add_i32 s86, s48, 2
	s_add_u32 s49, s46, 0xfff80080
	s_addc_u32 s50, s47, -1
	s_cmp_eq_u32 s83, s48
	s_cselect_b32 s48, s81, s84
	s_cselect_b32 s51, s3, s50
	s_cselect_b32 s50, s35, s49
	s_cselect_b32 s49, s37, s85
	v_lshl_add_u64 v[158:159], s[46:47], 0, v[146:147]
	s_add_i32 m0, s56, 0xc000
	ds_read_b128 v[184:187], v163
	ds_read_b128 v[188:191], v163 offset:1024
	ds_read_b128 v[192:195], v163 offset:2048
	ds_read_b128 v[196:199], v163 offset:3072
	ds_read_b128 v[200:203], v163 offset:4096
	ds_read_b128 v[204:207], v163 offset:5120
	ds_read_b128 v[208:211], v163 offset:6144
	ds_read_b128 v[212:215], v163 offset:7168
	global_load_lds_dwordx4 v[158:159], off
	v_lshl_add_u64 v[158:159], s[46:47], 0, v[148:149]
	s_add_i32 m0, s56, 0xe000
	s_nop 0
	global_load_lds_dwordx4 v[158:159], off
	s_waitcnt vmcnt(8)
	s_waitcnt lgkmcnt(0)
	s_barrier
	s_setprio 1
	v_mfma_f32_16x16x32_bf16 v[124:127], v[128:131], v[184:187], v[124:127]
	v_mfma_f32_16x16x32_bf16 v[120:123], v[154:157], v[184:187], v[120:123]
	v_mfma_f32_16x16x32_bf16 v[116:119], v[128:131], v[192:195], v[116:119]
	v_mfma_f32_16x16x32_bf16 v[108:111], v[154:157], v[192:195], v[108:111]
	v_mfma_f32_16x16x32_bf16 v[100:103], v[128:131], v[200:203], v[100:103]
	v_mfma_f32_16x16x32_bf16 v[92:95], v[154:157], v[200:203], v[92:95]
	v_mfma_f32_16x16x32_bf16 v[84:87], v[128:131], v[208:211], v[84:87]
	v_mfma_f32_16x16x32_bf16 v[76:79], v[154:157], v[208:211], v[76:79]
	v_mfma_f32_16x16x32_bf16 v[124:127], v[150:153], v[188:191], v[124:127]
	v_mfma_f32_16x16x32_bf16 v[120:123], v[164:167], v[188:191], v[120:123]
	v_mfma_f32_16x16x32_bf16 v[116:119], v[150:153], v[196:199], v[116:119]
	v_mfma_f32_16x16x32_bf16 v[108:111], v[164:167], v[196:199], v[108:111]
	v_mfma_f32_16x16x32_bf16 v[100:103], v[150:153], v[204:207], v[100:103]
	v_mfma_f32_16x16x32_bf16 v[92:95], v[164:167], v[204:207], v[92:95]
	v_mfma_f32_16x16x32_bf16 v[84:87], v[150:153], v[212:215], v[84:87]
	v_mfma_f32_16x16x32_bf16 v[76:79], v[164:167], v[212:215], v[76:79]
	s_setprio 0
	s_setprio 1
	v_mfma_f32_16x16x32_bf16 v[112:115], v[168:171], v[184:187], v[112:115]
	v_mfma_f32_16x16x32_bf16 v[104:107], v[176:179], v[184:187], v[104:107]
	v_mfma_f32_16x16x32_bf16 v[96:99], v[168:171], v[192:195], v[96:99]
	v_mfma_f32_16x16x32_bf16 v[88:91], v[176:179], v[192:195], v[88:91]
	v_mfma_f32_16x16x32_bf16 v[80:83], v[168:171], v[200:203], v[80:83]
	v_mfma_f32_16x16x32_bf16 v[72:75], v[176:179], v[200:203], v[72:75]
	v_mfma_f32_16x16x32_bf16 v[68:71], v[168:171], v[208:211], v[68:71]
	v_mfma_f32_16x16x32_bf16 v[64:67], v[176:179], v[208:211], v[64:67]
	v_mfma_f32_16x16x32_bf16 v[112:115], v[172:175], v[188:191], v[112:115]
	v_mfma_f32_16x16x32_bf16 v[104:107], v[180:183], v[188:191], v[104:107]
	v_mfma_f32_16x16x32_bf16 v[96:99], v[172:175], v[196:199], v[96:99]
	v_mfma_f32_16x16x32_bf16 v[88:91], v[180:183], v[196:199], v[88:91]
	v_mfma_f32_16x16x32_bf16 v[80:83], v[172:175], v[204:207], v[80:83]
	v_mfma_f32_16x16x32_bf16 v[72:75], v[180:183], v[204:207], v[72:75]
	v_mfma_f32_16x16x32_bf16 v[68:71], v[172:175], v[212:215], v[68:71]
	v_mfma_f32_16x16x32_bf16 v[64:67], v[180:183], v[212:215], v[64:67]
	s_setprio 0
	s_barrier
	s_add_i32 s87, s65, s55
	v_lshl_add_u64 v[158:159], s[48:49], 0, v[134:135]
	s_mov_b32 m0, s87
	ds_read_b128 v[184:187], v163 offset:16384
	ds_read_b128 v[188:191], v163 offset:17408
	ds_read_b128 v[192:195], v163 offset:18432
	ds_read_b128 v[196:199], v163 offset:19456
	ds_read_b128 v[200:203], v163 offset:20480
	ds_read_b128 v[204:207], v163 offset:21504
	ds_read_b128 v[208:211], v163 offset:22528
	ds_read_b128 v[212:215], v163 offset:23552
	global_load_lds_dwordx4 v[158:159], off
	s_add_i32 m0, s87, 0x2000
	s_add_u32 s88, s48, 0x80000
	v_lshl_add_u64 v[216:217], s[48:49], 0, v[138:139]
	s_addc_u32 s89, s49, 0
	s_add_i32 s87, s66, s55
	global_load_lds_dwordx4 v[216:217], off
	v_lshl_add_u64 v[218:219], s[88:89], 0, v[134:135]
	s_mov_b32 m0, s87
	v_lshl_add_u64 v[220:221], s[50:51], 0, v[136:137]
	global_load_lds_dwordx4 v[218:219], off
	v_lshl_add_u64 v[218:219], s[88:89], 0, v[138:139]
	s_add_i32 m0, s87, 0x2000
	s_nop 0
	global_load_lds_dwordx4 v[218:219], off
	v_lshl_add_u64 v[218:219], s[50:51], 0, v[132:133]
	s_mov_b32 m0, s56
	s_nop 0
	global_load_lds_dwordx4 v[218:219], off
	s_mov_b32 m0, s57
	s_nop 0
	global_load_lds_dwordx4 v[220:221], off
	s_waitcnt vmcnt(8)
	s_waitcnt lgkmcnt(0)
	s_barrier
	s_setprio 1
	v_mfma_f32_16x16x32_bf16 v[60:63], v[128:131], v[184:187], v[60:63]
	v_mfma_f32_16x16x32_bf16 v[56:59], v[154:157], v[184:187], v[56:59]
	v_mfma_f32_16x16x32_bf16 v[52:55], v[128:131], v[192:195], v[52:55]
	v_mfma_f32_16x16x32_bf16 v[44:47], v[154:157], v[192:195], v[44:47]
	v_mfma_f32_16x16x32_bf16 v[36:39], v[128:131], v[200:203], v[36:39]
	v_mfma_f32_16x16x32_bf16 v[28:31], v[154:157], v[200:203], v[28:31]
	v_mfma_f32_16x16x32_bf16 v[20:23], v[128:131], v[208:211], v[20:23]
	v_mfma_f32_16x16x32_bf16 v[12:15], v[154:157], v[208:211], v[12:15]
	v_mfma_f32_16x16x32_bf16 v[60:63], v[150:153], v[188:191], v[60:63]
	v_mfma_f32_16x16x32_bf16 v[56:59], v[164:167], v[188:191], v[56:59]
	v_mfma_f32_16x16x32_bf16 v[52:55], v[150:153], v[196:199], v[52:55]
	v_mfma_f32_16x16x32_bf16 v[44:47], v[164:167], v[196:199], v[44:47]
	v_mfma_f32_16x16x32_bf16 v[36:39], v[150:153], v[204:207], v[36:39]
	v_mfma_f32_16x16x32_bf16 v[28:31], v[164:167], v[204:207], v[28:31]
	v_mfma_f32_16x16x32_bf16 v[20:23], v[150:153], v[212:215], v[20:23]
	v_mfma_f32_16x16x32_bf16 v[12:15], v[164:167], v[212:215], v[12:15]
	s_setprio 0
	s_setprio 1
	v_mfma_f32_16x16x32_bf16 v[48:51], v[168:171], v[184:187], v[48:51]
	v_mfma_f32_16x16x32_bf16 v[40:43], v[176:179], v[184:187], v[40:43]
	v_mfma_f32_16x16x32_bf16 v[32:35], v[168:171], v[192:195], v[32:35]
	v_mfma_f32_16x16x32_bf16 v[24:27], v[176:179], v[192:195], v[24:27]
	v_mfma_f32_16x16x32_bf16 v[16:19], v[168:171], v[200:203], v[16:19]
	v_mfma_f32_16x16x32_bf16 v[8:11], v[176:179], v[200:203], v[8:11]
	v_mfma_f32_16x16x32_bf16 v[4:7], v[168:171], v[208:211], v[4:7]
	v_mfma_f32_16x16x32_bf16 v[0:3], v[176:179], v[208:211], v[0:3]
	v_mfma_f32_16x16x32_bf16 v[48:51], v[172:175], v[188:191], v[48:51]
	v_mfma_f32_16x16x32_bf16 v[40:43], v[180:183], v[188:191], v[40:43]
	v_mfma_f32_16x16x32_bf16 v[32:35], v[172:175], v[196:199], v[32:35]
	v_mfma_f32_16x16x32_bf16 v[24:27], v[180:183], v[196:199], v[24:27]
	v_mfma_f32_16x16x32_bf16 v[16:19], v[172:175], v[204:207], v[16:19]
	v_mfma_f32_16x16x32_bf16 v[8:11], v[180:183], v[204:207], v[8:11]
	v_mfma_f32_16x16x32_bf16 v[4:7], v[172:175], v[212:215], v[4:7]
	v_mfma_f32_16x16x32_bf16 v[0:3], v[180:183], v[212:215], v[0:3]
	s_setprio 0
	s_barrier
	s_add_i32 s87, 0, 0x18000
	v_add_u32_e32 v140, s87, v161
	s_add_i32 s88, 0, 0x1c000
	ds_read_b128 v[128:131], v140
	ds_read_b128 v[150:153], v140 offset:1024
	ds_read_b128 v[154:157], v140 offset:2048
	ds_read_b128 v[164:167], v140 offset:3072
	v_add_u32_e32 v140, s88, v161
	ds_read_b128 v[168:171], v140
	ds_read_b128 v[172:175], v140 offset:1024
	ds_read_b128 v[176:179], v140 offset:2048
	ds_read_b128 v[180:183], v140 offset:3072
	s_add_u32 s50, s50, 0x80000
	s_addc_u32 s51, s51, 0
	s_mov_b32 m0, s58
	v_lshl_add_u64 v[222:223], s[50:51], 0, v[132:133]
	ds_read_b128 v[184:187], v163 offset:32768
	ds_read_b128 v[188:191], v163 offset:33792
	ds_read_b128 v[192:195], v163 offset:34816
	ds_read_b128 v[196:199], v163 offset:35840
	ds_read_b128 v[200:203], v163 offset:36864
	ds_read_b128 v[204:207], v163 offset:37888
	ds_read_b128 v[208:211], v163 offset:38912
	ds_read_b128 v[212:215], v163 offset:39936
	global_load_lds_dwordx4 v[222:223], off
	v_lshl_add_u64 v[222:223], s[50:51], 0, v[136:137]
	s_mov_b32 m0, s59
	s_nop 0
	global_load_lds_dwordx4 v[222:223], off
	s_waitcnt vmcnt(8)
	s_waitcnt lgkmcnt(0)
	s_barrier
	s_setprio 1
	v_mfma_f32_16x16x32_bf16 v[124:127], v[128:131], v[184:187], v[124:127]
	v_mfma_f32_16x16x32_bf16 v[120:123], v[154:157], v[184:187], v[120:123]
	v_mfma_f32_16x16x32_bf16 v[116:119], v[128:131], v[192:195], v[116:119]
	v_mfma_f32_16x16x32_bf16 v[108:111], v[154:157], v[192:195], v[108:111]
	v_mfma_f32_16x16x32_bf16 v[100:103], v[128:131], v[200:203], v[100:103]
	v_mfma_f32_16x16x32_bf16 v[92:95], v[154:157], v[200:203], v[92:95]
	v_mfma_f32_16x16x32_bf16 v[84:87], v[128:131], v[208:211], v[84:87]
	v_mfma_f32_16x16x32_bf16 v[76:79], v[154:157], v[208:211], v[76:79]
	v_mfma_f32_16x16x32_bf16 v[124:127], v[150:153], v[188:191], v[124:127]
	v_mfma_f32_16x16x32_bf16 v[120:123], v[164:167], v[188:191], v[120:123]
	v_mfma_f32_16x16x32_bf16 v[116:119], v[150:153], v[196:199], v[116:119]
	v_mfma_f32_16x16x32_bf16 v[108:111], v[164:167], v[196:199], v[108:111]
	v_mfma_f32_16x16x32_bf16 v[100:103], v[150:153], v[204:207], v[100:103]
	v_mfma_f32_16x16x32_bf16 v[92:95], v[164:167], v[204:207], v[92:95]
	v_mfma_f32_16x16x32_bf16 v[84:87], v[150:153], v[212:215], v[84:87]
	v_mfma_f32_16x16x32_bf16 v[76:79], v[164:167], v[212:215], v[76:79]
	s_setprio 0
	s_setprio 1
	v_mfma_f32_16x16x32_bf16 v[112:115], v[168:171], v[184:187], v[112:115]
	v_mfma_f32_16x16x32_bf16 v[104:107], v[176:179], v[184:187], v[104:107]
	v_mfma_f32_16x16x32_bf16 v[96:99], v[168:171], v[192:195], v[96:99]
	v_mfma_f32_16x16x32_bf16 v[88:91], v[176:179], v[192:195], v[88:91]
	v_mfma_f32_16x16x32_bf16 v[80:83], v[168:171], v[200:203], v[80:83]
	v_mfma_f32_16x16x32_bf16 v[72:75], v[176:179], v[200:203], v[72:75]
	v_mfma_f32_16x16x32_bf16 v[68:71], v[168:171], v[208:211], v[68:71]
	v_mfma_f32_16x16x32_bf16 v[64:67], v[176:179], v[208:211], v[64:67]
	v_mfma_f32_16x16x32_bf16 v[112:115], v[172:175], v[188:191], v[112:115]
	v_mfma_f32_16x16x32_bf16 v[104:107], v[180:183], v[188:191], v[104:107]
	v_mfma_f32_16x16x32_bf16 v[96:99], v[172:175], v[196:199], v[96:99]
	v_mfma_f32_16x16x32_bf16 v[88:91], v[180:183], v[196:199], v[88:91]
	v_mfma_f32_16x16x32_bf16 v[80:83], v[172:175], v[204:207], v[80:83]
	v_mfma_f32_16x16x32_bf16 v[72:75], v[180:183], v[204:207], v[72:75]
	v_mfma_f32_16x16x32_bf16 v[68:71], v[172:175], v[212:215], v[68:71]
	v_mfma_f32_16x16x32_bf16 v[64:67], v[180:183], v[212:215], v[64:67]
	s_setprio 0
	s_barrier
	s_add_i32 s50, s87, s55
	v_lshl_add_u64 v[158:159], v[158:159], 0, s[10:11]
	s_mov_b32 m0, s50
	ds_read_b128 v[184:187], v163 offset:49152
	ds_read_b128 v[188:191], v163 offset:50176
	ds_read_b128 v[192:195], v163 offset:51200
	ds_read_b128 v[196:199], v163 offset:52224
	ds_read_b128 v[200:203], v163 offset:53248
	ds_read_b128 v[204:207], v163 offset:54272
	ds_read_b128 v[208:211], v163 offset:55296
	ds_read_b128 v[212:215], v163 offset:56320
	global_load_lds_dwordx4 v[158:159], off
	s_add_i32 m0, s50, 0x2000
	s_add_u32 s48, s48, 0x80080
	v_lshl_add_u64 v[158:159], v[216:217], 0, s[10:11]
	s_addc_u32 s49, s49, 0
	s_add_i32 s50, s88, s55
	global_load_lds_dwordx4 v[158:159], off
	v_lshl_add_u64 v[158:159], s[48:49], 0, v[134:135]
	s_mov_b32 m0, s50
	s_nop 0
	global_load_lds_dwordx4 v[158:159], off
	v_lshl_add_u64 v[158:159], s[48:49], 0, v[138:139]
	s_add_i32 m0, s50, 0x2000
	s_nop 0
	global_load_lds_dwordx4 v[158:159], off
	v_lshl_add_u64 v[158:159], v[218:219], 0, s[10:11]
	s_mov_b32 m0, s63
	s_nop 0
	global_load_lds_dwordx4 v[158:159], off
	v_lshl_add_u64 v[158:159], v[220:221], 0, s[10:11]
	s_mov_b32 m0, s64
	s_nop 0
	global_load_lds_dwordx4 v[158:159], off
	s_waitcnt vmcnt(8)
	s_waitcnt lgkmcnt(0)
	s_barrier
	s_setprio 1
	v_mfma_f32_16x16x32_bf16 v[60:63], v[128:131], v[184:187], v[60:63]
	v_mfma_f32_16x16x32_bf16 v[56:59], v[154:157], v[184:187], v[56:59]
	v_mfma_f32_16x16x32_bf16 v[52:55], v[128:131], v[192:195], v[52:55]
	v_mfma_f32_16x16x32_bf16 v[44:47], v[154:157], v[192:195], v[44:47]
	v_mfma_f32_16x16x32_bf16 v[36:39], v[128:131], v[200:203], v[36:39]
	v_mfma_f32_16x16x32_bf16 v[28:31], v[154:157], v[200:203], v[28:31]
	v_mfma_f32_16x16x32_bf16 v[20:23], v[128:131], v[208:211], v[20:23]
	v_mfma_f32_16x16x32_bf16 v[12:15], v[154:157], v[208:211], v[12:15]
	v_mfma_f32_16x16x32_bf16 v[60:63], v[150:153], v[188:191], v[60:63]
	v_mfma_f32_16x16x32_bf16 v[56:59], v[164:167], v[188:191], v[56:59]
	v_mfma_f32_16x16x32_bf16 v[52:55], v[150:153], v[196:199], v[52:55]
	v_mfma_f32_16x16x32_bf16 v[44:47], v[164:167], v[196:199], v[44:47]
	v_mfma_f32_16x16x32_bf16 v[36:39], v[150:153], v[204:207], v[36:39]
	v_mfma_f32_16x16x32_bf16 v[28:31], v[164:167], v[204:207], v[28:31]
	v_mfma_f32_16x16x32_bf16 v[20:23], v[150:153], v[212:215], v[20:23]
	v_mfma_f32_16x16x32_bf16 v[12:15], v[164:167], v[212:215], v[12:15]
	s_setprio 0
	s_setprio 1
	v_mfma_f32_16x16x32_bf16 v[48:51], v[168:171], v[184:187], v[48:51]
	v_mfma_f32_16x16x32_bf16 v[40:43], v[176:179], v[184:187], v[40:43]
	v_mfma_f32_16x16x32_bf16 v[32:35], v[168:171], v[192:195], v[32:35]
	v_mfma_f32_16x16x32_bf16 v[24:27], v[176:179], v[192:195], v[24:27]
	v_mfma_f32_16x16x32_bf16 v[16:19], v[168:171], v[200:203], v[16:19]
	v_mfma_f32_16x16x32_bf16 v[8:11], v[176:179], v[200:203], v[8:11]
	v_mfma_f32_16x16x32_bf16 v[4:7], v[168:171], v[208:211], v[4:7]
	v_mfma_f32_16x16x32_bf16 v[0:3], v[176:179], v[208:211], v[0:3]
	v_mfma_f32_16x16x32_bf16 v[48:51], v[172:175], v[188:191], v[48:51]
	v_mfma_f32_16x16x32_bf16 v[40:43], v[180:183], v[188:191], v[40:43]
	v_mfma_f32_16x16x32_bf16 v[32:35], v[172:175], v[196:199], v[32:35]
	v_mfma_f32_16x16x32_bf16 v[24:27], v[180:183], v[196:199], v[24:27]
	v_mfma_f32_16x16x32_bf16 v[16:19], v[172:175], v[204:207], v[16:19]
	v_mfma_f32_16x16x32_bf16 v[8:11], v[180:183], v[204:207], v[8:11]
	v_mfma_f32_16x16x32_bf16 v[4:7], v[172:175], v[212:215], v[4:7]
	v_mfma_f32_16x16x32_bf16 v[0:3], v[180:183], v[212:215], v[0:3]
	s_setprio 0
	s_barrier
	s_add_u32 s46, s46, 0x100
	s_addc_u32 s47, s47, 0
	s_add_u32 s84, s84, 0x100
	s_addc_u32 s85, s85, 0
	s_cmp_ge_u32 s86, s82
	s_mov_b32 s48, s86
	s_cbranch_scc0 .LBB0_340
	s_and_b64 vcc, exec, s[12:13]
	s_cbranch_vccz .LBB0_343
	s_barrier

.LBB0_416:
	ds_read_b128 v[152:155], v149
	ds_read_b128 v[156:159], v149 offset:1024
	ds_read_b128 v[160:163], v149 offset:2048
	ds_read_b128 v[164:167], v149 offset:3072
	ds_read_b128 v[168:171], v150
	ds_read_b128 v[172:175], v150 offset:1024
	ds_read_b128 v[176:179], v150 offset:2048
	ds_read_b128 v[180:183], v150 offset:3072
	s_add_u32 s34, s30, 0xfffc0080
	s_addc_u32 s35, s31, -1
	s_cmp_eq_u32 s62, 12
	s_cselect_b32 s37, s23, s35
	s_cselect_b32 s36, s58, s34
	s_cselect_b32 s35, s21, s61
	s_cselect_b32 s34, s59, s60
	v_lshl_add_u64 v[144:145], s[30:31], 0, v[136:137]
	s_add_i32 m0, s29, 0xc000
	ds_read_b128 v[184:187], v151
	ds_read_b128 v[188:191], v151 offset:1024
	ds_read_b128 v[192:195], v151 offset:2048
	ds_read_b128 v[196:199], v151 offset:3072
	ds_read_b128 v[200:203], v151 offset:4096
	ds_read_b128 v[204:207], v151 offset:5120
	ds_read_b128 v[208:211], v151 offset:6144
	ds_read_b128 v[212:215], v151 offset:7168
	global_load_lds_dwordx4 v[144:145], off
	v_lshl_add_u64 v[144:145], s[30:31], 0, v[138:139]
	s_add_i32 m0, s29, 0xe000
	s_nop 0
	global_load_lds_dwordx4 v[144:145], off
	s_waitcnt vmcnt(8)
	s_waitcnt lgkmcnt(0)
	s_barrier
	s_setprio 1
	v_mfma_f32_16x16x32_bf16 v[124:127], v[152:155], v[184:187], v[124:127]
	v_mfma_f32_16x16x32_bf16 v[120:123], v[160:163], v[184:187], v[120:123]
	v_mfma_f32_16x16x32_bf16 v[116:119], v[152:155], v[192:195], v[116:119]
	v_mfma_f32_16x16x32_bf16 v[108:111], v[160:163], v[192:195], v[108:111]
	v_mfma_f32_16x16x32_bf16 v[100:103], v[152:155], v[200:203], v[100:103]
	v_mfma_f32_16x16x32_bf16 v[92:95], v[160:163], v[200:203], v[92:95]
	v_mfma_f32_16x16x32_bf16 v[84:87], v[152:155], v[208:211], v[84:87]
	v_mfma_f32_16x16x32_bf16 v[76:79], v[160:163], v[208:211], v[76:79]
	v_mfma_f32_16x16x32_bf16 v[124:127], v[156:159], v[188:191], v[124:127]
	v_mfma_f32_16x16x32_bf16 v[120:123], v[164:167], v[188:191], v[120:123]
	v_mfma_f32_16x16x32_bf16 v[116:119], v[156:159], v[196:199], v[116:119]
	v_mfma_f32_16x16x32_bf16 v[108:111], v[164:167], v[196:199], v[108:111]
	v_mfma_f32_16x16x32_bf16 v[100:103], v[156:159], v[204:207], v[100:103]
	v_mfma_f32_16x16x32_bf16 v[92:95], v[164:167], v[204:207], v[92:95]
	v_mfma_f32_16x16x32_bf16 v[84:87], v[156:159], v[212:215], v[84:87]
	v_mfma_f32_16x16x32_bf16 v[76:79], v[164:167], v[212:215], v[76:79]
	s_setprio 0
	s_setprio 1
	v_mfma_f32_16x16x32_bf16 v[112:115], v[168:171], v[184:187], v[112:115]
	v_mfma_f32_16x16x32_bf16 v[104:107], v[176:179], v[184:187], v[104:107]
	v_mfma_f32_16x16x32_bf16 v[96:99], v[168:171], v[192:195], v[96:99]
	v_mfma_f32_16x16x32_bf16 v[88:91], v[176:179], v[192:195], v[88:91]
	v_mfma_f32_16x16x32_bf16 v[80:83], v[168:171], v[200:203], v[80:83]
	v_mfma_f32_16x16x32_bf16 v[72:75], v[176:179], v[200:203], v[72:75]
	v_mfma_f32_16x16x32_bf16 v[68:71], v[168:171], v[208:211], v[68:71]
	v_mfma_f32_16x16x32_bf16 v[64:67], v[176:179], v[208:211], v[64:67]
	v_mfma_f32_16x16x32_bf16 v[112:115], v[172:175], v[188:191], v[112:115]
	v_mfma_f32_16x16x32_bf16 v[104:107], v[180:183], v[188:191], v[104:107]
	v_mfma_f32_16x16x32_bf16 v[96:99], v[172:175], v[196:199], v[96:99]
	v_mfma_f32_16x16x32_bf16 v[88:91], v[180:183], v[196:199], v[88:91]
	v_mfma_f32_16x16x32_bf16 v[80:83], v[172:175], v[204:207], v[80:83]
	v_mfma_f32_16x16x32_bf16 v[72:75], v[180:183], v[204:207], v[72:75]
	v_mfma_f32_16x16x32_bf16 v[68:71], v[172:175], v[212:215], v[68:71]
	v_mfma_f32_16x16x32_bf16 v[64:67], v[180:183], v[212:215], v[64:67]
	s_setprio 0
	s_barrier
	s_add_i32 s63, s51, s43
	v_lshl_add_u64 v[144:145], s[34:35], 0, v[130:131]
	s_mov_b32 m0, s63
	ds_read_b128 v[184:187], v151 offset:16384
	ds_read_b128 v[188:191], v151 offset:17408
	ds_read_b128 v[192:195], v151 offset:18432
	ds_read_b128 v[196:199], v151 offset:19456
	ds_read_b128 v[200:203], v151 offset:20480
	ds_read_b128 v[204:207], v151 offset:21504
	ds_read_b128 v[208:211], v151 offset:22528
	ds_read_b128 v[212:215], v151 offset:23552
	global_load_lds_dwordx4 v[144:145], off
	s_add_i32 m0, s63, 0x2000
	s_add_u32 s64, s34, 0x40000
	v_lshl_add_u64 v[216:217], s[34:35], 0, v[134:135]
	s_addc_u32 s65, s35, 0
	s_add_i32 s63, s52, s43
	global_load_lds_dwordx4 v[216:217], off
	v_lshl_add_u64 v[218:219], s[64:65], 0, v[130:131]
	s_mov_b32 m0, s63
	v_lshl_add_u64 v[220:221], s[36:37], 0, v[132:133]
	global_load_lds_dwordx4 v[218:219], off
	v_lshl_add_u64 v[218:219], s[64:65], 0, v[134:135]
	s_add_i32 m0, s63, 0x2000
	s_nop 0
	global_load_lds_dwordx4 v[218:219], off
	v_lshl_add_u64 v[218:219], s[36:37], 0, v[128:129]
	s_mov_b32 m0, s29
	s_nop 0
	global_load_lds_dwordx4 v[218:219], off
	s_mov_b32 m0, s44
	s_nop 0
	global_load_lds_dwordx4 v[220:221], off
	s_waitcnt vmcnt(8)
	s_waitcnt lgkmcnt(0)
	s_barrier
	s_setprio 1
	v_mfma_f32_16x16x32_bf16 v[60:63], v[152:155], v[184:187], v[60:63]
	v_mfma_f32_16x16x32_bf16 v[56:59], v[160:163], v[184:187], v[56:59]
	v_mfma_f32_16x16x32_bf16 v[52:55], v[152:155], v[192:195], v[52:55]
	v_mfma_f32_16x16x32_bf16 v[44:47], v[160:163], v[192:195], v[44:47]
	v_mfma_f32_16x16x32_bf16 v[36:39], v[152:155], v[200:203], v[36:39]
	v_mfma_f32_16x16x32_bf16 v[28:31], v[160:163], v[200:203], v[28:31]
	v_mfma_f32_16x16x32_bf16 v[20:23], v[152:155], v[208:211], v[20:23]
	v_mfma_f32_16x16x32_bf16 v[12:15], v[160:163], v[208:211], v[12:15]
	v_mfma_f32_16x16x32_bf16 v[60:63], v[156:159], v[188:191], v[60:63]
	v_mfma_f32_16x16x32_bf16 v[56:59], v[164:167], v[188:191], v[56:59]
	v_mfma_f32_16x16x32_bf16 v[52:55], v[156:159], v[196:199], v[52:55]
	v_mfma_f32_16x16x32_bf16 v[44:47], v[164:167], v[196:199], v[44:47]
	v_mfma_f32_16x16x32_bf16 v[36:39], v[156:159], v[204:207], v[36:39]
	v_mfma_f32_16x16x32_bf16 v[28:31], v[164:167], v[204:207], v[28:31]
	v_mfma_f32_16x16x32_bf16 v[20:23], v[156:159], v[212:215], v[20:23]
	v_mfma_f32_16x16x32_bf16 v[12:15], v[164:167], v[212:215], v[12:15]
	s_setprio 0
	s_setprio 1
	v_mfma_f32_16x16x32_bf16 v[48:51], v[168:171], v[184:187], v[48:51]
	v_mfma_f32_16x16x32_bf16 v[40:43], v[176:179], v[184:187], v[40:43]
	v_mfma_f32_16x16x32_bf16 v[32:35], v[168:171], v[192:195], v[32:35]
	v_mfma_f32_16x16x32_bf16 v[24:27], v[176:179], v[192:195], v[24:27]
	v_mfma_f32_16x16x32_bf16 v[16:19], v[168:171], v[200:203], v[16:19]
	v_mfma_f32_16x16x32_bf16 v[8:11], v[176:179], v[200:203], v[8:11]
	v_mfma_f32_16x16x32_bf16 v[4:7], v[168:171], v[208:211], v[4:7]
	v_mfma_f32_16x16x32_bf16 v[0:3], v[176:179], v[208:211], v[0:3]
	v_mfma_f32_16x16x32_bf16 v[48:51], v[172:175], v[188:191], v[48:51]
	v_mfma_f32_16x16x32_bf16 v[40:43], v[180:183], v[188:191], v[40:43]
	v_mfma_f32_16x16x32_bf16 v[32:35], v[172:175], v[196:199], v[32:35]
	v_mfma_f32_16x16x32_bf16 v[24:27], v[180:183], v[196:199], v[24:27]
	v_mfma_f32_16x16x32_bf16 v[16:19], v[172:175], v[204:207], v[16:19]
	v_mfma_f32_16x16x32_bf16 v[8:11], v[180:183], v[204:207], v[8:11]
	v_mfma_f32_16x16x32_bf16 v[4:7], v[172:175], v[212:215], v[4:7]
	v_mfma_f32_16x16x32_bf16 v[0:3], v[180:183], v[212:215], v[0:3]
	s_setprio 0
	s_barrier
	s_add_i32 s63, 0, 0x18000
	s_add_i32 s64, 0, 0x1c000
	v_add_u32_e32 v164, s63, v147
	v_add_u32_e32 v180, s64, v147
	ds_read_b128 v[152:155], v164
	ds_read_b128 v[156:159], v164 offset:1024
	ds_read_b128 v[160:163], v164 offset:2048
	ds_read_b128 v[164:167], v164 offset:3072
	ds_read_b128 v[168:171], v180
	ds_read_b128 v[172:175], v180 offset:1024
	ds_read_b128 v[176:179], v180 offset:2048
	ds_read_b128 v[180:183], v180 offset:3072
	s_add_u32 s36, s36, 0x40000
	s_addc_u32 s37, s37, 0
	s_mov_b32 m0, s45
	v_lshl_add_u64 v[222:223], s[36:37], 0, v[128:129]
	ds_read_b128 v[184:187], v151 offset:32768
	ds_read_b128 v[188:191], v151 offset:33792
	ds_read_b128 v[192:195], v151 offset:34816
	ds_read_b128 v[196:199], v151 offset:35840
	ds_read_b128 v[200:203], v151 offset:36864
	ds_read_b128 v[204:207], v151 offset:37888
	ds_read_b128 v[208:211], v151 offset:38912
	ds_read_b128 v[212:215], v151 offset:39936
	global_load_lds_dwordx4 v[222:223], off
	v_lshl_add_u64 v[222:223], s[36:37], 0, v[132:133]
	s_mov_b32 m0, s46
	s_nop 0
	global_load_lds_dwordx4 v[222:223], off
	s_waitcnt vmcnt(8)
	s_waitcnt lgkmcnt(0)
	s_barrier
	s_setprio 1
	v_mfma_f32_16x16x32_bf16 v[124:127], v[152:155], v[184:187], v[124:127]
	v_mfma_f32_16x16x32_bf16 v[120:123], v[160:163], v[184:187], v[120:123]
	v_mfma_f32_16x16x32_bf16 v[116:119], v[152:155], v[192:195], v[116:119]
	v_mfma_f32_16x16x32_bf16 v[108:111], v[160:163], v[192:195], v[108:111]
	v_mfma_f32_16x16x32_bf16 v[100:103], v[152:155], v[200:203], v[100:103]
	v_mfma_f32_16x16x32_bf16 v[92:95], v[160:163], v[200:203], v[92:95]
	v_mfma_f32_16x16x32_bf16 v[84:87], v[152:155], v[208:211], v[84:87]
	v_mfma_f32_16x16x32_bf16 v[76:79], v[160:163], v[208:211], v[76:79]
	v_mfma_f32_16x16x32_bf16 v[124:127], v[156:159], v[188:191], v[124:127]
	v_mfma_f32_16x16x32_bf16 v[120:123], v[164:167], v[188:191], v[120:123]
	v_mfma_f32_16x16x32_bf16 v[116:119], v[156:159], v[196:199], v[116:119]
	v_mfma_f32_16x16x32_bf16 v[108:111], v[164:167], v[196:199], v[108:111]
	v_mfma_f32_16x16x32_bf16 v[100:103], v[156:159], v[204:207], v[100:103]
	v_mfma_f32_16x16x32_bf16 v[92:95], v[164:167], v[204:207], v[92:95]
	v_mfma_f32_16x16x32_bf16 v[84:87], v[156:159], v[212:215], v[84:87]
	v_mfma_f32_16x16x32_bf16 v[76:79], v[164:167], v[212:215], v[76:79]
	s_setprio 0
	s_setprio 1
	v_mfma_f32_16x16x32_bf16 v[112:115], v[168:171], v[184:187], v[112:115]
	v_mfma_f32_16x16x32_bf16 v[104:107], v[176:179], v[184:187], v[104:107]
	v_mfma_f32_16x16x32_bf16 v[96:99], v[168:171], v[192:195], v[96:99]
	v_mfma_f32_16x16x32_bf16 v[88:91], v[176:179], v[192:195], v[88:91]
	v_mfma_f32_16x16x32_bf16 v[80:83], v[168:171], v[200:203], v[80:83]
	v_mfma_f32_16x16x32_bf16 v[72:75], v[176:179], v[200:203], v[72:75]
	v_mfma_f32_16x16x32_bf16 v[68:71], v[168:171], v[208:211], v[68:71]
	v_mfma_f32_16x16x32_bf16 v[64:67], v[176:179], v[208:211], v[64:67]
	v_mfma_f32_16x16x32_bf16 v[112:115], v[172:175], v[188:191], v[112:115]
	v_mfma_f32_16x16x32_bf16 v[104:107], v[180:183], v[188:191], v[104:107]
	v_mfma_f32_16x16x32_bf16 v[96:99], v[172:175], v[196:199], v[96:99]
	v_mfma_f32_16x16x32_bf16 v[88:91], v[180:183], v[196:199], v[88:91]
	v_mfma_f32_16x16x32_bf16 v[80:83], v[172:175], v[204:207], v[80:83]
	v_mfma_f32_16x16x32_bf16 v[72:75], v[180:183], v[204:207], v[72:75]
	v_mfma_f32_16x16x32_bf16 v[68:71], v[172:175], v[212:215], v[68:71]
	v_mfma_f32_16x16x32_bf16 v[64:67], v[180:183], v[212:215], v[64:67]
	s_setprio 0
	s_barrier
	s_add_i32 s36, s63, s43
	v_lshl_add_u64 v[144:145], v[144:145], 0, s[10:11]
	s_mov_b32 m0, s36
	ds_read_b128 v[184:187], v151 offset:49152
	ds_read_b128 v[188:191], v151 offset:50176
	ds_read_b128 v[192:195], v151 offset:51200
	ds_read_b128 v[196:199], v151 offset:52224
	ds_read_b128 v[200:203], v151 offset:53248
	ds_read_b128 v[204:207], v151 offset:54272
	ds_read_b128 v[208:211], v151 offset:55296
	ds_read_b128 v[212:215], v151 offset:56320
	global_load_lds_dwordx4 v[144:145], off
	s_add_i32 m0, s36, 0x2000
	s_add_u32 s34, s34, 0x40080
	v_lshl_add_u64 v[144:145], v[216:217], 0, s[10:11]
	s_addc_u32 s35, s35, 0
	s_add_i32 s36, s64, s43
	global_load_lds_dwordx4 v[144:145], off
	v_lshl_add_u64 v[144:145], s[34:35], 0, v[130:131]
	s_mov_b32 m0, s36
	s_nop 0
	global_load_lds_dwordx4 v[144:145], off
	v_lshl_add_u64 v[144:145], s[34:35], 0, v[134:135]
	s_add_i32 m0, s36, 0x2000
	s_nop 0
	global_load_lds_dwordx4 v[144:145], off
	v_lshl_add_u64 v[144:145], v[218:219], 0, s[10:11]
	s_mov_b32 m0, s48
	s_nop 0
	global_load_lds_dwordx4 v[144:145], off
	v_lshl_add_u64 v[144:145], v[220:221], 0, s[10:11]
	s_mov_b32 m0, s49
	s_nop 0
	global_load_lds_dwordx4 v[144:145], off
	s_waitcnt vmcnt(8)
	s_waitcnt lgkmcnt(0)
	s_barrier
	s_setprio 1
	v_mfma_f32_16x16x32_bf16 v[60:63], v[152:155], v[184:187], v[60:63]
	v_mfma_f32_16x16x32_bf16 v[56:59], v[160:163], v[184:187], v[56:59]
	v_mfma_f32_16x16x32_bf16 v[52:55], v[152:155], v[192:195], v[52:55]
	v_mfma_f32_16x16x32_bf16 v[44:47], v[160:163], v[192:195], v[44:47]
	v_mfma_f32_16x16x32_bf16 v[36:39], v[152:155], v[200:203], v[36:39]
	v_mfma_f32_16x16x32_bf16 v[28:31], v[160:163], v[200:203], v[28:31]
	v_mfma_f32_16x16x32_bf16 v[20:23], v[152:155], v[208:211], v[20:23]
	v_mfma_f32_16x16x32_bf16 v[12:15], v[160:163], v[208:211], v[12:15]
	v_mfma_f32_16x16x32_bf16 v[60:63], v[156:159], v[188:191], v[60:63]
	v_mfma_f32_16x16x32_bf16 v[56:59], v[164:167], v[188:191], v[56:59]
	v_mfma_f32_16x16x32_bf16 v[52:55], v[156:159], v[196:199], v[52:55]
	v_mfma_f32_16x16x32_bf16 v[44:47], v[164:167], v[196:199], v[44:47]
	v_mfma_f32_16x16x32_bf16 v[36:39], v[156:159], v[204:207], v[36:39]
	v_mfma_f32_16x16x32_bf16 v[28:31], v[164:167], v[204:207], v[28:31]
	v_mfma_f32_16x16x32_bf16 v[20:23], v[156:159], v[212:215], v[20:23]
	v_mfma_f32_16x16x32_bf16 v[12:15], v[164:167], v[212:215], v[12:15]
	s_setprio 0
	s_setprio 1
	v_mfma_f32_16x16x32_bf16 v[48:51], v[168:171], v[184:187], v[48:51]
	v_mfma_f32_16x16x32_bf16 v[40:43], v[176:179], v[184:187], v[40:43]
	v_mfma_f32_16x16x32_bf16 v[32:35], v[168:171], v[192:195], v[32:35]
	v_mfma_f32_16x16x32_bf16 v[24:27], v[176:179], v[192:195], v[24:27]
	v_mfma_f32_16x16x32_bf16 v[16:19], v[168:171], v[200:203], v[16:19]
	v_mfma_f32_16x16x32_bf16 v[8:11], v[176:179], v[200:203], v[8:11]
	v_mfma_f32_16x16x32_bf16 v[4:7], v[168:171], v[208:211], v[4:7]
	v_mfma_f32_16x16x32_bf16 v[0:3], v[176:179], v[208:211], v[0:3]
	v_mfma_f32_16x16x32_bf16 v[48:51], v[172:175], v[188:191], v[48:51]
	v_mfma_f32_16x16x32_bf16 v[40:43], v[180:183], v[188:191], v[40:43]
	v_mfma_f32_16x16x32_bf16 v[32:35], v[172:175], v[196:199], v[32:35]
	v_mfma_f32_16x16x32_bf16 v[24:27], v[180:183], v[196:199], v[24:27]
	v_mfma_f32_16x16x32_bf16 v[16:19], v[172:175], v[204:207], v[16:19]
	v_mfma_f32_16x16x32_bf16 v[8:11], v[180:183], v[204:207], v[8:11]
	v_mfma_f32_16x16x32_bf16 v[4:7], v[172:175], v[212:215], v[4:7]
	v_mfma_f32_16x16x32_bf16 v[0:3], v[180:183], v[212:215], v[0:3]
	s_setprio 0
	s_barrier
	s_add_i32 s62, s62, 2
	s_add_u32 s30, s30, 0x100
	s_addc_u32 s31, s31, 0
	s_add_u32 s60, s60, 0x100
	s_addc_u32 s61, s61, 0
	s_cmp_gt_u32 s62, 13
	s_cbranch_scc0 .LBB0_416
	s_and_b64 vcc, exec, s[12:13]
	s_cbranch_vccz .LBB0_419
	s_barrier

.LBB0_440:
	ds_read_b128 v[152:155], v149
	ds_read_b128 v[156:159], v149 offset:1024
	ds_read_b128 v[160:163], v149 offset:2048
	ds_read_b128 v[164:167], v149 offset:3072
	ds_read_b128 v[168:171], v150
	ds_read_b128 v[172:175], v150 offset:1024
	ds_read_b128 v[176:179], v150 offset:2048
	ds_read_b128 v[180:183], v150 offset:3072
	s_add_u32 s30, s28, 0xfffc0080
	s_addc_u32 s31, s29, -1
	s_cmp_eq_u32 s60, 12
	s_cselect_b32 s35, s21, s31
	s_cselect_b32 s34, s56, s30
	s_cselect_b32 s31, s19, s59
	s_cselect_b32 s30, s57, s58
	v_lshl_add_u64 v[144:145], s[28:29], 0, v[136:137]
	s_add_i32 m0, s27, 0xc000
	ds_read_b128 v[184:187], v151
	ds_read_b128 v[188:191], v151 offset:1024
	ds_read_b128 v[192:195], v151 offset:2048
	ds_read_b128 v[196:199], v151 offset:3072
	ds_read_b128 v[200:203], v151 offset:4096
	ds_read_b128 v[204:207], v151 offset:5120
	ds_read_b128 v[208:211], v151 offset:6144
	ds_read_b128 v[212:215], v151 offset:7168
	global_load_lds_dwordx4 v[144:145], off
	v_lshl_add_u64 v[144:145], s[28:29], 0, v[138:139]
	s_add_i32 m0, s27, 0xe000
	s_nop 0
	global_load_lds_dwordx4 v[144:145], off
	s_waitcnt vmcnt(8)
	s_waitcnt lgkmcnt(0)
	s_barrier
	s_setprio 1
	v_mfma_f32_16x16x32_bf16 v[124:127], v[152:155], v[184:187], v[124:127]
	v_mfma_f32_16x16x32_bf16 v[120:123], v[160:163], v[184:187], v[120:123]
	v_mfma_f32_16x16x32_bf16 v[116:119], v[152:155], v[192:195], v[116:119]
	v_mfma_f32_16x16x32_bf16 v[108:111], v[160:163], v[192:195], v[108:111]
	v_mfma_f32_16x16x32_bf16 v[100:103], v[152:155], v[200:203], v[100:103]
	v_mfma_f32_16x16x32_bf16 v[92:95], v[160:163], v[200:203], v[92:95]
	v_mfma_f32_16x16x32_bf16 v[84:87], v[152:155], v[208:211], v[84:87]
	v_mfma_f32_16x16x32_bf16 v[76:79], v[160:163], v[208:211], v[76:79]
	v_mfma_f32_16x16x32_bf16 v[124:127], v[156:159], v[188:191], v[124:127]
	v_mfma_f32_16x16x32_bf16 v[120:123], v[164:167], v[188:191], v[120:123]
	v_mfma_f32_16x16x32_bf16 v[116:119], v[156:159], v[196:199], v[116:119]
	v_mfma_f32_16x16x32_bf16 v[108:111], v[164:167], v[196:199], v[108:111]
	v_mfma_f32_16x16x32_bf16 v[100:103], v[156:159], v[204:207], v[100:103]
	v_mfma_f32_16x16x32_bf16 v[92:95], v[164:167], v[204:207], v[92:95]
	v_mfma_f32_16x16x32_bf16 v[84:87], v[156:159], v[212:215], v[84:87]
	v_mfma_f32_16x16x32_bf16 v[76:79], v[164:167], v[212:215], v[76:79]
	s_setprio 0
	s_setprio 1
	v_mfma_f32_16x16x32_bf16 v[112:115], v[168:171], v[184:187], v[112:115]
	v_mfma_f32_16x16x32_bf16 v[104:107], v[176:179], v[184:187], v[104:107]
	v_mfma_f32_16x16x32_bf16 v[96:99], v[168:171], v[192:195], v[96:99]
	v_mfma_f32_16x16x32_bf16 v[88:91], v[176:179], v[192:195], v[88:91]
	v_mfma_f32_16x16x32_bf16 v[80:83], v[168:171], v[200:203], v[80:83]
	v_mfma_f32_16x16x32_bf16 v[72:75], v[176:179], v[200:203], v[72:75]
	v_mfma_f32_16x16x32_bf16 v[68:71], v[168:171], v[208:211], v[68:71]
	v_mfma_f32_16x16x32_bf16 v[64:67], v[176:179], v[208:211], v[64:67]
	v_mfma_f32_16x16x32_bf16 v[112:115], v[172:175], v[188:191], v[112:115]
	v_mfma_f32_16x16x32_bf16 v[104:107], v[180:183], v[188:191], v[104:107]
	v_mfma_f32_16x16x32_bf16 v[96:99], v[172:175], v[196:199], v[96:99]
	v_mfma_f32_16x16x32_bf16 v[88:91], v[180:183], v[196:199], v[88:91]
	v_mfma_f32_16x16x32_bf16 v[80:83], v[172:175], v[204:207], v[80:83]
	v_mfma_f32_16x16x32_bf16 v[72:75], v[180:183], v[204:207], v[72:75]
	v_mfma_f32_16x16x32_bf16 v[68:71], v[172:175], v[212:215], v[68:71]
	v_mfma_f32_16x16x32_bf16 v[64:67], v[180:183], v[212:215], v[64:67]
	s_setprio 0
	s_barrier
	s_add_i32 s61, s49, s41
	v_lshl_add_u64 v[144:145], s[30:31], 0, v[130:131]
	s_mov_b32 m0, s61
	ds_read_b128 v[184:187], v151 offset:16384
	ds_read_b128 v[188:191], v151 offset:17408
	ds_read_b128 v[192:195], v151 offset:18432
	ds_read_b128 v[196:199], v151 offset:19456
	ds_read_b128 v[200:203], v151 offset:20480
	ds_read_b128 v[204:207], v151 offset:21504
	ds_read_b128 v[208:211], v151 offset:22528
	ds_read_b128 v[212:215], v151 offset:23552
	global_load_lds_dwordx4 v[144:145], off
	s_add_i32 m0, s61, 0x2000
	s_add_u32 s62, s30, 0x40000
	v_lshl_add_u64 v[216:217], s[30:31], 0, v[134:135]
	s_addc_u32 s63, s31, 0
	s_add_i32 s61, s50, s41
	global_load_lds_dwordx4 v[216:217], off
	v_lshl_add_u64 v[218:219], s[62:63], 0, v[130:131]
	s_mov_b32 m0, s61
	v_lshl_add_u64 v[220:221], s[34:35], 0, v[132:133]
	global_load_lds_dwordx4 v[218:219], off
	v_lshl_add_u64 v[218:219], s[62:63], 0, v[134:135]
	s_add_i32 m0, s61, 0x2000
	s_nop 0
	global_load_lds_dwordx4 v[218:219], off
	v_lshl_add_u64 v[218:219], s[34:35], 0, v[128:129]
	s_mov_b32 m0, s27
	s_nop 0
	global_load_lds_dwordx4 v[218:219], off
	s_mov_b32 m0, s42
	s_nop 0
	global_load_lds_dwordx4 v[220:221], off
	s_waitcnt vmcnt(8)
	s_waitcnt lgkmcnt(0)
	s_barrier
	s_setprio 1
	v_mfma_f32_16x16x32_bf16 v[60:63], v[152:155], v[184:187], v[60:63]
	v_mfma_f32_16x16x32_bf16 v[56:59], v[160:163], v[184:187], v[56:59]
	v_mfma_f32_16x16x32_bf16 v[52:55], v[152:155], v[192:195], v[52:55]
	v_mfma_f32_16x16x32_bf16 v[44:47], v[160:163], v[192:195], v[44:47]
	v_mfma_f32_16x16x32_bf16 v[36:39], v[152:155], v[200:203], v[36:39]
	v_mfma_f32_16x16x32_bf16 v[28:31], v[160:163], v[200:203], v[28:31]
	v_mfma_f32_16x16x32_bf16 v[20:23], v[152:155], v[208:211], v[20:23]
	v_mfma_f32_16x16x32_bf16 v[12:15], v[160:163], v[208:211], v[12:15]
	v_mfma_f32_16x16x32_bf16 v[60:63], v[156:159], v[188:191], v[60:63]
	v_mfma_f32_16x16x32_bf16 v[56:59], v[164:167], v[188:191], v[56:59]
	v_mfma_f32_16x16x32_bf16 v[52:55], v[156:159], v[196:199], v[52:55]
	v_mfma_f32_16x16x32_bf16 v[44:47], v[164:167], v[196:199], v[44:47]
	v_mfma_f32_16x16x32_bf16 v[36:39], v[156:159], v[204:207], v[36:39]
	v_mfma_f32_16x16x32_bf16 v[28:31], v[164:167], v[204:207], v[28:31]
	v_mfma_f32_16x16x32_bf16 v[20:23], v[156:159], v[212:215], v[20:23]
	v_mfma_f32_16x16x32_bf16 v[12:15], v[164:167], v[212:215], v[12:15]
	s_setprio 0
	s_setprio 1
	v_mfma_f32_16x16x32_bf16 v[48:51], v[168:171], v[184:187], v[48:51]
	v_mfma_f32_16x16x32_bf16 v[40:43], v[176:179], v[184:187], v[40:43]
	v_mfma_f32_16x16x32_bf16 v[32:35], v[168:171], v[192:195], v[32:35]
	v_mfma_f32_16x16x32_bf16 v[24:27], v[176:179], v[192:195], v[24:27]
	v_mfma_f32_16x16x32_bf16 v[16:19], v[168:171], v[200:203], v[16:19]
	v_mfma_f32_16x16x32_bf16 v[8:11], v[176:179], v[200:203], v[8:11]
	v_mfma_f32_16x16x32_bf16 v[4:7], v[168:171], v[208:211], v[4:7]
	v_mfma_f32_16x16x32_bf16 v[0:3], v[176:179], v[208:211], v[0:3]
	v_mfma_f32_16x16x32_bf16 v[48:51], v[172:175], v[188:191], v[48:51]
	v_mfma_f32_16x16x32_bf16 v[40:43], v[180:183], v[188:191], v[40:43]
	v_mfma_f32_16x16x32_bf16 v[32:35], v[172:175], v[196:199], v[32:35]
	v_mfma_f32_16x16x32_bf16 v[24:27], v[180:183], v[196:199], v[24:27]
	v_mfma_f32_16x16x32_bf16 v[16:19], v[172:175], v[204:207], v[16:19]
	v_mfma_f32_16x16x32_bf16 v[8:11], v[180:183], v[204:207], v[8:11]
	v_mfma_f32_16x16x32_bf16 v[4:7], v[172:175], v[212:215], v[4:7]
	v_mfma_f32_16x16x32_bf16 v[0:3], v[180:183], v[212:215], v[0:3]
	s_setprio 0
	s_barrier
	s_add_i32 s61, 0, 0x18000
	s_add_i32 s62, 0, 0x1c000
	v_add_u32_e32 v164, s61, v147
	v_add_u32_e32 v180, s62, v147
	ds_read_b128 v[152:155], v164
	ds_read_b128 v[156:159], v164 offset:1024
	ds_read_b128 v[160:163], v164 offset:2048
	ds_read_b128 v[164:167], v164 offset:3072
	ds_read_b128 v[168:171], v180
	ds_read_b128 v[172:175], v180 offset:1024
	ds_read_b128 v[176:179], v180 offset:2048
	ds_read_b128 v[180:183], v180 offset:3072
	s_add_u32 s34, s34, 0x40000
	s_addc_u32 s35, s35, 0
	s_mov_b32 m0, s43
	v_lshl_add_u64 v[222:223], s[34:35], 0, v[128:129]
	ds_read_b128 v[184:187], v151 offset:32768
	ds_read_b128 v[188:191], v151 offset:33792
	ds_read_b128 v[192:195], v151 offset:34816
	ds_read_b128 v[196:199], v151 offset:35840
	ds_read_b128 v[200:203], v151 offset:36864
	ds_read_b128 v[204:207], v151 offset:37888
	ds_read_b128 v[208:211], v151 offset:38912
	ds_read_b128 v[212:215], v151 offset:39936
	global_load_lds_dwordx4 v[222:223], off
	v_lshl_add_u64 v[222:223], s[34:35], 0, v[132:133]
	s_mov_b32 m0, s44
	s_nop 0
	global_load_lds_dwordx4 v[222:223], off
	s_waitcnt vmcnt(8)
	s_waitcnt lgkmcnt(0)
	s_barrier
	s_setprio 1
	v_mfma_f32_16x16x32_bf16 v[124:127], v[152:155], v[184:187], v[124:127]
	v_mfma_f32_16x16x32_bf16 v[120:123], v[160:163], v[184:187], v[120:123]
	v_mfma_f32_16x16x32_bf16 v[116:119], v[152:155], v[192:195], v[116:119]
	v_mfma_f32_16x16x32_bf16 v[108:111], v[160:163], v[192:195], v[108:111]
	v_mfma_f32_16x16x32_bf16 v[100:103], v[152:155], v[200:203], v[100:103]
	v_mfma_f32_16x16x32_bf16 v[92:95], v[160:163], v[200:203], v[92:95]
	v_mfma_f32_16x16x32_bf16 v[84:87], v[152:155], v[208:211], v[84:87]
	v_mfma_f32_16x16x32_bf16 v[76:79], v[160:163], v[208:211], v[76:79]
	v_mfma_f32_16x16x32_bf16 v[124:127], v[156:159], v[188:191], v[124:127]
	v_mfma_f32_16x16x32_bf16 v[120:123], v[164:167], v[188:191], v[120:123]
	v_mfma_f32_16x16x32_bf16 v[116:119], v[156:159], v[196:199], v[116:119]
	v_mfma_f32_16x16x32_bf16 v[108:111], v[164:167], v[196:199], v[108:111]
	v_mfma_f32_16x16x32_bf16 v[100:103], v[156:159], v[204:207], v[100:103]
	v_mfma_f32_16x16x32_bf16 v[92:95], v[164:167], v[204:207], v[92:95]
	v_mfma_f32_16x16x32_bf16 v[84:87], v[156:159], v[212:215], v[84:87]
	v_mfma_f32_16x16x32_bf16 v[76:79], v[164:167], v[212:215], v[76:79]
	s_setprio 0
	s_setprio 1
	v_mfma_f32_16x16x32_bf16 v[112:115], v[168:171], v[184:187], v[112:115]
	v_mfma_f32_16x16x32_bf16 v[104:107], v[176:179], v[184:187], v[104:107]
	v_mfma_f32_16x16x32_bf16 v[96:99], v[168:171], v[192:195], v[96:99]
	v_mfma_f32_16x16x32_bf16 v[88:91], v[176:179], v[192:195], v[88:91]
	v_mfma_f32_16x16x32_bf16 v[80:83], v[168:171], v[200:203], v[80:83]
	v_mfma_f32_16x16x32_bf16 v[72:75], v[176:179], v[200:203], v[72:75]
	v_mfma_f32_16x16x32_bf16 v[68:71], v[168:171], v[208:211], v[68:71]
	v_mfma_f32_16x16x32_bf16 v[64:67], v[176:179], v[208:211], v[64:67]
	v_mfma_f32_16x16x32_bf16 v[112:115], v[172:175], v[188:191], v[112:115]
	v_mfma_f32_16x16x32_bf16 v[104:107], v[180:183], v[188:191], v[104:107]
	v_mfma_f32_16x16x32_bf16 v[96:99], v[172:175], v[196:199], v[96:99]
	v_mfma_f32_16x16x32_bf16 v[88:91], v[180:183], v[196:199], v[88:91]
	v_mfma_f32_16x16x32_bf16 v[80:83], v[172:175], v[204:207], v[80:83]
	v_mfma_f32_16x16x32_bf16 v[72:75], v[180:183], v[204:207], v[72:75]
	v_mfma_f32_16x16x32_bf16 v[68:71], v[172:175], v[212:215], v[68:71]
	v_mfma_f32_16x16x32_bf16 v[64:67], v[180:183], v[212:215], v[64:67]
	s_setprio 0
	s_barrier
	s_add_i32 s34, s61, s41
	v_lshl_add_u64 v[144:145], v[144:145], 0, s[8:9]
	s_mov_b32 m0, s34
	ds_read_b128 v[184:187], v151 offset:49152
	ds_read_b128 v[188:191], v151 offset:50176
	ds_read_b128 v[192:195], v151 offset:51200
	ds_read_b128 v[196:199], v151 offset:52224
	ds_read_b128 v[200:203], v151 offset:53248
	ds_read_b128 v[204:207], v151 offset:54272
	ds_read_b128 v[208:211], v151 offset:55296
	ds_read_b128 v[212:215], v151 offset:56320
	global_load_lds_dwordx4 v[144:145], off
	s_add_i32 m0, s34, 0x2000
	s_add_u32 s30, s30, 0x40080
	v_lshl_add_u64 v[144:145], v[216:217], 0, s[8:9]
	s_addc_u32 s31, s31, 0
	s_add_i32 s34, s62, s41
	global_load_lds_dwordx4 v[144:145], off
	v_lshl_add_u64 v[144:145], s[30:31], 0, v[130:131]
	s_mov_b32 m0, s34
	s_nop 0
	global_load_lds_dwordx4 v[144:145], off
	v_lshl_add_u64 v[144:145], s[30:31], 0, v[134:135]
	s_add_i32 m0, s34, 0x2000
	s_nop 0
	global_load_lds_dwordx4 v[144:145], off
	v_lshl_add_u64 v[144:145], v[218:219], 0, s[8:9]
	s_mov_b32 m0, s46
	s_nop 0
	global_load_lds_dwordx4 v[144:145], off
	v_lshl_add_u64 v[144:145], v[220:221], 0, s[8:9]
	s_mov_b32 m0, s47
	s_nop 0
	global_load_lds_dwordx4 v[144:145], off
	s_waitcnt vmcnt(8)
	s_waitcnt lgkmcnt(0)
	s_barrier
	s_setprio 1
	v_mfma_f32_16x16x32_bf16 v[60:63], v[152:155], v[184:187], v[60:63]
	v_mfma_f32_16x16x32_bf16 v[56:59], v[160:163], v[184:187], v[56:59]
	v_mfma_f32_16x16x32_bf16 v[52:55], v[152:155], v[192:195], v[52:55]
	v_mfma_f32_16x16x32_bf16 v[44:47], v[160:163], v[192:195], v[44:47]
	v_mfma_f32_16x16x32_bf16 v[36:39], v[152:155], v[200:203], v[36:39]
	v_mfma_f32_16x16x32_bf16 v[28:31], v[160:163], v[200:203], v[28:31]
	v_mfma_f32_16x16x32_bf16 v[20:23], v[152:155], v[208:211], v[20:23]
	v_mfma_f32_16x16x32_bf16 v[12:15], v[160:163], v[208:211], v[12:15]
	v_mfma_f32_16x16x32_bf16 v[60:63], v[156:159], v[188:191], v[60:63]
	v_mfma_f32_16x16x32_bf16 v[56:59], v[164:167], v[188:191], v[56:59]
	v_mfma_f32_16x16x32_bf16 v[52:55], v[156:159], v[196:199], v[52:55]
	v_mfma_f32_16x16x32_bf16 v[44:47], v[164:167], v[196:199], v[44:47]
	v_mfma_f32_16x16x32_bf16 v[36:39], v[156:159], v[204:207], v[36:39]
	v_mfma_f32_16x16x32_bf16 v[28:31], v[164:167], v[204:207], v[28:31]
	v_mfma_f32_16x16x32_bf16 v[20:23], v[156:159], v[212:215], v[20:23]
	v_mfma_f32_16x16x32_bf16 v[12:15], v[164:167], v[212:215], v[12:15]
	s_setprio 0
	s_setprio 1
	v_mfma_f32_16x16x32_bf16 v[48:51], v[168:171], v[184:187], v[48:51]
	v_mfma_f32_16x16x32_bf16 v[40:43], v[176:179], v[184:187], v[40:43]
	v_mfma_f32_16x16x32_bf16 v[32:35], v[168:171], v[192:195], v[32:35]
	v_mfma_f32_16x16x32_bf16 v[24:27], v[176:179], v[192:195], v[24:27]
	v_mfma_f32_16x16x32_bf16 v[16:19], v[168:171], v[200:203], v[16:19]
	v_mfma_f32_16x16x32_bf16 v[8:11], v[176:179], v[200:203], v[8:11]
	v_mfma_f32_16x16x32_bf16 v[4:7], v[168:171], v[208:211], v[4:7]
	v_mfma_f32_16x16x32_bf16 v[0:3], v[176:179], v[208:211], v[0:3]
	v_mfma_f32_16x16x32_bf16 v[48:51], v[172:175], v[188:191], v[48:51]
	v_mfma_f32_16x16x32_bf16 v[40:43], v[180:183], v[188:191], v[40:43]
	v_mfma_f32_16x16x32_bf16 v[32:35], v[172:175], v[196:199], v[32:35]
	v_mfma_f32_16x16x32_bf16 v[24:27], v[180:183], v[196:199], v[24:27]
	v_mfma_f32_16x16x32_bf16 v[16:19], v[172:175], v[204:207], v[16:19]
	v_mfma_f32_16x16x32_bf16 v[8:11], v[180:183], v[204:207], v[8:11]
	v_mfma_f32_16x16x32_bf16 v[4:7], v[172:175], v[212:215], v[4:7]
	v_mfma_f32_16x16x32_bf16 v[0:3], v[180:183], v[212:215], v[0:3]
	s_setprio 0
	s_barrier
	s_add_i32 s60, s60, 2
	s_add_u32 s28, s28, 0x100
	s_addc_u32 s29, s29, 0
	s_add_u32 s58, s58, 0x100
	s_addc_u32 s59, s59, 0
	s_cmp_gt_u32 s60, 13
	s_cbranch_scc0 .LBB0_440
	s_and_b64 vcc, exec, s[10:11]
	s_cbranch_vccz .LBB0_443
	s_barrier

.LBB0_465:
	s_ashr_i32 s35, s34, 31
	s_lshl_b64 s[36:37], s[34:35], 17
	s_add_u32 s36, s50, s36
	s_addc_u32 s37, s51, s37
	s_and_b64 s[38:39], s[2:3], exec
	s_cselect_b32 s49, s37, s43
	s_cselect_b32 s48, s36, s42
	s_ashr_i32 s31, s30, 31
	s_lshl_b64 s[38:39], s[30:31], 17
	s_add_u32 s38, s52, s38
	s_addc_u32 s39, s53, s39
	s_and_b64 s[46:47], s[2:3], exec
	s_cselect_b32 s47, s39, s45
	s_cselect_b32 s46, s38, s44
	s_add_u32 s68, s42, 0x10080
	s_addc_u32 s69, s43, 0
	v_lshl_add_u64 v[64:65], s[68:69], 0, v[128:129]
	v_lshl_add_u64 v[64:65], s[68:69], 0, v[132:133]
	s_add_i32 s41, s62, s54
	v_lshl_add_u64 v[214:215], s[44:45], 0, v[130:131]
	s_add_i32 s5, s41, 0x2000
	v_lshl_add_u64 v[144:145], v[214:215], 0, s[18:19]
	v_lshl_add_u64 v[216:217], s[44:45], 0, v[134:135]
	s_add_u32 s68, s44, 0x10100
	v_lshl_add_u64 v[144:145], v[216:217], 0, s[18:19]
	s_addc_u32 s69, s45, 0
	s_add_i32 s31, s63, s54
	v_lshl_add_u64 v[144:145], s[68:69], 0, v[130:131]
	s_add_i32 s35, s31, 0x2000
	v_lshl_add_u64 v[144:145], s[68:69], 0, v[134:135]
	v_lshl_add_u64 v[218:219], s[42:43], 0, v[128:129]
	v_lshl_add_u64 v[144:145], v[218:219], 0, s[18:19]
	v_lshl_add_u64 v[220:221], s[42:43], 0, v[132:133]
	v_lshl_add_u64 v[144:145], v[220:221], 0, s[18:19]
	s_add_i32 s67, 0, 0x18000
	s_add_i32 s80, 0, 0x1c000
	v_add_u32_e32 v136, s67, v152
	v_add_u32_e32 v142, s80, v152
	s_add_u32 s68, s42, 0x10100
	s_addc_u32 s69, s43, 0
	v_lshl_add_u64 v[222:223], s[68:69], 0, v[128:129]
	v_lshl_add_u64 v[222:223], s[68:69], 0, v[132:133]
	s_add_i32 s68, s67, s54
	s_add_i32 s67, s68, 0x2000
	v_lshl_add_u64 v[214:215], v[214:215], 0, s[20:21]
	s_add_u32 s78, s44, 0x10180
	v_lshl_add_u64 v[214:215], v[216:217], 0, s[20:21]
	s_addc_u32 s79, s45, 0
	s_add_i32 s44, s80, s54
	v_lshl_add_u64 v[214:215], s[78:79], 0, v[130:131]
	s_add_i32 s45, s44, 0x2000
	v_lshl_add_u64 v[214:215], s[78:79], 0, v[134:135]
	v_lshl_add_u64 v[214:215], v[218:219], 0, s[20:21]
	v_lshl_add_u64 v[214:215], v[220:221], 0, s[20:21]
	ds_read_b128 v[104:107], v154
	ds_read_b128 v[108:111], v154 offset:1024
	ds_read_b128 v[112:115], v154 offset:2048
	ds_read_b128 v[116:119], v154 offset:3072
	ds_read_b128 v[120:123], v155
	ds_read_b128 v[124:127], v155 offset:1024
	ds_read_b128 v[174:177], v155 offset:2048
	ds_read_b128 v[178:181], v155 offset:3072
	s_add_u32 s42, s42, 0x10080
	s_addc_u32 s43, s43, 0
	s_mov_b32 m0, s64
	v_lshl_add_u64 v[214:215], s[42:43], 0, v[128:129]
	ds_read_b128 v[182:185], v156
	ds_read_b128 v[186:189], v156 offset:1024
	ds_read_b128 v[190:193], v156 offset:2048
	ds_read_b128 v[194:197], v156 offset:3072
	ds_read_b128 v[198:201], v156 offset:4096
	ds_read_b128 v[202:205], v156 offset:5120
	ds_read_b128 v[206:209], v156 offset:6144
	ds_read_b128 v[210:213], v156 offset:7168
	global_load_lds_dwordx4 v[214:215], off
	v_lshl_add_u64 v[214:215], s[42:43], 0, v[132:133]
	s_mov_b32 m0, s65
	s_nop 0
	global_load_lds_dwordx4 v[214:215], off
	s_waitcnt vmcnt(8)
	s_waitcnt lgkmcnt(0)
	s_barrier
	s_setprio 1
	v_mfma_f32_16x16x32_bf16 v[64:67], v[104:107], v[182:185], 0
	v_mfma_f32_16x16x32_bf16 v[68:71], v[112:115], v[182:185], 0
	v_mfma_f32_16x16x32_bf16 v[72:75], v[104:107], v[190:193], 0
	v_mfma_f32_16x16x32_bf16 v[76:79], v[112:115], v[190:193], 0
	v_mfma_f32_16x16x32_bf16 v[80:83], v[104:107], v[198:201], 0
	v_mfma_f32_16x16x32_bf16 v[84:87], v[112:115], v[198:201], 0
	v_mfma_f32_16x16x32_bf16 v[88:91], v[104:107], v[206:209], 0
	v_mfma_f32_16x16x32_bf16 v[64:67], v[108:111], v[186:189], v[64:67]
	v_mfma_f32_16x16x32_bf16 v[68:71], v[116:119], v[186:189], v[68:71]
	v_mfma_f32_16x16x32_bf16 v[72:75], v[108:111], v[194:197], v[72:75]
	v_mfma_f32_16x16x32_bf16 v[76:79], v[116:119], v[194:197], v[76:79]
	v_mfma_f32_16x16x32_bf16 v[80:83], v[108:111], v[202:205], v[80:83]
	v_mfma_f32_16x16x32_bf16 v[84:87], v[116:119], v[202:205], v[84:87]
	v_mfma_f32_16x16x32_bf16 v[214:217], v[108:111], v[210:213], v[88:91]
	v_mfma_f32_16x16x32_bf16 v[88:91], v[112:115], v[206:209], 0
	v_mfma_f32_16x16x32_bf16 v[218:221], v[116:119], v[210:213], v[88:91]
	s_setprio 0
	s_setprio 1
	v_mfma_f32_16x16x32_bf16 v[88:91], v[120:123], v[182:185], 0
	v_mfma_f32_16x16x32_bf16 v[32:35], v[174:177], v[182:185], 0
	v_mfma_f32_16x16x32_bf16 v[36:39], v[120:123], v[190:193], 0
	v_mfma_f32_16x16x32_bf16 v[40:43], v[174:177], v[190:193], 0
	v_mfma_f32_16x16x32_bf16 v[44:47], v[120:123], v[198:201], 0
	v_mfma_f32_16x16x32_bf16 v[48:51], v[174:177], v[198:201], 0
	v_mfma_f32_16x16x32_bf16 v[52:55], v[120:123], v[206:209], 0
	v_mfma_f32_16x16x32_bf16 v[56:59], v[174:177], v[206:209], 0
	v_mfma_f32_16x16x32_bf16 v[96:99], v[124:127], v[186:189], v[88:91]
	v_mfma_f32_16x16x32_bf16 v[32:35], v[178:181], v[186:189], v[32:35]
	v_mfma_f32_16x16x32_bf16 v[36:39], v[124:127], v[194:197], v[36:39]
	v_mfma_f32_16x16x32_bf16 v[40:43], v[178:181], v[194:197], v[40:43]
	v_mfma_f32_16x16x32_bf16 v[44:47], v[124:127], v[202:205], v[44:47]
	v_mfma_f32_16x16x32_bf16 v[48:51], v[178:181], v[202:205], v[48:51]
	v_mfma_f32_16x16x32_bf16 v[52:55], v[124:127], v[210:213], v[52:55]
	v_mfma_f32_16x16x32_bf16 v[56:59], v[178:181], v[210:213], v[56:59]
	s_setprio 0
	s_barrier
	s_mov_b32 m0, s41
	v_lshl_add_u64 v[250:251], s[46:47], 0, v[130:131]
	s_add_u32 s42, s46, 0x10000
	ds_read_b128 v[88:91], v156 offset:16384
	ds_read_b128 v[92:95], v156 offset:17408
	ds_read_b128 v[182:185], v156 offset:18432
	ds_read_b128 v[186:189], v156 offset:19456
	ds_read_b128 v[190:193], v156 offset:20480
	ds_read_b128 v[194:197], v156 offset:21504
	ds_read_b128 v[198:201], v156 offset:22528
	ds_read_b128 v[202:205], v156 offset:23552
	global_load_lds_dwordx4 v[250:251], off
	v_lshl_add_u64 v[252:253], s[46:47], 0, v[134:135]
	s_mov_b32 m0, s5
	s_addc_u32 s43, s47, 0
	global_load_lds_dwordx4 v[252:253], off
	v_lshl_add_u64 v[206:207], s[42:43], 0, v[130:131]
	s_mov_b32 m0, s31
	v_lshl_add_u64 v[138:139], s[48:49], 0, v[128:129]
	global_load_lds_dwordx4 v[206:207], off
	v_lshl_add_u64 v[206:207], s[42:43], 0, v[134:135]
	s_mov_b32 m0, s35
	v_lshl_add_u64 v[140:141], s[48:49], 0, v[132:133]
	global_load_lds_dwordx4 v[206:207], off
	s_mov_b32 m0, s55
	s_nop 0
	global_load_lds_dwordx4 v[138:139], off
	s_mov_b32 m0, s56
	s_nop 0
	global_load_lds_dwordx4 v[140:141], off
	s_waitcnt vmcnt(8)
	s_waitcnt lgkmcnt(0)
	s_barrier
	s_setprio 1
	v_mfma_f32_16x16x32_bf16 v[0:3], v[104:107], v[198:201], 0
	v_mfma_f32_16x16x32_bf16 v[4:7], v[112:115], v[198:201], 0
	v_mfma_f32_16x16x32_bf16 v[144:147], v[104:107], v[88:91], 0
	v_mfma_f32_16x16x32_bf16 v[148:151], v[112:115], v[88:91], 0
	v_mfma_f32_16x16x32_bf16 v[158:161], v[104:107], v[182:185], 0
	v_mfma_f32_16x16x32_bf16 v[162:165], v[112:115], v[182:185], 0
	v_mfma_f32_16x16x32_bf16 v[166:169], v[104:107], v[190:193], 0
	v_mfma_f32_16x16x32_bf16 v[170:173], v[112:115], v[190:193], 0
	v_mfma_f32_16x16x32_bf16 v[0:3], v[108:111], v[202:205], v[0:3]
	v_mfma_f32_16x16x32_bf16 v[4:7], v[116:119], v[202:205], v[4:7]
	v_mfma_f32_16x16x32_bf16 v[144:147], v[108:111], v[92:95], v[144:147]
	v_mfma_f32_16x16x32_bf16 v[148:151], v[116:119], v[92:95], v[148:151]
	v_mfma_f32_16x16x32_bf16 v[158:161], v[108:111], v[186:189], v[158:161]
	v_mfma_f32_16x16x32_bf16 v[162:165], v[116:119], v[186:189], v[162:165]
	v_mfma_f32_16x16x32_bf16 v[166:169], v[108:111], v[194:197], v[166:169]
	v_mfma_f32_16x16x32_bf16 v[170:173], v[116:119], v[194:197], v[170:173]
	s_setprio 0
	s_setprio 1
	v_mfma_f32_16x16x32_bf16 v[8:11], v[120:123], v[88:91], 0
	v_mfma_f32_16x16x32_bf16 v[206:209], v[124:127], v[92:95], v[8:11]
	v_mfma_f32_16x16x32_bf16 v[8:11], v[174:177], v[88:91], 0
	v_mfma_f32_16x16x32_bf16 v[210:213], v[178:181], v[92:95], v[8:11]
	v_mfma_f32_16x16x32_bf16 v[8:11], v[120:123], v[182:185], 0
	v_mfma_f32_16x16x32_bf16 v[222:225], v[124:127], v[186:189], v[8:11]
	v_mfma_f32_16x16x32_bf16 v[8:11], v[174:177], v[182:185], 0
	v_mfma_f32_16x16x32_bf16 v[182:185], v[178:181], v[186:189], v[8:11]
	v_mfma_f32_16x16x32_bf16 v[8:11], v[120:123], v[190:193], 0
	v_mfma_f32_16x16x32_bf16 v[186:189], v[124:127], v[194:197], v[8:11]
	v_mfma_f32_16x16x32_bf16 v[8:11], v[174:177], v[190:193], 0
	v_mfma_f32_16x16x32_bf16 v[190:193], v[178:181], v[194:197], v[8:11]
	v_mfma_f32_16x16x32_bf16 v[8:11], v[120:123], v[198:201], 0
	v_mfma_f32_16x16x32_bf16 v[194:197], v[124:127], v[202:205], v[8:11]
	v_mfma_f32_16x16x32_bf16 v[8:11], v[174:177], v[198:201], 0
	v_mfma_f32_16x16x32_bf16 v[174:177], v[178:181], v[202:205], v[8:11]
	s_setprio 0
	s_barrier
	s_nop 4
	ds_read_b128 v[8:11], v136
	ds_read_b128 v[12:15], v136 offset:1024
	ds_read_b128 v[16:19], v136 offset:2048
	ds_read_b128 v[20:23], v136 offset:3072
	ds_read_b128 v[178:181], v142
	ds_read_b128 v[198:201], v142 offset:1024
	ds_read_b128 v[202:205], v142 offset:2048
	ds_read_b128 v[226:229], v142 offset:3072
	s_add_u32 s42, s48, 0x10000
	s_addc_u32 s43, s49, 0
	s_mov_b32 m0, s57
	v_lshl_add_u64 v[88:89], s[42:43], 0, v[128:129]
	ds_read_b128 v[24:27], v156 offset:32768
	ds_read_b128 v[28:31], v156 offset:33792
	ds_read_b128 v[60:63], v156 offset:34816
	ds_read_b128 v[230:233], v156 offset:35840
	ds_read_b128 v[234:237], v156 offset:36864
	ds_read_b128 v[238:241], v156 offset:37888
	ds_read_b128 v[242:245], v156 offset:38912
	ds_read_b128 v[246:249], v156 offset:39936
	global_load_lds_dwordx4 v[88:89], off
	v_lshl_add_u64 v[88:89], s[42:43], 0, v[132:133]
	s_mov_b32 m0, s58
	s_nop 0
	global_load_lds_dwordx4 v[88:89], off
	s_waitcnt vmcnt(8)
	s_waitcnt lgkmcnt(0)
	s_barrier
	s_setprio 1
	v_mfma_f32_16x16x32_bf16 v[64:67], v[8:11], v[24:27], v[64:67]
	v_mfma_f32_16x16x32_bf16 v[124:127], v[12:15], v[28:31], v[64:67]
	v_mfma_f32_16x16x32_bf16 v[64:67], v[16:19], v[24:27], v[68:71]
	v_mfma_f32_16x16x32_bf16 v[120:123], v[20:23], v[28:31], v[64:67]
	v_mfma_f32_16x16x32_bf16 v[64:67], v[8:11], v[60:63], v[72:75]
	v_mfma_f32_16x16x32_bf16 v[108:111], v[12:15], v[230:233], v[64:67]
	v_mfma_f32_16x16x32_bf16 v[64:67], v[16:19], v[60:63], v[76:79]
	v_mfma_f32_16x16x32_bf16 v[104:107], v[20:23], v[230:233], v[64:67]
	v_mfma_f32_16x16x32_bf16 v[64:67], v[8:11], v[234:237], v[80:83]
	v_mfma_f32_16x16x32_bf16 v[92:95], v[12:15], v[238:241], v[64:67]
	v_mfma_f32_16x16x32_bf16 v[64:67], v[16:19], v[234:237], v[84:87]
	v_mfma_f32_16x16x32_bf16 v[88:91], v[20:23], v[238:241], v[64:67]
	v_mfma_f32_16x16x32_bf16 v[64:67], v[8:11], v[242:245], v[214:217]
	v_mfma_f32_16x16x32_bf16 v[76:79], v[12:15], v[246:249], v[64:67]
	v_mfma_f32_16x16x32_bf16 v[64:67], v[16:19], v[242:245], v[218:221]
	v_mfma_f32_16x16x32_bf16 v[72:75], v[20:23], v[246:249], v[64:67]
	s_setprio 0
	s_setprio 1
	v_mfma_f32_16x16x32_bf16 v[64:67], v[178:181], v[24:27], v[96:99]
	v_mfma_f32_16x16x32_bf16 v[24:27], v[202:205], v[24:27], v[32:35]
	v_mfma_f32_16x16x32_bf16 v[112:115], v[226:229], v[28:31], v[24:27]
	v_mfma_f32_16x16x32_bf16 v[24:27], v[178:181], v[60:63], v[36:39]
	v_mfma_f32_16x16x32_bf16 v[100:103], v[198:201], v[230:233], v[24:27]
	v_mfma_f32_16x16x32_bf16 v[24:27], v[202:205], v[60:63], v[40:43]
	v_mfma_f32_16x16x32_bf16 v[96:99], v[226:229], v[230:233], v[24:27]
	v_mfma_f32_16x16x32_bf16 v[24:27], v[178:181], v[234:237], v[44:47]
	v_mfma_f32_16x16x32_bf16 v[84:87], v[198:201], v[238:241], v[24:27]
	v_mfma_f32_16x16x32_bf16 v[24:27], v[202:205], v[234:237], v[48:51]
	v_mfma_f32_16x16x32_bf16 v[80:83], v[226:229], v[238:241], v[24:27]
	v_mfma_f32_16x16x32_bf16 v[24:27], v[178:181], v[242:245], v[52:55]
	v_mfma_f32_16x16x32_bf16 v[68:71], v[198:201], v[246:249], v[24:27]
	v_mfma_f32_16x16x32_bf16 v[24:27], v[202:205], v[242:245], v[56:59]
	v_mfma_f32_16x16x32_bf16 v[116:119], v[198:201], v[28:31], v[64:67]
	v_mfma_f32_16x16x32_bf16 v[64:67], v[226:229], v[246:249], v[24:27]
	s_setprio 0
	s_barrier
	s_mov_b32 m0, s68
	s_nop 2
	v_lshl_add_u64 v[24:25], v[250:251], 0, s[12:13]
	s_add_u32 s42, s46, 0x10080
	ds_read_b128 v[32:35], v156 offset:49152
	ds_read_b128 v[36:39], v156 offset:50176
	ds_read_b128 v[214:217], v156 offset:51200
	ds_read_b128 v[218:221], v156 offset:52224
	ds_read_b128 v[230:233], v156 offset:53248
	ds_read_b128 v[234:237], v156 offset:54272
	ds_read_b128 v[238:241], v156 offset:55296
	ds_read_b128 v[242:245], v156 offset:56320
	global_load_lds_dwordx4 v[24:25], off
	v_lshl_add_u64 v[24:25], v[252:253], 0, s[12:13]
	s_mov_b32 m0, s67
	s_addc_u32 s43, s47, 0
	global_load_lds_dwordx4 v[24:25], off
	v_lshl_add_u64 v[24:25], s[42:43], 0, v[130:131]
	s_mov_b32 m0, s44
	s_nop 0
	global_load_lds_dwordx4 v[24:25], off
	v_lshl_add_u64 v[24:25], s[42:43], 0, v[134:135]
	s_mov_b32 m0, s45
	s_nop 0
	global_load_lds_dwordx4 v[24:25], off
	v_lshl_add_u64 v[24:25], v[138:139], 0, s[12:13]
	s_mov_b32 m0, s59
	s_nop 0
	global_load_lds_dwordx4 v[24:25], off
	v_lshl_add_u64 v[24:25], v[140:141], 0, s[12:13]
	s_mov_b32 m0, s60
	s_nop 0
	global_load_lds_dwordx4 v[24:25], off
	s_waitcnt vmcnt(8)
	s_waitcnt lgkmcnt(0)
	s_barrier
	s_setprio 1
	v_mfma_f32_16x16x32_bf16 v[24:27], v[8:11], v[32:35], v[144:147]
	v_mfma_f32_16x16x32_bf16 v[60:63], v[12:15], v[36:39], v[24:27]
	v_mfma_f32_16x16x32_bf16 v[24:27], v[16:19], v[32:35], v[148:151]
	v_mfma_f32_16x16x32_bf16 v[56:59], v[20:23], v[36:39], v[24:27]
	v_mfma_f32_16x16x32_bf16 v[24:27], v[8:11], v[214:217], v[158:161]
	v_mfma_f32_16x16x32_bf16 v[44:47], v[12:15], v[218:221], v[24:27]
	v_mfma_f32_16x16x32_bf16 v[24:27], v[16:19], v[214:217], v[162:165]
	v_mfma_f32_16x16x32_bf16 v[40:43], v[20:23], v[218:221], v[24:27]
	v_mfma_f32_16x16x32_bf16 v[24:27], v[8:11], v[230:233], v[166:169]
	v_mfma_f32_16x16x32_bf16 v[0:3], v[8:11], v[238:241], v[0:3]
	v_mfma_f32_16x16x32_bf16 v[28:31], v[12:15], v[234:237], v[24:27]
	v_mfma_f32_16x16x32_bf16 v[24:27], v[16:19], v[230:233], v[170:173]
	v_mfma_f32_16x16x32_bf16 v[12:15], v[12:15], v[242:245], v[0:3]
	v_mfma_f32_16x16x32_bf16 v[0:3], v[16:19], v[238:241], v[4:7]
	v_mfma_f32_16x16x32_bf16 v[24:27], v[20:23], v[234:237], v[24:27]
	v_mfma_f32_16x16x32_bf16 v[8:11], v[20:23], v[242:245], v[0:3]
	s_setprio 0
	s_setprio 1
	v_mfma_f32_16x16x32_bf16 v[0:3], v[178:181], v[32:35], v[206:209]
	v_mfma_f32_16x16x32_bf16 v[52:55], v[198:201], v[36:39], v[0:3]
	v_mfma_f32_16x16x32_bf16 v[0:3], v[202:205], v[32:35], v[210:213]
	v_mfma_f32_16x16x32_bf16 v[48:51], v[226:229], v[36:39], v[0:3]
	v_mfma_f32_16x16x32_bf16 v[0:3], v[178:181], v[214:217], v[222:225]
	v_mfma_f32_16x16x32_bf16 v[36:39], v[198:201], v[218:221], v[0:3]
	v_mfma_f32_16x16x32_bf16 v[0:3], v[202:205], v[214:217], v[182:185]
	v_mfma_f32_16x16x32_bf16 v[32:35], v[226:229], v[218:221], v[0:3]
	v_mfma_f32_16x16x32_bf16 v[0:3], v[178:181], v[230:233], v[186:189]
	v_mfma_f32_16x16x32_bf16 v[20:23], v[198:201], v[234:237], v[0:3]
	v_mfma_f32_16x16x32_bf16 v[0:3], v[202:205], v[230:233], v[190:193]
	v_mfma_f32_16x16x32_bf16 v[16:19], v[226:229], v[234:237], v[0:3]
	v_mfma_f32_16x16x32_bf16 v[0:3], v[178:181], v[238:241], v[194:197]
	v_mfma_f32_16x16x32_bf16 v[4:7], v[198:201], v[242:245], v[0:3]
	v_mfma_f32_16x16x32_bf16 v[0:3], v[202:205], v[238:241], v[174:177]
	v_mfma_f32_16x16x32_bf16 v[0:3], v[226:229], v[242:245], v[0:3]
	s_setprio 0
	s_barrier
	s_andn2_b64 vcc, exec, s[14:15]
	s_cbranch_vccnz .LBB0_467
	s_barrier

.LBB0_911:
	ds_read_b128 v[140:143], v147
	ds_read_b128 v[152:155], v147 offset:1024
	ds_read_b128 v[156:159], v147 offset:2048
	ds_read_b128 v[160:163], v147 offset:3072
	ds_read_b128 v[164:167], v148
	ds_read_b128 v[168:171], v148 offset:1024
	ds_read_b128 v[172:175], v148 offset:2048
	ds_read_b128 v[176:179], v148 offset:3072
	s_add_u32 s30, s28, 0xfffc0080
	s_addc_u32 s31, s29, -1
	s_cmp_eq_u32 s56, 12
	s_cselect_b32 s35, s21, s31
	s_cselect_b32 s34, s27, s30
	s_cselect_b32 s31, s19, s55
	s_cselect_b32 s30, s53, s54
	v_lshl_add_u64 v[212:213], s[28:29], 0, v[132:133]
	s_add_i32 m0, s41, 0xc000
	ds_read_b128 v[180:183], v149
	ds_read_b128 v[184:187], v149 offset:1024
	ds_read_b128 v[188:191], v149 offset:2048
	ds_read_b128 v[192:195], v149 offset:3072
	ds_read_b128 v[196:199], v149 offset:4096
	ds_read_b128 v[200:203], v149 offset:5120
	ds_read_b128 v[204:207], v149 offset:6144
	ds_read_b128 v[208:211], v149 offset:7168
	global_load_lds_dwordx4 v[212:213], off
	v_lshl_add_u64 v[212:213], s[28:29], 0, v[134:135]
	s_add_i32 m0, s41, 0xe000
	s_nop 0
	global_load_lds_dwordx4 v[212:213], off
	s_waitcnt vmcnt(8)
	s_waitcnt lgkmcnt(0)
	s_barrier
	s_setprio 1
	v_mfma_f32_16x16x32_bf16 v[124:127], v[140:143], v[180:183], v[124:127]
	v_mfma_f32_16x16x32_bf16 v[120:123], v[156:159], v[180:183], v[120:123]
	v_mfma_f32_16x16x32_bf16 v[108:111], v[140:143], v[188:191], v[108:111]
	v_mfma_f32_16x16x32_bf16 v[104:107], v[156:159], v[188:191], v[104:107]
	v_mfma_f32_16x16x32_bf16 v[92:95], v[140:143], v[196:199], v[92:95]
	v_mfma_f32_16x16x32_bf16 v[88:91], v[156:159], v[196:199], v[88:91]
	v_mfma_f32_16x16x32_bf16 v[76:79], v[140:143], v[204:207], v[76:79]
	v_mfma_f32_16x16x32_bf16 v[72:75], v[156:159], v[204:207], v[72:75]
	v_mfma_f32_16x16x32_bf16 v[124:127], v[152:155], v[184:187], v[124:127]
	v_mfma_f32_16x16x32_bf16 v[120:123], v[160:163], v[184:187], v[120:123]
	v_mfma_f32_16x16x32_bf16 v[108:111], v[152:155], v[192:195], v[108:111]
	v_mfma_f32_16x16x32_bf16 v[104:107], v[160:163], v[192:195], v[104:107]
	v_mfma_f32_16x16x32_bf16 v[92:95], v[152:155], v[200:203], v[92:95]
	v_mfma_f32_16x16x32_bf16 v[88:91], v[160:163], v[200:203], v[88:91]
	v_mfma_f32_16x16x32_bf16 v[76:79], v[152:155], v[208:211], v[76:79]
	v_mfma_f32_16x16x32_bf16 v[72:75], v[160:163], v[208:211], v[72:75]
	s_setprio 0
	s_setprio 1
	v_mfma_f32_16x16x32_bf16 v[116:119], v[164:167], v[180:183], v[116:119]
	v_mfma_f32_16x16x32_bf16 v[112:115], v[172:175], v[180:183], v[112:115]
	v_mfma_f32_16x16x32_bf16 v[100:103], v[164:167], v[188:191], v[100:103]
	v_mfma_f32_16x16x32_bf16 v[96:99], v[172:175], v[188:191], v[96:99]
	v_mfma_f32_16x16x32_bf16 v[84:87], v[164:167], v[196:199], v[84:87]
	v_mfma_f32_16x16x32_bf16 v[80:83], v[172:175], v[196:199], v[80:83]
	v_mfma_f32_16x16x32_bf16 v[68:71], v[164:167], v[204:207], v[68:71]
	v_mfma_f32_16x16x32_bf16 v[64:67], v[172:175], v[204:207], v[64:67]
	v_mfma_f32_16x16x32_bf16 v[116:119], v[168:171], v[184:187], v[116:119]
	v_mfma_f32_16x16x32_bf16 v[112:115], v[176:179], v[184:187], v[112:115]
	v_mfma_f32_16x16x32_bf16 v[100:103], v[168:171], v[192:195], v[100:103]
	v_mfma_f32_16x16x32_bf16 v[96:99], v[176:179], v[192:195], v[96:99]
	v_mfma_f32_16x16x32_bf16 v[84:87], v[168:171], v[200:203], v[84:87]
	v_mfma_f32_16x16x32_bf16 v[80:83], v[176:179], v[200:203], v[80:83]
	v_mfma_f32_16x16x32_bf16 v[68:71], v[168:171], v[208:211], v[68:71]
	v_mfma_f32_16x16x32_bf16 v[64:67], v[176:179], v[208:211], v[64:67]
	s_setprio 0
	s_barrier
	s_add_i32 s57, s50, s40
	v_lshl_add_u64 v[212:213], s[30:31], 0, v[128:129]
	s_mov_b32 m0, s57
	ds_read_b128 v[180:183], v149 offset:16384
	ds_read_b128 v[184:187], v149 offset:17408
	ds_read_b128 v[188:191], v149 offset:18432
	ds_read_b128 v[192:195], v149 offset:19456
	ds_read_b128 v[196:199], v149 offset:20480
	ds_read_b128 v[200:203], v149 offset:21504
	ds_read_b128 v[204:207], v149 offset:22528
	ds_read_b128 v[208:211], v149 offset:23552
	global_load_lds_dwordx4 v[212:213], off
	s_add_i32 m0, s57, 0x2000
	s_add_u32 s58, s30, 0x40000
	v_lshl_add_u64 v[214:215], s[30:31], 0, v[130:131]
	s_addc_u32 s59, s31, 0
	s_add_i32 s57, s51, s40
	global_load_lds_dwordx4 v[214:215], off
	v_lshl_add_u64 v[216:217], s[58:59], 0, v[128:129]
	s_mov_b32 m0, s57
	v_lshl_add_u64 v[218:219], s[34:35], 0, v[130:131]
	global_load_lds_dwordx4 v[216:217], off
	v_lshl_add_u64 v[216:217], s[58:59], 0, v[130:131]
	s_add_i32 m0, s57, 0x2000
	s_nop 0
	global_load_lds_dwordx4 v[216:217], off
	v_lshl_add_u64 v[216:217], s[34:35], 0, v[128:129]
	s_mov_b32 m0, s41
	s_nop 0
	global_load_lds_dwordx4 v[216:217], off
	s_mov_b32 m0, s42
	s_nop 0
	global_load_lds_dwordx4 v[218:219], off
	s_waitcnt vmcnt(8)
	s_waitcnt lgkmcnt(0)
	s_barrier
	s_setprio 1
	v_mfma_f32_16x16x32_bf16 v[60:63], v[140:143], v[180:183], v[60:63]
	v_mfma_f32_16x16x32_bf16 v[56:59], v[156:159], v[180:183], v[56:59]
	v_mfma_f32_16x16x32_bf16 v[44:47], v[140:143], v[188:191], v[44:47]
	v_mfma_f32_16x16x32_bf16 v[40:43], v[156:159], v[188:191], v[40:43]
	v_mfma_f32_16x16x32_bf16 v[28:31], v[140:143], v[196:199], v[28:31]
	v_mfma_f32_16x16x32_bf16 v[24:27], v[156:159], v[196:199], v[24:27]
	v_mfma_f32_16x16x32_bf16 v[12:15], v[140:143], v[204:207], v[12:15]
	v_mfma_f32_16x16x32_bf16 v[8:11], v[156:159], v[204:207], v[8:11]
	v_mfma_f32_16x16x32_bf16 v[60:63], v[152:155], v[184:187], v[60:63]
	v_mfma_f32_16x16x32_bf16 v[56:59], v[160:163], v[184:187], v[56:59]
	v_mfma_f32_16x16x32_bf16 v[44:47], v[152:155], v[192:195], v[44:47]
	v_mfma_f32_16x16x32_bf16 v[40:43], v[160:163], v[192:195], v[40:43]
	v_mfma_f32_16x16x32_bf16 v[28:31], v[152:155], v[200:203], v[28:31]
	v_mfma_f32_16x16x32_bf16 v[24:27], v[160:163], v[200:203], v[24:27]
	v_mfma_f32_16x16x32_bf16 v[12:15], v[152:155], v[208:211], v[12:15]
	v_mfma_f32_16x16x32_bf16 v[8:11], v[160:163], v[208:211], v[8:11]
	s_setprio 0
	s_setprio 1
	v_mfma_f32_16x16x32_bf16 v[52:55], v[164:167], v[180:183], v[52:55]
	v_mfma_f32_16x16x32_bf16 v[48:51], v[172:175], v[180:183], v[48:51]
	v_mfma_f32_16x16x32_bf16 v[36:39], v[164:167], v[188:191], v[36:39]
	v_mfma_f32_16x16x32_bf16 v[32:35], v[172:175], v[188:191], v[32:35]
	v_mfma_f32_16x16x32_bf16 v[20:23], v[164:167], v[196:199], v[20:23]
	v_mfma_f32_16x16x32_bf16 v[16:19], v[172:175], v[196:199], v[16:19]
	v_mfma_f32_16x16x32_bf16 v[4:7], v[164:167], v[204:207], v[4:7]
	v_mfma_f32_16x16x32_bf16 v[0:3], v[172:175], v[204:207], v[0:3]
	v_mfma_f32_16x16x32_bf16 v[52:55], v[168:171], v[184:187], v[52:55]
	v_mfma_f32_16x16x32_bf16 v[48:51], v[176:179], v[184:187], v[48:51]
	v_mfma_f32_16x16x32_bf16 v[36:39], v[168:171], v[192:195], v[36:39]
	v_mfma_f32_16x16x32_bf16 v[32:35], v[176:179], v[192:195], v[32:35]
	v_mfma_f32_16x16x32_bf16 v[20:23], v[168:171], v[200:203], v[20:23]
	v_mfma_f32_16x16x32_bf16 v[16:19], v[176:179], v[200:203], v[16:19]
	v_mfma_f32_16x16x32_bf16 v[4:7], v[168:171], v[208:211], v[4:7]
	v_mfma_f32_16x16x32_bf16 v[0:3], v[176:179], v[208:211], v[0:3]
	s_setprio 0
	s_barrier
	s_add_i32 s57, 0, 0x18000
	v_add_u32_e32 v151, s57, v145
	s_add_i32 s58, 0, 0x1c000
	ds_read_b128 v[140:143], v151
	ds_read_b128 v[152:155], v151 offset:1024
	ds_read_b128 v[156:159], v151 offset:2048
	ds_read_b128 v[160:163], v151 offset:3072
	v_add_u32_e32 v151, s58, v145
	ds_read_b128 v[164:167], v151
	ds_read_b128 v[168:171], v151 offset:1024
	ds_read_b128 v[172:175], v151 offset:2048
	ds_read_b128 v[176:179], v151 offset:3072
	s_add_u32 s34, s34, 0x40000
	s_addc_u32 s35, s35, 0
	s_mov_b32 m0, s43
	v_lshl_add_u64 v[220:221], s[34:35], 0, v[128:129]
	ds_read_b128 v[180:183], v149 offset:32768
	ds_read_b128 v[184:187], v149 offset:33792
	ds_read_b128 v[188:191], v149 offset:34816
	ds_read_b128 v[192:195], v149 offset:35840
	ds_read_b128 v[196:199], v149 offset:36864
	ds_read_b128 v[200:203], v149 offset:37888
	ds_read_b128 v[204:207], v149 offset:38912
	ds_read_b128 v[208:211], v149 offset:39936
	global_load_lds_dwordx4 v[220:221], off
	v_lshl_add_u64 v[220:221], s[34:35], 0, v[130:131]
	s_mov_b32 m0, s44
	s_nop 0
	global_load_lds_dwordx4 v[220:221], off
	s_waitcnt vmcnt(8)
	s_waitcnt lgkmcnt(0)
	s_barrier
	s_setprio 1
	v_mfma_f32_16x16x32_bf16 v[124:127], v[140:143], v[180:183], v[124:127]
	v_mfma_f32_16x16x32_bf16 v[120:123], v[156:159], v[180:183], v[120:123]
	v_mfma_f32_16x16x32_bf16 v[108:111], v[140:143], v[188:191], v[108:111]
	v_mfma_f32_16x16x32_bf16 v[104:107], v[156:159], v[188:191], v[104:107]
	v_mfma_f32_16x16x32_bf16 v[92:95], v[140:143], v[196:199], v[92:95]
	v_mfma_f32_16x16x32_bf16 v[88:91], v[156:159], v[196:199], v[88:91]
	v_mfma_f32_16x16x32_bf16 v[76:79], v[140:143], v[204:207], v[76:79]
	v_mfma_f32_16x16x32_bf16 v[72:75], v[156:159], v[204:207], v[72:75]
	v_mfma_f32_16x16x32_bf16 v[124:127], v[152:155], v[184:187], v[124:127]
	v_mfma_f32_16x16x32_bf16 v[120:123], v[160:163], v[184:187], v[120:123]
	v_mfma_f32_16x16x32_bf16 v[108:111], v[152:155], v[192:195], v[108:111]
	v_mfma_f32_16x16x32_bf16 v[104:107], v[160:163], v[192:195], v[104:107]
	v_mfma_f32_16x16x32_bf16 v[92:95], v[152:155], v[200:203], v[92:95]
	v_mfma_f32_16x16x32_bf16 v[88:91], v[160:163], v[200:203], v[88:91]
	v_mfma_f32_16x16x32_bf16 v[76:79], v[152:155], v[208:211], v[76:79]
	v_mfma_f32_16x16x32_bf16 v[72:75], v[160:163], v[208:211], v[72:75]
	s_setprio 0
	s_setprio 1
	v_mfma_f32_16x16x32_bf16 v[116:119], v[164:167], v[180:183], v[116:119]
	v_mfma_f32_16x16x32_bf16 v[112:115], v[172:175], v[180:183], v[112:115]
	v_mfma_f32_16x16x32_bf16 v[100:103], v[164:167], v[188:191], v[100:103]
	v_mfma_f32_16x16x32_bf16 v[96:99], v[172:175], v[188:191], v[96:99]
	v_mfma_f32_16x16x32_bf16 v[84:87], v[164:167], v[196:199], v[84:87]
	v_mfma_f32_16x16x32_bf16 v[80:83], v[172:175], v[196:199], v[80:83]
	v_mfma_f32_16x16x32_bf16 v[68:71], v[164:167], v[204:207], v[68:71]
	v_mfma_f32_16x16x32_bf16 v[64:67], v[172:175], v[204:207], v[64:67]
	v_mfma_f32_16x16x32_bf16 v[116:119], v[168:171], v[184:187], v[116:119]
	v_mfma_f32_16x16x32_bf16 v[112:115], v[176:179], v[184:187], v[112:115]
	v_mfma_f32_16x16x32_bf16 v[100:103], v[168:171], v[192:195], v[100:103]
	v_mfma_f32_16x16x32_bf16 v[96:99], v[176:179], v[192:195], v[96:99]
	v_mfma_f32_16x16x32_bf16 v[84:87], v[168:171], v[200:203], v[84:87]
	v_mfma_f32_16x16x32_bf16 v[80:83], v[176:179], v[200:203], v[80:83]
	v_mfma_f32_16x16x32_bf16 v[68:71], v[168:171], v[208:211], v[68:71]
	v_mfma_f32_16x16x32_bf16 v[64:67], v[176:179], v[208:211], v[64:67]
	s_setprio 0
	s_barrier
	s_add_i32 s34, s57, s40
	v_lshl_add_u64 v[212:213], v[212:213], 0, s[14:15]
	s_mov_b32 m0, s34
	ds_read_b128 v[180:183], v149 offset:49152
	ds_read_b128 v[184:187], v149 offset:50176
	ds_read_b128 v[188:191], v149 offset:51200
	ds_read_b128 v[192:195], v149 offset:52224
	ds_read_b128 v[196:199], v149 offset:53248
	ds_read_b128 v[200:203], v149 offset:54272
	ds_read_b128 v[204:207], v149 offset:55296
	ds_read_b128 v[208:211], v149 offset:56320
	global_load_lds_dwordx4 v[212:213], off
	s_add_i32 m0, s34, 0x2000
	s_add_u32 s30, s30, 0x40080
	v_lshl_add_u64 v[212:213], v[214:215], 0, s[14:15]
	s_addc_u32 s31, s31, 0
	s_add_i32 s34, s58, s40
	global_load_lds_dwordx4 v[212:213], off
	v_lshl_add_u64 v[212:213], s[30:31], 0, v[128:129]
	s_mov_b32 m0, s34
	s_nop 0
	global_load_lds_dwordx4 v[212:213], off
	v_lshl_add_u64 v[212:213], s[30:31], 0, v[130:131]
	s_add_i32 m0, s34, 0x2000
	s_nop 0
	global_load_lds_dwordx4 v[212:213], off
	v_lshl_add_u64 v[212:213], v[216:217], 0, s[14:15]
	s_mov_b32 m0, s46
	s_nop 0
	global_load_lds_dwordx4 v[212:213], off
	v_lshl_add_u64 v[212:213], v[218:219], 0, s[14:15]
	s_mov_b32 m0, s47
	s_nop 0
	global_load_lds_dwordx4 v[212:213], off
	s_waitcnt vmcnt(8)
	s_waitcnt lgkmcnt(0)
	s_barrier
	s_setprio 1
	v_mfma_f32_16x16x32_bf16 v[60:63], v[140:143], v[180:183], v[60:63]
	v_mfma_f32_16x16x32_bf16 v[56:59], v[156:159], v[180:183], v[56:59]
	v_mfma_f32_16x16x32_bf16 v[44:47], v[140:143], v[188:191], v[44:47]
	v_mfma_f32_16x16x32_bf16 v[40:43], v[156:159], v[188:191], v[40:43]
	v_mfma_f32_16x16x32_bf16 v[28:31], v[140:143], v[196:199], v[28:31]
	v_mfma_f32_16x16x32_bf16 v[24:27], v[156:159], v[196:199], v[24:27]
	v_mfma_f32_16x16x32_bf16 v[12:15], v[140:143], v[204:207], v[12:15]
	v_mfma_f32_16x16x32_bf16 v[8:11], v[156:159], v[204:207], v[8:11]
	v_mfma_f32_16x16x32_bf16 v[60:63], v[152:155], v[184:187], v[60:63]
	v_mfma_f32_16x16x32_bf16 v[56:59], v[160:163], v[184:187], v[56:59]
	v_mfma_f32_16x16x32_bf16 v[44:47], v[152:155], v[192:195], v[44:47]
	v_mfma_f32_16x16x32_bf16 v[40:43], v[160:163], v[192:195], v[40:43]
	v_mfma_f32_16x16x32_bf16 v[28:31], v[152:155], v[200:203], v[28:31]
	v_mfma_f32_16x16x32_bf16 v[24:27], v[160:163], v[200:203], v[24:27]
	v_mfma_f32_16x16x32_bf16 v[12:15], v[152:155], v[208:211], v[12:15]
	v_mfma_f32_16x16x32_bf16 v[8:11], v[160:163], v[208:211], v[8:11]
	s_setprio 0
	s_setprio 1
	v_mfma_f32_16x16x32_bf16 v[52:55], v[164:167], v[180:183], v[52:55]
	v_mfma_f32_16x16x32_bf16 v[48:51], v[172:175], v[180:183], v[48:51]
	v_mfma_f32_16x16x32_bf16 v[36:39], v[164:167], v[188:191], v[36:39]
	v_mfma_f32_16x16x32_bf16 v[32:35], v[172:175], v[188:191], v[32:35]
	v_mfma_f32_16x16x32_bf16 v[20:23], v[164:167], v[196:199], v[20:23]
	v_mfma_f32_16x16x32_bf16 v[16:19], v[172:175], v[196:199], v[16:19]
	v_mfma_f32_16x16x32_bf16 v[4:7], v[164:167], v[204:207], v[4:7]
	v_mfma_f32_16x16x32_bf16 v[0:3], v[172:175], v[204:207], v[0:3]
	v_mfma_f32_16x16x32_bf16 v[52:55], v[168:171], v[184:187], v[52:55]
	v_mfma_f32_16x16x32_bf16 v[48:51], v[176:179], v[184:187], v[48:51]
	v_mfma_f32_16x16x32_bf16 v[36:39], v[168:171], v[192:195], v[36:39]
	v_mfma_f32_16x16x32_bf16 v[32:35], v[176:179], v[192:195], v[32:35]
	v_mfma_f32_16x16x32_bf16 v[20:23], v[168:171], v[200:203], v[20:23]
	v_mfma_f32_16x16x32_bf16 v[16:19], v[176:179], v[200:203], v[16:19]
	v_mfma_f32_16x16x32_bf16 v[4:7], v[168:171], v[208:211], v[4:7]
	v_mfma_f32_16x16x32_bf16 v[0:3], v[176:179], v[208:211], v[0:3]
	s_setprio 0
	s_barrier
	s_add_i32 s56, s56, 2
	s_add_u32 s28, s28, 0x100
	s_addc_u32 s29, s29, 0
	s_add_u32 s54, s54, 0x100
	s_addc_u32 s55, s55, 0
	s_cmp_gt_u32 s56, 13
	s_cbranch_scc0 .LBB0_911
	s_and_b64 vcc, exec, s[16:17]
	s_cbranch_vccz .LBB0_914
	s_barrier

.LBB0_977:
	ds_read_b128 v[152:155], v143
	ds_read_b128 v[162:165], v143 offset:1024
	ds_read_b128 v[166:169], v143 offset:2048
	ds_read_b128 v[170:173], v143 offset:3072
	ds_read_b128 v[174:177], v158
	ds_read_b128 v[178:181], v158 offset:1024
	ds_read_b128 v[182:185], v158 offset:2048
	ds_read_b128 v[186:189], v158 offset:3072
	s_add_u32 s34, s30, 0xfffc0080
	s_addc_u32 s35, s31, -1
	s_cmp_eq_u32 s57, 12
	s_cselect_b32 s37, s21, s35
	s_cselect_b32 s36, s27, s34
	s_cselect_b32 s35, s19, s56
	s_cselect_b32 s34, s29, s55
	s_waitcnt lgkmcnt(0)
	v_lshl_add_u64 v[156:157], s[30:31], 0, v[144:145]
	s_add_i32 m0, s41, 0xc000
	ds_read_b128 v[190:193], v159
	ds_read_b128 v[194:197], v159 offset:1024
	ds_read_b128 v[198:201], v159 offset:2048
	ds_read_b128 v[202:205], v159 offset:3072
	ds_read_b128 v[206:209], v159 offset:4096
	ds_read_b128 v[210:213], v159 offset:5120
	ds_read_b128 v[214:217], v159 offset:6144
	ds_read_b128 v[218:221], v159 offset:7168
	global_load_lds_dwordx4 v[156:157], off
	v_lshl_add_u64 v[156:157], s[30:31], 0, v[146:147]
	s_add_i32 m0, s41, 0xe000
	s_nop 0
	global_load_lds_dwordx4 v[156:157], off
	s_waitcnt vmcnt(8)
	s_waitcnt lgkmcnt(0)
	s_barrier
	s_setprio 1
	v_mfma_f32_16x16x32_bf16 v[116:119], v[152:155], v[190:193], v[116:119]
	v_mfma_f32_16x16x32_bf16 v[112:115], v[166:169], v[190:193], v[112:115]
	v_mfma_f32_16x16x32_bf16 v[100:103], v[152:155], v[198:201], v[100:103]
	v_mfma_f32_16x16x32_bf16 v[96:99], v[166:169], v[198:201], v[96:99]
	v_mfma_f32_16x16x32_bf16 v[88:91], v[152:155], v[206:209], v[88:91]
	v_mfma_f32_16x16x32_bf16 v[84:87], v[166:169], v[206:209], v[84:87]
	v_mfma_f32_16x16x32_bf16 v[72:75], v[152:155], v[214:217], v[72:75]
	v_mfma_f32_16x16x32_bf16 v[68:71], v[166:169], v[214:217], v[68:71]
	v_mfma_f32_16x16x32_bf16 v[116:119], v[162:165], v[194:197], v[116:119]
	v_mfma_f32_16x16x32_bf16 v[112:115], v[170:173], v[194:197], v[112:115]
	v_mfma_f32_16x16x32_bf16 v[100:103], v[162:165], v[202:205], v[100:103]
	v_mfma_f32_16x16x32_bf16 v[96:99], v[170:173], v[202:205], v[96:99]
	v_mfma_f32_16x16x32_bf16 v[88:91], v[162:165], v[210:213], v[88:91]
	v_mfma_f32_16x16x32_bf16 v[84:87], v[170:173], v[210:213], v[84:87]
	v_mfma_f32_16x16x32_bf16 v[72:75], v[162:165], v[218:221], v[72:75]
	v_mfma_f32_16x16x32_bf16 v[68:71], v[170:173], v[218:221], v[68:71]
	s_setprio 0
	s_setprio 1
	v_mfma_f32_16x16x32_bf16 v[124:127], v[174:177], v[190:193], v[124:127]
	v_mfma_f32_16x16x32_bf16 v[120:123], v[182:185], v[190:193], v[120:123]
	v_mfma_f32_16x16x32_bf16 v[108:111], v[174:177], v[198:201], v[108:111]
	v_mfma_f32_16x16x32_bf16 v[104:107], v[182:185], v[198:201], v[104:107]
	v_mfma_f32_16x16x32_bf16 v[92:95], v[174:177], v[206:209], v[92:95]
	v_mfma_f32_16x16x32_bf16 v[80:83], v[182:185], v[206:209], v[80:83]
	v_mfma_f32_16x16x32_bf16 v[76:79], v[174:177], v[214:217], v[76:79]
	v_mfma_f32_16x16x32_bf16 v[64:67], v[182:185], v[214:217], v[64:67]
	v_mfma_f32_16x16x32_bf16 v[124:127], v[178:181], v[194:197], v[124:127]
	v_mfma_f32_16x16x32_bf16 v[120:123], v[186:189], v[194:197], v[120:123]
	v_mfma_f32_16x16x32_bf16 v[108:111], v[178:181], v[202:205], v[108:111]
	v_mfma_f32_16x16x32_bf16 v[104:107], v[186:189], v[202:205], v[104:107]
	v_mfma_f32_16x16x32_bf16 v[92:95], v[178:181], v[210:213], v[92:95]
	v_mfma_f32_16x16x32_bf16 v[80:83], v[186:189], v[210:213], v[80:83]
	v_mfma_f32_16x16x32_bf16 v[76:79], v[178:181], v[218:221], v[76:79]
	v_mfma_f32_16x16x32_bf16 v[64:67], v[186:189], v[218:221], v[64:67]
	s_setprio 0
	s_barrier
	s_add_i32 s58, s51, s40
	v_lshl_add_u64 v[156:157], s[34:35], 0, v[130:131]
	s_mov_b32 m0, s58
	ds_read_b128 v[190:193], v159 offset:16384
	ds_read_b128 v[194:197], v159 offset:17408
	ds_read_b128 v[198:201], v159 offset:18432
	ds_read_b128 v[202:205], v159 offset:19456
	ds_read_b128 v[206:209], v159 offset:20480
	ds_read_b128 v[210:213], v159 offset:21504
	ds_read_b128 v[214:217], v159 offset:22528
	ds_read_b128 v[218:221], v159 offset:23552
	global_load_lds_dwordx4 v[156:157], off
	s_add_i32 m0, s58, 0x2000
	s_add_u32 s58, s34, 0x40000
	v_lshl_add_u64 v[222:223], s[34:35], 0, v[134:135]
	s_addc_u32 s59, s35, 0
	s_add_i32 s60, s52, s40
	global_load_lds_dwordx4 v[222:223], off
	v_lshl_add_u64 v[224:225], s[58:59], 0, v[130:131]
	s_mov_b32 m0, s60
	v_lshl_add_u64 v[226:227], s[36:37], 0, v[132:133]
	global_load_lds_dwordx4 v[224:225], off
	v_lshl_add_u64 v[224:225], s[58:59], 0, v[134:135]
	s_add_i32 m0, s60, 0x2000
	s_nop 0
	global_load_lds_dwordx4 v[224:225], off
	v_lshl_add_u64 v[224:225], s[36:37], 0, v[128:129]
	s_mov_b32 m0, s41
	s_nop 0
	global_load_lds_dwordx4 v[224:225], off
	s_mov_b32 m0, s42
	s_nop 0
	global_load_lds_dwordx4 v[226:227], off
	s_waitcnt vmcnt(8)
	s_waitcnt lgkmcnt(0)
	s_barrier
	s_setprio 1
	v_mfma_f32_16x16x32_bf16 v[56:59], v[152:155], v[190:193], v[56:59]
	v_mfma_f32_16x16x32_bf16 v[52:55], v[166:169], v[190:193], v[52:55]
	v_mfma_f32_16x16x32_bf16 v[40:43], v[152:155], v[198:201], v[40:43]
	v_mfma_f32_16x16x32_bf16 v[36:39], v[166:169], v[198:201], v[36:39]
	v_mfma_f32_16x16x32_bf16 v[24:27], v[152:155], v[206:209], v[24:27]
	v_mfma_f32_16x16x32_bf16 v[20:23], v[166:169], v[206:209], v[20:23]
	v_mfma_f32_16x16x32_bf16 v[8:11], v[152:155], v[214:217], v[8:11]
	v_mfma_f32_16x16x32_bf16 v[4:7], v[166:169], v[214:217], v[4:7]
	v_mfma_f32_16x16x32_bf16 v[56:59], v[162:165], v[194:197], v[56:59]
	v_mfma_f32_16x16x32_bf16 v[52:55], v[170:173], v[194:197], v[52:55]
	v_mfma_f32_16x16x32_bf16 v[40:43], v[162:165], v[202:205], v[40:43]
	v_mfma_f32_16x16x32_bf16 v[36:39], v[170:173], v[202:205], v[36:39]
	v_mfma_f32_16x16x32_bf16 v[24:27], v[162:165], v[210:213], v[24:27]
	v_mfma_f32_16x16x32_bf16 v[20:23], v[170:173], v[210:213], v[20:23]
	v_mfma_f32_16x16x32_bf16 v[8:11], v[162:165], v[218:221], v[8:11]
	v_mfma_f32_16x16x32_bf16 v[4:7], v[170:173], v[218:221], v[4:7]
	s_setprio 0
	s_setprio 1
	v_mfma_f32_16x16x32_bf16 v[60:63], v[174:177], v[190:193], v[60:63]
	v_mfma_f32_16x16x32_bf16 v[48:51], v[182:185], v[190:193], v[48:51]
	v_mfma_f32_16x16x32_bf16 v[44:47], v[174:177], v[198:201], v[44:47]
	v_mfma_f32_16x16x32_bf16 v[32:35], v[182:185], v[198:201], v[32:35]
	v_mfma_f32_16x16x32_bf16 v[28:31], v[174:177], v[206:209], v[28:31]
	v_mfma_f32_16x16x32_bf16 v[16:19], v[182:185], v[206:209], v[16:19]
	v_mfma_f32_16x16x32_bf16 v[12:15], v[174:177], v[214:217], v[12:15]
	v_mfma_f32_16x16x32_bf16 v[0:3], v[182:185], v[214:217], v[0:3]
	v_mfma_f32_16x16x32_bf16 v[60:63], v[178:181], v[194:197], v[60:63]
	v_mfma_f32_16x16x32_bf16 v[48:51], v[186:189], v[194:197], v[48:51]
	v_mfma_f32_16x16x32_bf16 v[44:47], v[178:181], v[202:205], v[44:47]
	v_mfma_f32_16x16x32_bf16 v[32:35], v[186:189], v[202:205], v[32:35]
	v_mfma_f32_16x16x32_bf16 v[28:31], v[178:181], v[210:213], v[28:31]
	v_mfma_f32_16x16x32_bf16 v[16:19], v[186:189], v[210:213], v[16:19]
	v_mfma_f32_16x16x32_bf16 v[12:15], v[178:181], v[218:221], v[12:15]
	v_mfma_f32_16x16x32_bf16 v[0:3], v[186:189], v[218:221], v[0:3]
	s_setprio 0
	s_barrier
	s_add_i32 s58, 0, 0x18000
	s_add_i32 s59, 0, 0x1c000
	v_add_u32_e32 v170, s58, v141
	v_add_u32_e32 v186, s59, v141
	ds_read_b128 v[152:155], v170
	ds_read_b128 v[162:165], v170 offset:1024
	ds_read_b128 v[166:169], v170 offset:2048
	ds_read_b128 v[170:173], v170 offset:3072
	ds_read_b128 v[174:177], v186
	ds_read_b128 v[178:181], v186 offset:1024
	ds_read_b128 v[182:185], v186 offset:2048
	ds_read_b128 v[186:189], v186 offset:3072
	s_add_u32 s36, s36, 0x40000
	s_addc_u32 s37, s37, 0
	s_mov_b32 m0, s43
	v_lshl_add_u64 v[228:229], s[36:37], 0, v[128:129]
	ds_read_b128 v[190:193], v159 offset:32768
	ds_read_b128 v[194:197], v159 offset:33792
	ds_read_b128 v[198:201], v159 offset:34816
	ds_read_b128 v[202:205], v159 offset:35840
	ds_read_b128 v[206:209], v159 offset:36864
	ds_read_b128 v[210:213], v159 offset:37888
	ds_read_b128 v[214:217], v159 offset:38912
	ds_read_b128 v[218:221], v159 offset:39936
	global_load_lds_dwordx4 v[228:229], off
	v_lshl_add_u64 v[228:229], s[36:37], 0, v[132:133]
	s_mov_b32 m0, s44
	s_nop 0
	global_load_lds_dwordx4 v[228:229], off
	s_waitcnt vmcnt(8)
	s_waitcnt lgkmcnt(0)
	s_barrier
	s_setprio 1
	v_mfma_f32_16x16x32_bf16 v[116:119], v[152:155], v[190:193], v[116:119]
	v_mfma_f32_16x16x32_bf16 v[112:115], v[166:169], v[190:193], v[112:115]
	v_mfma_f32_16x16x32_bf16 v[100:103], v[152:155], v[198:201], v[100:103]
	v_mfma_f32_16x16x32_bf16 v[96:99], v[166:169], v[198:201], v[96:99]
	v_mfma_f32_16x16x32_bf16 v[88:91], v[152:155], v[206:209], v[88:91]
	v_mfma_f32_16x16x32_bf16 v[84:87], v[166:169], v[206:209], v[84:87]
	v_mfma_f32_16x16x32_bf16 v[72:75], v[152:155], v[214:217], v[72:75]
	v_mfma_f32_16x16x32_bf16 v[68:71], v[166:169], v[214:217], v[68:71]
	v_mfma_f32_16x16x32_bf16 v[116:119], v[162:165], v[194:197], v[116:119]
	v_mfma_f32_16x16x32_bf16 v[112:115], v[170:173], v[194:197], v[112:115]
	v_mfma_f32_16x16x32_bf16 v[100:103], v[162:165], v[202:205], v[100:103]
	v_mfma_f32_16x16x32_bf16 v[96:99], v[170:173], v[202:205], v[96:99]
	v_mfma_f32_16x16x32_bf16 v[88:91], v[162:165], v[210:213], v[88:91]
	v_mfma_f32_16x16x32_bf16 v[84:87], v[170:173], v[210:213], v[84:87]
	v_mfma_f32_16x16x32_bf16 v[72:75], v[162:165], v[218:221], v[72:75]
	v_mfma_f32_16x16x32_bf16 v[68:71], v[170:173], v[218:221], v[68:71]
	s_setprio 0
	s_setprio 1
	v_mfma_f32_16x16x32_bf16 v[124:127], v[174:177], v[190:193], v[124:127]
	v_mfma_f32_16x16x32_bf16 v[120:123], v[182:185], v[190:193], v[120:123]
	v_mfma_f32_16x16x32_bf16 v[108:111], v[174:177], v[198:201], v[108:111]
	v_mfma_f32_16x16x32_bf16 v[104:107], v[182:185], v[198:201], v[104:107]
	v_mfma_f32_16x16x32_bf16 v[92:95], v[174:177], v[206:209], v[92:95]
	v_mfma_f32_16x16x32_bf16 v[80:83], v[182:185], v[206:209], v[80:83]
	v_mfma_f32_16x16x32_bf16 v[76:79], v[174:177], v[214:217], v[76:79]
	v_mfma_f32_16x16x32_bf16 v[64:67], v[182:185], v[214:217], v[64:67]
	v_mfma_f32_16x16x32_bf16 v[124:127], v[178:181], v[194:197], v[124:127]
	v_mfma_f32_16x16x32_bf16 v[120:123], v[186:189], v[194:197], v[120:123]
	v_mfma_f32_16x16x32_bf16 v[108:111], v[178:181], v[202:205], v[108:111]
	v_mfma_f32_16x16x32_bf16 v[104:107], v[186:189], v[202:205], v[104:107]
	v_mfma_f32_16x16x32_bf16 v[92:95], v[178:181], v[210:213], v[92:95]
	v_mfma_f32_16x16x32_bf16 v[80:83], v[186:189], v[210:213], v[80:83]
	v_mfma_f32_16x16x32_bf16 v[76:79], v[178:181], v[218:221], v[76:79]
	v_mfma_f32_16x16x32_bf16 v[64:67], v[186:189], v[218:221], v[64:67]
	s_setprio 0
	s_barrier
	s_add_i32 s36, s58, s40
	v_lshl_add_u64 v[156:157], v[156:157], 0, s[12:13]
	s_mov_b32 m0, s36
	ds_read_b128 v[190:193], v159 offset:49152
	ds_read_b128 v[194:197], v159 offset:50176
	ds_read_b128 v[198:201], v159 offset:51200
	ds_read_b128 v[202:205], v159 offset:52224
	ds_read_b128 v[206:209], v159 offset:53248
	ds_read_b128 v[210:213], v159 offset:54272
	ds_read_b128 v[214:217], v159 offset:55296
	ds_read_b128 v[218:221], v159 offset:56320
	global_load_lds_dwordx4 v[156:157], off
	s_add_i32 m0, s36, 0x2000
	s_add_u32 s34, s34, 0x40080
	v_lshl_add_u64 v[156:157], v[222:223], 0, s[12:13]
	s_addc_u32 s35, s35, 0
	s_add_i32 s36, s59, s40
	global_load_lds_dwordx4 v[156:157], off
	v_lshl_add_u64 v[156:157], s[34:35], 0, v[130:131]
	s_mov_b32 m0, s36
	s_nop 0
	global_load_lds_dwordx4 v[156:157], off
	v_lshl_add_u64 v[156:157], s[34:35], 0, v[134:135]
	s_add_i32 m0, s36, 0x2000
	s_nop 0
	global_load_lds_dwordx4 v[156:157], off
	v_lshl_add_u64 v[156:157], v[224:225], 0, s[12:13]
	s_mov_b32 m0, s45
	s_nop 0
	global_load_lds_dwordx4 v[156:157], off
	v_lshl_add_u64 v[156:157], v[226:227], 0, s[12:13]
	s_mov_b32 m0, s46
	s_nop 0
	global_load_lds_dwordx4 v[156:157], off
	s_waitcnt vmcnt(8)
	s_waitcnt lgkmcnt(0)
	s_barrier
	s_setprio 1
	v_mfma_f32_16x16x32_bf16 v[56:59], v[152:155], v[190:193], v[56:59]
	v_mfma_f32_16x16x32_bf16 v[52:55], v[166:169], v[190:193], v[52:55]
	v_mfma_f32_16x16x32_bf16 v[40:43], v[152:155], v[198:201], v[40:43]
	v_mfma_f32_16x16x32_bf16 v[36:39], v[166:169], v[198:201], v[36:39]
	v_mfma_f32_16x16x32_bf16 v[24:27], v[152:155], v[206:209], v[24:27]
	v_mfma_f32_16x16x32_bf16 v[20:23], v[166:169], v[206:209], v[20:23]
	v_mfma_f32_16x16x32_bf16 v[8:11], v[152:155], v[214:217], v[8:11]
	v_mfma_f32_16x16x32_bf16 v[4:7], v[166:169], v[214:217], v[4:7]
	v_mfma_f32_16x16x32_bf16 v[56:59], v[162:165], v[194:197], v[56:59]
	v_mfma_f32_16x16x32_bf16 v[52:55], v[170:173], v[194:197], v[52:55]
	v_mfma_f32_16x16x32_bf16 v[40:43], v[162:165], v[202:205], v[40:43]
	v_mfma_f32_16x16x32_bf16 v[36:39], v[170:173], v[202:205], v[36:39]
	v_mfma_f32_16x16x32_bf16 v[24:27], v[162:165], v[210:213], v[24:27]
	v_mfma_f32_16x16x32_bf16 v[20:23], v[170:173], v[210:213], v[20:23]
	v_mfma_f32_16x16x32_bf16 v[8:11], v[162:165], v[218:221], v[8:11]
	v_mfma_f32_16x16x32_bf16 v[4:7], v[170:173], v[218:221], v[4:7]
	s_setprio 0
	s_setprio 1
	v_mfma_f32_16x16x32_bf16 v[60:63], v[174:177], v[190:193], v[60:63]
	v_mfma_f32_16x16x32_bf16 v[48:51], v[182:185], v[190:193], v[48:51]
	v_mfma_f32_16x16x32_bf16 v[44:47], v[174:177], v[198:201], v[44:47]
	v_mfma_f32_16x16x32_bf16 v[32:35], v[182:185], v[198:201], v[32:35]
	v_mfma_f32_16x16x32_bf16 v[28:31], v[174:177], v[206:209], v[28:31]
	v_mfma_f32_16x16x32_bf16 v[16:19], v[182:185], v[206:209], v[16:19]
	v_mfma_f32_16x16x32_bf16 v[12:15], v[174:177], v[214:217], v[12:15]
	v_mfma_f32_16x16x32_bf16 v[0:3], v[182:185], v[214:217], v[0:3]
	v_mfma_f32_16x16x32_bf16 v[60:63], v[178:181], v[194:197], v[60:63]
	v_mfma_f32_16x16x32_bf16 v[48:51], v[186:189], v[194:197], v[48:51]
	v_mfma_f32_16x16x32_bf16 v[44:47], v[178:181], v[202:205], v[44:47]
	v_mfma_f32_16x16x32_bf16 v[32:35], v[186:189], v[202:205], v[32:35]
	v_mfma_f32_16x16x32_bf16 v[28:31], v[178:181], v[210:213], v[28:31]
	v_mfma_f32_16x16x32_bf16 v[16:19], v[186:189], v[210:213], v[16:19]
	v_mfma_f32_16x16x32_bf16 v[12:15], v[178:181], v[218:221], v[12:15]
	v_mfma_f32_16x16x32_bf16 v[0:3], v[186:189], v[218:221], v[0:3]
	s_setprio 0
	s_barrier
	s_add_i32 s57, s57, 2
	s_add_u32 s30, s30, 0x100
	s_addc_u32 s31, s31, 0
	s_add_u32 s55, s55, 0x100
	s_addc_u32 s56, s56, 0
	s_cmp_gt_u32 s57, 13
	s_cbranch_scc0 .LBB0_977
	s_and_b64 vcc, exec, s[14:15]
	s_cbranch_vccz .LBB0_982
	s_barrier
	v_lshl_add_u32 v152, s28, 8, v139
	s_cmp_gt_i32 s26, 21
	s_mov_b64 s[28:29], -1
	s_cbranch_scc1 .LBB0_983

.LBB0_1065:
	ds_read_b128 v[140:143], v147
	ds_read_b128 v[152:155], v147 offset:1024
	ds_read_b128 v[156:159], v147 offset:2048
	ds_read_b128 v[160:163], v147 offset:3072
	ds_read_b128 v[164:167], v148
	ds_read_b128 v[168:171], v148 offset:1024
	ds_read_b128 v[172:175], v148 offset:2048
	ds_read_b128 v[176:179], v148 offset:3072
	s_add_u32 s24, s22, 0x100
	s_addc_u32 s25, s23, 0
	s_cmp_eq_u32 s52, 40
	s_cselect_b32 s29, s7, s25
	s_cselect_b32 s28, s6, s24
	s_cselect_b32 s27, s21, s51
	s_cselect_b32 s26, s20, s50
	v_lshl_add_u64 v[212:213], s[22:23], 0, v[132:133]
	s_add_i32 m0, s35, 0xc000
	ds_read_b128 v[180:183], v149
	ds_read_b128 v[184:187], v149 offset:1024
	ds_read_b128 v[188:191], v149 offset:2048
	ds_read_b128 v[192:195], v149 offset:3072
	ds_read_b128 v[196:199], v149 offset:4096
	ds_read_b128 v[200:203], v149 offset:5120
	ds_read_b128 v[204:207], v149 offset:6144
	ds_read_b128 v[208:211], v149 offset:7168
	global_load_lds_dwordx4 v[212:213], off
	v_lshl_add_u64 v[212:213], s[22:23], 0, v[134:135]
	s_add_i32 m0, s35, 0xe000
	s_nop 0
	global_load_lds_dwordx4 v[212:213], off
	s_waitcnt vmcnt(8)
	s_waitcnt lgkmcnt(0)
	s_barrier
	s_setprio 1
	v_mfma_f32_16x16x32_bf16 v[124:127], v[140:143], v[180:183], v[124:127]
	v_mfma_f32_16x16x32_bf16 v[120:123], v[156:159], v[180:183], v[120:123]
	v_mfma_f32_16x16x32_bf16 v[108:111], v[140:143], v[188:191], v[108:111]
	v_mfma_f32_16x16x32_bf16 v[104:107], v[156:159], v[188:191], v[104:107]
	v_mfma_f32_16x16x32_bf16 v[92:95], v[140:143], v[196:199], v[92:95]
	v_mfma_f32_16x16x32_bf16 v[88:91], v[156:159], v[196:199], v[88:91]
	v_mfma_f32_16x16x32_bf16 v[76:79], v[140:143], v[204:207], v[76:79]
	v_mfma_f32_16x16x32_bf16 v[72:75], v[156:159], v[204:207], v[72:75]
	v_mfma_f32_16x16x32_bf16 v[124:127], v[152:155], v[184:187], v[124:127]
	v_mfma_f32_16x16x32_bf16 v[120:123], v[160:163], v[184:187], v[120:123]
	v_mfma_f32_16x16x32_bf16 v[108:111], v[152:155], v[192:195], v[108:111]
	v_mfma_f32_16x16x32_bf16 v[104:107], v[160:163], v[192:195], v[104:107]
	v_mfma_f32_16x16x32_bf16 v[92:95], v[152:155], v[200:203], v[92:95]
	v_mfma_f32_16x16x32_bf16 v[88:91], v[160:163], v[200:203], v[88:91]
	v_mfma_f32_16x16x32_bf16 v[76:79], v[152:155], v[208:211], v[76:79]
	v_mfma_f32_16x16x32_bf16 v[72:75], v[160:163], v[208:211], v[72:75]
	s_setprio 0
	s_setprio 1
	v_mfma_f32_16x16x32_bf16 v[116:119], v[164:167], v[180:183], v[116:119]
	v_mfma_f32_16x16x32_bf16 v[112:115], v[172:175], v[180:183], v[112:115]
	v_mfma_f32_16x16x32_bf16 v[100:103], v[164:167], v[188:191], v[100:103]
	v_mfma_f32_16x16x32_bf16 v[96:99], v[172:175], v[188:191], v[96:99]
	v_mfma_f32_16x16x32_bf16 v[84:87], v[164:167], v[196:199], v[84:87]
	v_mfma_f32_16x16x32_bf16 v[80:83], v[172:175], v[196:199], v[80:83]
	v_mfma_f32_16x16x32_bf16 v[68:71], v[164:167], v[204:207], v[68:71]
	v_mfma_f32_16x16x32_bf16 v[64:67], v[172:175], v[204:207], v[64:67]
	v_mfma_f32_16x16x32_bf16 v[116:119], v[168:171], v[184:187], v[116:119]
	v_mfma_f32_16x16x32_bf16 v[112:115], v[176:179], v[184:187], v[112:115]
	v_mfma_f32_16x16x32_bf16 v[100:103], v[168:171], v[192:195], v[100:103]
	v_mfma_f32_16x16x32_bf16 v[96:99], v[176:179], v[192:195], v[96:99]
	v_mfma_f32_16x16x32_bf16 v[84:87], v[168:171], v[200:203], v[84:87]
	v_mfma_f32_16x16x32_bf16 v[80:83], v[176:179], v[200:203], v[80:83]
	v_mfma_f32_16x16x32_bf16 v[68:71], v[168:171], v[208:211], v[68:71]
	v_mfma_f32_16x16x32_bf16 v[64:67], v[176:179], v[208:211], v[64:67]
	s_setprio 0
	s_barrier
	s_add_i32 s22, s44, s34
	v_lshl_add_u64 v[212:213], s[26:27], 0, v[128:129]
	s_mov_b32 m0, s22
	ds_read_b128 v[180:183], v149 offset:16384
	ds_read_b128 v[184:187], v149 offset:17408
	ds_read_b128 v[188:191], v149 offset:18432
	ds_read_b128 v[192:195], v149 offset:19456
	ds_read_b128 v[196:199], v149 offset:20480
	ds_read_b128 v[200:203], v149 offset:21504
	ds_read_b128 v[204:207], v149 offset:22528
	ds_read_b128 v[208:211], v149 offset:23552
	global_load_lds_dwordx4 v[212:213], off
	s_add_i32 m0, s22, 0x2000
	s_add_u32 s22, s26, 0xb0000
	v_lshl_add_u64 v[214:215], s[26:27], 0, v[130:131]
	s_addc_u32 s23, s27, 0
	s_add_i32 s53, s45, s34
	global_load_lds_dwordx4 v[214:215], off
	v_lshl_add_u64 v[216:217], s[22:23], 0, v[128:129]
	s_mov_b32 m0, s53
	v_lshl_add_u64 v[218:219], s[28:29], 0, v[130:131]
	global_load_lds_dwordx4 v[216:217], off
	v_lshl_add_u64 v[216:217], s[22:23], 0, v[130:131]
	s_add_i32 m0, s53, 0x2000
	s_nop 0
	global_load_lds_dwordx4 v[216:217], off
	v_lshl_add_u64 v[216:217], s[28:29], 0, v[128:129]
	s_mov_b32 m0, s35
	s_nop 0
	global_load_lds_dwordx4 v[216:217], off
	s_mov_b32 m0, s36
	s_nop 0
	global_load_lds_dwordx4 v[218:219], off
	s_waitcnt vmcnt(8)
	s_waitcnt lgkmcnt(0)
	s_barrier
	s_setprio 1
	v_mfma_f32_16x16x32_bf16 v[60:63], v[140:143], v[180:183], v[60:63]
	v_mfma_f32_16x16x32_bf16 v[56:59], v[156:159], v[180:183], v[56:59]
	v_mfma_f32_16x16x32_bf16 v[44:47], v[140:143], v[188:191], v[44:47]
	v_mfma_f32_16x16x32_bf16 v[40:43], v[156:159], v[188:191], v[40:43]
	v_mfma_f32_16x16x32_bf16 v[28:31], v[140:143], v[196:199], v[28:31]
	v_mfma_f32_16x16x32_bf16 v[24:27], v[156:159], v[196:199], v[24:27]
	v_mfma_f32_16x16x32_bf16 v[12:15], v[140:143], v[204:207], v[12:15]
	v_mfma_f32_16x16x32_bf16 v[8:11], v[156:159], v[204:207], v[8:11]
	v_mfma_f32_16x16x32_bf16 v[60:63], v[152:155], v[184:187], v[60:63]
	v_mfma_f32_16x16x32_bf16 v[56:59], v[160:163], v[184:187], v[56:59]
	v_mfma_f32_16x16x32_bf16 v[44:47], v[152:155], v[192:195], v[44:47]
	v_mfma_f32_16x16x32_bf16 v[40:43], v[160:163], v[192:195], v[40:43]
	v_mfma_f32_16x16x32_bf16 v[28:31], v[152:155], v[200:203], v[28:31]
	v_mfma_f32_16x16x32_bf16 v[24:27], v[160:163], v[200:203], v[24:27]
	v_mfma_f32_16x16x32_bf16 v[12:15], v[152:155], v[208:211], v[12:15]
	v_mfma_f32_16x16x32_bf16 v[8:11], v[160:163], v[208:211], v[8:11]
	s_setprio 0
	s_setprio 1
	v_mfma_f32_16x16x32_bf16 v[52:55], v[164:167], v[180:183], v[52:55]
	v_mfma_f32_16x16x32_bf16 v[48:51], v[172:175], v[180:183], v[48:51]
	v_mfma_f32_16x16x32_bf16 v[36:39], v[164:167], v[188:191], v[36:39]
	v_mfma_f32_16x16x32_bf16 v[32:35], v[172:175], v[188:191], v[32:35]
	v_mfma_f32_16x16x32_bf16 v[20:23], v[164:167], v[196:199], v[20:23]
	v_mfma_f32_16x16x32_bf16 v[16:19], v[172:175], v[196:199], v[16:19]
	v_mfma_f32_16x16x32_bf16 v[4:7], v[164:167], v[204:207], v[4:7]
	v_mfma_f32_16x16x32_bf16 v[0:3], v[172:175], v[204:207], v[0:3]
	v_mfma_f32_16x16x32_bf16 v[52:55], v[168:171], v[184:187], v[52:55]
	v_mfma_f32_16x16x32_bf16 v[48:51], v[176:179], v[184:187], v[48:51]
	v_mfma_f32_16x16x32_bf16 v[36:39], v[168:171], v[192:195], v[36:39]
	v_mfma_f32_16x16x32_bf16 v[32:35], v[176:179], v[192:195], v[32:35]
	v_mfma_f32_16x16x32_bf16 v[20:23], v[168:171], v[200:203], v[20:23]
	v_mfma_f32_16x16x32_bf16 v[16:19], v[176:179], v[200:203], v[16:19]
	v_mfma_f32_16x16x32_bf16 v[4:7], v[168:171], v[208:211], v[4:7]
	v_mfma_f32_16x16x32_bf16 v[0:3], v[176:179], v[208:211], v[0:3]
	s_setprio 0
	s_barrier
	s_add_i32 s53, 0, 0x18000
	v_add_u32_e32 v151, s53, v145
	s_add_i32 s54, 0, 0x1c000
	ds_read_b128 v[140:143], v151
	ds_read_b128 v[152:155], v151 offset:1024
	ds_read_b128 v[156:159], v151 offset:2048
	ds_read_b128 v[160:163], v151 offset:3072
	v_add_u32_e32 v151, s54, v145
	ds_read_b128 v[164:167], v151
	ds_read_b128 v[168:171], v151 offset:1024
	ds_read_b128 v[172:175], v151 offset:2048
	ds_read_b128 v[176:179], v151 offset:3072
	s_add_u32 s22, s28, 0xb0000
	s_addc_u32 s23, s29, 0
	s_mov_b32 m0, s37
	v_lshl_add_u64 v[220:221], s[22:23], 0, v[128:129]
	ds_read_b128 v[180:183], v149 offset:32768
	ds_read_b128 v[184:187], v149 offset:33792
	ds_read_b128 v[188:191], v149 offset:34816
	ds_read_b128 v[192:195], v149 offset:35840
	ds_read_b128 v[196:199], v149 offset:36864
	ds_read_b128 v[200:203], v149 offset:37888
	ds_read_b128 v[204:207], v149 offset:38912
	ds_read_b128 v[208:211], v149 offset:39936
	global_load_lds_dwordx4 v[220:221], off
	v_lshl_add_u64 v[220:221], s[22:23], 0, v[130:131]
	s_mov_b32 m0, s38
	s_nop 0
	global_load_lds_dwordx4 v[220:221], off
	s_waitcnt vmcnt(8)
	s_waitcnt lgkmcnt(0)
	s_barrier
	s_setprio 1
	v_mfma_f32_16x16x32_bf16 v[124:127], v[140:143], v[180:183], v[124:127]
	v_mfma_f32_16x16x32_bf16 v[120:123], v[156:159], v[180:183], v[120:123]
	v_mfma_f32_16x16x32_bf16 v[108:111], v[140:143], v[188:191], v[108:111]
	v_mfma_f32_16x16x32_bf16 v[104:107], v[156:159], v[188:191], v[104:107]
	v_mfma_f32_16x16x32_bf16 v[92:95], v[140:143], v[196:199], v[92:95]
	v_mfma_f32_16x16x32_bf16 v[88:91], v[156:159], v[196:199], v[88:91]
	v_mfma_f32_16x16x32_bf16 v[76:79], v[140:143], v[204:207], v[76:79]
	v_mfma_f32_16x16x32_bf16 v[72:75], v[156:159], v[204:207], v[72:75]
	v_mfma_f32_16x16x32_bf16 v[124:127], v[152:155], v[184:187], v[124:127]
	v_mfma_f32_16x16x32_bf16 v[120:123], v[160:163], v[184:187], v[120:123]
	v_mfma_f32_16x16x32_bf16 v[108:111], v[152:155], v[192:195], v[108:111]
	v_mfma_f32_16x16x32_bf16 v[104:107], v[160:163], v[192:195], v[104:107]
	v_mfma_f32_16x16x32_bf16 v[92:95], v[152:155], v[200:203], v[92:95]
	v_mfma_f32_16x16x32_bf16 v[88:91], v[160:163], v[200:203], v[88:91]
	v_mfma_f32_16x16x32_bf16 v[76:79], v[152:155], v[208:211], v[76:79]
	v_mfma_f32_16x16x32_bf16 v[72:75], v[160:163], v[208:211], v[72:75]
	s_setprio 0
	s_setprio 1
	v_mfma_f32_16x16x32_bf16 v[116:119], v[164:167], v[180:183], v[116:119]
	v_mfma_f32_16x16x32_bf16 v[112:115], v[172:175], v[180:183], v[112:115]
	v_mfma_f32_16x16x32_bf16 v[100:103], v[164:167], v[188:191], v[100:103]
	v_mfma_f32_16x16x32_bf16 v[96:99], v[172:175], v[188:191], v[96:99]
	v_mfma_f32_16x16x32_bf16 v[84:87], v[164:167], v[196:199], v[84:87]
	v_mfma_f32_16x16x32_bf16 v[80:83], v[172:175], v[196:199], v[80:83]
	v_mfma_f32_16x16x32_bf16 v[68:71], v[164:167], v[204:207], v[68:71]
	v_mfma_f32_16x16x32_bf16 v[64:67], v[172:175], v[204:207], v[64:67]
	v_mfma_f32_16x16x32_bf16 v[116:119], v[168:171], v[184:187], v[116:119]
	v_mfma_f32_16x16x32_bf16 v[112:115], v[176:179], v[184:187], v[112:115]
	v_mfma_f32_16x16x32_bf16 v[100:103], v[168:171], v[192:195], v[100:103]
	v_mfma_f32_16x16x32_bf16 v[96:99], v[176:179], v[192:195], v[96:99]
	v_mfma_f32_16x16x32_bf16 v[84:87], v[168:171], v[200:203], v[84:87]
	v_mfma_f32_16x16x32_bf16 v[80:83], v[176:179], v[200:203], v[80:83]
	v_mfma_f32_16x16x32_bf16 v[68:71], v[168:171], v[208:211], v[68:71]
	v_mfma_f32_16x16x32_bf16 v[64:67], v[176:179], v[208:211], v[64:67]
	s_setprio 0
	s_barrier
	s_add_i32 s22, s53, s34
	v_lshl_add_u64 v[212:213], v[212:213], 0, s[16:17]
	s_mov_b32 m0, s22
	ds_read_b128 v[180:183], v149 offset:49152
	ds_read_b128 v[184:187], v149 offset:50176
	ds_read_b128 v[188:191], v149 offset:51200
	ds_read_b128 v[192:195], v149 offset:52224
	ds_read_b128 v[196:199], v149 offset:53248
	ds_read_b128 v[200:203], v149 offset:54272
	ds_read_b128 v[204:207], v149 offset:55296
	ds_read_b128 v[208:211], v149 offset:56320
	global_load_lds_dwordx4 v[212:213], off
	s_add_i32 m0, s22, 0x2000
	s_add_u32 s22, s26, 0xb0080
	v_lshl_add_u64 v[212:213], v[214:215], 0, s[16:17]
	s_addc_u32 s23, s27, 0
	s_add_i32 s26, s54, s34
	global_load_lds_dwordx4 v[212:213], off
	v_lshl_add_u64 v[212:213], s[22:23], 0, v[128:129]
	s_mov_b32 m0, s26
	s_nop 0
	global_load_lds_dwordx4 v[212:213], off
	v_lshl_add_u64 v[212:213], s[22:23], 0, v[130:131]
	s_add_i32 m0, s26, 0x2000
	s_nop 0
	global_load_lds_dwordx4 v[212:213], off
	v_lshl_add_u64 v[212:213], v[216:217], 0, s[16:17]
	s_mov_b32 m0, s40
	s_nop 0
	global_load_lds_dwordx4 v[212:213], off
	v_lshl_add_u64 v[212:213], v[218:219], 0, s[16:17]
	s_mov_b32 m0, s41
	s_nop 0
	global_load_lds_dwordx4 v[212:213], off
	s_waitcnt vmcnt(8)
	s_waitcnt lgkmcnt(0)
	s_barrier
	s_setprio 1
	v_mfma_f32_16x16x32_bf16 v[60:63], v[140:143], v[180:183], v[60:63]
	v_mfma_f32_16x16x32_bf16 v[56:59], v[156:159], v[180:183], v[56:59]
	v_mfma_f32_16x16x32_bf16 v[44:47], v[140:143], v[188:191], v[44:47]
	v_mfma_f32_16x16x32_bf16 v[40:43], v[156:159], v[188:191], v[40:43]
	v_mfma_f32_16x16x32_bf16 v[28:31], v[140:143], v[196:199], v[28:31]
	v_mfma_f32_16x16x32_bf16 v[24:27], v[156:159], v[196:199], v[24:27]
	v_mfma_f32_16x16x32_bf16 v[12:15], v[140:143], v[204:207], v[12:15]
	v_mfma_f32_16x16x32_bf16 v[8:11], v[156:159], v[204:207], v[8:11]
	v_mfma_f32_16x16x32_bf16 v[60:63], v[152:155], v[184:187], v[60:63]
	v_mfma_f32_16x16x32_bf16 v[56:59], v[160:163], v[184:187], v[56:59]
	v_mfma_f32_16x16x32_bf16 v[44:47], v[152:155], v[192:195], v[44:47]
	v_mfma_f32_16x16x32_bf16 v[40:43], v[160:163], v[192:195], v[40:43]
	v_mfma_f32_16x16x32_bf16 v[28:31], v[152:155], v[200:203], v[28:31]
	v_mfma_f32_16x16x32_bf16 v[24:27], v[160:163], v[200:203], v[24:27]
	v_mfma_f32_16x16x32_bf16 v[12:15], v[152:155], v[208:211], v[12:15]
	v_mfma_f32_16x16x32_bf16 v[8:11], v[160:163], v[208:211], v[8:11]
	s_setprio 0
	s_setprio 1
	v_mfma_f32_16x16x32_bf16 v[52:55], v[164:167], v[180:183], v[52:55]
	v_mfma_f32_16x16x32_bf16 v[48:51], v[172:175], v[180:183], v[48:51]
	v_mfma_f32_16x16x32_bf16 v[36:39], v[164:167], v[188:191], v[36:39]
	v_mfma_f32_16x16x32_bf16 v[32:35], v[172:175], v[188:191], v[32:35]
	v_mfma_f32_16x16x32_bf16 v[20:23], v[164:167], v[196:199], v[20:23]
	v_mfma_f32_16x16x32_bf16 v[16:19], v[172:175], v[196:199], v[16:19]
	v_mfma_f32_16x16x32_bf16 v[4:7], v[164:167], v[204:207], v[4:7]
	v_mfma_f32_16x16x32_bf16 v[0:3], v[172:175], v[204:207], v[0:3]
	v_mfma_f32_16x16x32_bf16 v[52:55], v[168:171], v[184:187], v[52:55]
	v_mfma_f32_16x16x32_bf16 v[48:51], v[176:179], v[184:187], v[48:51]
	v_mfma_f32_16x16x32_bf16 v[36:39], v[168:171], v[192:195], v[36:39]
	v_mfma_f32_16x16x32_bf16 v[32:35], v[176:179], v[192:195], v[32:35]
	v_mfma_f32_16x16x32_bf16 v[20:23], v[168:171], v[200:203], v[20:23]
	v_mfma_f32_16x16x32_bf16 v[16:19], v[176:179], v[200:203], v[16:19]
	v_mfma_f32_16x16x32_bf16 v[4:7], v[168:171], v[208:211], v[4:7]
	v_mfma_f32_16x16x32_bf16 v[0:3], v[176:179], v[208:211], v[0:3]
	s_setprio 0
	s_barrier
	s_add_i32 s52, s52, 2
	s_add_u32 s50, s50, 0x100
	s_addc_u32 s51, s51, 0
	s_cmp_gt_u32 s52, 41
	s_mov_b64 s[22:23], s[24:25]
	s_cbranch_scc0 .LBB0_1065
	s_and_b64 vcc, exec, s[18:19]
	s_cbranch_vccz .LBB0_1068
	s_barrier

.LBB0_1131:
	ds_read_b128 v[154:157], v160
	ds_read_b128 v[166:169], v160 offset:1024
	ds_read_b128 v[170:173], v160 offset:2048
	ds_read_b128 v[174:177], v160 offset:3072
	ds_read_b128 v[178:181], v161
	ds_read_b128 v[182:185], v161 offset:1024
	ds_read_b128 v[186:189], v161 offset:2048
	ds_read_b128 v[190:193], v161 offset:3072
	s_add_u32 s36, s34, 0xfffc0080
	s_addc_u32 s37, s35, -1
	s_cmp_eq_u32 s58, 12
	s_cselect_b32 s39, s23, s37
	s_cselect_b32 s38, s29, s36
	s_cselect_b32 s37, s21, s57
	s_cselect_b32 s36, s31, s56
	v_lshl_add_u64 v[226:227], s[34:35], 0, v[146:147]
	s_add_i32 m0, s43, 0xc000
	ds_read_b128 v[194:197], v162
	ds_read_b128 v[198:201], v162 offset:1024
	ds_read_b128 v[202:205], v162 offset:2048
	ds_read_b128 v[206:209], v162 offset:3072
	ds_read_b128 v[210:213], v162 offset:4096
	ds_read_b128 v[214:217], v162 offset:5120
	ds_read_b128 v[218:221], v162 offset:6144
	ds_read_b128 v[222:225], v162 offset:7168
	global_load_lds_dwordx4 v[226:227], off
	v_lshl_add_u64 v[226:227], s[34:35], 0, v[148:149]
	s_add_i32 m0, s43, 0xe000
	s_nop 0
	global_load_lds_dwordx4 v[226:227], off
	s_waitcnt vmcnt(8)
	s_waitcnt lgkmcnt(0)
	s_barrier
	s_setprio 1
	v_mfma_f32_16x16x32_bf16 v[116:119], v[154:157], v[194:197], v[116:119]
	v_mfma_f32_16x16x32_bf16 v[112:115], v[170:173], v[194:197], v[112:115]
	v_mfma_f32_16x16x32_bf16 v[100:103], v[154:157], v[202:205], v[100:103]
	v_mfma_f32_16x16x32_bf16 v[96:99], v[170:173], v[202:205], v[96:99]
	v_mfma_f32_16x16x32_bf16 v[88:91], v[154:157], v[210:213], v[88:91]
	v_mfma_f32_16x16x32_bf16 v[84:87], v[170:173], v[210:213], v[84:87]
	v_mfma_f32_16x16x32_bf16 v[72:75], v[154:157], v[218:221], v[72:75]
	v_mfma_f32_16x16x32_bf16 v[68:71], v[170:173], v[218:221], v[68:71]
	v_mfma_f32_16x16x32_bf16 v[116:119], v[166:169], v[198:201], v[116:119]
	v_mfma_f32_16x16x32_bf16 v[112:115], v[174:177], v[198:201], v[112:115]
	v_mfma_f32_16x16x32_bf16 v[100:103], v[166:169], v[206:209], v[100:103]
	v_mfma_f32_16x16x32_bf16 v[96:99], v[174:177], v[206:209], v[96:99]
	v_mfma_f32_16x16x32_bf16 v[88:91], v[166:169], v[214:217], v[88:91]
	v_mfma_f32_16x16x32_bf16 v[84:87], v[174:177], v[214:217], v[84:87]
	v_mfma_f32_16x16x32_bf16 v[72:75], v[166:169], v[222:225], v[72:75]
	v_mfma_f32_16x16x32_bf16 v[68:71], v[174:177], v[222:225], v[68:71]
	s_setprio 0
	s_setprio 1
	v_mfma_f32_16x16x32_bf16 v[124:127], v[178:181], v[194:197], v[124:127]
	v_mfma_f32_16x16x32_bf16 v[120:123], v[186:189], v[194:197], v[120:123]
	v_mfma_f32_16x16x32_bf16 v[108:111], v[178:181], v[202:205], v[108:111]
	v_mfma_f32_16x16x32_bf16 v[104:107], v[186:189], v[202:205], v[104:107]
	v_mfma_f32_16x16x32_bf16 v[92:95], v[178:181], v[210:213], v[92:95]
	v_mfma_f32_16x16x32_bf16 v[80:83], v[186:189], v[210:213], v[80:83]
	v_mfma_f32_16x16x32_bf16 v[76:79], v[178:181], v[218:221], v[76:79]
	v_mfma_f32_16x16x32_bf16 v[64:67], v[186:189], v[218:221], v[64:67]
	v_mfma_f32_16x16x32_bf16 v[124:127], v[182:185], v[198:201], v[124:127]
	v_mfma_f32_16x16x32_bf16 v[120:123], v[190:193], v[198:201], v[120:123]
	v_mfma_f32_16x16x32_bf16 v[108:111], v[182:185], v[206:209], v[108:111]
	v_mfma_f32_16x16x32_bf16 v[104:107], v[190:193], v[206:209], v[104:107]
	v_mfma_f32_16x16x32_bf16 v[92:95], v[182:185], v[214:217], v[92:95]
	v_mfma_f32_16x16x32_bf16 v[80:83], v[190:193], v[214:217], v[80:83]
	v_mfma_f32_16x16x32_bf16 v[76:79], v[182:185], v[222:225], v[76:79]
	v_mfma_f32_16x16x32_bf16 v[64:67], v[190:193], v[222:225], v[64:67]
	s_setprio 0
	s_barrier
	s_add_i32 s59, s52, s42
	v_lshl_add_u64 v[226:227], s[36:37], 0, v[130:131]
	s_mov_b32 m0, s59
	ds_read_b128 v[194:197], v162 offset:16384
	ds_read_b128 v[198:201], v162 offset:17408
	ds_read_b128 v[202:205], v162 offset:18432
	ds_read_b128 v[206:209], v162 offset:19456
	ds_read_b128 v[210:213], v162 offset:20480
	ds_read_b128 v[214:217], v162 offset:21504
	ds_read_b128 v[218:221], v162 offset:22528
	ds_read_b128 v[222:225], v162 offset:23552
	global_load_lds_dwordx4 v[226:227], off
	s_add_i32 m0, s59, 0x2000
	s_add_u32 s60, s36, 0x40000
	v_lshl_add_u64 v[228:229], s[36:37], 0, v[134:135]
	s_addc_u32 s61, s37, 0
	s_add_i32 s59, s53, s42
	global_load_lds_dwordx4 v[228:229], off
	v_lshl_add_u64 v[230:231], s[60:61], 0, v[130:131]
	s_mov_b32 m0, s59
	v_lshl_add_u64 v[232:233], s[38:39], 0, v[132:133]
	global_load_lds_dwordx4 v[230:231], off
	v_lshl_add_u64 v[230:231], s[60:61], 0, v[134:135]
	s_add_i32 m0, s59, 0x2000
	s_nop 0
	global_load_lds_dwordx4 v[230:231], off
	v_lshl_add_u64 v[230:231], s[38:39], 0, v[128:129]
	s_mov_b32 m0, s43
	s_nop 0
	global_load_lds_dwordx4 v[230:231], off
	s_mov_b32 m0, s44
	s_nop 0
	global_load_lds_dwordx4 v[232:233], off
	s_waitcnt vmcnt(8)
	s_waitcnt lgkmcnt(0)
	s_barrier
	s_setprio 1
	v_mfma_f32_16x16x32_bf16 v[56:59], v[154:157], v[194:197], v[56:59]
	v_mfma_f32_16x16x32_bf16 v[52:55], v[170:173], v[194:197], v[52:55]
	v_mfma_f32_16x16x32_bf16 v[40:43], v[154:157], v[202:205], v[40:43]
	v_mfma_f32_16x16x32_bf16 v[36:39], v[170:173], v[202:205], v[36:39]
	v_mfma_f32_16x16x32_bf16 v[24:27], v[154:157], v[210:213], v[24:27]
	v_mfma_f32_16x16x32_bf16 v[20:23], v[170:173], v[210:213], v[20:23]
	v_mfma_f32_16x16x32_bf16 v[8:11], v[154:157], v[218:221], v[8:11]
	v_mfma_f32_16x16x32_bf16 v[4:7], v[170:173], v[218:221], v[4:7]
	v_mfma_f32_16x16x32_bf16 v[56:59], v[166:169], v[198:201], v[56:59]
	v_mfma_f32_16x16x32_bf16 v[52:55], v[174:177], v[198:201], v[52:55]
	v_mfma_f32_16x16x32_bf16 v[40:43], v[166:169], v[206:209], v[40:43]
	v_mfma_f32_16x16x32_bf16 v[36:39], v[174:177], v[206:209], v[36:39]
	v_mfma_f32_16x16x32_bf16 v[24:27], v[166:169], v[214:217], v[24:27]
	v_mfma_f32_16x16x32_bf16 v[20:23], v[174:177], v[214:217], v[20:23]
	v_mfma_f32_16x16x32_bf16 v[8:11], v[166:169], v[222:225], v[8:11]
	v_mfma_f32_16x16x32_bf16 v[4:7], v[174:177], v[222:225], v[4:7]
	s_setprio 0
	s_setprio 1
	v_mfma_f32_16x16x32_bf16 v[60:63], v[178:181], v[194:197], v[60:63]
	v_mfma_f32_16x16x32_bf16 v[48:51], v[186:189], v[194:197], v[48:51]
	v_mfma_f32_16x16x32_bf16 v[44:47], v[178:181], v[202:205], v[44:47]
	v_mfma_f32_16x16x32_bf16 v[32:35], v[186:189], v[202:205], v[32:35]
	v_mfma_f32_16x16x32_bf16 v[28:31], v[178:181], v[210:213], v[28:31]
	v_mfma_f32_16x16x32_bf16 v[16:19], v[186:189], v[210:213], v[16:19]
	v_mfma_f32_16x16x32_bf16 v[12:15], v[178:181], v[218:221], v[12:15]
	v_mfma_f32_16x16x32_bf16 v[0:3], v[186:189], v[218:221], v[0:3]
	v_mfma_f32_16x16x32_bf16 v[60:63], v[182:185], v[198:201], v[60:63]
	v_mfma_f32_16x16x32_bf16 v[48:51], v[190:193], v[198:201], v[48:51]
	v_mfma_f32_16x16x32_bf16 v[44:47], v[182:185], v[206:209], v[44:47]
	v_mfma_f32_16x16x32_bf16 v[32:35], v[190:193], v[206:209], v[32:35]
	v_mfma_f32_16x16x32_bf16 v[28:31], v[182:185], v[214:217], v[28:31]
	v_mfma_f32_16x16x32_bf16 v[16:19], v[190:193], v[214:217], v[16:19]
	v_mfma_f32_16x16x32_bf16 v[12:15], v[182:185], v[222:225], v[12:15]
	v_mfma_f32_16x16x32_bf16 v[0:3], v[190:193], v[222:225], v[0:3]
	s_setprio 0
	s_barrier
	s_add_i32 s59, 0, 0x18000
	v_add_u32_e32 v165, s59, v159
	s_add_i32 s60, 0, 0x1c000
	ds_read_b128 v[154:157], v165
	ds_read_b128 v[166:169], v165 offset:1024
	ds_read_b128 v[170:173], v165 offset:2048
	ds_read_b128 v[174:177], v165 offset:3072
	v_add_u32_e32 v165, s60, v159
	ds_read_b128 v[178:181], v165
	ds_read_b128 v[182:185], v165 offset:1024
	ds_read_b128 v[186:189], v165 offset:2048
	ds_read_b128 v[190:193], v165 offset:3072
	s_add_u32 s38, s38, 0x40000
	s_addc_u32 s39, s39, 0
	s_mov_b32 m0, s45
	v_lshl_add_u64 v[234:235], s[38:39], 0, v[128:129]
	ds_read_b128 v[194:197], v162 offset:32768
	ds_read_b128 v[198:201], v162 offset:33792
	ds_read_b128 v[202:205], v162 offset:34816
	ds_read_b128 v[206:209], v162 offset:35840
	ds_read_b128 v[210:213], v162 offset:36864
	ds_read_b128 v[214:217], v162 offset:37888
	ds_read_b128 v[218:221], v162 offset:38912
	ds_read_b128 v[222:225], v162 offset:39936
	global_load_lds_dwordx4 v[234:235], off
	v_lshl_add_u64 v[234:235], s[38:39], 0, v[132:133]
	s_mov_b32 m0, s46
	s_nop 0
	global_load_lds_dwordx4 v[234:235], off
	s_waitcnt vmcnt(8)
	s_waitcnt lgkmcnt(0)
	s_barrier
	s_setprio 1
	v_mfma_f32_16x16x32_bf16 v[116:119], v[154:157], v[194:197], v[116:119]
	v_mfma_f32_16x16x32_bf16 v[112:115], v[170:173], v[194:197], v[112:115]
	v_mfma_f32_16x16x32_bf16 v[100:103], v[154:157], v[202:205], v[100:103]
	v_mfma_f32_16x16x32_bf16 v[96:99], v[170:173], v[202:205], v[96:99]
	v_mfma_f32_16x16x32_bf16 v[88:91], v[154:157], v[210:213], v[88:91]
	v_mfma_f32_16x16x32_bf16 v[84:87], v[170:173], v[210:213], v[84:87]
	v_mfma_f32_16x16x32_bf16 v[72:75], v[154:157], v[218:221], v[72:75]
	v_mfma_f32_16x16x32_bf16 v[68:71], v[170:173], v[218:221], v[68:71]
	v_mfma_f32_16x16x32_bf16 v[116:119], v[166:169], v[198:201], v[116:119]
	v_mfma_f32_16x16x32_bf16 v[112:115], v[174:177], v[198:201], v[112:115]
	v_mfma_f32_16x16x32_bf16 v[100:103], v[166:169], v[206:209], v[100:103]
	v_mfma_f32_16x16x32_bf16 v[96:99], v[174:177], v[206:209], v[96:99]
	v_mfma_f32_16x16x32_bf16 v[88:91], v[166:169], v[214:217], v[88:91]
	v_mfma_f32_16x16x32_bf16 v[84:87], v[174:177], v[214:217], v[84:87]
	v_mfma_f32_16x16x32_bf16 v[72:75], v[166:169], v[222:225], v[72:75]
	v_mfma_f32_16x16x32_bf16 v[68:71], v[174:177], v[222:225], v[68:71]
	s_setprio 0
	s_setprio 1
	v_mfma_f32_16x16x32_bf16 v[124:127], v[178:181], v[194:197], v[124:127]
	v_mfma_f32_16x16x32_bf16 v[120:123], v[186:189], v[194:197], v[120:123]
	v_mfma_f32_16x16x32_bf16 v[108:111], v[178:181], v[202:205], v[108:111]
	v_mfma_f32_16x16x32_bf16 v[104:107], v[186:189], v[202:205], v[104:107]
	v_mfma_f32_16x16x32_bf16 v[92:95], v[178:181], v[210:213], v[92:95]
	v_mfma_f32_16x16x32_bf16 v[80:83], v[186:189], v[210:213], v[80:83]
	v_mfma_f32_16x16x32_bf16 v[76:79], v[178:181], v[218:221], v[76:79]
	v_mfma_f32_16x16x32_bf16 v[64:67], v[186:189], v[218:221], v[64:67]
	v_mfma_f32_16x16x32_bf16 v[124:127], v[182:185], v[198:201], v[124:127]
	v_mfma_f32_16x16x32_bf16 v[120:123], v[190:193], v[198:201], v[120:123]
	v_mfma_f32_16x16x32_bf16 v[108:111], v[182:185], v[206:209], v[108:111]
	v_mfma_f32_16x16x32_bf16 v[104:107], v[190:193], v[206:209], v[104:107]
	v_mfma_f32_16x16x32_bf16 v[92:95], v[182:185], v[214:217], v[92:95]
	v_mfma_f32_16x16x32_bf16 v[80:83], v[190:193], v[214:217], v[80:83]
	v_mfma_f32_16x16x32_bf16 v[76:79], v[182:185], v[222:225], v[76:79]
	v_mfma_f32_16x16x32_bf16 v[64:67], v[190:193], v[222:225], v[64:67]
	s_setprio 0
	s_barrier
	s_add_i32 s38, s59, s42
	v_lshl_add_u64 v[226:227], v[226:227], 0, s[12:13]
	s_mov_b32 m0, s38
	ds_read_b128 v[194:197], v162 offset:49152
	ds_read_b128 v[198:201], v162 offset:50176
	ds_read_b128 v[202:205], v162 offset:51200
	ds_read_b128 v[206:209], v162 offset:52224
	ds_read_b128 v[210:213], v162 offset:53248
	ds_read_b128 v[214:217], v162 offset:54272
	ds_read_b128 v[218:221], v162 offset:55296
	ds_read_b128 v[222:225], v162 offset:56320
	global_load_lds_dwordx4 v[226:227], off
	s_add_i32 m0, s38, 0x2000
	s_add_u32 s36, s36, 0x40080
	v_lshl_add_u64 v[226:227], v[228:229], 0, s[12:13]
	s_addc_u32 s37, s37, 0
	s_add_i32 s38, s60, s42
	global_load_lds_dwordx4 v[226:227], off
	v_lshl_add_u64 v[226:227], s[36:37], 0, v[130:131]
	s_mov_b32 m0, s38
	s_nop 0
	global_load_lds_dwordx4 v[226:227], off
	v_lshl_add_u64 v[226:227], s[36:37], 0, v[134:135]
	s_add_i32 m0, s38, 0x2000
	s_nop 0
	global_load_lds_dwordx4 v[226:227], off
	v_lshl_add_u64 v[226:227], v[230:231], 0, s[12:13]
	s_mov_b32 m0, s47
	s_nop 0
	global_load_lds_dwordx4 v[226:227], off
	v_lshl_add_u64 v[226:227], v[232:233], 0, s[12:13]
	s_mov_b32 m0, s48
	s_nop 0
	global_load_lds_dwordx4 v[226:227], off
	s_waitcnt vmcnt(8)
	s_waitcnt lgkmcnt(0)
	s_barrier
	s_setprio 1
	v_mfma_f32_16x16x32_bf16 v[56:59], v[154:157], v[194:197], v[56:59]
	v_mfma_f32_16x16x32_bf16 v[52:55], v[170:173], v[194:197], v[52:55]
	v_mfma_f32_16x16x32_bf16 v[40:43], v[154:157], v[202:205], v[40:43]
	v_mfma_f32_16x16x32_bf16 v[36:39], v[170:173], v[202:205], v[36:39]
	v_mfma_f32_16x16x32_bf16 v[24:27], v[154:157], v[210:213], v[24:27]
	v_mfma_f32_16x16x32_bf16 v[20:23], v[170:173], v[210:213], v[20:23]
	v_mfma_f32_16x16x32_bf16 v[8:11], v[154:157], v[218:221], v[8:11]
	v_mfma_f32_16x16x32_bf16 v[4:7], v[170:173], v[218:221], v[4:7]
	v_mfma_f32_16x16x32_bf16 v[56:59], v[166:169], v[198:201], v[56:59]
	v_mfma_f32_16x16x32_bf16 v[52:55], v[174:177], v[198:201], v[52:55]
	v_mfma_f32_16x16x32_bf16 v[40:43], v[166:169], v[206:209], v[40:43]
	v_mfma_f32_16x16x32_bf16 v[36:39], v[174:177], v[206:209], v[36:39]
	v_mfma_f32_16x16x32_bf16 v[24:27], v[166:169], v[214:217], v[24:27]
	v_mfma_f32_16x16x32_bf16 v[20:23], v[174:177], v[214:217], v[20:23]
	v_mfma_f32_16x16x32_bf16 v[8:11], v[166:169], v[222:225], v[8:11]
	v_mfma_f32_16x16x32_bf16 v[4:7], v[174:177], v[222:225], v[4:7]
	s_setprio 0
	s_setprio 1
	v_mfma_f32_16x16x32_bf16 v[60:63], v[178:181], v[194:197], v[60:63]
	v_mfma_f32_16x16x32_bf16 v[48:51], v[186:189], v[194:197], v[48:51]
	v_mfma_f32_16x16x32_bf16 v[44:47], v[178:181], v[202:205], v[44:47]
	v_mfma_f32_16x16x32_bf16 v[32:35], v[186:189], v[202:205], v[32:35]
	v_mfma_f32_16x16x32_bf16 v[28:31], v[178:181], v[210:213], v[28:31]
	v_mfma_f32_16x16x32_bf16 v[16:19], v[186:189], v[210:213], v[16:19]
	v_mfma_f32_16x16x32_bf16 v[12:15], v[178:181], v[218:221], v[12:15]
	v_mfma_f32_16x16x32_bf16 v[0:3], v[186:189], v[218:221], v[0:3]
	v_mfma_f32_16x16x32_bf16 v[60:63], v[182:185], v[198:201], v[60:63]
	v_mfma_f32_16x16x32_bf16 v[48:51], v[190:193], v[198:201], v[48:51]
	v_mfma_f32_16x16x32_bf16 v[44:47], v[182:185], v[206:209], v[44:47]
	v_mfma_f32_16x16x32_bf16 v[32:35], v[190:193], v[206:209], v[32:35]
	v_mfma_f32_16x16x32_bf16 v[28:31], v[182:185], v[214:217], v[28:31]
	v_mfma_f32_16x16x32_bf16 v[16:19], v[190:193], v[214:217], v[16:19]
	v_mfma_f32_16x16x32_bf16 v[12:15], v[182:185], v[222:225], v[12:15]
	v_mfma_f32_16x16x32_bf16 v[0:3], v[190:193], v[222:225], v[0:3]
	s_setprio 0
	s_barrier
	s_add_i32 s58, s58, 2
	s_add_u32 s34, s34, 0x100
	s_addc_u32 s35, s35, 0
	s_add_u32 s56, s56, 0x100
	s_addc_u32 s57, s57, 0
	s_cmp_gt_u32 s58, 13
	s_cbranch_scc0 .LBB0_1131
	s_and_b64 vcc, exec, s[14:15]
	s_cbranch_vccz .LBB0_1136
	s_barrier
	v_lshl_add_u32 v154, s30, 8, v158
	s_cmp_gt_i32 s28, 21
	s_mov_b64 s[30:31], -1
	s_cbranch_scc1 .LBB0_1137

.LBB0_1219:
	ds_read_b128 v[140:143], v147
	ds_read_b128 v[152:155], v147 offset:1024
	ds_read_b128 v[156:159], v147 offset:2048
	ds_read_b128 v[160:163], v147 offset:3072
	ds_read_b128 v[164:167], v148
	ds_read_b128 v[168:171], v148 offset:1024
	ds_read_b128 v[172:175], v148 offset:2048
	ds_read_b128 v[176:179], v148 offset:3072
	s_add_u32 s26, s24, 0x100
	s_addc_u32 s27, s25, 0
	s_cmp_eq_u32 s54, 40
	s_cselect_b32 s31, s9, s27
	s_cselect_b32 s30, s8, s26
	s_cselect_b32 s29, s23, s53
	s_cselect_b32 s28, s22, s52
	v_lshl_add_u64 v[212:213], s[24:25], 0, v[132:133]
	s_add_i32 m0, s37, 0xc000
	ds_read_b128 v[180:183], v149
	ds_read_b128 v[184:187], v149 offset:1024
	ds_read_b128 v[188:191], v149 offset:2048
	ds_read_b128 v[192:195], v149 offset:3072
	ds_read_b128 v[196:199], v149 offset:4096
	ds_read_b128 v[200:203], v149 offset:5120
	ds_read_b128 v[204:207], v149 offset:6144
	ds_read_b128 v[208:211], v149 offset:7168
	global_load_lds_dwordx4 v[212:213], off
	v_lshl_add_u64 v[212:213], s[24:25], 0, v[134:135]
	s_add_i32 m0, s37, 0xe000
	s_nop 0
	global_load_lds_dwordx4 v[212:213], off
	s_waitcnt vmcnt(8)
	s_waitcnt lgkmcnt(0)
	s_barrier
	s_setprio 1
	v_mfma_f32_16x16x32_bf16 v[124:127], v[140:143], v[180:183], v[124:127]
	v_mfma_f32_16x16x32_bf16 v[120:123], v[156:159], v[180:183], v[120:123]
	v_mfma_f32_16x16x32_bf16 v[108:111], v[140:143], v[188:191], v[108:111]
	v_mfma_f32_16x16x32_bf16 v[104:107], v[156:159], v[188:191], v[104:107]
	v_mfma_f32_16x16x32_bf16 v[92:95], v[140:143], v[196:199], v[92:95]
	v_mfma_f32_16x16x32_bf16 v[88:91], v[156:159], v[196:199], v[88:91]
	v_mfma_f32_16x16x32_bf16 v[76:79], v[140:143], v[204:207], v[76:79]
	v_mfma_f32_16x16x32_bf16 v[72:75], v[156:159], v[204:207], v[72:75]
	v_mfma_f32_16x16x32_bf16 v[124:127], v[152:155], v[184:187], v[124:127]
	v_mfma_f32_16x16x32_bf16 v[120:123], v[160:163], v[184:187], v[120:123]
	v_mfma_f32_16x16x32_bf16 v[108:111], v[152:155], v[192:195], v[108:111]
	v_mfma_f32_16x16x32_bf16 v[104:107], v[160:163], v[192:195], v[104:107]
	v_mfma_f32_16x16x32_bf16 v[92:95], v[152:155], v[200:203], v[92:95]
	v_mfma_f32_16x16x32_bf16 v[88:91], v[160:163], v[200:203], v[88:91]
	v_mfma_f32_16x16x32_bf16 v[76:79], v[152:155], v[208:211], v[76:79]
	v_mfma_f32_16x16x32_bf16 v[72:75], v[160:163], v[208:211], v[72:75]
	s_setprio 0
	s_setprio 1
	v_mfma_f32_16x16x32_bf16 v[116:119], v[164:167], v[180:183], v[116:119]
	v_mfma_f32_16x16x32_bf16 v[112:115], v[172:175], v[180:183], v[112:115]
	v_mfma_f32_16x16x32_bf16 v[100:103], v[164:167], v[188:191], v[100:103]
	v_mfma_f32_16x16x32_bf16 v[96:99], v[172:175], v[188:191], v[96:99]
	v_mfma_f32_16x16x32_bf16 v[84:87], v[164:167], v[196:199], v[84:87]
	v_mfma_f32_16x16x32_bf16 v[80:83], v[172:175], v[196:199], v[80:83]
	v_mfma_f32_16x16x32_bf16 v[68:71], v[164:167], v[204:207], v[68:71]
	v_mfma_f32_16x16x32_bf16 v[64:67], v[172:175], v[204:207], v[64:67]
	v_mfma_f32_16x16x32_bf16 v[116:119], v[168:171], v[184:187], v[116:119]
	v_mfma_f32_16x16x32_bf16 v[112:115], v[176:179], v[184:187], v[112:115]
	v_mfma_f32_16x16x32_bf16 v[100:103], v[168:171], v[192:195], v[100:103]
	v_mfma_f32_16x16x32_bf16 v[96:99], v[176:179], v[192:195], v[96:99]
	v_mfma_f32_16x16x32_bf16 v[84:87], v[168:171], v[200:203], v[84:87]
	v_mfma_f32_16x16x32_bf16 v[80:83], v[176:179], v[200:203], v[80:83]
	v_mfma_f32_16x16x32_bf16 v[68:71], v[168:171], v[208:211], v[68:71]
	v_mfma_f32_16x16x32_bf16 v[64:67], v[176:179], v[208:211], v[64:67]
	s_setprio 0
	s_barrier
	s_add_i32 s24, s46, s36
	v_lshl_add_u64 v[212:213], s[28:29], 0, v[128:129]
	s_mov_b32 m0, s24
	ds_read_b128 v[180:183], v149 offset:16384
	ds_read_b128 v[184:187], v149 offset:17408
	ds_read_b128 v[188:191], v149 offset:18432
	ds_read_b128 v[192:195], v149 offset:19456
	ds_read_b128 v[196:199], v149 offset:20480
	ds_read_b128 v[200:203], v149 offset:21504
	ds_read_b128 v[204:207], v149 offset:22528
	ds_read_b128 v[208:211], v149 offset:23552
	global_load_lds_dwordx4 v[212:213], off
	s_add_i32 m0, s24, 0x2000
	s_add_u32 s24, s28, 0xb0000
	v_lshl_add_u64 v[214:215], s[28:29], 0, v[130:131]
	s_addc_u32 s25, s29, 0
	s_add_i32 s55, s47, s36
	global_load_lds_dwordx4 v[214:215], off
	v_lshl_add_u64 v[216:217], s[24:25], 0, v[128:129]
	s_mov_b32 m0, s55
	v_lshl_add_u64 v[218:219], s[30:31], 0, v[130:131]
	global_load_lds_dwordx4 v[216:217], off
	v_lshl_add_u64 v[216:217], s[24:25], 0, v[130:131]
	s_add_i32 m0, s55, 0x2000
	s_nop 0
	global_load_lds_dwordx4 v[216:217], off
	v_lshl_add_u64 v[216:217], s[30:31], 0, v[128:129]
	s_mov_b32 m0, s37
	s_nop 0
	global_load_lds_dwordx4 v[216:217], off
	s_mov_b32 m0, s38
	s_nop 0
	global_load_lds_dwordx4 v[218:219], off
	s_waitcnt vmcnt(8)
	s_waitcnt lgkmcnt(0)
	s_barrier
	s_setprio 1
	v_mfma_f32_16x16x32_bf16 v[60:63], v[140:143], v[180:183], v[60:63]
	v_mfma_f32_16x16x32_bf16 v[56:59], v[156:159], v[180:183], v[56:59]
	v_mfma_f32_16x16x32_bf16 v[44:47], v[140:143], v[188:191], v[44:47]
	v_mfma_f32_16x16x32_bf16 v[40:43], v[156:159], v[188:191], v[40:43]
	v_mfma_f32_16x16x32_bf16 v[28:31], v[140:143], v[196:199], v[28:31]
	v_mfma_f32_16x16x32_bf16 v[24:27], v[156:159], v[196:199], v[24:27]
	v_mfma_f32_16x16x32_bf16 v[12:15], v[140:143], v[204:207], v[12:15]
	v_mfma_f32_16x16x32_bf16 v[8:11], v[156:159], v[204:207], v[8:11]
	v_mfma_f32_16x16x32_bf16 v[60:63], v[152:155], v[184:187], v[60:63]
	v_mfma_f32_16x16x32_bf16 v[56:59], v[160:163], v[184:187], v[56:59]
	v_mfma_f32_16x16x32_bf16 v[44:47], v[152:155], v[192:195], v[44:47]
	v_mfma_f32_16x16x32_bf16 v[40:43], v[160:163], v[192:195], v[40:43]
	v_mfma_f32_16x16x32_bf16 v[28:31], v[152:155], v[200:203], v[28:31]
	v_mfma_f32_16x16x32_bf16 v[24:27], v[160:163], v[200:203], v[24:27]
	v_mfma_f32_16x16x32_bf16 v[12:15], v[152:155], v[208:211], v[12:15]
	v_mfma_f32_16x16x32_bf16 v[8:11], v[160:163], v[208:211], v[8:11]
	s_setprio 0
	s_setprio 1
	v_mfma_f32_16x16x32_bf16 v[52:55], v[164:167], v[180:183], v[52:55]
	v_mfma_f32_16x16x32_bf16 v[48:51], v[172:175], v[180:183], v[48:51]
	v_mfma_f32_16x16x32_bf16 v[36:39], v[164:167], v[188:191], v[36:39]
	v_mfma_f32_16x16x32_bf16 v[32:35], v[172:175], v[188:191], v[32:35]
	v_mfma_f32_16x16x32_bf16 v[20:23], v[164:167], v[196:199], v[20:23]
	v_mfma_f32_16x16x32_bf16 v[16:19], v[172:175], v[196:199], v[16:19]
	v_mfma_f32_16x16x32_bf16 v[4:7], v[164:167], v[204:207], v[4:7]
	v_mfma_f32_16x16x32_bf16 v[0:3], v[172:175], v[204:207], v[0:3]
	v_mfma_f32_16x16x32_bf16 v[52:55], v[168:171], v[184:187], v[52:55]
	v_mfma_f32_16x16x32_bf16 v[48:51], v[176:179], v[184:187], v[48:51]
	v_mfma_f32_16x16x32_bf16 v[36:39], v[168:171], v[192:195], v[36:39]
	v_mfma_f32_16x16x32_bf16 v[32:35], v[176:179], v[192:195], v[32:35]
	v_mfma_f32_16x16x32_bf16 v[20:23], v[168:171], v[200:203], v[20:23]
	v_mfma_f32_16x16x32_bf16 v[16:19], v[176:179], v[200:203], v[16:19]
	v_mfma_f32_16x16x32_bf16 v[4:7], v[168:171], v[208:211], v[4:7]
	v_mfma_f32_16x16x32_bf16 v[0:3], v[176:179], v[208:211], v[0:3]
	s_setprio 0
	s_barrier
	s_add_i32 s55, 0, 0x18000
	v_add_u32_e32 v151, s55, v145
	s_add_i32 s56, 0, 0x1c000
	ds_read_b128 v[140:143], v151
	ds_read_b128 v[152:155], v151 offset:1024
	ds_read_b128 v[156:159], v151 offset:2048
	ds_read_b128 v[160:163], v151 offset:3072
	v_add_u32_e32 v151, s56, v145
	ds_read_b128 v[164:167], v151
	ds_read_b128 v[168:171], v151 offset:1024
	ds_read_b128 v[172:175], v151 offset:2048
	ds_read_b128 v[176:179], v151 offset:3072
	s_add_u32 s24, s30, 0xb0000
	s_addc_u32 s25, s31, 0
	s_mov_b32 m0, s39
	v_lshl_add_u64 v[220:221], s[24:25], 0, v[128:129]
	ds_read_b128 v[180:183], v149 offset:32768
	ds_read_b128 v[184:187], v149 offset:33792
	ds_read_b128 v[188:191], v149 offset:34816
	ds_read_b128 v[192:195], v149 offset:35840
	ds_read_b128 v[196:199], v149 offset:36864
	ds_read_b128 v[200:203], v149 offset:37888
	ds_read_b128 v[204:207], v149 offset:38912
	ds_read_b128 v[208:211], v149 offset:39936
	global_load_lds_dwordx4 v[220:221], off
	v_lshl_add_u64 v[220:221], s[24:25], 0, v[130:131]
	s_mov_b32 m0, s40
	s_nop 0
	global_load_lds_dwordx4 v[220:221], off
	s_waitcnt vmcnt(8)
	s_waitcnt lgkmcnt(0)
	s_barrier
	s_setprio 1
	v_mfma_f32_16x16x32_bf16 v[124:127], v[140:143], v[180:183], v[124:127]
	v_mfma_f32_16x16x32_bf16 v[120:123], v[156:159], v[180:183], v[120:123]
	v_mfma_f32_16x16x32_bf16 v[108:111], v[140:143], v[188:191], v[108:111]
	v_mfma_f32_16x16x32_bf16 v[104:107], v[156:159], v[188:191], v[104:107]
	v_mfma_f32_16x16x32_bf16 v[92:95], v[140:143], v[196:199], v[92:95]
	v_mfma_f32_16x16x32_bf16 v[88:91], v[156:159], v[196:199], v[88:91]
	v_mfma_f32_16x16x32_bf16 v[76:79], v[140:143], v[204:207], v[76:79]
	v_mfma_f32_16x16x32_bf16 v[72:75], v[156:159], v[204:207], v[72:75]
	v_mfma_f32_16x16x32_bf16 v[124:127], v[152:155], v[184:187], v[124:127]
	v_mfma_f32_16x16x32_bf16 v[120:123], v[160:163], v[184:187], v[120:123]
	v_mfma_f32_16x16x32_bf16 v[108:111], v[152:155], v[192:195], v[108:111]
	v_mfma_f32_16x16x32_bf16 v[104:107], v[160:163], v[192:195], v[104:107]
	v_mfma_f32_16x16x32_bf16 v[92:95], v[152:155], v[200:203], v[92:95]
	v_mfma_f32_16x16x32_bf16 v[88:91], v[160:163], v[200:203], v[88:91]
	v_mfma_f32_16x16x32_bf16 v[76:79], v[152:155], v[208:211], v[76:79]
	v_mfma_f32_16x16x32_bf16 v[72:75], v[160:163], v[208:211], v[72:75]
	s_setprio 0
	s_setprio 1
	v_mfma_f32_16x16x32_bf16 v[116:119], v[164:167], v[180:183], v[116:119]
	v_mfma_f32_16x16x32_bf16 v[112:115], v[172:175], v[180:183], v[112:115]
	v_mfma_f32_16x16x32_bf16 v[100:103], v[164:167], v[188:191], v[100:103]
	v_mfma_f32_16x16x32_bf16 v[96:99], v[172:175], v[188:191], v[96:99]
	v_mfma_f32_16x16x32_bf16 v[84:87], v[164:167], v[196:199], v[84:87]
	v_mfma_f32_16x16x32_bf16 v[80:83], v[172:175], v[196:199], v[80:83]
	v_mfma_f32_16x16x32_bf16 v[68:71], v[164:167], v[204:207], v[68:71]
	v_mfma_f32_16x16x32_bf16 v[64:67], v[172:175], v[204:207], v[64:67]
	v_mfma_f32_16x16x32_bf16 v[116:119], v[168:171], v[184:187], v[116:119]
	v_mfma_f32_16x16x32_bf16 v[112:115], v[176:179], v[184:187], v[112:115]
	v_mfma_f32_16x16x32_bf16 v[100:103], v[168:171], v[192:195], v[100:103]
	v_mfma_f32_16x16x32_bf16 v[96:99], v[176:179], v[192:195], v[96:99]
	v_mfma_f32_16x16x32_bf16 v[84:87], v[168:171], v[200:203], v[84:87]
	v_mfma_f32_16x16x32_bf16 v[80:83], v[176:179], v[200:203], v[80:83]
	v_mfma_f32_16x16x32_bf16 v[68:71], v[168:171], v[208:211], v[68:71]
	v_mfma_f32_16x16x32_bf16 v[64:67], v[176:179], v[208:211], v[64:67]
	s_setprio 0
	s_barrier
	s_add_i32 s24, s55, s36
	v_lshl_add_u64 v[212:213], v[212:213], 0, s[18:19]
	s_mov_b32 m0, s24
	ds_read_b128 v[180:183], v149 offset:49152
	ds_read_b128 v[184:187], v149 offset:50176
	ds_read_b128 v[188:191], v149 offset:51200
	ds_read_b128 v[192:195], v149 offset:52224
	ds_read_b128 v[196:199], v149 offset:53248
	ds_read_b128 v[200:203], v149 offset:54272
	ds_read_b128 v[204:207], v149 offset:55296
	ds_read_b128 v[208:211], v149 offset:56320
	global_load_lds_dwordx4 v[212:213], off
	s_add_i32 m0, s24, 0x2000
	s_add_u32 s24, s28, 0xb0080
	v_lshl_add_u64 v[212:213], v[214:215], 0, s[18:19]
	s_addc_u32 s25, s29, 0
	s_add_i32 s28, s56, s36
	global_load_lds_dwordx4 v[212:213], off
	v_lshl_add_u64 v[212:213], s[24:25], 0, v[128:129]
	s_mov_b32 m0, s28
	s_nop 0
	global_load_lds_dwordx4 v[212:213], off
	v_lshl_add_u64 v[212:213], s[24:25], 0, v[130:131]
	s_add_i32 m0, s28, 0x2000
	s_nop 0
	global_load_lds_dwordx4 v[212:213], off
	v_lshl_add_u64 v[212:213], v[216:217], 0, s[18:19]
	s_mov_b32 m0, s42
	s_nop 0
	global_load_lds_dwordx4 v[212:213], off
	v_lshl_add_u64 v[212:213], v[218:219], 0, s[18:19]
	s_mov_b32 m0, s43
	s_nop 0
	global_load_lds_dwordx4 v[212:213], off
	s_waitcnt vmcnt(8)
	s_waitcnt lgkmcnt(0)
	s_barrier
	s_setprio 1
	v_mfma_f32_16x16x32_bf16 v[60:63], v[140:143], v[180:183], v[60:63]
	v_mfma_f32_16x16x32_bf16 v[56:59], v[156:159], v[180:183], v[56:59]
	v_mfma_f32_16x16x32_bf16 v[44:47], v[140:143], v[188:191], v[44:47]
	v_mfma_f32_16x16x32_bf16 v[40:43], v[156:159], v[188:191], v[40:43]
	v_mfma_f32_16x16x32_bf16 v[28:31], v[140:143], v[196:199], v[28:31]
	v_mfma_f32_16x16x32_bf16 v[24:27], v[156:159], v[196:199], v[24:27]
	v_mfma_f32_16x16x32_bf16 v[12:15], v[140:143], v[204:207], v[12:15]
	v_mfma_f32_16x16x32_bf16 v[8:11], v[156:159], v[204:207], v[8:11]
	v_mfma_f32_16x16x32_bf16 v[60:63], v[152:155], v[184:187], v[60:63]
	v_mfma_f32_16x16x32_bf16 v[56:59], v[160:163], v[184:187], v[56:59]
	v_mfma_f32_16x16x32_bf16 v[44:47], v[152:155], v[192:195], v[44:47]
	v_mfma_f32_16x16x32_bf16 v[40:43], v[160:163], v[192:195], v[40:43]
	v_mfma_f32_16x16x32_bf16 v[28:31], v[152:155], v[200:203], v[28:31]
	v_mfma_f32_16x16x32_bf16 v[24:27], v[160:163], v[200:203], v[24:27]
	v_mfma_f32_16x16x32_bf16 v[12:15], v[152:155], v[208:211], v[12:15]
	v_mfma_f32_16x16x32_bf16 v[8:11], v[160:163], v[208:211], v[8:11]
	s_setprio 0
	s_setprio 1
	v_mfma_f32_16x16x32_bf16 v[52:55], v[164:167], v[180:183], v[52:55]
	v_mfma_f32_16x16x32_bf16 v[48:51], v[172:175], v[180:183], v[48:51]
	v_mfma_f32_16x16x32_bf16 v[36:39], v[164:167], v[188:191], v[36:39]
	v_mfma_f32_16x16x32_bf16 v[32:35], v[172:175], v[188:191], v[32:35]
	v_mfma_f32_16x16x32_bf16 v[20:23], v[164:167], v[196:199], v[20:23]
	v_mfma_f32_16x16x32_bf16 v[16:19], v[172:175], v[196:199], v[16:19]
	v_mfma_f32_16x16x32_bf16 v[4:7], v[164:167], v[204:207], v[4:7]
	v_mfma_f32_16x16x32_bf16 v[0:3], v[172:175], v[204:207], v[0:3]
	v_mfma_f32_16x16x32_bf16 v[52:55], v[168:171], v[184:187], v[52:55]
	v_mfma_f32_16x16x32_bf16 v[48:51], v[176:179], v[184:187], v[48:51]
	v_mfma_f32_16x16x32_bf16 v[36:39], v[168:171], v[192:195], v[36:39]
	v_mfma_f32_16x16x32_bf16 v[32:35], v[176:179], v[192:195], v[32:35]
	v_mfma_f32_16x16x32_bf16 v[20:23], v[168:171], v[200:203], v[20:23]
	v_mfma_f32_16x16x32_bf16 v[16:19], v[176:179], v[200:203], v[16:19]
	v_mfma_f32_16x16x32_bf16 v[4:7], v[168:171], v[208:211], v[4:7]
	v_mfma_f32_16x16x32_bf16 v[0:3], v[176:179], v[208:211], v[0:3]
	s_setprio 0
	s_barrier
	s_add_i32 s54, s54, 2
	s_add_u32 s52, s52, 0x100
	s_addc_u32 s53, s53, 0
	s_cmp_gt_u32 s54, 41
	s_mov_b64 s[24:25], s[26:27]
	s_cbranch_scc0 .LBB0_1219
	s_and_b64 vcc, exec, s[20:21]
	s_cbranch_vccz .LBB0_1222
	s_barrier

.LBB0_1258:
	ds_read_b128 v[0:3], v147
	ds_read_b128 v[4:7], v147 offset:1024
	ds_read_b128 v[8:11], v147 offset:2048
	ds_read_b128 v[12:15], v147 offset:3072
	ds_read_b128 v[16:19], v148
	ds_read_b128 v[20:23], v148 offset:1024
	ds_read_b128 v[24:27], v148 offset:2048
	ds_read_b128 v[28:31], v148 offset:3072
	s_ashr_i32 s25, s24, 31
	s_lshl_b64 s[26:27], s[24:25], 17
	s_add_u32 s26, s48, s26
	s_addc_u32 s27, s49, s27
	s_and_b64 s[28:29], s[4:5], exec
	s_cselect_b32 s41, s27, s35
	s_cselect_b32 s40, s26, s34
	s_ashr_i32 s23, s22, 31
	s_lshl_b64 s[28:29], s[22:23], 17
	s_add_u32 s28, s42, s28
	s_addc_u32 s29, s43, s29
	s_and_b64 s[38:39], s[4:5], exec
	s_cselect_b32 s39, s29, s37
	s_cselect_b32 s38, s28, s36
	s_add_u32 s58, s34, 0x10080
	s_addc_u32 s59, s35, 0
	s_mov_b32 m0, s55
	v_lshl_add_u64 v[64:65], s[58:59], 0, v[128:129]
	ds_read_b128 v[32:35], v149
	ds_read_b128 v[36:39], v149 offset:1024
	ds_read_b128 v[40:43], v149 offset:2048
	ds_read_b128 v[44:47], v149 offset:3072
	ds_read_b128 v[48:51], v149 offset:4096
	ds_read_b128 v[52:55], v149 offset:5120
	ds_read_b128 v[56:59], v149 offset:6144
	ds_read_b128 v[60:63], v149 offset:7168
	global_load_lds_dwordx4 v[64:65], off
	v_lshl_add_u64 v[64:65], s[58:59], 0, v[132:133]
	s_mov_b32 m0, s56
	s_nop 0
	global_load_lds_dwordx4 v[64:65], off
	s_waitcnt vmcnt(8)
	s_waitcnt lgkmcnt(0)
	s_barrier
	s_setprio 1
	v_mfma_f32_16x16x32_bf16 v[64:67], v[0:3], v[32:35], 0
	v_mfma_f32_16x16x32_bf16 v[68:71], v[8:11], v[32:35], 0
	v_mfma_f32_16x16x32_bf16 v[72:75], v[0:3], v[40:43], 0
	v_mfma_f32_16x16x32_bf16 v[76:79], v[8:11], v[40:43], 0
	v_mfma_f32_16x16x32_bf16 v[80:83], v[0:3], v[48:51], 0
	v_mfma_f32_16x16x32_bf16 v[84:87], v[8:11], v[48:51], 0
	v_mfma_f32_16x16x32_bf16 v[88:91], v[0:3], v[56:59], 0
	v_mfma_f32_16x16x32_bf16 v[92:95], v[8:11], v[56:59], 0
	v_mfma_f32_16x16x32_bf16 v[64:67], v[4:7], v[36:39], v[64:67]
	v_mfma_f32_16x16x32_bf16 v[68:71], v[12:15], v[36:39], v[68:71]
	v_mfma_f32_16x16x32_bf16 v[72:75], v[4:7], v[44:47], v[72:75]
	v_mfma_f32_16x16x32_bf16 v[76:79], v[12:15], v[44:47], v[76:79]
	v_mfma_f32_16x16x32_bf16 v[80:83], v[4:7], v[52:55], v[80:83]
	v_mfma_f32_16x16x32_bf16 v[84:87], v[12:15], v[52:55], v[84:87]
	v_mfma_f32_16x16x32_bf16 v[88:91], v[4:7], v[60:63], v[88:91]
	v_mfma_f32_16x16x32_bf16 v[92:95], v[12:15], v[60:63], v[92:95]
	s_setprio 0
	s_setprio 1
	v_mfma_f32_16x16x32_bf16 v[96:99], v[16:19], v[32:35], 0
	v_mfma_f32_16x16x32_bf16 v[32:35], v[24:27], v[32:35], 0
	v_mfma_f32_16x16x32_bf16 v[96:99], v[20:23], v[36:39], v[96:99]
	v_mfma_f32_16x16x32_bf16 v[32:35], v[28:31], v[36:39], v[32:35]
	v_mfma_f32_16x16x32_bf16 v[36:39], v[16:19], v[40:43], 0
	v_mfma_f32_16x16x32_bf16 v[40:43], v[24:27], v[40:43], 0
	v_mfma_f32_16x16x32_bf16 v[36:39], v[20:23], v[44:47], v[36:39]
	v_mfma_f32_16x16x32_bf16 v[40:43], v[28:31], v[44:47], v[40:43]
	v_mfma_f32_16x16x32_bf16 v[44:47], v[16:19], v[48:51], 0
	v_mfma_f32_16x16x32_bf16 v[48:51], v[24:27], v[48:51], 0
	v_mfma_f32_16x16x32_bf16 v[44:47], v[20:23], v[52:55], v[44:47]
	v_mfma_f32_16x16x32_bf16 v[48:51], v[28:31], v[52:55], v[48:51]
	v_mfma_f32_16x16x32_bf16 v[52:55], v[16:19], v[56:59], 0
	v_mfma_f32_16x16x32_bf16 v[56:59], v[24:27], v[56:59], 0
	v_mfma_f32_16x16x32_bf16 v[52:55], v[20:23], v[60:63], v[52:55]
	v_mfma_f32_16x16x32_bf16 v[56:59], v[28:31], v[60:63], v[56:59]
	s_setprio 0
	s_barrier
	s_add_i32 s59, s53, s44
	v_lshl_add_u64 v[212:213], s[36:37], 0, v[130:131]
	s_add_i32 s23, s59, 0x2000
	v_lshl_add_u64 v[140:141], v[212:213], 0, s[18:19]
	s_mov_b32 m0, s59
	v_lshl_add_u64 v[214:215], s[36:37], 0, v[134:135]
	s_add_u32 s60, s36, 0x10100
	ds_read_b128 v[60:63], v149 offset:16384
	ds_read_b128 v[100:103], v149 offset:17408
	ds_read_b128 v[104:107], v149 offset:18432
	ds_read_b128 v[108:111], v149 offset:19456
	ds_read_b128 v[112:115], v149 offset:20480
	ds_read_b128 v[116:119], v149 offset:21504
	ds_read_b128 v[120:123], v149 offset:22528
	ds_read_b128 v[124:127], v149 offset:23552
	global_load_lds_dwordx4 v[140:141], off
	v_lshl_add_u64 v[140:141], v[214:215], 0, s[18:19]
	s_mov_b32 m0, s23
	s_addc_u32 s61, s37, 0
	s_add_i32 s25, s54, s44
	global_load_lds_dwordx4 v[140:141], off
	v_lshl_add_u64 v[140:141], s[60:61], 0, v[130:131]
	s_mov_b32 m0, s25
	s_add_i32 s58, s25, 0x2000
	global_load_lds_dwordx4 v[140:141], off
	v_lshl_add_u64 v[140:141], s[60:61], 0, v[134:135]
	s_mov_b32 m0, s58
	v_lshl_add_u64 v[216:217], s[34:35], 0, v[128:129]
	global_load_lds_dwordx4 v[140:141], off
	v_lshl_add_u64 v[140:141], v[216:217], 0, s[18:19]
	s_mov_b32 m0, s31
	v_lshl_add_u64 v[218:219], s[34:35], 0, v[132:133]
	global_load_lds_dwordx4 v[140:141], off
	v_lshl_add_u64 v[140:141], v[218:219], 0, s[18:19]
	s_mov_b32 m0, s45
	s_nop 0
	global_load_lds_dwordx4 v[140:141], off
	s_waitcnt vmcnt(8)
	s_waitcnt lgkmcnt(0)
	s_barrier
	s_setprio 1
	v_mfma_f32_16x16x32_bf16 v[140:143], v[0:3], v[60:63], 0
	v_mfma_f32_16x16x32_bf16 v[156:159], v[0:3], v[104:107], 0
	v_mfma_f32_16x16x32_bf16 v[164:167], v[0:3], v[112:115], 0
	v_mfma_f32_16x16x32_bf16 v[0:3], v[0:3], v[120:123], 0
	v_mfma_f32_16x16x32_bf16 v[140:143], v[4:7], v[100:103], v[140:143]
	v_mfma_f32_16x16x32_bf16 v[156:159], v[4:7], v[108:111], v[156:159]
	v_mfma_f32_16x16x32_bf16 v[164:167], v[4:7], v[116:119], v[164:167]
	v_mfma_f32_16x16x32_bf16 v[0:3], v[4:7], v[124:127], v[0:3]
	v_mfma_f32_16x16x32_bf16 v[4:7], v[8:11], v[120:123], 0
	v_mfma_f32_16x16x32_bf16 v[152:155], v[8:11], v[60:63], 0
	v_mfma_f32_16x16x32_bf16 v[160:163], v[8:11], v[104:107], 0
	v_mfma_f32_16x16x32_bf16 v[168:171], v[8:11], v[112:115], 0
	v_mfma_f32_16x16x32_bf16 v[4:7], v[12:15], v[124:127], v[4:7]
	v_mfma_f32_16x16x32_bf16 v[152:155], v[12:15], v[100:103], v[152:155]
	v_mfma_f32_16x16x32_bf16 v[160:163], v[12:15], v[108:111], v[160:163]
	v_mfma_f32_16x16x32_bf16 v[168:171], v[12:15], v[116:119], v[168:171]
	s_setprio 0
	s_setprio 1
	v_mfma_f32_16x16x32_bf16 v[8:11], v[16:19], v[60:63], 0
	v_mfma_f32_16x16x32_bf16 v[12:15], v[24:27], v[60:63], 0
	v_mfma_f32_16x16x32_bf16 v[8:11], v[20:23], v[100:103], v[8:11]
	v_mfma_f32_16x16x32_bf16 v[12:15], v[28:31], v[100:103], v[12:15]
	v_mfma_f32_16x16x32_bf16 v[60:63], v[16:19], v[104:107], 0
	v_mfma_f32_16x16x32_bf16 v[100:103], v[24:27], v[104:107], 0
	v_mfma_f32_16x16x32_bf16 v[104:107], v[16:19], v[112:115], 0
	v_mfma_f32_16x16x32_bf16 v[16:19], v[16:19], v[120:123], 0
	v_mfma_f32_16x16x32_bf16 v[60:63], v[20:23], v[108:111], v[60:63]
	v_mfma_f32_16x16x32_bf16 v[100:103], v[28:31], v[108:111], v[100:103]
	v_mfma_f32_16x16x32_bf16 v[104:107], v[20:23], v[116:119], v[104:107]
	v_mfma_f32_16x16x32_bf16 v[108:111], v[24:27], v[112:115], 0
	v_mfma_f32_16x16x32_bf16 v[16:19], v[20:23], v[124:127], v[16:19]
	v_mfma_f32_16x16x32_bf16 v[20:23], v[24:27], v[120:123], 0
	v_mfma_f32_16x16x32_bf16 v[108:111], v[28:31], v[116:119], v[108:111]
	v_mfma_f32_16x16x32_bf16 v[20:23], v[28:31], v[124:127], v[20:23]
	s_setprio 0
	s_barrier
	s_add_i32 s62, 0, 0x18000
	s_add_i32 s64, 0, 0x1c000
	v_add_u32_e32 v151, s62, v145
	v_add_u32_e32 v222, s64, v145
	ds_read_b128 v[24:27], v151
	ds_read_b128 v[28:31], v151 offset:1024
	ds_read_b128 v[112:115], v151 offset:2048
	ds_read_b128 v[116:119], v151 offset:3072
	ds_read_b128 v[120:123], v222
	ds_read_b128 v[124:127], v222 offset:1024
	ds_read_b128 v[172:175], v222 offset:2048
	ds_read_b128 v[176:179], v222 offset:3072
	s_add_u32 s60, s34, 0x10100
	s_addc_u32 s61, s35, 0
	s_mov_b32 m0, s46
	v_lshl_add_u64 v[220:221], s[60:61], 0, v[128:129]
	ds_read_b128 v[180:183], v149 offset:32768
	ds_read_b128 v[184:187], v149 offset:33792
	ds_read_b128 v[188:191], v149 offset:34816
	ds_read_b128 v[192:195], v149 offset:35840
	ds_read_b128 v[196:199], v149 offset:36864
	ds_read_b128 v[200:203], v149 offset:37888
	ds_read_b128 v[204:207], v149 offset:38912
	ds_read_b128 v[208:211], v149 offset:39936
	global_load_lds_dwordx4 v[220:221], off
	v_lshl_add_u64 v[220:221], s[60:61], 0, v[132:133]
	s_mov_b32 m0, s47
	s_nop 0
	global_load_lds_dwordx4 v[220:221], off
	s_waitcnt vmcnt(8)
	s_waitcnt lgkmcnt(0)
	s_barrier
	s_setprio 1
	v_mfma_f32_16x16x32_bf16 v[64:67], v[24:27], v[180:183], v[64:67]
	v_mfma_f32_16x16x32_bf16 v[68:71], v[112:115], v[180:183], v[68:71]
	v_mfma_f32_16x16x32_bf16 v[72:75], v[24:27], v[188:191], v[72:75]
	v_mfma_f32_16x16x32_bf16 v[76:79], v[112:115], v[188:191], v[76:79]
	v_mfma_f32_16x16x32_bf16 v[80:83], v[24:27], v[196:199], v[80:83]
	v_mfma_f32_16x16x32_bf16 v[84:87], v[112:115], v[196:199], v[84:87]
	v_mfma_f32_16x16x32_bf16 v[88:91], v[24:27], v[204:207], v[88:91]
	v_mfma_f32_16x16x32_bf16 v[92:95], v[112:115], v[204:207], v[92:95]
	v_mfma_f32_16x16x32_bf16 v[64:67], v[28:31], v[184:187], v[64:67]
	v_mfma_f32_16x16x32_bf16 v[68:71], v[116:119], v[184:187], v[68:71]
	v_mfma_f32_16x16x32_bf16 v[72:75], v[28:31], v[192:195], v[72:75]
	v_mfma_f32_16x16x32_bf16 v[76:79], v[116:119], v[192:195], v[76:79]
	v_mfma_f32_16x16x32_bf16 v[80:83], v[28:31], v[200:203], v[80:83]
	v_mfma_f32_16x16x32_bf16 v[84:87], v[116:119], v[200:203], v[84:87]
	v_mfma_f32_16x16x32_bf16 v[88:91], v[28:31], v[208:211], v[88:91]
	v_mfma_f32_16x16x32_bf16 v[92:95], v[116:119], v[208:211], v[92:95]
	s_setprio 0
	s_setprio 1
	v_mfma_f32_16x16x32_bf16 v[96:99], v[120:123], v[180:183], v[96:99]
	v_mfma_f32_16x16x32_bf16 v[32:35], v[172:175], v[180:183], v[32:35]
	v_mfma_f32_16x16x32_bf16 v[36:39], v[120:123], v[188:191], v[36:39]
	v_mfma_f32_16x16x32_bf16 v[40:43], v[172:175], v[188:191], v[40:43]
	v_mfma_f32_16x16x32_bf16 v[44:47], v[120:123], v[196:199], v[44:47]
	v_mfma_f32_16x16x32_bf16 v[48:51], v[172:175], v[196:199], v[48:51]
	v_mfma_f32_16x16x32_bf16 v[52:55], v[120:123], v[204:207], v[52:55]
	v_mfma_f32_16x16x32_bf16 v[56:59], v[172:175], v[204:207], v[56:59]
	v_mfma_f32_16x16x32_bf16 v[96:99], v[124:127], v[184:187], v[96:99]
	v_mfma_f32_16x16x32_bf16 v[32:35], v[176:179], v[184:187], v[32:35]
	v_mfma_f32_16x16x32_bf16 v[36:39], v[124:127], v[192:195], v[36:39]
	v_mfma_f32_16x16x32_bf16 v[40:43], v[176:179], v[192:195], v[40:43]
	v_mfma_f32_16x16x32_bf16 v[44:47], v[124:127], v[200:203], v[44:47]
	v_mfma_f32_16x16x32_bf16 v[48:51], v[176:179], v[200:203], v[48:51]
	v_mfma_f32_16x16x32_bf16 v[52:55], v[124:127], v[208:211], v[52:55]
	v_mfma_f32_16x16x32_bf16 v[56:59], v[176:179], v[208:211], v[56:59]
	s_setprio 0
	s_barrier
	s_add_i32 s61, s62, s44
	s_add_i32 s60, s61, 0x2000
	v_lshl_add_u64 v[212:213], v[212:213], 0, s[20:21]
	s_mov_b32 m0, s61
	s_add_u32 s62, s36, 0x10180
	ds_read_b128 v[180:183], v149 offset:49152
	ds_read_b128 v[184:187], v149 offset:50176
	ds_read_b128 v[188:191], v149 offset:51200
	ds_read_b128 v[192:195], v149 offset:52224
	ds_read_b128 v[196:199], v149 offset:53248
	ds_read_b128 v[200:203], v149 offset:54272
	ds_read_b128 v[204:207], v149 offset:55296
	ds_read_b128 v[208:211], v149 offset:56320
	global_load_lds_dwordx4 v[212:213], off
	v_lshl_add_u64 v[212:213], v[214:215], 0, s[20:21]
	s_mov_b32 m0, s60
	s_addc_u32 s63, s37, 0
	s_add_i32 s36, s64, s44
	global_load_lds_dwordx4 v[212:213], off
	v_lshl_add_u64 v[212:213], s[62:63], 0, v[130:131]
	s_mov_b32 m0, s36
	s_add_i32 s37, s36, 0x2000
	global_load_lds_dwordx4 v[212:213], off
	v_lshl_add_u64 v[212:213], s[62:63], 0, v[134:135]
	s_mov_b32 m0, s37
	s_nop 0
	global_load_lds_dwordx4 v[212:213], off
	v_lshl_add_u64 v[212:213], v[216:217], 0, s[20:21]
	s_mov_b32 m0, s50
	s_nop 0
	global_load_lds_dwordx4 v[212:213], off
	v_lshl_add_u64 v[212:213], v[218:219], 0, s[20:21]
	s_mov_b32 m0, s51
	s_nop 0
	global_load_lds_dwordx4 v[212:213], off
	s_waitcnt vmcnt(8)
	s_waitcnt lgkmcnt(0)
	s_barrier
	s_setprio 1
	v_mfma_f32_16x16x32_bf16 v[0:3], v[24:27], v[204:207], v[0:3]
	v_mfma_f32_16x16x32_bf16 v[4:7], v[112:115], v[204:207], v[4:7]
	v_mfma_f32_16x16x32_bf16 v[140:143], v[24:27], v[180:183], v[140:143]
	v_mfma_f32_16x16x32_bf16 v[152:155], v[112:115], v[180:183], v[152:155]
	v_mfma_f32_16x16x32_bf16 v[156:159], v[24:27], v[188:191], v[156:159]
	v_mfma_f32_16x16x32_bf16 v[160:163], v[112:115], v[188:191], v[160:163]
	v_mfma_f32_16x16x32_bf16 v[164:167], v[24:27], v[196:199], v[164:167]
	v_mfma_f32_16x16x32_bf16 v[168:171], v[112:115], v[196:199], v[168:171]
	v_mfma_f32_16x16x32_bf16 v[0:3], v[28:31], v[208:211], v[0:3]
	v_mfma_f32_16x16x32_bf16 v[4:7], v[116:119], v[208:211], v[4:7]
	v_mfma_f32_16x16x32_bf16 v[140:143], v[28:31], v[184:187], v[140:143]
	v_mfma_f32_16x16x32_bf16 v[152:155], v[116:119], v[184:187], v[152:155]
	v_mfma_f32_16x16x32_bf16 v[156:159], v[28:31], v[192:195], v[156:159]
	v_mfma_f32_16x16x32_bf16 v[160:163], v[116:119], v[192:195], v[160:163]
	v_mfma_f32_16x16x32_bf16 v[164:167], v[28:31], v[200:203], v[164:167]
	v_mfma_f32_16x16x32_bf16 v[168:171], v[116:119], v[200:203], v[168:171]
	s_setprio 0
	s_setprio 1
	v_mfma_f32_16x16x32_bf16 v[8:11], v[120:123], v[180:183], v[8:11]
	v_mfma_f32_16x16x32_bf16 v[12:15], v[172:175], v[180:183], v[12:15]
	v_mfma_f32_16x16x32_bf16 v[24:27], v[120:123], v[188:191], v[60:63]
	v_mfma_f32_16x16x32_bf16 v[28:31], v[172:175], v[188:191], v[100:103]
	v_mfma_f32_16x16x32_bf16 v[60:63], v[120:123], v[196:199], v[104:107]
	v_mfma_f32_16x16x32_bf16 v[100:103], v[172:175], v[196:199], v[108:111]
	v_mfma_f32_16x16x32_bf16 v[16:19], v[120:123], v[204:207], v[16:19]
	v_mfma_f32_16x16x32_bf16 v[20:23], v[172:175], v[204:207], v[20:23]
	v_mfma_f32_16x16x32_bf16 v[8:11], v[124:127], v[184:187], v[8:11]
	v_mfma_f32_16x16x32_bf16 v[12:15], v[176:179], v[184:187], v[12:15]
	v_mfma_f32_16x16x32_bf16 v[24:27], v[124:127], v[192:195], v[24:27]
	v_mfma_f32_16x16x32_bf16 v[28:31], v[176:179], v[192:195], v[28:31]
	v_mfma_f32_16x16x32_bf16 v[60:63], v[124:127], v[200:203], v[60:63]
	v_mfma_f32_16x16x32_bf16 v[100:103], v[176:179], v[200:203], v[100:103]
	v_mfma_f32_16x16x32_bf16 v[16:19], v[124:127], v[208:211], v[16:19]
	v_mfma_f32_16x16x32_bf16 v[20:23], v[176:179], v[208:211], v[20:23]
	s_setprio 0
	s_barrier
	ds_read_b128 v[104:107], v147
	ds_read_b128 v[108:111], v147 offset:1024
	ds_read_b128 v[112:115], v147 offset:2048
	ds_read_b128 v[116:119], v147 offset:3072
	ds_read_b128 v[120:123], v148
	ds_read_b128 v[124:127], v148 offset:1024
	ds_read_b128 v[172:175], v148 offset:2048
	ds_read_b128 v[176:179], v148 offset:3072
	s_add_u32 s34, s34, 0x10180
	s_addc_u32 s35, s35, 0
	s_mov_b32 m0, s55
	v_lshl_add_u64 v[212:213], s[34:35], 0, v[128:129]
	ds_read_b128 v[180:183], v149
	ds_read_b128 v[184:187], v149 offset:1024
	ds_read_b128 v[188:191], v149 offset:2048
	ds_read_b128 v[192:195], v149 offset:3072
	ds_read_b128 v[196:199], v149 offset:4096
	ds_read_b128 v[200:203], v149 offset:5120
	ds_read_b128 v[204:207], v149 offset:6144
	ds_read_b128 v[208:211], v149 offset:7168
	global_load_lds_dwordx4 v[212:213], off
	v_lshl_add_u64 v[212:213], s[34:35], 0, v[132:133]
	s_mov_b32 m0, s56
	s_nop 0
	global_load_lds_dwordx4 v[212:213], off
	s_waitcnt vmcnt(8)
	s_waitcnt lgkmcnt(0)
	s_barrier
	s_setprio 1
	v_mfma_f32_16x16x32_bf16 v[64:67], v[104:107], v[180:183], v[64:67]
	v_mfma_f32_16x16x32_bf16 v[68:71], v[112:115], v[180:183], v[68:71]
	v_mfma_f32_16x16x32_bf16 v[72:75], v[104:107], v[188:191], v[72:75]
	v_mfma_f32_16x16x32_bf16 v[76:79], v[112:115], v[188:191], v[76:79]
	v_mfma_f32_16x16x32_bf16 v[80:83], v[104:107], v[196:199], v[80:83]
	v_mfma_f32_16x16x32_bf16 v[84:87], v[112:115], v[196:199], v[84:87]
	v_mfma_f32_16x16x32_bf16 v[88:91], v[104:107], v[204:207], v[88:91]
	v_mfma_f32_16x16x32_bf16 v[92:95], v[112:115], v[204:207], v[92:95]
	v_mfma_f32_16x16x32_bf16 v[64:67], v[108:111], v[184:187], v[64:67]
	v_mfma_f32_16x16x32_bf16 v[68:71], v[116:119], v[184:187], v[68:71]
	v_mfma_f32_16x16x32_bf16 v[72:75], v[108:111], v[192:195], v[72:75]
	v_mfma_f32_16x16x32_bf16 v[76:79], v[116:119], v[192:195], v[76:79]
	v_mfma_f32_16x16x32_bf16 v[80:83], v[108:111], v[200:203], v[80:83]
	v_mfma_f32_16x16x32_bf16 v[84:87], v[116:119], v[200:203], v[84:87]
	v_mfma_f32_16x16x32_bf16 v[88:91], v[108:111], v[208:211], v[88:91]
	v_mfma_f32_16x16x32_bf16 v[92:95], v[116:119], v[208:211], v[92:95]
	s_setprio 0
	s_setprio 1
	v_mfma_f32_16x16x32_bf16 v[32:35], v[172:175], v[180:183], v[32:35]
	v_mfma_f32_16x16x32_bf16 v[36:39], v[120:123], v[188:191], v[36:39]
	v_mfma_f32_16x16x32_bf16 v[40:43], v[172:175], v[188:191], v[40:43]
	v_mfma_f32_16x16x32_bf16 v[44:47], v[120:123], v[196:199], v[44:47]
	v_mfma_f32_16x16x32_bf16 v[48:51], v[172:175], v[196:199], v[48:51]
	v_mfma_f32_16x16x32_bf16 v[52:55], v[120:123], v[204:207], v[52:55]
	v_mfma_f32_16x16x32_bf16 v[56:59], v[172:175], v[204:207], v[56:59]
	v_mfma_f32_16x16x32_bf16 v[96:99], v[120:123], v[180:183], v[96:99]
	v_mfma_f32_16x16x32_bf16 v[32:35], v[176:179], v[184:187], v[32:35]
	v_mfma_f32_16x16x32_bf16 v[36:39], v[124:127], v[192:195], v[36:39]
	v_mfma_f32_16x16x32_bf16 v[40:43], v[176:179], v[192:195], v[40:43]
	v_mfma_f32_16x16x32_bf16 v[44:47], v[124:127], v[200:203], v[44:47]
	v_mfma_f32_16x16x32_bf16 v[48:51], v[176:179], v[200:203], v[48:51]
	v_mfma_f32_16x16x32_bf16 v[52:55], v[124:127], v[208:211], v[52:55]
	v_mfma_f32_16x16x32_bf16 v[56:59], v[176:179], v[208:211], v[56:59]
	v_mfma_f32_16x16x32_bf16 v[212:215], v[124:127], v[184:187], v[96:99]
	s_setprio 0
	s_barrier
	s_mov_b32 m0, s59
	v_lshl_add_u64 v[240:241], s[38:39], 0, v[130:131]
	s_add_u32 s34, s38, 0x10000
	ds_read_b128 v[96:99], v149 offset:16384
	ds_read_b128 v[180:183], v149 offset:17408
	ds_read_b128 v[184:187], v149 offset:18432
	ds_read_b128 v[188:191], v149 offset:19456
	ds_read_b128 v[192:195], v149 offset:20480
	ds_read_b128 v[196:199], v149 offset:21504
	ds_read_b128 v[200:203], v149 offset:22528
	ds_read_b128 v[204:207], v149 offset:23552
	global_load_lds_dwordx4 v[240:241], off
	v_lshl_add_u64 v[242:243], s[38:39], 0, v[134:135]
	s_mov_b32 m0, s23
	s_addc_u32 s35, s39, 0
	global_load_lds_dwordx4 v[242:243], off
	v_lshl_add_u64 v[208:209], s[34:35], 0, v[130:131]
	s_mov_b32 m0, s25
	v_lshl_add_u64 v[244:245], s[40:41], 0, v[128:129]
	global_load_lds_dwordx4 v[208:209], off
	v_lshl_add_u64 v[208:209], s[34:35], 0, v[134:135]
	s_mov_b32 m0, s58
	v_lshl_add_u64 v[246:247], s[40:41], 0, v[132:133]
	global_load_lds_dwordx4 v[208:209], off
	s_mov_b32 m0, s31
	s_nop 0
	global_load_lds_dwordx4 v[244:245], off
	s_mov_b32 m0, s45
	s_nop 0
	global_load_lds_dwordx4 v[246:247], off
	s_waitcnt vmcnt(8)
	s_waitcnt lgkmcnt(0)
	s_barrier
	s_setprio 1
	v_mfma_f32_16x16x32_bf16 v[0:3], v[104:107], v[200:203], v[0:3]
	v_mfma_f32_16x16x32_bf16 v[4:7], v[112:115], v[200:203], v[4:7]
	v_mfma_f32_16x16x32_bf16 v[140:143], v[104:107], v[96:99], v[140:143]
	v_mfma_f32_16x16x32_bf16 v[152:155], v[112:115], v[96:99], v[152:155]
	v_mfma_f32_16x16x32_bf16 v[156:159], v[104:107], v[184:187], v[156:159]
	v_mfma_f32_16x16x32_bf16 v[160:163], v[112:115], v[184:187], v[160:163]
	v_mfma_f32_16x16x32_bf16 v[164:167], v[104:107], v[192:195], v[164:167]
	v_mfma_f32_16x16x32_bf16 v[168:171], v[112:115], v[192:195], v[168:171]
	v_mfma_f32_16x16x32_bf16 v[0:3], v[108:111], v[204:207], v[0:3]
	v_mfma_f32_16x16x32_bf16 v[4:7], v[116:119], v[204:207], v[4:7]
	v_mfma_f32_16x16x32_bf16 v[140:143], v[108:111], v[180:183], v[140:143]
	v_mfma_f32_16x16x32_bf16 v[152:155], v[116:119], v[180:183], v[152:155]
	v_mfma_f32_16x16x32_bf16 v[156:159], v[108:111], v[188:191], v[156:159]
	v_mfma_f32_16x16x32_bf16 v[160:163], v[116:119], v[188:191], v[160:163]
	v_mfma_f32_16x16x32_bf16 v[164:167], v[108:111], v[196:199], v[164:167]
	v_mfma_f32_16x16x32_bf16 v[168:171], v[116:119], v[196:199], v[168:171]
	s_setprio 0
	s_setprio 1
	v_mfma_f32_16x16x32_bf16 v[8:11], v[120:123], v[96:99], v[8:11]
	v_mfma_f32_16x16x32_bf16 v[12:15], v[172:175], v[96:99], v[12:15]
	v_mfma_f32_16x16x32_bf16 v[24:27], v[120:123], v[184:187], v[24:27]
	v_mfma_f32_16x16x32_bf16 v[28:31], v[172:175], v[184:187], v[28:31]
	v_mfma_f32_16x16x32_bf16 v[60:63], v[120:123], v[192:195], v[60:63]
	v_mfma_f32_16x16x32_bf16 v[16:19], v[120:123], v[200:203], v[16:19]
	v_mfma_f32_16x16x32_bf16 v[8:11], v[124:127], v[180:183], v[8:11]
	v_mfma_f32_16x16x32_bf16 v[12:15], v[176:179], v[180:183], v[12:15]
	v_mfma_f32_16x16x32_bf16 v[24:27], v[124:127], v[188:191], v[24:27]
	v_mfma_f32_16x16x32_bf16 v[28:31], v[176:179], v[188:191], v[28:31]
	v_mfma_f32_16x16x32_bf16 v[180:183], v[124:127], v[196:199], v[60:63]
	v_mfma_f32_16x16x32_bf16 v[60:63], v[172:175], v[192:195], v[100:103]
	v_mfma_f32_16x16x32_bf16 v[188:191], v[124:127], v[204:207], v[16:19]
	v_mfma_f32_16x16x32_bf16 v[16:19], v[172:175], v[200:203], v[20:23]
	v_mfma_f32_16x16x32_bf16 v[184:187], v[176:179], v[196:199], v[60:63]
	v_mfma_f32_16x16x32_bf16 v[172:175], v[176:179], v[204:207], v[16:19]
	s_setprio 0
	s_barrier
	s_nop 1
	ds_read_b128 v[60:63], v151
	ds_read_b128 v[176:179], v151 offset:1024
	ds_read_b128 v[192:195], v151 offset:2048
	ds_read_b128 v[196:199], v151 offset:3072
	ds_read_b128 v[200:203], v222
	ds_read_b128 v[204:207], v222 offset:1024
	ds_read_b128 v[208:211], v222 offset:2048
	ds_read_b128 v[216:219], v222 offset:3072
	s_add_u32 s34, s40, 0x10000
	s_addc_u32 s35, s41, 0
	s_mov_b32 m0, s46
	v_lshl_add_u64 v[96:97], s[34:35], 0, v[128:129]
	ds_read_b128 v[16:19], v149 offset:32768
	ds_read_b128 v[20:23], v149 offset:33792
	ds_read_b128 v[108:111], v149 offset:34816
	ds_read_b128 v[220:223], v149 offset:35840
	ds_read_b128 v[224:227], v149 offset:36864
	ds_read_b128 v[228:231], v149 offset:37888
	ds_read_b128 v[232:235], v149 offset:38912
	ds_read_b128 v[236:239], v149 offset:39936
	global_load_lds_dwordx4 v[96:97], off
	v_lshl_add_u64 v[96:97], s[34:35], 0, v[132:133]
	s_mov_b32 m0, s47
	s_nop 0
	global_load_lds_dwordx4 v[96:97], off
	s_waitcnt vmcnt(8)
	s_waitcnt lgkmcnt(0)
	s_barrier
	s_setprio 1
	v_mfma_f32_16x16x32_bf16 v[64:67], v[60:63], v[16:19], v[64:67]
	v_mfma_f32_16x16x32_bf16 v[112:115], v[176:179], v[20:23], v[64:67]
	v_mfma_f32_16x16x32_bf16 v[64:67], v[192:195], v[16:19], v[68:71]
	v_mfma_f32_16x16x32_bf16 v[116:119], v[196:199], v[20:23], v[64:67]
	v_mfma_f32_16x16x32_bf16 v[64:67], v[60:63], v[108:111], v[72:75]
	v_mfma_f32_16x16x32_bf16 v[96:99], v[176:179], v[220:223], v[64:67]
	v_mfma_f32_16x16x32_bf16 v[64:67], v[192:195], v[108:111], v[76:79]
	v_mfma_f32_16x16x32_bf16 v[100:103], v[196:199], v[220:223], v[64:67]
	v_mfma_f32_16x16x32_bf16 v[64:67], v[60:63], v[224:227], v[80:83]
	v_mfma_f32_16x16x32_bf16 v[80:83], v[176:179], v[228:231], v[64:67]
	v_mfma_f32_16x16x32_bf16 v[64:67], v[192:195], v[224:227], v[84:87]
	v_mfma_f32_16x16x32_bf16 v[84:87], v[196:199], v[228:231], v[64:67]
	v_mfma_f32_16x16x32_bf16 v[64:67], v[60:63], v[232:235], v[88:91]
	v_mfma_f32_16x16x32_bf16 v[68:71], v[192:195], v[232:235], v[92:95]
	v_mfma_f32_16x16x32_bf16 v[64:67], v[176:179], v[236:239], v[64:67]
	v_mfma_f32_16x16x32_bf16 v[68:71], v[196:199], v[236:239], v[68:71]
	s_setprio 0
	s_setprio 1
	v_mfma_f32_16x16x32_bf16 v[72:75], v[200:203], v[16:19], v[212:215]
	v_mfma_f32_16x16x32_bf16 v[16:19], v[208:211], v[16:19], v[32:35]
	v_mfma_f32_16x16x32_bf16 v[124:127], v[216:219], v[20:23], v[16:19]
	v_mfma_f32_16x16x32_bf16 v[16:19], v[200:203], v[108:111], v[36:39]
	v_mfma_f32_16x16x32_bf16 v[104:107], v[204:207], v[220:223], v[16:19]
	v_mfma_f32_16x16x32_bf16 v[16:19], v[208:211], v[108:111], v[40:43]
	v_mfma_f32_16x16x32_bf16 v[108:111], v[216:219], v[220:223], v[16:19]
	v_mfma_f32_16x16x32_bf16 v[16:19], v[200:203], v[224:227], v[44:47]
	v_mfma_f32_16x16x32_bf16 v[88:91], v[204:207], v[228:231], v[16:19]
	v_mfma_f32_16x16x32_bf16 v[16:19], v[208:211], v[224:227], v[48:51]
	v_mfma_f32_16x16x32_bf16 v[92:95], v[216:219], v[228:231], v[16:19]
	v_mfma_f32_16x16x32_bf16 v[16:19], v[200:203], v[232:235], v[52:55]
	v_mfma_f32_16x16x32_bf16 v[120:123], v[204:207], v[20:23], v[72:75]
	v_mfma_f32_16x16x32_bf16 v[72:75], v[204:207], v[236:239], v[16:19]
	v_mfma_f32_16x16x32_bf16 v[16:19], v[208:211], v[232:235], v[56:59]
	v_mfma_f32_16x16x32_bf16 v[76:79], v[216:219], v[236:239], v[16:19]
	s_setprio 0
	s_barrier
	s_mov_b32 m0, s61
	s_nop 3
	v_lshl_add_u64 v[16:17], v[240:241], 0, s[12:13]
	s_add_u32 s34, s38, 0x10080
	ds_read_b128 v[40:43], v149 offset:49152
	ds_read_b128 v[44:47], v149 offset:50176
	ds_read_b128 v[212:215], v149 offset:51200
	ds_read_b128 v[220:223], v149 offset:52224
	ds_read_b128 v[224:227], v149 offset:53248
	ds_read_b128 v[228:231], v149 offset:54272
	ds_read_b128 v[232:235], v149 offset:55296
	ds_read_b128 v[236:239], v149 offset:56320
	global_load_lds_dwordx4 v[16:17], off
	v_lshl_add_u64 v[16:17], v[242:243], 0, s[12:13]
	s_mov_b32 m0, s60
	s_addc_u32 s35, s39, 0
	global_load_lds_dwordx4 v[16:17], off
	v_lshl_add_u64 v[16:17], s[34:35], 0, v[130:131]
	s_mov_b32 m0, s36
	s_nop 0
	global_load_lds_dwordx4 v[16:17], off
	v_lshl_add_u64 v[16:17], s[34:35], 0, v[134:135]
	s_mov_b32 m0, s37
	s_nop 0
	global_load_lds_dwordx4 v[16:17], off
	v_lshl_add_u64 v[16:17], v[244:245], 0, s[12:13]
	s_mov_b32 m0, s50
	s_nop 0
	global_load_lds_dwordx4 v[16:17], off
	v_lshl_add_u64 v[16:17], v[246:247], 0, s[12:13]
	s_mov_b32 m0, s51
	s_nop 0
	global_load_lds_dwordx4 v[16:17], off
	s_waitcnt vmcnt(8)
	s_waitcnt lgkmcnt(0)
	s_barrier
	s_setprio 1
	v_mfma_f32_16x16x32_bf16 v[16:19], v[60:63], v[40:43], v[140:143]
	v_mfma_f32_16x16x32_bf16 v[48:51], v[176:179], v[44:47], v[16:19]
	v_mfma_f32_16x16x32_bf16 v[16:19], v[192:195], v[40:43], v[152:155]
	v_mfma_f32_16x16x32_bf16 v[52:55], v[196:199], v[44:47], v[16:19]
	v_mfma_f32_16x16x32_bf16 v[16:19], v[60:63], v[212:215], v[156:159]
	v_mfma_f32_16x16x32_bf16 v[32:35], v[176:179], v[220:223], v[16:19]
	v_mfma_f32_16x16x32_bf16 v[16:19], v[192:195], v[212:215], v[160:163]
	v_mfma_f32_16x16x32_bf16 v[36:39], v[196:199], v[220:223], v[16:19]
	v_mfma_f32_16x16x32_bf16 v[16:19], v[60:63], v[224:227], v[164:167]
	v_mfma_f32_16x16x32_bf16 v[20:23], v[192:195], v[224:227], v[168:171]
	v_mfma_f32_16x16x32_bf16 v[0:3], v[60:63], v[232:235], v[0:3]
	v_mfma_f32_16x16x32_bf16 v[4:7], v[192:195], v[232:235], v[4:7]
	v_mfma_f32_16x16x32_bf16 v[16:19], v[176:179], v[228:231], v[16:19]
	v_mfma_f32_16x16x32_bf16 v[20:23], v[196:199], v[228:231], v[20:23]
	v_mfma_f32_16x16x32_bf16 v[0:3], v[176:179], v[236:239], v[0:3]
	v_mfma_f32_16x16x32_bf16 v[4:7], v[196:199], v[236:239], v[4:7]
	s_setprio 0
	s_setprio 1
	v_mfma_f32_16x16x32_bf16 v[8:11], v[200:203], v[40:43], v[8:11]
	v_mfma_f32_16x16x32_bf16 v[56:59], v[204:207], v[44:47], v[8:11]
	v_mfma_f32_16x16x32_bf16 v[8:11], v[208:211], v[40:43], v[12:15]
	v_mfma_f32_16x16x32_bf16 v[60:63], v[216:219], v[44:47], v[8:11]
	v_mfma_f32_16x16x32_bf16 v[8:11], v[200:203], v[212:215], v[24:27]
	v_mfma_f32_16x16x32_bf16 v[40:43], v[204:207], v[220:223], v[8:11]
	v_mfma_f32_16x16x32_bf16 v[8:11], v[208:211], v[212:215], v[28:31]
	v_mfma_f32_16x16x32_bf16 v[44:47], v[216:219], v[220:223], v[8:11]
	v_mfma_f32_16x16x32_bf16 v[8:11], v[200:203], v[224:227], v[180:183]
	v_mfma_f32_16x16x32_bf16 v[24:27], v[204:207], v[228:231], v[8:11]
	v_mfma_f32_16x16x32_bf16 v[8:11], v[208:211], v[224:227], v[184:187]
	v_mfma_f32_16x16x32_bf16 v[28:31], v[216:219], v[228:231], v[8:11]
	v_mfma_f32_16x16x32_bf16 v[8:11], v[200:203], v[232:235], v[188:191]
	v_mfma_f32_16x16x32_bf16 v[12:15], v[208:211], v[232:235], v[172:175]
	v_mfma_f32_16x16x32_bf16 v[8:11], v[204:207], v[236:239], v[8:11]
	v_mfma_f32_16x16x32_bf16 v[12:15], v[216:219], v[236:239], v[12:15]
	s_setprio 0
	s_barrier
	s_andn2_b64 vcc, exec, s[14:15]
	s_cbranch_vccnz .LBB0_1260
	s_barrier

.LBB0_1280:
	ds_read_b128 v[0:3], v161
	ds_read_b128 v[4:7], v161 offset:1024
	ds_read_b128 v[8:11], v161 offset:2048
	ds_read_b128 v[12:15], v161 offset:3072
	ds_read_b128 v[16:19], v162
	ds_read_b128 v[20:23], v162 offset:1024
	ds_read_b128 v[24:27], v162 offset:2048
	ds_read_b128 v[28:31], v162 offset:3072
	s_ashr_i32 s31, s30, 31
	s_lshl_b64 s[34:35], s[30:31], 17
	s_add_u32 s34, s50, s34
	s_addc_u32 s35, s51, s35
	s_and_b64 s[36:37], s[2:3], exec
	s_cselect_b32 s47, s35, s41
	s_cselect_b32 s46, s34, s40
	s_ashr_i32 s29, s28, 31
	s_lshl_b64 s[36:37], s[28:29], 17
	s_add_u32 s36, s48, s36
	s_addc_u32 s37, s49, s37
	s_and_b64 s[44:45], s[2:3], exec
	s_cselect_b32 s45, s37, s43
	s_cselect_b32 s44, s36, s42
	s_add_u32 s66, s40, 0x10080
	s_addc_u32 s67, s41, 0
	s_add_i32 s84, s39, 0xc000
	v_lshl_add_u64 v[64:65], s[66:67], 0, v[128:129]
	s_mov_b32 m0, s84
	s_add_i32 s29, s39, 0xe000
	ds_read_b128 v[32:35], v163
	ds_read_b128 v[36:39], v163 offset:1024
	ds_read_b128 v[40:43], v163 offset:2048
	ds_read_b128 v[44:47], v163 offset:3072
	ds_read_b128 v[48:51], v163 offset:4096
	ds_read_b128 v[52:55], v163 offset:5120
	ds_read_b128 v[56:59], v163 offset:6144
	ds_read_b128 v[60:63], v163 offset:7168
	global_load_lds_dwordx4 v[64:65], off
	v_lshl_add_u64 v[64:65], s[66:67], 0, v[132:133]
	s_mov_b32 m0, s29
	s_nop 0
	global_load_lds_dwordx4 v[64:65], off
	s_waitcnt vmcnt(8)
	s_waitcnt lgkmcnt(0)
	s_barrier
	s_setprio 1
	v_mfma_f32_16x16x32_bf16 v[64:67], v[0:3], v[32:35], 0
	v_mfma_f32_16x16x32_bf16 v[68:71], v[8:11], v[32:35], 0
	v_mfma_f32_16x16x32_bf16 v[72:75], v[0:3], v[40:43], 0
	v_mfma_f32_16x16x32_bf16 v[76:79], v[8:11], v[40:43], 0
	v_mfma_f32_16x16x32_bf16 v[80:83], v[0:3], v[48:51], 0
	v_mfma_f32_16x16x32_bf16 v[84:87], v[8:11], v[48:51], 0
	v_mfma_f32_16x16x32_bf16 v[88:91], v[0:3], v[56:59], 0
	v_mfma_f32_16x16x32_bf16 v[92:95], v[8:11], v[56:59], 0
	v_mfma_f32_16x16x32_bf16 v[64:67], v[4:7], v[36:39], v[64:67]
	v_mfma_f32_16x16x32_bf16 v[68:71], v[12:15], v[36:39], v[68:71]
	v_mfma_f32_16x16x32_bf16 v[72:75], v[4:7], v[44:47], v[72:75]
	v_mfma_f32_16x16x32_bf16 v[76:79], v[12:15], v[44:47], v[76:79]
	v_mfma_f32_16x16x32_bf16 v[80:83], v[4:7], v[52:55], v[80:83]
	v_mfma_f32_16x16x32_bf16 v[84:87], v[12:15], v[52:55], v[84:87]
	v_mfma_f32_16x16x32_bf16 v[88:91], v[4:7], v[60:63], v[88:91]
	v_mfma_f32_16x16x32_bf16 v[92:95], v[12:15], v[60:63], v[92:95]
	s_setprio 0
	s_setprio 1
	v_mfma_f32_16x16x32_bf16 v[96:99], v[16:19], v[32:35], 0
	v_mfma_f32_16x16x32_bf16 v[32:35], v[24:27], v[32:35], 0
	v_mfma_f32_16x16x32_bf16 v[96:99], v[20:23], v[36:39], v[96:99]
	v_mfma_f32_16x16x32_bf16 v[32:35], v[28:31], v[36:39], v[32:35]
	v_mfma_f32_16x16x32_bf16 v[36:39], v[16:19], v[40:43], 0
	v_mfma_f32_16x16x32_bf16 v[40:43], v[24:27], v[40:43], 0
	v_mfma_f32_16x16x32_bf16 v[36:39], v[20:23], v[44:47], v[36:39]
	v_mfma_f32_16x16x32_bf16 v[40:43], v[28:31], v[44:47], v[40:43]
	v_mfma_f32_16x16x32_bf16 v[44:47], v[16:19], v[48:51], 0
	v_mfma_f32_16x16x32_bf16 v[48:51], v[24:27], v[48:51], 0
	v_mfma_f32_16x16x32_bf16 v[44:47], v[20:23], v[52:55], v[44:47]
	v_mfma_f32_16x16x32_bf16 v[48:51], v[28:31], v[52:55], v[48:51]
	v_mfma_f32_16x16x32_bf16 v[52:55], v[16:19], v[56:59], 0
	v_mfma_f32_16x16x32_bf16 v[56:59], v[24:27], v[56:59], 0
	v_mfma_f32_16x16x32_bf16 v[52:55], v[20:23], v[60:63], v[52:55]
	v_mfma_f32_16x16x32_bf16 v[56:59], v[28:31], v[60:63], v[56:59]
	s_setprio 0
	s_barrier
	s_add_i32 s68, s59, s52
	v_lshl_add_u64 v[156:157], s[42:43], 0, v[130:131]
	s_add_i32 s31, s68, 0x2000
	v_lshl_add_u64 v[140:141], v[156:157], 0, s[16:17]
	s_mov_b32 m0, s68
	v_lshl_add_u64 v[214:215], s[42:43], 0, v[134:135]
	s_add_u32 s86, s42, 0x10100
	ds_read_b128 v[60:63], v163 offset:16384
	ds_read_b128 v[100:103], v163 offset:17408
	ds_read_b128 v[104:107], v163 offset:18432
	ds_read_b128 v[108:111], v163 offset:19456
	ds_read_b128 v[112:115], v163 offset:20480
	ds_read_b128 v[116:119], v163 offset:21504
	ds_read_b128 v[120:123], v163 offset:22528
	ds_read_b128 v[124:127], v163 offset:23552
	global_load_lds_dwordx4 v[140:141], off
	v_lshl_add_u64 v[140:141], v[214:215], 0, s[16:17]
	s_mov_b32 m0, s31
	s_addc_u32 s87, s43, 0
	s_add_i32 s66, s60, s52
	global_load_lds_dwordx4 v[140:141], off
	v_lshl_add_u64 v[140:141], s[86:87], 0, v[130:131]
	s_mov_b32 m0, s66
	s_add_i32 s67, s66, 0x2000
	global_load_lds_dwordx4 v[140:141], off
	v_lshl_add_u64 v[140:141], s[86:87], 0, v[134:135]
	s_mov_b32 m0, s67
	v_lshl_add_u64 v[216:217], s[40:41], 0, v[128:129]
	global_load_lds_dwordx4 v[140:141], off
	v_lshl_add_u64 v[140:141], v[216:217], 0, s[16:17]
	s_mov_b32 m0, s39
	v_lshl_add_u64 v[218:219], s[40:41], 0, v[132:133]
	global_load_lds_dwordx4 v[140:141], off
	v_lshl_add_u64 v[140:141], v[218:219], 0, s[16:17]
	s_mov_b32 m0, s53
	s_nop 0
	global_load_lds_dwordx4 v[140:141], off
	s_waitcnt vmcnt(8)
	s_waitcnt lgkmcnt(0)
	s_barrier
	s_setprio 1
	v_mfma_f32_16x16x32_bf16 v[140:143], v[0:3], v[60:63], 0
	v_mfma_f32_16x16x32_bf16 v[148:151], v[0:3], v[104:107], 0
	v_mfma_f32_16x16x32_bf16 v[166:169], v[0:3], v[112:115], 0
	v_mfma_f32_16x16x32_bf16 v[0:3], v[0:3], v[120:123], 0
	v_mfma_f32_16x16x32_bf16 v[140:143], v[4:7], v[100:103], v[140:143]
	v_mfma_f32_16x16x32_bf16 v[148:151], v[4:7], v[108:111], v[148:151]
	v_mfma_f32_16x16x32_bf16 v[166:169], v[4:7], v[116:119], v[166:169]
	v_mfma_f32_16x16x32_bf16 v[0:3], v[4:7], v[124:127], v[0:3]
	v_mfma_f32_16x16x32_bf16 v[4:7], v[8:11], v[120:123], 0
	v_mfma_f32_16x16x32_bf16 v[144:147], v[8:11], v[60:63], 0
	v_mfma_f32_16x16x32_bf16 v[152:155], v[8:11], v[104:107], 0
	v_mfma_f32_16x16x32_bf16 v[170:173], v[8:11], v[112:115], 0
	v_mfma_f32_16x16x32_bf16 v[4:7], v[12:15], v[124:127], v[4:7]
	v_mfma_f32_16x16x32_bf16 v[144:147], v[12:15], v[100:103], v[144:147]
	v_mfma_f32_16x16x32_bf16 v[152:155], v[12:15], v[108:111], v[152:155]
	v_mfma_f32_16x16x32_bf16 v[170:173], v[12:15], v[116:119], v[170:173]
	s_setprio 0
	s_setprio 1
	v_mfma_f32_16x16x32_bf16 v[8:11], v[16:19], v[60:63], 0
	v_mfma_f32_16x16x32_bf16 v[12:15], v[24:27], v[60:63], 0
	v_mfma_f32_16x16x32_bf16 v[8:11], v[20:23], v[100:103], v[8:11]
	v_mfma_f32_16x16x32_bf16 v[12:15], v[28:31], v[100:103], v[12:15]
	v_mfma_f32_16x16x32_bf16 v[60:63], v[16:19], v[104:107], 0
	v_mfma_f32_16x16x32_bf16 v[100:103], v[24:27], v[104:107], 0
	v_mfma_f32_16x16x32_bf16 v[104:107], v[16:19], v[112:115], 0
	v_mfma_f32_16x16x32_bf16 v[16:19], v[16:19], v[120:123], 0
	v_mfma_f32_16x16x32_bf16 v[60:63], v[20:23], v[108:111], v[60:63]
	v_mfma_f32_16x16x32_bf16 v[100:103], v[28:31], v[108:111], v[100:103]
	v_mfma_f32_16x16x32_bf16 v[104:107], v[20:23], v[116:119], v[104:107]
	v_mfma_f32_16x16x32_bf16 v[108:111], v[24:27], v[112:115], 0
	v_mfma_f32_16x16x32_bf16 v[16:19], v[20:23], v[124:127], v[16:19]
	v_mfma_f32_16x16x32_bf16 v[20:23], v[24:27], v[120:123], 0
	v_mfma_f32_16x16x32_bf16 v[108:111], v[28:31], v[116:119], v[108:111]
	v_mfma_f32_16x16x32_bf16 v[20:23], v[28:31], v[124:127], v[20:23]
	s_setprio 0
	s_barrier
	s_add_i32 s85, 0, 0x18000
	s_add_i32 s88, 0, 0x1c000
	v_add_u32_e32 v165, s85, v159
	v_add_u32_e32 v226, s88, v159
	ds_read_b128 v[24:27], v165
	ds_read_b128 v[28:31], v165 offset:1024
	ds_read_b128 v[112:115], v165 offset:2048
	ds_read_b128 v[116:119], v165 offset:3072
	ds_read_b128 v[120:123], v226
	ds_read_b128 v[124:127], v226 offset:1024
	ds_read_b128 v[174:177], v226 offset:2048
	ds_read_b128 v[178:181], v226 offset:3072
	s_add_u32 s86, s40, 0x10100
	s_addc_u32 s87, s41, 0
	s_mov_b32 m0, s54
	v_lshl_add_u64 v[220:221], s[86:87], 0, v[128:129]
	ds_read_b128 v[182:185], v163 offset:32768
	ds_read_b128 v[186:189], v163 offset:33792
	ds_read_b128 v[190:193], v163 offset:34816
	ds_read_b128 v[194:197], v163 offset:35840
	ds_read_b128 v[198:201], v163 offset:36864
	ds_read_b128 v[202:205], v163 offset:37888
	ds_read_b128 v[206:209], v163 offset:38912
	ds_read_b128 v[210:213], v163 offset:39936
	global_load_lds_dwordx4 v[220:221], off
	v_lshl_add_u64 v[220:221], s[86:87], 0, v[132:133]
	s_mov_b32 m0, s55
	s_nop 0
	global_load_lds_dwordx4 v[220:221], off
	s_waitcnt vmcnt(8)
	s_waitcnt lgkmcnt(0)
	s_barrier
	s_setprio 1
	v_mfma_f32_16x16x32_bf16 v[64:67], v[24:27], v[182:185], v[64:67]
	v_mfma_f32_16x16x32_bf16 v[68:71], v[112:115], v[182:185], v[68:71]
	v_mfma_f32_16x16x32_bf16 v[72:75], v[24:27], v[190:193], v[72:75]
	v_mfma_f32_16x16x32_bf16 v[76:79], v[112:115], v[190:193], v[76:79]
	v_mfma_f32_16x16x32_bf16 v[80:83], v[24:27], v[198:201], v[80:83]
	v_mfma_f32_16x16x32_bf16 v[84:87], v[112:115], v[198:201], v[84:87]
	v_mfma_f32_16x16x32_bf16 v[88:91], v[24:27], v[206:209], v[88:91]
	v_mfma_f32_16x16x32_bf16 v[92:95], v[112:115], v[206:209], v[92:95]
	v_mfma_f32_16x16x32_bf16 v[64:67], v[28:31], v[186:189], v[64:67]
	v_mfma_f32_16x16x32_bf16 v[68:71], v[116:119], v[186:189], v[68:71]
	v_mfma_f32_16x16x32_bf16 v[72:75], v[28:31], v[194:197], v[72:75]
	v_mfma_f32_16x16x32_bf16 v[76:79], v[116:119], v[194:197], v[76:79]
	v_mfma_f32_16x16x32_bf16 v[80:83], v[28:31], v[202:205], v[80:83]
	v_mfma_f32_16x16x32_bf16 v[84:87], v[116:119], v[202:205], v[84:87]
	v_mfma_f32_16x16x32_bf16 v[88:91], v[28:31], v[210:213], v[88:91]
	v_mfma_f32_16x16x32_bf16 v[92:95], v[116:119], v[210:213], v[92:95]
	s_setprio 0
	s_setprio 1
	v_mfma_f32_16x16x32_bf16 v[96:99], v[120:123], v[182:185], v[96:99]
	v_mfma_f32_16x16x32_bf16 v[32:35], v[174:177], v[182:185], v[32:35]
	v_mfma_f32_16x16x32_bf16 v[36:39], v[120:123], v[190:193], v[36:39]
	v_mfma_f32_16x16x32_bf16 v[40:43], v[174:177], v[190:193], v[40:43]
	v_mfma_f32_16x16x32_bf16 v[44:47], v[120:123], v[198:201], v[44:47]
	v_mfma_f32_16x16x32_bf16 v[48:51], v[174:177], v[198:201], v[48:51]
	v_mfma_f32_16x16x32_bf16 v[52:55], v[120:123], v[206:209], v[52:55]
	v_mfma_f32_16x16x32_bf16 v[56:59], v[174:177], v[206:209], v[56:59]
	v_mfma_f32_16x16x32_bf16 v[96:99], v[124:127], v[186:189], v[96:99]
	v_mfma_f32_16x16x32_bf16 v[32:35], v[178:181], v[186:189], v[32:35]
	v_mfma_f32_16x16x32_bf16 v[36:39], v[124:127], v[194:197], v[36:39]
	v_mfma_f32_16x16x32_bf16 v[40:43], v[178:181], v[194:197], v[40:43]
	v_mfma_f32_16x16x32_bf16 v[44:47], v[124:127], v[202:205], v[44:47]
	v_mfma_f32_16x16x32_bf16 v[48:51], v[178:181], v[202:205], v[48:51]
	v_mfma_f32_16x16x32_bf16 v[52:55], v[124:127], v[210:213], v[52:55]
	v_mfma_f32_16x16x32_bf16 v[56:59], v[178:181], v[210:213], v[56:59]
	s_setprio 0
	s_barrier
	s_add_i32 s85, s85, s52
	s_add_i32 s69, s85, 0x2000
	v_lshl_add_u64 v[156:157], v[156:157], 0, s[18:19]
	s_mov_b32 m0, s85
	s_add_u32 s86, s42, 0x10180
	ds_read_b128 v[182:185], v163 offset:49152
	ds_read_b128 v[186:189], v163 offset:50176
	ds_read_b128 v[190:193], v163 offset:51200
	ds_read_b128 v[194:197], v163 offset:52224
	ds_read_b128 v[198:201], v163 offset:53248
	ds_read_b128 v[202:205], v163 offset:54272
	ds_read_b128 v[206:209], v163 offset:55296
	ds_read_b128 v[210:213], v163 offset:56320
	global_load_lds_dwordx4 v[156:157], off
	v_lshl_add_u64 v[156:157], v[214:215], 0, s[18:19]
	s_mov_b32 m0, s69
	s_addc_u32 s87, s43, 0
	s_add_i32 s42, s88, s52
	global_load_lds_dwordx4 v[156:157], off
	v_lshl_add_u64 v[156:157], s[86:87], 0, v[130:131]
	s_mov_b32 m0, s42
	s_add_i32 s43, s42, 0x2000
	global_load_lds_dwordx4 v[156:157], off
	v_lshl_add_u64 v[156:157], s[86:87], 0, v[134:135]
	s_mov_b32 m0, s43
	s_nop 0
	global_load_lds_dwordx4 v[156:157], off
	v_lshl_add_u64 v[156:157], v[216:217], 0, s[18:19]
	s_mov_b32 m0, s56
	s_nop 0
	global_load_lds_dwordx4 v[156:157], off
	v_lshl_add_u64 v[156:157], v[218:219], 0, s[18:19]
	s_mov_b32 m0, s57
	s_nop 0
	global_load_lds_dwordx4 v[156:157], off
	s_waitcnt vmcnt(8)
	s_waitcnt lgkmcnt(0)
	s_barrier
	s_setprio 1
	v_mfma_f32_16x16x32_bf16 v[0:3], v[24:27], v[206:209], v[0:3]
	v_mfma_f32_16x16x32_bf16 v[4:7], v[112:115], v[206:209], v[4:7]
	v_mfma_f32_16x16x32_bf16 v[140:143], v[24:27], v[182:185], v[140:143]
	v_mfma_f32_16x16x32_bf16 v[144:147], v[112:115], v[182:185], v[144:147]
	v_mfma_f32_16x16x32_bf16 v[148:151], v[24:27], v[190:193], v[148:151]
	v_mfma_f32_16x16x32_bf16 v[152:155], v[112:115], v[190:193], v[152:155]
	v_mfma_f32_16x16x32_bf16 v[166:169], v[24:27], v[198:201], v[166:169]
	v_mfma_f32_16x16x32_bf16 v[170:173], v[112:115], v[198:201], v[170:173]
	v_mfma_f32_16x16x32_bf16 v[0:3], v[28:31], v[210:213], v[0:3]
	v_mfma_f32_16x16x32_bf16 v[4:7], v[116:119], v[210:213], v[4:7]
	v_mfma_f32_16x16x32_bf16 v[140:143], v[28:31], v[186:189], v[140:143]
	v_mfma_f32_16x16x32_bf16 v[144:147], v[116:119], v[186:189], v[144:147]
	v_mfma_f32_16x16x32_bf16 v[148:151], v[28:31], v[194:197], v[148:151]
	v_mfma_f32_16x16x32_bf16 v[152:155], v[116:119], v[194:197], v[152:155]
	v_mfma_f32_16x16x32_bf16 v[166:169], v[28:31], v[202:205], v[166:169]
	v_mfma_f32_16x16x32_bf16 v[170:173], v[116:119], v[202:205], v[170:173]
	s_setprio 0
	s_setprio 1
	v_mfma_f32_16x16x32_bf16 v[8:11], v[120:123], v[182:185], v[8:11]
	v_mfma_f32_16x16x32_bf16 v[12:15], v[174:177], v[182:185], v[12:15]
	v_mfma_f32_16x16x32_bf16 v[24:27], v[120:123], v[190:193], v[60:63]
	v_mfma_f32_16x16x32_bf16 v[28:31], v[174:177], v[190:193], v[100:103]
	v_mfma_f32_16x16x32_bf16 v[60:63], v[120:123], v[198:201], v[104:107]
	v_mfma_f32_16x16x32_bf16 v[100:103], v[174:177], v[198:201], v[108:111]
	v_mfma_f32_16x16x32_bf16 v[16:19], v[120:123], v[206:209], v[16:19]
	v_mfma_f32_16x16x32_bf16 v[20:23], v[174:177], v[206:209], v[20:23]
	v_mfma_f32_16x16x32_bf16 v[8:11], v[124:127], v[186:189], v[8:11]
	v_mfma_f32_16x16x32_bf16 v[12:15], v[178:181], v[186:189], v[12:15]
	v_mfma_f32_16x16x32_bf16 v[24:27], v[124:127], v[194:197], v[24:27]
	v_mfma_f32_16x16x32_bf16 v[28:31], v[178:181], v[194:197], v[28:31]
	v_mfma_f32_16x16x32_bf16 v[60:63], v[124:127], v[202:205], v[60:63]
	v_mfma_f32_16x16x32_bf16 v[100:103], v[178:181], v[202:205], v[100:103]
	v_mfma_f32_16x16x32_bf16 v[16:19], v[124:127], v[210:213], v[16:19]
	v_mfma_f32_16x16x32_bf16 v[20:23], v[178:181], v[210:213], v[20:23]
	s_setprio 0
	s_barrier
	ds_read_b128 v[104:107], v161
	ds_read_b128 v[108:111], v161 offset:1024
	ds_read_b128 v[112:115], v161 offset:2048
	ds_read_b128 v[116:119], v161 offset:3072
	ds_read_b128 v[120:123], v162
	ds_read_b128 v[124:127], v162 offset:1024
	ds_read_b128 v[174:177], v162 offset:2048
	ds_read_b128 v[178:181], v162 offset:3072
	s_add_u32 s40, s40, 0x10180
	s_addc_u32 s41, s41, 0
	s_mov_b32 m0, s84
	v_lshl_add_u64 v[156:157], s[40:41], 0, v[128:129]
	ds_read_b128 v[182:185], v163
	ds_read_b128 v[186:189], v163 offset:1024
	ds_read_b128 v[190:193], v163 offset:2048
	ds_read_b128 v[194:197], v163 offset:3072
	ds_read_b128 v[198:201], v163 offset:4096
	ds_read_b128 v[202:205], v163 offset:5120
	ds_read_b128 v[206:209], v163 offset:6144
	ds_read_b128 v[210:213], v163 offset:7168
	global_load_lds_dwordx4 v[156:157], off
	v_lshl_add_u64 v[156:157], s[40:41], 0, v[132:133]
	s_mov_b32 m0, s29
	s_nop 0
	global_load_lds_dwordx4 v[156:157], off
	s_waitcnt vmcnt(8)
	s_waitcnt lgkmcnt(0)
	s_barrier
	s_setprio 1
	v_mfma_f32_16x16x32_bf16 v[64:67], v[104:107], v[182:185], v[64:67]
	v_mfma_f32_16x16x32_bf16 v[68:71], v[112:115], v[182:185], v[68:71]
	v_mfma_f32_16x16x32_bf16 v[72:75], v[104:107], v[190:193], v[72:75]
	v_mfma_f32_16x16x32_bf16 v[76:79], v[112:115], v[190:193], v[76:79]
	v_mfma_f32_16x16x32_bf16 v[80:83], v[104:107], v[198:201], v[80:83]
	v_mfma_f32_16x16x32_bf16 v[84:87], v[112:115], v[198:201], v[84:87]
	v_mfma_f32_16x16x32_bf16 v[88:91], v[104:107], v[206:209], v[88:91]
	v_mfma_f32_16x16x32_bf16 v[64:67], v[108:111], v[186:189], v[64:67]
	v_mfma_f32_16x16x32_bf16 v[68:71], v[116:119], v[186:189], v[68:71]
	v_mfma_f32_16x16x32_bf16 v[72:75], v[108:111], v[194:197], v[72:75]
	v_mfma_f32_16x16x32_bf16 v[76:79], v[116:119], v[194:197], v[76:79]
	v_mfma_f32_16x16x32_bf16 v[80:83], v[108:111], v[202:205], v[80:83]
	v_mfma_f32_16x16x32_bf16 v[84:87], v[116:119], v[202:205], v[84:87]
	v_mfma_f32_16x16x32_bf16 v[214:217], v[108:111], v[210:213], v[88:91]
	v_mfma_f32_16x16x32_bf16 v[88:91], v[112:115], v[206:209], v[92:95]
	v_mfma_f32_16x16x32_bf16 v[218:221], v[116:119], v[210:213], v[88:91]
	s_setprio 0
	s_setprio 1
	v_mfma_f32_16x16x32_bf16 v[88:91], v[120:123], v[182:185], v[96:99]
	v_mfma_f32_16x16x32_bf16 v[32:35], v[174:177], v[182:185], v[32:35]
	v_mfma_f32_16x16x32_bf16 v[36:39], v[120:123], v[190:193], v[36:39]
	v_mfma_f32_16x16x32_bf16 v[40:43], v[174:177], v[190:193], v[40:43]
	v_mfma_f32_16x16x32_bf16 v[44:47], v[120:123], v[198:201], v[44:47]
	v_mfma_f32_16x16x32_bf16 v[48:51], v[174:177], v[198:201], v[48:51]
	v_mfma_f32_16x16x32_bf16 v[52:55], v[120:123], v[206:209], v[52:55]
	v_mfma_f32_16x16x32_bf16 v[56:59], v[174:177], v[206:209], v[56:59]
	v_mfma_f32_16x16x32_bf16 v[96:99], v[124:127], v[186:189], v[88:91]
	v_mfma_f32_16x16x32_bf16 v[32:35], v[178:181], v[186:189], v[32:35]
	v_mfma_f32_16x16x32_bf16 v[36:39], v[124:127], v[194:197], v[36:39]
	v_mfma_f32_16x16x32_bf16 v[40:43], v[178:181], v[194:197], v[40:43]
	v_mfma_f32_16x16x32_bf16 v[44:47], v[124:127], v[202:205], v[44:47]
	v_mfma_f32_16x16x32_bf16 v[48:51], v[178:181], v[202:205], v[48:51]
	v_mfma_f32_16x16x32_bf16 v[52:55], v[124:127], v[210:213], v[52:55]
	v_mfma_f32_16x16x32_bf16 v[56:59], v[178:181], v[210:213], v[56:59]
	s_setprio 0
	s_barrier
	s_mov_b32 m0, s68
	v_lshl_add_u64 v[156:157], s[44:45], 0, v[130:131]
	s_add_u32 s40, s44, 0x10000
	ds_read_b128 v[88:91], v163 offset:16384
	ds_read_b128 v[92:95], v163 offset:17408
	ds_read_b128 v[182:185], v163 offset:18432
	ds_read_b128 v[186:189], v163 offset:19456
	ds_read_b128 v[190:193], v163 offset:20480
	ds_read_b128 v[194:197], v163 offset:21504
	ds_read_b128 v[198:201], v163 offset:22528
	ds_read_b128 v[202:205], v163 offset:23552
	global_load_lds_dwordx4 v[156:157], off
	v_lshl_add_u64 v[250:251], s[44:45], 0, v[134:135]
	s_mov_b32 m0, s31
	s_addc_u32 s41, s45, 0
	global_load_lds_dwordx4 v[250:251], off
	v_lshl_add_u64 v[206:207], s[40:41], 0, v[130:131]
	s_mov_b32 m0, s66
	v_lshl_add_u64 v[252:253], s[46:47], 0, v[128:129]
	global_load_lds_dwordx4 v[206:207], off
	v_lshl_add_u64 v[206:207], s[40:41], 0, v[134:135]
	s_mov_b32 m0, s67
	v_lshl_add_u64 v[136:137], s[46:47], 0, v[132:133]
	global_load_lds_dwordx4 v[206:207], off
	s_mov_b32 m0, s39
	s_nop 0
	global_load_lds_dwordx4 v[252:253], off
	s_mov_b32 m0, s53
	s_nop 0
	global_load_lds_dwordx4 v[136:137], off
	s_waitcnt vmcnt(8)
	s_waitcnt lgkmcnt(0)
	s_barrier
	s_setprio 1
	v_mfma_f32_16x16x32_bf16 v[0:3], v[104:107], v[198:201], v[0:3]
	v_mfma_f32_16x16x32_bf16 v[4:7], v[112:115], v[198:201], v[4:7]
	v_mfma_f32_16x16x32_bf16 v[140:143], v[104:107], v[88:91], v[140:143]
	v_mfma_f32_16x16x32_bf16 v[144:147], v[112:115], v[88:91], v[144:147]
	v_mfma_f32_16x16x32_bf16 v[148:151], v[104:107], v[182:185], v[148:151]
	v_mfma_f32_16x16x32_bf16 v[152:155], v[112:115], v[182:185], v[152:155]
	v_mfma_f32_16x16x32_bf16 v[166:169], v[104:107], v[190:193], v[166:169]
	v_mfma_f32_16x16x32_bf16 v[170:173], v[112:115], v[190:193], v[170:173]
	v_mfma_f32_16x16x32_bf16 v[0:3], v[108:111], v[202:205], v[0:3]
	v_mfma_f32_16x16x32_bf16 v[4:7], v[116:119], v[202:205], v[4:7]
	v_mfma_f32_16x16x32_bf16 v[140:143], v[108:111], v[92:95], v[140:143]
	v_mfma_f32_16x16x32_bf16 v[144:147], v[116:119], v[92:95], v[144:147]
	v_mfma_f32_16x16x32_bf16 v[148:151], v[108:111], v[186:189], v[148:151]
	v_mfma_f32_16x16x32_bf16 v[152:155], v[116:119], v[186:189], v[152:155]
	v_mfma_f32_16x16x32_bf16 v[166:169], v[108:111], v[194:197], v[166:169]
	v_mfma_f32_16x16x32_bf16 v[170:173], v[116:119], v[194:197], v[170:173]
	s_setprio 0
	s_setprio 1
	v_mfma_f32_16x16x32_bf16 v[8:11], v[120:123], v[88:91], v[8:11]
	v_mfma_f32_16x16x32_bf16 v[206:209], v[124:127], v[92:95], v[8:11]
	v_mfma_f32_16x16x32_bf16 v[8:11], v[174:177], v[88:91], v[12:15]
	v_mfma_f32_16x16x32_bf16 v[210:213], v[178:181], v[92:95], v[8:11]
	v_mfma_f32_16x16x32_bf16 v[8:11], v[120:123], v[182:185], v[24:27]
	v_mfma_f32_16x16x32_bf16 v[222:225], v[124:127], v[186:189], v[8:11]
	v_mfma_f32_16x16x32_bf16 v[8:11], v[174:177], v[182:185], v[28:31]
	v_mfma_f32_16x16x32_bf16 v[182:185], v[178:181], v[186:189], v[8:11]
	v_mfma_f32_16x16x32_bf16 v[8:11], v[120:123], v[190:193], v[60:63]
	v_mfma_f32_16x16x32_bf16 v[186:189], v[124:127], v[194:197], v[8:11]
	v_mfma_f32_16x16x32_bf16 v[8:11], v[174:177], v[190:193], v[100:103]
	v_mfma_f32_16x16x32_bf16 v[190:193], v[178:181], v[194:197], v[8:11]
	v_mfma_f32_16x16x32_bf16 v[8:11], v[120:123], v[198:201], v[16:19]
	v_mfma_f32_16x16x32_bf16 v[194:197], v[124:127], v[202:205], v[8:11]
	v_mfma_f32_16x16x32_bf16 v[8:11], v[174:177], v[198:201], v[20:23]
	v_mfma_f32_16x16x32_bf16 v[174:177], v[178:181], v[202:205], v[8:11]
	s_setprio 0
	s_barrier
	s_nop 4
	ds_read_b128 v[8:11], v165
	ds_read_b128 v[12:15], v165 offset:1024
	ds_read_b128 v[16:19], v165 offset:2048
	ds_read_b128 v[20:23], v165 offset:3072
	ds_read_b128 v[178:181], v226
	ds_read_b128 v[198:201], v226 offset:1024
	ds_read_b128 v[202:205], v226 offset:2048
	ds_read_b128 v[226:229], v226 offset:3072
	s_add_u32 s40, s46, 0x10000
	s_addc_u32 s41, s47, 0
	s_mov_b32 m0, s54
	v_lshl_add_u64 v[88:89], s[40:41], 0, v[128:129]
	ds_read_b128 v[24:27], v163 offset:32768
	ds_read_b128 v[28:31], v163 offset:33792
	ds_read_b128 v[60:63], v163 offset:34816
	ds_read_b128 v[230:233], v163 offset:35840
	ds_read_b128 v[234:237], v163 offset:36864
	ds_read_b128 v[238:241], v163 offset:37888
	ds_read_b128 v[242:245], v163 offset:38912
	ds_read_b128 v[246:249], v163 offset:39936
	global_load_lds_dwordx4 v[88:89], off
	v_lshl_add_u64 v[88:89], s[40:41], 0, v[132:133]
	s_mov_b32 m0, s55
	s_nop 0
	global_load_lds_dwordx4 v[88:89], off
	s_waitcnt vmcnt(8)
	s_waitcnt lgkmcnt(0)
	s_barrier
	s_setprio 1
	v_mfma_f32_16x16x32_bf16 v[64:67], v[8:11], v[24:27], v[64:67]
	v_mfma_f32_16x16x32_bf16 v[124:127], v[12:15], v[28:31], v[64:67]
	v_mfma_f32_16x16x32_bf16 v[64:67], v[16:19], v[24:27], v[68:71]
	v_mfma_f32_16x16x32_bf16 v[120:123], v[20:23], v[28:31], v[64:67]
	v_mfma_f32_16x16x32_bf16 v[64:67], v[8:11], v[60:63], v[72:75]
	v_mfma_f32_16x16x32_bf16 v[108:111], v[12:15], v[230:233], v[64:67]
	v_mfma_f32_16x16x32_bf16 v[64:67], v[16:19], v[60:63], v[76:79]
	v_mfma_f32_16x16x32_bf16 v[104:107], v[20:23], v[230:233], v[64:67]
	v_mfma_f32_16x16x32_bf16 v[64:67], v[8:11], v[234:237], v[80:83]
	v_mfma_f32_16x16x32_bf16 v[92:95], v[12:15], v[238:241], v[64:67]
	v_mfma_f32_16x16x32_bf16 v[64:67], v[16:19], v[234:237], v[84:87]
	v_mfma_f32_16x16x32_bf16 v[88:91], v[20:23], v[238:241], v[64:67]
	v_mfma_f32_16x16x32_bf16 v[64:67], v[8:11], v[242:245], v[214:217]
	v_mfma_f32_16x16x32_bf16 v[68:71], v[12:15], v[246:249], v[64:67]
	v_mfma_f32_16x16x32_bf16 v[64:67], v[16:19], v[242:245], v[218:221]
	v_mfma_f32_16x16x32_bf16 v[64:67], v[20:23], v[246:249], v[64:67]
	s_setprio 0
	s_setprio 1
	v_mfma_f32_16x16x32_bf16 v[72:75], v[178:181], v[24:27], v[96:99]
	v_mfma_f32_16x16x32_bf16 v[24:27], v[202:205], v[24:27], v[32:35]
	v_mfma_f32_16x16x32_bf16 v[112:115], v[226:229], v[28:31], v[24:27]
	v_mfma_f32_16x16x32_bf16 v[24:27], v[178:181], v[60:63], v[36:39]
	v_mfma_f32_16x16x32_bf16 v[100:103], v[198:201], v[230:233], v[24:27]
	v_mfma_f32_16x16x32_bf16 v[24:27], v[202:205], v[60:63], v[40:43]
	v_mfma_f32_16x16x32_bf16 v[96:99], v[226:229], v[230:233], v[24:27]
	v_mfma_f32_16x16x32_bf16 v[24:27], v[178:181], v[234:237], v[44:47]
	v_mfma_f32_16x16x32_bf16 v[84:87], v[198:201], v[238:241], v[24:27]
	v_mfma_f32_16x16x32_bf16 v[24:27], v[202:205], v[234:237], v[48:51]
	v_mfma_f32_16x16x32_bf16 v[80:83], v[226:229], v[238:241], v[24:27]
	v_mfma_f32_16x16x32_bf16 v[24:27], v[178:181], v[242:245], v[52:55]
	v_mfma_f32_16x16x32_bf16 v[52:55], v[198:201], v[246:249], v[24:27]
	v_mfma_f32_16x16x32_bf16 v[24:27], v[202:205], v[242:245], v[56:59]
	v_mfma_f32_16x16x32_bf16 v[116:119], v[198:201], v[28:31], v[72:75]
	v_mfma_f32_16x16x32_bf16 v[48:51], v[226:229], v[246:249], v[24:27]
	s_setprio 0
	s_barrier
	s_mov_b32 m0, s85
	s_nop 2
	v_lshl_add_u64 v[24:25], v[156:157], 0, s[8:9]
	s_add_u32 s40, s44, 0x10080
	ds_read_b128 v[32:35], v163 offset:49152
	ds_read_b128 v[36:39], v163 offset:50176
	ds_read_b128 v[214:217], v163 offset:51200
	ds_read_b128 v[218:221], v163 offset:52224
	ds_read_b128 v[230:233], v163 offset:53248
	ds_read_b128 v[234:237], v163 offset:54272
	ds_read_b128 v[238:241], v163 offset:55296
	ds_read_b128 v[242:245], v163 offset:56320
	global_load_lds_dwordx4 v[24:25], off
	v_lshl_add_u64 v[24:25], v[250:251], 0, s[8:9]
	s_mov_b32 m0, s69
	s_addc_u32 s41, s45, 0
	global_load_lds_dwordx4 v[24:25], off
	v_lshl_add_u64 v[24:25], s[40:41], 0, v[130:131]
	s_mov_b32 m0, s42
	s_nop 0
	global_load_lds_dwordx4 v[24:25], off
	v_lshl_add_u64 v[24:25], s[40:41], 0, v[134:135]
	s_mov_b32 m0, s43
	s_nop 0
	global_load_lds_dwordx4 v[24:25], off
	v_lshl_add_u64 v[24:25], v[252:253], 0, s[8:9]
	s_mov_b32 m0, s56
	s_nop 0
	global_load_lds_dwordx4 v[24:25], off
	v_lshl_add_u64 v[24:25], v[136:137], 0, s[8:9]
	s_mov_b32 m0, s57
	s_nop 0
	global_load_lds_dwordx4 v[24:25], off
	s_waitcnt vmcnt(8)
	s_waitcnt lgkmcnt(0)
	s_barrier
	s_setprio 1
	v_mfma_f32_16x16x32_bf16 v[24:27], v[8:11], v[32:35], v[140:143]
	v_mfma_f32_16x16x32_bf16 v[76:79], v[12:15], v[36:39], v[24:27]
	v_mfma_f32_16x16x32_bf16 v[24:27], v[16:19], v[32:35], v[144:147]
	v_mfma_f32_16x16x32_bf16 v[72:75], v[20:23], v[36:39], v[24:27]
	v_mfma_f32_16x16x32_bf16 v[24:27], v[8:11], v[214:217], v[148:151]
	v_mfma_f32_16x16x32_bf16 v[44:47], v[12:15], v[218:221], v[24:27]
	v_mfma_f32_16x16x32_bf16 v[24:27], v[16:19], v[214:217], v[152:155]
	v_mfma_f32_16x16x32_bf16 v[40:43], v[20:23], v[218:221], v[24:27]
	v_mfma_f32_16x16x32_bf16 v[24:27], v[8:11], v[230:233], v[166:169]
	v_mfma_f32_16x16x32_bf16 v[0:3], v[8:11], v[238:241], v[0:3]
	v_mfma_f32_16x16x32_bf16 v[28:31], v[12:15], v[234:237], v[24:27]
	v_mfma_f32_16x16x32_bf16 v[24:27], v[16:19], v[230:233], v[170:173]
	v_mfma_f32_16x16x32_bf16 v[12:15], v[12:15], v[242:245], v[0:3]
	v_mfma_f32_16x16x32_bf16 v[0:3], v[16:19], v[238:241], v[4:7]
	v_mfma_f32_16x16x32_bf16 v[24:27], v[20:23], v[234:237], v[24:27]
	v_mfma_f32_16x16x32_bf16 v[8:11], v[20:23], v[242:245], v[0:3]
	s_setprio 0
	s_setprio 1
	v_mfma_f32_16x16x32_bf16 v[0:3], v[178:181], v[32:35], v[206:209]
	v_mfma_f32_16x16x32_bf16 v[60:63], v[198:201], v[36:39], v[0:3]
	v_mfma_f32_16x16x32_bf16 v[0:3], v[202:205], v[32:35], v[210:213]
	v_mfma_f32_16x16x32_bf16 v[56:59], v[226:229], v[36:39], v[0:3]
	v_mfma_f32_16x16x32_bf16 v[0:3], v[178:181], v[214:217], v[222:225]
	v_mfma_f32_16x16x32_bf16 v[36:39], v[198:201], v[218:221], v[0:3]
	v_mfma_f32_16x16x32_bf16 v[0:3], v[202:205], v[214:217], v[182:185]
	v_mfma_f32_16x16x32_bf16 v[32:35], v[226:229], v[218:221], v[0:3]
	v_mfma_f32_16x16x32_bf16 v[0:3], v[178:181], v[230:233], v[186:189]
	v_mfma_f32_16x16x32_bf16 v[20:23], v[198:201], v[234:237], v[0:3]
	v_mfma_f32_16x16x32_bf16 v[0:3], v[202:205], v[230:233], v[190:193]
	v_mfma_f32_16x16x32_bf16 v[16:19], v[226:229], v[234:237], v[0:3]
	v_mfma_f32_16x16x32_bf16 v[0:3], v[178:181], v[238:241], v[194:197]
	v_mfma_f32_16x16x32_bf16 v[4:7], v[198:201], v[242:245], v[0:3]
	v_mfma_f32_16x16x32_bf16 v[0:3], v[202:205], v[238:241], v[174:177]
	v_mfma_f32_16x16x32_bf16 v[0:3], v[226:229], v[242:245], v[0:3]
	s_setprio 0
	s_barrier
	s_andn2_b64 vcc, exec, s[12:13]
	s_cbranch_vccnz .LBB0_1282
	s_barrier

.LBB0_1337:
	ds_read_b128 v[144:147], v151
	ds_read_b128 v[156:159], v151 offset:1024
	ds_read_b128 v[160:163], v151 offset:2048
	ds_read_b128 v[164:167], v151 offset:3072
	ds_read_b128 v[168:171], v152
	ds_read_b128 v[172:175], v152 offset:1024
	ds_read_b128 v[176:179], v152 offset:2048
	ds_read_b128 v[180:183], v152 offset:3072
	s_add_u32 s26, s24, 0xfffc0080
	s_addc_u32 s27, s25, -1
	s_cmp_eq_u32 s50, 12
	s_cselect_b32 s29, s17, s27
	s_cselect_b32 s28, s23, s26
	s_cselect_b32 s27, s15, s49
	s_cselect_b32 s26, s47, s48
	v_lshl_add_u64 v[216:217], s[24:25], 0, v[136:137]
	s_add_i32 m0, s35, 0xc000
	ds_read_b128 v[184:187], v153
	ds_read_b128 v[188:191], v153 offset:1024
	ds_read_b128 v[192:195], v153 offset:2048
	ds_read_b128 v[196:199], v153 offset:3072
	ds_read_b128 v[200:203], v153 offset:4096
	ds_read_b128 v[204:207], v153 offset:5120
	ds_read_b128 v[208:211], v153 offset:6144
	ds_read_b128 v[212:215], v153 offset:7168
	global_load_lds_dwordx4 v[216:217], off
	v_lshl_add_u64 v[216:217], s[24:25], 0, v[138:139]
	s_add_i32 m0, s35, 0xe000
	s_nop 0
	global_load_lds_dwordx4 v[216:217], off
	s_waitcnt vmcnt(8)
	s_waitcnt lgkmcnt(0)
	s_barrier
	s_setprio 1
	v_mfma_f32_16x16x32_bf16 v[124:127], v[144:147], v[184:187], v[124:127]
	v_mfma_f32_16x16x32_bf16 v[120:123], v[160:163], v[184:187], v[120:123]
	v_mfma_f32_16x16x32_bf16 v[108:111], v[144:147], v[192:195], v[108:111]
	v_mfma_f32_16x16x32_bf16 v[104:107], v[160:163], v[192:195], v[104:107]
	v_mfma_f32_16x16x32_bf16 v[92:95], v[144:147], v[200:203], v[92:95]
	v_mfma_f32_16x16x32_bf16 v[88:91], v[160:163], v[200:203], v[88:91]
	v_mfma_f32_16x16x32_bf16 v[76:79], v[144:147], v[208:211], v[76:79]
	v_mfma_f32_16x16x32_bf16 v[72:75], v[160:163], v[208:211], v[72:75]
	v_mfma_f32_16x16x32_bf16 v[124:127], v[156:159], v[188:191], v[124:127]
	v_mfma_f32_16x16x32_bf16 v[120:123], v[164:167], v[188:191], v[120:123]
	v_mfma_f32_16x16x32_bf16 v[108:111], v[156:159], v[196:199], v[108:111]
	v_mfma_f32_16x16x32_bf16 v[104:107], v[164:167], v[196:199], v[104:107]
	v_mfma_f32_16x16x32_bf16 v[92:95], v[156:159], v[204:207], v[92:95]
	v_mfma_f32_16x16x32_bf16 v[88:91], v[164:167], v[204:207], v[88:91]
	v_mfma_f32_16x16x32_bf16 v[76:79], v[156:159], v[212:215], v[76:79]
	v_mfma_f32_16x16x32_bf16 v[72:75], v[164:167], v[212:215], v[72:75]
	s_setprio 0
	s_setprio 1
	v_mfma_f32_16x16x32_bf16 v[116:119], v[168:171], v[184:187], v[116:119]
	v_mfma_f32_16x16x32_bf16 v[112:115], v[176:179], v[184:187], v[112:115]
	v_mfma_f32_16x16x32_bf16 v[100:103], v[168:171], v[192:195], v[100:103]
	v_mfma_f32_16x16x32_bf16 v[96:99], v[176:179], v[192:195], v[96:99]
	v_mfma_f32_16x16x32_bf16 v[84:87], v[168:171], v[200:203], v[84:87]
	v_mfma_f32_16x16x32_bf16 v[80:83], v[176:179], v[200:203], v[80:83]
	v_mfma_f32_16x16x32_bf16 v[68:71], v[168:171], v[208:211], v[68:71]
	v_mfma_f32_16x16x32_bf16 v[64:67], v[176:179], v[208:211], v[64:67]
	v_mfma_f32_16x16x32_bf16 v[116:119], v[172:175], v[188:191], v[116:119]
	v_mfma_f32_16x16x32_bf16 v[112:115], v[180:183], v[188:191], v[112:115]
	v_mfma_f32_16x16x32_bf16 v[100:103], v[172:175], v[196:199], v[100:103]
	v_mfma_f32_16x16x32_bf16 v[96:99], v[180:183], v[196:199], v[96:99]
	v_mfma_f32_16x16x32_bf16 v[84:87], v[172:175], v[204:207], v[84:87]
	v_mfma_f32_16x16x32_bf16 v[80:83], v[180:183], v[204:207], v[80:83]
	v_mfma_f32_16x16x32_bf16 v[68:71], v[172:175], v[212:215], v[68:71]
	v_mfma_f32_16x16x32_bf16 v[64:67], v[180:183], v[212:215], v[64:67]
	s_setprio 0
	s_barrier
	s_add_i32 s51, s44, s34
	v_lshl_add_u64 v[216:217], s[26:27], 0, v[130:131]
	s_mov_b32 m0, s51
	ds_read_b128 v[184:187], v153 offset:16384
	ds_read_b128 v[188:191], v153 offset:17408
	ds_read_b128 v[192:195], v153 offset:18432
	ds_read_b128 v[196:199], v153 offset:19456
	ds_read_b128 v[200:203], v153 offset:20480
	ds_read_b128 v[204:207], v153 offset:21504
	ds_read_b128 v[208:211], v153 offset:22528
	ds_read_b128 v[212:215], v153 offset:23552
	global_load_lds_dwordx4 v[216:217], off
	s_add_i32 m0, s51, 0x2000
	s_add_u32 s52, s26, 0x40000
	v_lshl_add_u64 v[218:219], s[26:27], 0, v[134:135]
	s_addc_u32 s53, s27, 0
	s_add_i32 s51, s45, s34
	global_load_lds_dwordx4 v[218:219], off
	v_lshl_add_u64 v[220:221], s[52:53], 0, v[130:131]
	s_mov_b32 m0, s51
	v_lshl_add_u64 v[222:223], s[28:29], 0, v[132:133]
	global_load_lds_dwordx4 v[220:221], off
	v_lshl_add_u64 v[220:221], s[52:53], 0, v[134:135]
	s_add_i32 m0, s51, 0x2000
	s_nop 0
	global_load_lds_dwordx4 v[220:221], off
	v_lshl_add_u64 v[220:221], s[28:29], 0, v[128:129]
	s_mov_b32 m0, s35
	s_nop 0
	global_load_lds_dwordx4 v[220:221], off
	s_mov_b32 m0, s36
	s_nop 0
	global_load_lds_dwordx4 v[222:223], off
	s_waitcnt vmcnt(8)
	s_waitcnt lgkmcnt(0)
	s_barrier
	s_setprio 1
	v_mfma_f32_16x16x32_bf16 v[60:63], v[144:147], v[184:187], v[60:63]
	v_mfma_f32_16x16x32_bf16 v[56:59], v[160:163], v[184:187], v[56:59]
	v_mfma_f32_16x16x32_bf16 v[44:47], v[144:147], v[192:195], v[44:47]
	v_mfma_f32_16x16x32_bf16 v[40:43], v[160:163], v[192:195], v[40:43]
	v_mfma_f32_16x16x32_bf16 v[28:31], v[144:147], v[200:203], v[28:31]
	v_mfma_f32_16x16x32_bf16 v[24:27], v[160:163], v[200:203], v[24:27]
	v_mfma_f32_16x16x32_bf16 v[12:15], v[144:147], v[208:211], v[12:15]
	v_mfma_f32_16x16x32_bf16 v[8:11], v[160:163], v[208:211], v[8:11]
	v_mfma_f32_16x16x32_bf16 v[60:63], v[156:159], v[188:191], v[60:63]
	v_mfma_f32_16x16x32_bf16 v[56:59], v[164:167], v[188:191], v[56:59]
	v_mfma_f32_16x16x32_bf16 v[44:47], v[156:159], v[196:199], v[44:47]
	v_mfma_f32_16x16x32_bf16 v[40:43], v[164:167], v[196:199], v[40:43]
	v_mfma_f32_16x16x32_bf16 v[28:31], v[156:159], v[204:207], v[28:31]
	v_mfma_f32_16x16x32_bf16 v[24:27], v[164:167], v[204:207], v[24:27]
	v_mfma_f32_16x16x32_bf16 v[12:15], v[156:159], v[212:215], v[12:15]
	v_mfma_f32_16x16x32_bf16 v[8:11], v[164:167], v[212:215], v[8:11]
	s_setprio 0
	s_setprio 1
	v_mfma_f32_16x16x32_bf16 v[52:55], v[168:171], v[184:187], v[52:55]
	v_mfma_f32_16x16x32_bf16 v[48:51], v[176:179], v[184:187], v[48:51]
	v_mfma_f32_16x16x32_bf16 v[36:39], v[168:171], v[192:195], v[36:39]
	v_mfma_f32_16x16x32_bf16 v[32:35], v[176:179], v[192:195], v[32:35]
	v_mfma_f32_16x16x32_bf16 v[20:23], v[168:171], v[200:203], v[20:23]
	v_mfma_f32_16x16x32_bf16 v[16:19], v[176:179], v[200:203], v[16:19]
	v_mfma_f32_16x16x32_bf16 v[4:7], v[168:171], v[208:211], v[4:7]
	v_mfma_f32_16x16x32_bf16 v[0:3], v[176:179], v[208:211], v[0:3]
	v_mfma_f32_16x16x32_bf16 v[52:55], v[172:175], v[188:191], v[52:55]
	v_mfma_f32_16x16x32_bf16 v[48:51], v[180:183], v[188:191], v[48:51]
	v_mfma_f32_16x16x32_bf16 v[36:39], v[172:175], v[196:199], v[36:39]
	v_mfma_f32_16x16x32_bf16 v[32:35], v[180:183], v[196:199], v[32:35]
	v_mfma_f32_16x16x32_bf16 v[20:23], v[172:175], v[204:207], v[20:23]
	v_mfma_f32_16x16x32_bf16 v[16:19], v[180:183], v[204:207], v[16:19]
	v_mfma_f32_16x16x32_bf16 v[4:7], v[172:175], v[212:215], v[4:7]
	v_mfma_f32_16x16x32_bf16 v[0:3], v[180:183], v[212:215], v[0:3]
	s_setprio 0
	s_barrier
	s_add_i32 s51, 0, 0x18000
	s_add_i32 s52, 0, 0x1c000
	v_add_u32_e32 v164, s51, v149
	v_add_u32_e32 v180, s52, v149
	ds_read_b128 v[144:147], v164
	ds_read_b128 v[156:159], v164 offset:1024
	ds_read_b128 v[160:163], v164 offset:2048
	ds_read_b128 v[164:167], v164 offset:3072
	ds_read_b128 v[168:171], v180
	ds_read_b128 v[172:175], v180 offset:1024
	ds_read_b128 v[176:179], v180 offset:2048
	ds_read_b128 v[180:183], v180 offset:3072
	s_add_u32 s28, s28, 0x40000
	s_addc_u32 s29, s29, 0
	s_mov_b32 m0, s37
	v_lshl_add_u64 v[224:225], s[28:29], 0, v[128:129]
	ds_read_b128 v[184:187], v153 offset:32768
	ds_read_b128 v[188:191], v153 offset:33792
	ds_read_b128 v[192:195], v153 offset:34816
	ds_read_b128 v[196:199], v153 offset:35840
	ds_read_b128 v[200:203], v153 offset:36864
	ds_read_b128 v[204:207], v153 offset:37888
	ds_read_b128 v[208:211], v153 offset:38912
	ds_read_b128 v[212:215], v153 offset:39936
	global_load_lds_dwordx4 v[224:225], off
	v_lshl_add_u64 v[224:225], s[28:29], 0, v[132:133]
	s_mov_b32 m0, s38
	s_nop 0
	global_load_lds_dwordx4 v[224:225], off
	s_waitcnt vmcnt(8)
	s_waitcnt lgkmcnt(0)
	s_barrier
	s_setprio 1
	v_mfma_f32_16x16x32_bf16 v[124:127], v[144:147], v[184:187], v[124:127]
	v_mfma_f32_16x16x32_bf16 v[120:123], v[160:163], v[184:187], v[120:123]
	v_mfma_f32_16x16x32_bf16 v[108:111], v[144:147], v[192:195], v[108:111]
	v_mfma_f32_16x16x32_bf16 v[104:107], v[160:163], v[192:195], v[104:107]
	v_mfma_f32_16x16x32_bf16 v[92:95], v[144:147], v[200:203], v[92:95]
	v_mfma_f32_16x16x32_bf16 v[88:91], v[160:163], v[200:203], v[88:91]
	v_mfma_f32_16x16x32_bf16 v[76:79], v[144:147], v[208:211], v[76:79]
	v_mfma_f32_16x16x32_bf16 v[72:75], v[160:163], v[208:211], v[72:75]
	v_mfma_f32_16x16x32_bf16 v[124:127], v[156:159], v[188:191], v[124:127]
	v_mfma_f32_16x16x32_bf16 v[120:123], v[164:167], v[188:191], v[120:123]
	v_mfma_f32_16x16x32_bf16 v[108:111], v[156:159], v[196:199], v[108:111]
	v_mfma_f32_16x16x32_bf16 v[104:107], v[164:167], v[196:199], v[104:107]
	v_mfma_f32_16x16x32_bf16 v[92:95], v[156:159], v[204:207], v[92:95]
	v_mfma_f32_16x16x32_bf16 v[88:91], v[164:167], v[204:207], v[88:91]
	v_mfma_f32_16x16x32_bf16 v[76:79], v[156:159], v[212:215], v[76:79]
	v_mfma_f32_16x16x32_bf16 v[72:75], v[164:167], v[212:215], v[72:75]
	s_setprio 0
	s_setprio 1
	v_mfma_f32_16x16x32_bf16 v[116:119], v[168:171], v[184:187], v[116:119]
	v_mfma_f32_16x16x32_bf16 v[112:115], v[176:179], v[184:187], v[112:115]
	v_mfma_f32_16x16x32_bf16 v[100:103], v[168:171], v[192:195], v[100:103]
	v_mfma_f32_16x16x32_bf16 v[96:99], v[176:179], v[192:195], v[96:99]
	v_mfma_f32_16x16x32_bf16 v[84:87], v[168:171], v[200:203], v[84:87]
	v_mfma_f32_16x16x32_bf16 v[80:83], v[176:179], v[200:203], v[80:83]
	v_mfma_f32_16x16x32_bf16 v[68:71], v[168:171], v[208:211], v[68:71]
	v_mfma_f32_16x16x32_bf16 v[64:67], v[176:179], v[208:211], v[64:67]
	v_mfma_f32_16x16x32_bf16 v[116:119], v[172:175], v[188:191], v[116:119]
	v_mfma_f32_16x16x32_bf16 v[112:115], v[180:183], v[188:191], v[112:115]
	v_mfma_f32_16x16x32_bf16 v[100:103], v[172:175], v[196:199], v[100:103]
	v_mfma_f32_16x16x32_bf16 v[96:99], v[180:183], v[196:199], v[96:99]
	v_mfma_f32_16x16x32_bf16 v[84:87], v[172:175], v[204:207], v[84:87]
	v_mfma_f32_16x16x32_bf16 v[80:83], v[180:183], v[204:207], v[80:83]
	v_mfma_f32_16x16x32_bf16 v[68:71], v[172:175], v[212:215], v[68:71]
	v_mfma_f32_16x16x32_bf16 v[64:67], v[180:183], v[212:215], v[64:67]
	s_setprio 0
	s_barrier
	s_add_i32 s28, s51, s34
	v_lshl_add_u64 v[216:217], v[216:217], 0, s[10:11]
	s_mov_b32 m0, s28
	ds_read_b128 v[184:187], v153 offset:49152
	ds_read_b128 v[188:191], v153 offset:50176
	ds_read_b128 v[192:195], v153 offset:51200
	ds_read_b128 v[196:199], v153 offset:52224
	ds_read_b128 v[200:203], v153 offset:53248
	ds_read_b128 v[204:207], v153 offset:54272
	ds_read_b128 v[208:211], v153 offset:55296
	ds_read_b128 v[212:215], v153 offset:56320
	global_load_lds_dwordx4 v[216:217], off
	s_add_i32 m0, s28, 0x2000
	s_add_u32 s26, s26, 0x40080
	v_lshl_add_u64 v[216:217], v[218:219], 0, s[10:11]
	s_addc_u32 s27, s27, 0
	s_add_i32 s28, s52, s34
	global_load_lds_dwordx4 v[216:217], off
	v_lshl_add_u64 v[216:217], s[26:27], 0, v[130:131]
	s_mov_b32 m0, s28
	s_nop 0
	global_load_lds_dwordx4 v[216:217], off
	v_lshl_add_u64 v[216:217], s[26:27], 0, v[134:135]
	s_add_i32 m0, s28, 0x2000
	s_nop 0
	global_load_lds_dwordx4 v[216:217], off
	v_lshl_add_u64 v[216:217], v[220:221], 0, s[10:11]
	s_mov_b32 m0, s40
	s_nop 0
	global_load_lds_dwordx4 v[216:217], off
	v_lshl_add_u64 v[216:217], v[222:223], 0, s[10:11]
	s_mov_b32 m0, s41
	s_nop 0
	global_load_lds_dwordx4 v[216:217], off
	s_waitcnt vmcnt(8)
	s_waitcnt lgkmcnt(0)
	s_barrier
	s_setprio 1
	v_mfma_f32_16x16x32_bf16 v[60:63], v[144:147], v[184:187], v[60:63]
	v_mfma_f32_16x16x32_bf16 v[56:59], v[160:163], v[184:187], v[56:59]
	v_mfma_f32_16x16x32_bf16 v[44:47], v[144:147], v[192:195], v[44:47]
	v_mfma_f32_16x16x32_bf16 v[40:43], v[160:163], v[192:195], v[40:43]
	v_mfma_f32_16x16x32_bf16 v[28:31], v[144:147], v[200:203], v[28:31]
	v_mfma_f32_16x16x32_bf16 v[24:27], v[160:163], v[200:203], v[24:27]
	v_mfma_f32_16x16x32_bf16 v[12:15], v[144:147], v[208:211], v[12:15]
	v_mfma_f32_16x16x32_bf16 v[8:11], v[160:163], v[208:211], v[8:11]
	v_mfma_f32_16x16x32_bf16 v[60:63], v[156:159], v[188:191], v[60:63]
	v_mfma_f32_16x16x32_bf16 v[56:59], v[164:167], v[188:191], v[56:59]
	v_mfma_f32_16x16x32_bf16 v[44:47], v[156:159], v[196:199], v[44:47]
	v_mfma_f32_16x16x32_bf16 v[40:43], v[164:167], v[196:199], v[40:43]
	v_mfma_f32_16x16x32_bf16 v[28:31], v[156:159], v[204:207], v[28:31]
	v_mfma_f32_16x16x32_bf16 v[24:27], v[164:167], v[204:207], v[24:27]
	v_mfma_f32_16x16x32_bf16 v[12:15], v[156:159], v[212:215], v[12:15]
	v_mfma_f32_16x16x32_bf16 v[8:11], v[164:167], v[212:215], v[8:11]
	s_setprio 0
	s_setprio 1
	v_mfma_f32_16x16x32_bf16 v[52:55], v[168:171], v[184:187], v[52:55]
	v_mfma_f32_16x16x32_bf16 v[48:51], v[176:179], v[184:187], v[48:51]
	v_mfma_f32_16x16x32_bf16 v[36:39], v[168:171], v[192:195], v[36:39]
	v_mfma_f32_16x16x32_bf16 v[32:35], v[176:179], v[192:195], v[32:35]
	v_mfma_f32_16x16x32_bf16 v[20:23], v[168:171], v[200:203], v[20:23]
	v_mfma_f32_16x16x32_bf16 v[16:19], v[176:179], v[200:203], v[16:19]
	v_mfma_f32_16x16x32_bf16 v[4:7], v[168:171], v[208:211], v[4:7]
	v_mfma_f32_16x16x32_bf16 v[0:3], v[176:179], v[208:211], v[0:3]
	v_mfma_f32_16x16x32_bf16 v[52:55], v[172:175], v[188:191], v[52:55]
	v_mfma_f32_16x16x32_bf16 v[48:51], v[180:183], v[188:191], v[48:51]
	v_mfma_f32_16x16x32_bf16 v[36:39], v[172:175], v[196:199], v[36:39]
	v_mfma_f32_16x16x32_bf16 v[32:35], v[180:183], v[196:199], v[32:35]
	v_mfma_f32_16x16x32_bf16 v[20:23], v[172:175], v[204:207], v[20:23]
	v_mfma_f32_16x16x32_bf16 v[16:19], v[180:183], v[204:207], v[16:19]
	v_mfma_f32_16x16x32_bf16 v[4:7], v[172:175], v[212:215], v[4:7]
	v_mfma_f32_16x16x32_bf16 v[0:3], v[180:183], v[212:215], v[0:3]
	s_setprio 0
	s_barrier
	s_add_i32 s50, s50, 2
	s_add_u32 s24, s24, 0x100
	s_addc_u32 s25, s25, 0
	s_add_u32 s48, s48, 0x100
	s_addc_u32 s49, s49, 0
	s_cmp_gt_u32 s50, 13
	s_cbranch_scc0 .LBB0_1337
	s_and_b64 vcc, exec, s[12:13]
	s_cbranch_vccz .LBB0_1340
	s_barrier

.LBB0_1403:
	ds_read_b128 v[128:131], v164
	ds_read_b128 v[160:163], v164 offset:1024
	ds_read_b128 v[168:171], v164 offset:2048
	ds_read_b128 v[172:175], v164 offset:3072
	ds_read_b128 v[176:179], v165
	ds_read_b128 v[180:183], v165 offset:1024
	ds_read_b128 v[184:187], v165 offset:2048
	ds_read_b128 v[188:191], v165 offset:3072
	s_add_u32 s30, s28, 0xfffe0080
	s_addc_u32 s31, s29, -1
	s_cmp_eq_u32 s56, 4
	s_cselect_b32 s35, s5, s31
	s_cselect_b32 s34, s23, s30
	s_cselect_b32 s31, s21, s55
	s_cselect_b32 s30, s53, s54
	v_lshl_add_u64 v[156:157], s[28:29], 0, v[148:149]
	s_add_i32 m0, s39, 0xc000
	ds_read_b128 v[192:195], v166
	ds_read_b128 v[196:199], v166 offset:1024
	ds_read_b128 v[200:203], v166 offset:2048
	ds_read_b128 v[204:207], v166 offset:3072
	ds_read_b128 v[208:211], v166 offset:4096
	ds_read_b128 v[212:215], v166 offset:5120
	ds_read_b128 v[216:219], v166 offset:6144
	ds_read_b128 v[220:223], v166 offset:7168
	global_load_lds_dwordx4 v[156:157], off
	v_lshl_add_u64 v[156:157], s[28:29], 0, v[150:151]
	s_add_i32 m0, s39, 0xe000
	s_nop 0
	global_load_lds_dwordx4 v[156:157], off
	s_waitcnt vmcnt(8)
	s_waitcnt lgkmcnt(0)
	s_barrier
	s_setprio 1
	v_mfma_f32_16x16x32_bf16 v[124:127], v[128:131], v[192:195], v[124:127]
	v_mfma_f32_16x16x32_bf16 v[120:123], v[168:171], v[192:195], v[120:123]
	v_mfma_f32_16x16x32_bf16 v[108:111], v[128:131], v[200:203], v[108:111]
	v_mfma_f32_16x16x32_bf16 v[104:107], v[168:171], v[200:203], v[104:107]
	v_mfma_f32_16x16x32_bf16 v[92:95], v[128:131], v[208:211], v[92:95]
	v_mfma_f32_16x16x32_bf16 v[88:91], v[168:171], v[208:211], v[88:91]
	v_mfma_f32_16x16x32_bf16 v[76:79], v[128:131], v[216:219], v[76:79]
	v_mfma_f32_16x16x32_bf16 v[72:75], v[168:171], v[216:219], v[72:75]
	v_mfma_f32_16x16x32_bf16 v[124:127], v[160:163], v[196:199], v[124:127]
	v_mfma_f32_16x16x32_bf16 v[120:123], v[172:175], v[196:199], v[120:123]
	v_mfma_f32_16x16x32_bf16 v[108:111], v[160:163], v[204:207], v[108:111]
	v_mfma_f32_16x16x32_bf16 v[104:107], v[172:175], v[204:207], v[104:107]
	v_mfma_f32_16x16x32_bf16 v[92:95], v[160:163], v[212:215], v[92:95]
	v_mfma_f32_16x16x32_bf16 v[88:91], v[172:175], v[212:215], v[88:91]
	v_mfma_f32_16x16x32_bf16 v[76:79], v[160:163], v[220:223], v[76:79]
	v_mfma_f32_16x16x32_bf16 v[72:75], v[172:175], v[220:223], v[72:75]
	s_setprio 0
	s_setprio 1
	v_mfma_f32_16x16x32_bf16 v[116:119], v[176:179], v[192:195], v[116:119]
	v_mfma_f32_16x16x32_bf16 v[112:115], v[184:187], v[192:195], v[112:115]
	v_mfma_f32_16x16x32_bf16 v[100:103], v[176:179], v[200:203], v[100:103]
	v_mfma_f32_16x16x32_bf16 v[96:99], v[184:187], v[200:203], v[96:99]
	v_mfma_f32_16x16x32_bf16 v[84:87], v[176:179], v[208:211], v[84:87]
	v_mfma_f32_16x16x32_bf16 v[80:83], v[184:187], v[208:211], v[80:83]
	v_mfma_f32_16x16x32_bf16 v[68:71], v[176:179], v[216:219], v[68:71]
	v_mfma_f32_16x16x32_bf16 v[64:67], v[184:187], v[216:219], v[64:67]
	v_mfma_f32_16x16x32_bf16 v[116:119], v[180:183], v[196:199], v[116:119]
	v_mfma_f32_16x16x32_bf16 v[112:115], v[188:191], v[196:199], v[112:115]
	v_mfma_f32_16x16x32_bf16 v[100:103], v[180:183], v[204:207], v[100:103]
	v_mfma_f32_16x16x32_bf16 v[96:99], v[188:191], v[204:207], v[96:99]
	v_mfma_f32_16x16x32_bf16 v[84:87], v[180:183], v[212:215], v[84:87]
	v_mfma_f32_16x16x32_bf16 v[80:83], v[188:191], v[212:215], v[80:83]
	v_mfma_f32_16x16x32_bf16 v[68:71], v[180:183], v[220:223], v[68:71]
	v_mfma_f32_16x16x32_bf16 v[64:67], v[188:191], v[220:223], v[64:67]
	s_setprio 0
	s_barrier
	s_add_i32 s57, s50, s38
	v_lshl_add_u64 v[156:157], s[30:31], 0, v[134:135]
	s_mov_b32 m0, s57
	ds_read_b128 v[192:195], v166 offset:16384
	ds_read_b128 v[196:199], v166 offset:17408
	ds_read_b128 v[200:203], v166 offset:18432
	ds_read_b128 v[204:207], v166 offset:19456
	ds_read_b128 v[208:211], v166 offset:20480
	ds_read_b128 v[212:215], v166 offset:21504
	ds_read_b128 v[216:219], v166 offset:22528
	ds_read_b128 v[220:223], v166 offset:23552
	global_load_lds_dwordx4 v[156:157], off
	s_add_i32 m0, s57, 0x2000
	s_add_u32 s58, s30, 0x20000
	v_lshl_add_u64 v[224:225], s[30:31], 0, v[138:139]
	s_addc_u32 s59, s31, 0
	s_add_i32 s57, s51, s38
	global_load_lds_dwordx4 v[224:225], off
	v_lshl_add_u64 v[226:227], s[58:59], 0, v[134:135]
	s_mov_b32 m0, s57
	v_lshl_add_u64 v[228:229], s[34:35], 0, v[136:137]
	global_load_lds_dwordx4 v[226:227], off
	v_lshl_add_u64 v[226:227], s[58:59], 0, v[138:139]
	s_add_i32 m0, s57, 0x2000
	s_nop 0
	global_load_lds_dwordx4 v[226:227], off
	v_lshl_add_u64 v[226:227], s[34:35], 0, v[132:133]
	s_mov_b32 m0, s39
	s_nop 0
	global_load_lds_dwordx4 v[226:227], off
	s_mov_b32 m0, s40
	s_nop 0
	global_load_lds_dwordx4 v[228:229], off
	s_waitcnt vmcnt(8)
	s_waitcnt lgkmcnt(0)
	s_barrier
	s_setprio 1
	v_mfma_f32_16x16x32_bf16 v[60:63], v[128:131], v[192:195], v[60:63]
	v_mfma_f32_16x16x32_bf16 v[56:59], v[168:171], v[192:195], v[56:59]
	v_mfma_f32_16x16x32_bf16 v[44:47], v[128:131], v[200:203], v[44:47]
	v_mfma_f32_16x16x32_bf16 v[40:43], v[168:171], v[200:203], v[40:43]
	v_mfma_f32_16x16x32_bf16 v[28:31], v[128:131], v[208:211], v[28:31]
	v_mfma_f32_16x16x32_bf16 v[24:27], v[168:171], v[208:211], v[24:27]
	v_mfma_f32_16x16x32_bf16 v[12:15], v[128:131], v[216:219], v[12:15]
	v_mfma_f32_16x16x32_bf16 v[8:11], v[168:171], v[216:219], v[8:11]
	v_mfma_f32_16x16x32_bf16 v[60:63], v[160:163], v[196:199], v[60:63]
	v_mfma_f32_16x16x32_bf16 v[56:59], v[172:175], v[196:199], v[56:59]
	v_mfma_f32_16x16x32_bf16 v[44:47], v[160:163], v[204:207], v[44:47]
	v_mfma_f32_16x16x32_bf16 v[40:43], v[172:175], v[204:207], v[40:43]
	v_mfma_f32_16x16x32_bf16 v[28:31], v[160:163], v[212:215], v[28:31]
	v_mfma_f32_16x16x32_bf16 v[24:27], v[172:175], v[212:215], v[24:27]
	v_mfma_f32_16x16x32_bf16 v[12:15], v[160:163], v[220:223], v[12:15]
	v_mfma_f32_16x16x32_bf16 v[8:11], v[172:175], v[220:223], v[8:11]
	s_setprio 0
	s_setprio 1
	v_mfma_f32_16x16x32_bf16 v[52:55], v[176:179], v[192:195], v[52:55]
	v_mfma_f32_16x16x32_bf16 v[48:51], v[184:187], v[192:195], v[48:51]
	v_mfma_f32_16x16x32_bf16 v[36:39], v[176:179], v[200:203], v[36:39]
	v_mfma_f32_16x16x32_bf16 v[32:35], v[184:187], v[200:203], v[32:35]
	v_mfma_f32_16x16x32_bf16 v[20:23], v[176:179], v[208:211], v[20:23]
	v_mfma_f32_16x16x32_bf16 v[16:19], v[184:187], v[208:211], v[16:19]
	v_mfma_f32_16x16x32_bf16 v[4:7], v[176:179], v[216:219], v[4:7]
	v_mfma_f32_16x16x32_bf16 v[0:3], v[184:187], v[216:219], v[0:3]
	v_mfma_f32_16x16x32_bf16 v[52:55], v[180:183], v[196:199], v[52:55]
	v_mfma_f32_16x16x32_bf16 v[48:51], v[188:191], v[196:199], v[48:51]
	v_mfma_f32_16x16x32_bf16 v[36:39], v[180:183], v[204:207], v[36:39]
	v_mfma_f32_16x16x32_bf16 v[32:35], v[188:191], v[204:207], v[32:35]
	v_mfma_f32_16x16x32_bf16 v[20:23], v[180:183], v[212:215], v[20:23]
	v_mfma_f32_16x16x32_bf16 v[16:19], v[188:191], v[212:215], v[16:19]
	v_mfma_f32_16x16x32_bf16 v[4:7], v[180:183], v[220:223], v[4:7]
	v_mfma_f32_16x16x32_bf16 v[0:3], v[188:191], v[220:223], v[0:3]
	s_setprio 0
	s_barrier
	s_add_i32 s57, 0, 0x18000
	v_add_u32_e32 v140, s57, v159
	s_add_i32 s58, 0, 0x1c000
	ds_read_b128 v[128:131], v140
	ds_read_b128 v[160:163], v140 offset:1024
	ds_read_b128 v[168:171], v140 offset:2048
	ds_read_b128 v[172:175], v140 offset:3072
	v_add_u32_e32 v140, s58, v159
	ds_read_b128 v[176:179], v140
	ds_read_b128 v[180:183], v140 offset:1024
	ds_read_b128 v[184:187], v140 offset:2048
	ds_read_b128 v[188:191], v140 offset:3072
	s_add_u32 s34, s34, 0x20000
	s_addc_u32 s35, s35, 0
	s_mov_b32 m0, s41
	v_lshl_add_u64 v[230:231], s[34:35], 0, v[132:133]
	ds_read_b128 v[192:195], v166 offset:32768
	ds_read_b128 v[196:199], v166 offset:33792
	ds_read_b128 v[200:203], v166 offset:34816
	ds_read_b128 v[204:207], v166 offset:35840
	ds_read_b128 v[208:211], v166 offset:36864
	ds_read_b128 v[212:215], v166 offset:37888
	ds_read_b128 v[216:219], v166 offset:38912
	ds_read_b128 v[220:223], v166 offset:39936
	global_load_lds_dwordx4 v[230:231], off
	v_lshl_add_u64 v[230:231], s[34:35], 0, v[136:137]
	s_mov_b32 m0, s42
	s_nop 0
	global_load_lds_dwordx4 v[230:231], off
	s_waitcnt vmcnt(8)
	s_waitcnt lgkmcnt(0)
	s_barrier
	s_setprio 1
	v_mfma_f32_16x16x32_bf16 v[124:127], v[128:131], v[192:195], v[124:127]
	v_mfma_f32_16x16x32_bf16 v[120:123], v[168:171], v[192:195], v[120:123]
	v_mfma_f32_16x16x32_bf16 v[108:111], v[128:131], v[200:203], v[108:111]
	v_mfma_f32_16x16x32_bf16 v[104:107], v[168:171], v[200:203], v[104:107]
	v_mfma_f32_16x16x32_bf16 v[92:95], v[128:131], v[208:211], v[92:95]
	v_mfma_f32_16x16x32_bf16 v[88:91], v[168:171], v[208:211], v[88:91]
	v_mfma_f32_16x16x32_bf16 v[76:79], v[128:131], v[216:219], v[76:79]
	v_mfma_f32_16x16x32_bf16 v[72:75], v[168:171], v[216:219], v[72:75]
	v_mfma_f32_16x16x32_bf16 v[124:127], v[160:163], v[196:199], v[124:127]
	v_mfma_f32_16x16x32_bf16 v[120:123], v[172:175], v[196:199], v[120:123]
	v_mfma_f32_16x16x32_bf16 v[108:111], v[160:163], v[204:207], v[108:111]
	v_mfma_f32_16x16x32_bf16 v[104:107], v[172:175], v[204:207], v[104:107]
	v_mfma_f32_16x16x32_bf16 v[92:95], v[160:163], v[212:215], v[92:95]
	v_mfma_f32_16x16x32_bf16 v[88:91], v[172:175], v[212:215], v[88:91]
	v_mfma_f32_16x16x32_bf16 v[76:79], v[160:163], v[220:223], v[76:79]
	v_mfma_f32_16x16x32_bf16 v[72:75], v[172:175], v[220:223], v[72:75]
	s_setprio 0
	s_setprio 1
	v_mfma_f32_16x16x32_bf16 v[116:119], v[176:179], v[192:195], v[116:119]
	v_mfma_f32_16x16x32_bf16 v[112:115], v[184:187], v[192:195], v[112:115]
	v_mfma_f32_16x16x32_bf16 v[100:103], v[176:179], v[200:203], v[100:103]
	v_mfma_f32_16x16x32_bf16 v[96:99], v[184:187], v[200:203], v[96:99]
	v_mfma_f32_16x16x32_bf16 v[84:87], v[176:179], v[208:211], v[84:87]
	v_mfma_f32_16x16x32_bf16 v[80:83], v[184:187], v[208:211], v[80:83]
	v_mfma_f32_16x16x32_bf16 v[68:71], v[176:179], v[216:219], v[68:71]
	v_mfma_f32_16x16x32_bf16 v[64:67], v[184:187], v[216:219], v[64:67]
	v_mfma_f32_16x16x32_bf16 v[116:119], v[180:183], v[196:199], v[116:119]
	v_mfma_f32_16x16x32_bf16 v[112:115], v[188:191], v[196:199], v[112:115]
	v_mfma_f32_16x16x32_bf16 v[100:103], v[180:183], v[204:207], v[100:103]
	v_mfma_f32_16x16x32_bf16 v[96:99], v[188:191], v[204:207], v[96:99]
	v_mfma_f32_16x16x32_bf16 v[84:87], v[180:183], v[212:215], v[84:87]
	v_mfma_f32_16x16x32_bf16 v[80:83], v[188:191], v[212:215], v[80:83]
	v_mfma_f32_16x16x32_bf16 v[68:71], v[180:183], v[220:223], v[68:71]
	v_mfma_f32_16x16x32_bf16 v[64:67], v[188:191], v[220:223], v[64:67]
	s_setprio 0
	s_barrier
	s_add_i32 s34, s57, s38
	v_lshl_add_u64 v[156:157], v[156:157], 0, s[14:15]
	s_mov_b32 m0, s34
	ds_read_b128 v[192:195], v166 offset:49152
	ds_read_b128 v[196:199], v166 offset:50176
	ds_read_b128 v[200:203], v166 offset:51200
	ds_read_b128 v[204:207], v166 offset:52224
	ds_read_b128 v[208:211], v166 offset:53248
	ds_read_b128 v[212:215], v166 offset:54272
	ds_read_b128 v[216:219], v166 offset:55296
	ds_read_b128 v[220:223], v166 offset:56320
	global_load_lds_dwordx4 v[156:157], off
	s_add_i32 m0, s34, 0x2000
	s_add_u32 s30, s30, 0x20080
	v_lshl_add_u64 v[156:157], v[224:225], 0, s[14:15]
	s_addc_u32 s31, s31, 0
	s_add_i32 s34, s58, s38
	global_load_lds_dwordx4 v[156:157], off
	v_lshl_add_u64 v[156:157], s[30:31], 0, v[134:135]
	s_mov_b32 m0, s34
	s_nop 0
	global_load_lds_dwordx4 v[156:157], off
	v_lshl_add_u64 v[156:157], s[30:31], 0, v[138:139]
	s_add_i32 m0, s34, 0x2000
	s_nop 0
	global_load_lds_dwordx4 v[156:157], off
	v_lshl_add_u64 v[156:157], v[226:227], 0, s[14:15]
	s_mov_b32 m0, s44
	s_nop 0
	global_load_lds_dwordx4 v[156:157], off
	v_lshl_add_u64 v[156:157], v[228:229], 0, s[14:15]
	s_mov_b32 m0, s45
	s_nop 0
	global_load_lds_dwordx4 v[156:157], off
	s_waitcnt vmcnt(8)
	s_waitcnt lgkmcnt(0)
	s_barrier
	s_setprio 1
	v_mfma_f32_16x16x32_bf16 v[60:63], v[128:131], v[192:195], v[60:63]
	v_mfma_f32_16x16x32_bf16 v[56:59], v[168:171], v[192:195], v[56:59]
	v_mfma_f32_16x16x32_bf16 v[44:47], v[128:131], v[200:203], v[44:47]
	v_mfma_f32_16x16x32_bf16 v[40:43], v[168:171], v[200:203], v[40:43]
	v_mfma_f32_16x16x32_bf16 v[28:31], v[128:131], v[208:211], v[28:31]
	v_mfma_f32_16x16x32_bf16 v[24:27], v[168:171], v[208:211], v[24:27]
	v_mfma_f32_16x16x32_bf16 v[12:15], v[128:131], v[216:219], v[12:15]
	v_mfma_f32_16x16x32_bf16 v[8:11], v[168:171], v[216:219], v[8:11]
	v_mfma_f32_16x16x32_bf16 v[60:63], v[160:163], v[196:199], v[60:63]
	v_mfma_f32_16x16x32_bf16 v[56:59], v[172:175], v[196:199], v[56:59]
	v_mfma_f32_16x16x32_bf16 v[44:47], v[160:163], v[204:207], v[44:47]
	v_mfma_f32_16x16x32_bf16 v[40:43], v[172:175], v[204:207], v[40:43]
	v_mfma_f32_16x16x32_bf16 v[28:31], v[160:163], v[212:215], v[28:31]
	v_mfma_f32_16x16x32_bf16 v[24:27], v[172:175], v[212:215], v[24:27]
	v_mfma_f32_16x16x32_bf16 v[12:15], v[160:163], v[220:223], v[12:15]
	v_mfma_f32_16x16x32_bf16 v[8:11], v[172:175], v[220:223], v[8:11]
	s_setprio 0
	s_setprio 1
	v_mfma_f32_16x16x32_bf16 v[52:55], v[176:179], v[192:195], v[52:55]
	v_mfma_f32_16x16x32_bf16 v[48:51], v[184:187], v[192:195], v[48:51]
	v_mfma_f32_16x16x32_bf16 v[36:39], v[176:179], v[200:203], v[36:39]
	v_mfma_f32_16x16x32_bf16 v[32:35], v[184:187], v[200:203], v[32:35]
	v_mfma_f32_16x16x32_bf16 v[20:23], v[176:179], v[208:211], v[20:23]
	v_mfma_f32_16x16x32_bf16 v[16:19], v[184:187], v[208:211], v[16:19]
	v_mfma_f32_16x16x32_bf16 v[4:7], v[176:179], v[216:219], v[4:7]
	v_mfma_f32_16x16x32_bf16 v[0:3], v[184:187], v[216:219], v[0:3]
	v_mfma_f32_16x16x32_bf16 v[52:55], v[180:183], v[196:199], v[52:55]
	v_mfma_f32_16x16x32_bf16 v[48:51], v[188:191], v[196:199], v[48:51]
	v_mfma_f32_16x16x32_bf16 v[36:39], v[180:183], v[204:207], v[36:39]
	v_mfma_f32_16x16x32_bf16 v[32:35], v[188:191], v[204:207], v[32:35]
	v_mfma_f32_16x16x32_bf16 v[20:23], v[180:183], v[212:215], v[20:23]
	v_mfma_f32_16x16x32_bf16 v[16:19], v[188:191], v[212:215], v[16:19]
	v_mfma_f32_16x16x32_bf16 v[4:7], v[180:183], v[220:223], v[4:7]
	v_mfma_f32_16x16x32_bf16 v[0:3], v[188:191], v[220:223], v[0:3]
	s_setprio 0
	s_barrier
	s_add_i32 s56, s56, 2
	s_add_u32 s28, s28, 0x100
	s_addc_u32 s29, s29, 0
	s_add_u32 s54, s54, 0x100
	s_addc_u32 s55, s55, 0
	s_cmp_gt_u32 s56, 5
	s_cbranch_scc0 .LBB0_1403
	s_and_b64 vcc, exec, s[16:17]
	s_cbranch_vccz .LBB0_1406
	s_barrier

.LBB0_1553:
	ds_read_b128 v[140:143], v147
	ds_read_b128 v[152:155], v147 offset:1024
	ds_read_b128 v[156:159], v147 offset:2048
	ds_read_b128 v[160:163], v147 offset:3072
	ds_read_b128 v[164:167], v148
	ds_read_b128 v[168:171], v148 offset:1024
	ds_read_b128 v[172:175], v148 offset:2048
	ds_read_b128 v[176:179], v148 offset:3072
	s_add_u32 s28, s26, 0xfffc0080
	s_addc_u32 s29, s27, -1
	s_cmp_eq_u32 s54, 12
	s_cselect_b32 s31, s19, s29
	s_cselect_b32 s30, s25, s28
	s_cselect_b32 s29, s17, s53
	s_cselect_b32 s28, s51, s52
	v_lshl_add_u64 v[212:213], s[26:27], 0, v[132:133]
	s_add_i32 m0, s39, 0xc000
	ds_read_b128 v[180:183], v149
	ds_read_b128 v[184:187], v149 offset:1024
	ds_read_b128 v[188:191], v149 offset:2048
	ds_read_b128 v[192:195], v149 offset:3072
	ds_read_b128 v[196:199], v149 offset:4096
	ds_read_b128 v[200:203], v149 offset:5120
	ds_read_b128 v[204:207], v149 offset:6144
	ds_read_b128 v[208:211], v149 offset:7168
	global_load_lds_dwordx4 v[212:213], off
	v_lshl_add_u64 v[212:213], s[26:27], 0, v[134:135]
	s_add_i32 m0, s39, 0xe000
	s_nop 0
	global_load_lds_dwordx4 v[212:213], off
	s_waitcnt vmcnt(8)
	s_waitcnt lgkmcnt(0)
	s_barrier
	s_setprio 1
	v_mfma_f32_16x16x32_bf16 v[124:127], v[140:143], v[180:183], v[124:127]
	v_mfma_f32_16x16x32_bf16 v[120:123], v[156:159], v[180:183], v[120:123]
	v_mfma_f32_16x16x32_bf16 v[108:111], v[140:143], v[188:191], v[108:111]
	v_mfma_f32_16x16x32_bf16 v[104:107], v[156:159], v[188:191], v[104:107]
	v_mfma_f32_16x16x32_bf16 v[92:95], v[140:143], v[196:199], v[92:95]
	v_mfma_f32_16x16x32_bf16 v[88:91], v[156:159], v[196:199], v[88:91]
	v_mfma_f32_16x16x32_bf16 v[76:79], v[140:143], v[204:207], v[76:79]
	v_mfma_f32_16x16x32_bf16 v[72:75], v[156:159], v[204:207], v[72:75]
	v_mfma_f32_16x16x32_bf16 v[124:127], v[152:155], v[184:187], v[124:127]
	v_mfma_f32_16x16x32_bf16 v[120:123], v[160:163], v[184:187], v[120:123]
	v_mfma_f32_16x16x32_bf16 v[108:111], v[152:155], v[192:195], v[108:111]
	v_mfma_f32_16x16x32_bf16 v[104:107], v[160:163], v[192:195], v[104:107]
	v_mfma_f32_16x16x32_bf16 v[92:95], v[152:155], v[200:203], v[92:95]
	v_mfma_f32_16x16x32_bf16 v[88:91], v[160:163], v[200:203], v[88:91]
	v_mfma_f32_16x16x32_bf16 v[76:79], v[152:155], v[208:211], v[76:79]
	v_mfma_f32_16x16x32_bf16 v[72:75], v[160:163], v[208:211], v[72:75]
	s_setprio 0
	s_setprio 1
	v_mfma_f32_16x16x32_bf16 v[116:119], v[164:167], v[180:183], v[116:119]
	v_mfma_f32_16x16x32_bf16 v[112:115], v[172:175], v[180:183], v[112:115]
	v_mfma_f32_16x16x32_bf16 v[100:103], v[164:167], v[188:191], v[100:103]
	v_mfma_f32_16x16x32_bf16 v[96:99], v[172:175], v[188:191], v[96:99]
	v_mfma_f32_16x16x32_bf16 v[84:87], v[164:167], v[196:199], v[84:87]
	v_mfma_f32_16x16x32_bf16 v[80:83], v[172:175], v[196:199], v[80:83]
	v_mfma_f32_16x16x32_bf16 v[68:71], v[164:167], v[204:207], v[68:71]
	v_mfma_f32_16x16x32_bf16 v[64:67], v[172:175], v[204:207], v[64:67]
	v_mfma_f32_16x16x32_bf16 v[116:119], v[168:171], v[184:187], v[116:119]
	v_mfma_f32_16x16x32_bf16 v[112:115], v[176:179], v[184:187], v[112:115]
	v_mfma_f32_16x16x32_bf16 v[100:103], v[168:171], v[192:195], v[100:103]
	v_mfma_f32_16x16x32_bf16 v[96:99], v[176:179], v[192:195], v[96:99]
	v_mfma_f32_16x16x32_bf16 v[84:87], v[168:171], v[200:203], v[84:87]
	v_mfma_f32_16x16x32_bf16 v[80:83], v[176:179], v[200:203], v[80:83]
	v_mfma_f32_16x16x32_bf16 v[68:71], v[168:171], v[208:211], v[68:71]
	v_mfma_f32_16x16x32_bf16 v[64:67], v[176:179], v[208:211], v[64:67]
	s_setprio 0
	s_barrier
	s_add_i32 s55, s48, s38
	v_lshl_add_u64 v[212:213], s[28:29], 0, v[128:129]
	s_mov_b32 m0, s55
	ds_read_b128 v[180:183], v149 offset:16384
	ds_read_b128 v[184:187], v149 offset:17408
	ds_read_b128 v[188:191], v149 offset:18432
	ds_read_b128 v[192:195], v149 offset:19456
	ds_read_b128 v[196:199], v149 offset:20480
	ds_read_b128 v[200:203], v149 offset:21504
	ds_read_b128 v[204:207], v149 offset:22528
	ds_read_b128 v[208:211], v149 offset:23552
	global_load_lds_dwordx4 v[212:213], off
	s_add_i32 m0, s55, 0x2000
	s_add_u32 s56, s28, 0x40000
	v_lshl_add_u64 v[214:215], s[28:29], 0, v[130:131]
	s_addc_u32 s57, s29, 0
	s_add_i32 s55, s49, s38
	global_load_lds_dwordx4 v[214:215], off
	v_lshl_add_u64 v[216:217], s[56:57], 0, v[128:129]
	s_mov_b32 m0, s55
	v_lshl_add_u64 v[218:219], s[30:31], 0, v[130:131]
	global_load_lds_dwordx4 v[216:217], off
	v_lshl_add_u64 v[216:217], s[56:57], 0, v[130:131]
	s_add_i32 m0, s55, 0x2000
	s_nop 0
	global_load_lds_dwordx4 v[216:217], off
	v_lshl_add_u64 v[216:217], s[30:31], 0, v[128:129]
	s_mov_b32 m0, s39
	s_nop 0
	global_load_lds_dwordx4 v[216:217], off
	s_mov_b32 m0, s40
	s_nop 0
	global_load_lds_dwordx4 v[218:219], off
	s_waitcnt vmcnt(8)
	s_waitcnt lgkmcnt(0)
	s_barrier
	s_setprio 1
	v_mfma_f32_16x16x32_bf16 v[60:63], v[140:143], v[180:183], v[60:63]
	v_mfma_f32_16x16x32_bf16 v[56:59], v[156:159], v[180:183], v[56:59]
	v_mfma_f32_16x16x32_bf16 v[44:47], v[140:143], v[188:191], v[44:47]
	v_mfma_f32_16x16x32_bf16 v[40:43], v[156:159], v[188:191], v[40:43]
	v_mfma_f32_16x16x32_bf16 v[28:31], v[140:143], v[196:199], v[28:31]
	v_mfma_f32_16x16x32_bf16 v[24:27], v[156:159], v[196:199], v[24:27]
	v_mfma_f32_16x16x32_bf16 v[12:15], v[140:143], v[204:207], v[12:15]
	v_mfma_f32_16x16x32_bf16 v[8:11], v[156:159], v[204:207], v[8:11]
	v_mfma_f32_16x16x32_bf16 v[60:63], v[152:155], v[184:187], v[60:63]
	v_mfma_f32_16x16x32_bf16 v[56:59], v[160:163], v[184:187], v[56:59]
	v_mfma_f32_16x16x32_bf16 v[44:47], v[152:155], v[192:195], v[44:47]
	v_mfma_f32_16x16x32_bf16 v[40:43], v[160:163], v[192:195], v[40:43]
	v_mfma_f32_16x16x32_bf16 v[28:31], v[152:155], v[200:203], v[28:31]
	v_mfma_f32_16x16x32_bf16 v[24:27], v[160:163], v[200:203], v[24:27]
	v_mfma_f32_16x16x32_bf16 v[12:15], v[152:155], v[208:211], v[12:15]
	v_mfma_f32_16x16x32_bf16 v[8:11], v[160:163], v[208:211], v[8:11]
	s_setprio 0
	s_setprio 1
	v_mfma_f32_16x16x32_bf16 v[52:55], v[164:167], v[180:183], v[52:55]
	v_mfma_f32_16x16x32_bf16 v[48:51], v[172:175], v[180:183], v[48:51]
	v_mfma_f32_16x16x32_bf16 v[36:39], v[164:167], v[188:191], v[36:39]
	v_mfma_f32_16x16x32_bf16 v[32:35], v[172:175], v[188:191], v[32:35]
	v_mfma_f32_16x16x32_bf16 v[20:23], v[164:167], v[196:199], v[20:23]
	v_mfma_f32_16x16x32_bf16 v[16:19], v[172:175], v[196:199], v[16:19]
	v_mfma_f32_16x16x32_bf16 v[4:7], v[164:167], v[204:207], v[4:7]
	v_mfma_f32_16x16x32_bf16 v[0:3], v[172:175], v[204:207], v[0:3]
	v_mfma_f32_16x16x32_bf16 v[52:55], v[168:171], v[184:187], v[52:55]
	v_mfma_f32_16x16x32_bf16 v[48:51], v[176:179], v[184:187], v[48:51]
	v_mfma_f32_16x16x32_bf16 v[36:39], v[168:171], v[192:195], v[36:39]
	v_mfma_f32_16x16x32_bf16 v[32:35], v[176:179], v[192:195], v[32:35]
	v_mfma_f32_16x16x32_bf16 v[20:23], v[168:171], v[200:203], v[20:23]
	v_mfma_f32_16x16x32_bf16 v[16:19], v[176:179], v[200:203], v[16:19]
	v_mfma_f32_16x16x32_bf16 v[4:7], v[168:171], v[208:211], v[4:7]
	v_mfma_f32_16x16x32_bf16 v[0:3], v[176:179], v[208:211], v[0:3]
	s_setprio 0
	s_barrier
	s_add_i32 s55, 0, 0x18000
	v_add_u32_e32 v151, s55, v145
	s_add_i32 s56, 0, 0x1c000
	ds_read_b128 v[140:143], v151
	ds_read_b128 v[152:155], v151 offset:1024
	ds_read_b128 v[156:159], v151 offset:2048
	ds_read_b128 v[160:163], v151 offset:3072
	v_add_u32_e32 v151, s56, v145
	ds_read_b128 v[164:167], v151
	ds_read_b128 v[168:171], v151 offset:1024
	ds_read_b128 v[172:175], v151 offset:2048
	ds_read_b128 v[176:179], v151 offset:3072
	s_add_u32 s30, s30, 0x40000
	s_addc_u32 s31, s31, 0
	s_mov_b32 m0, s41
	v_lshl_add_u64 v[220:221], s[30:31], 0, v[128:129]
	ds_read_b128 v[180:183], v149 offset:32768
	ds_read_b128 v[184:187], v149 offset:33792
	ds_read_b128 v[188:191], v149 offset:34816
	ds_read_b128 v[192:195], v149 offset:35840
	ds_read_b128 v[196:199], v149 offset:36864
	ds_read_b128 v[200:203], v149 offset:37888
	ds_read_b128 v[204:207], v149 offset:38912
	ds_read_b128 v[208:211], v149 offset:39936
	global_load_lds_dwordx4 v[220:221], off
	v_lshl_add_u64 v[220:221], s[30:31], 0, v[130:131]
	s_mov_b32 m0, s42
	s_nop 0
	global_load_lds_dwordx4 v[220:221], off
	s_waitcnt vmcnt(8)
	s_waitcnt lgkmcnt(0)
	s_barrier
	s_setprio 1
	v_mfma_f32_16x16x32_bf16 v[124:127], v[140:143], v[180:183], v[124:127]
	v_mfma_f32_16x16x32_bf16 v[120:123], v[156:159], v[180:183], v[120:123]
	v_mfma_f32_16x16x32_bf16 v[108:111], v[140:143], v[188:191], v[108:111]
	v_mfma_f32_16x16x32_bf16 v[104:107], v[156:159], v[188:191], v[104:107]
	v_mfma_f32_16x16x32_bf16 v[92:95], v[140:143], v[196:199], v[92:95]
	v_mfma_f32_16x16x32_bf16 v[88:91], v[156:159], v[196:199], v[88:91]
	v_mfma_f32_16x16x32_bf16 v[76:79], v[140:143], v[204:207], v[76:79]
	v_mfma_f32_16x16x32_bf16 v[72:75], v[156:159], v[204:207], v[72:75]
	v_mfma_f32_16x16x32_bf16 v[124:127], v[152:155], v[184:187], v[124:127]
	v_mfma_f32_16x16x32_bf16 v[120:123], v[160:163], v[184:187], v[120:123]
	v_mfma_f32_16x16x32_bf16 v[108:111], v[152:155], v[192:195], v[108:111]
	v_mfma_f32_16x16x32_bf16 v[104:107], v[160:163], v[192:195], v[104:107]
	v_mfma_f32_16x16x32_bf16 v[92:95], v[152:155], v[200:203], v[92:95]
	v_mfma_f32_16x16x32_bf16 v[88:91], v[160:163], v[200:203], v[88:91]
	v_mfma_f32_16x16x32_bf16 v[76:79], v[152:155], v[208:211], v[76:79]
	v_mfma_f32_16x16x32_bf16 v[72:75], v[160:163], v[208:211], v[72:75]
	s_setprio 0
	s_setprio 1
	v_mfma_f32_16x16x32_bf16 v[116:119], v[164:167], v[180:183], v[116:119]
	v_mfma_f32_16x16x32_bf16 v[112:115], v[172:175], v[180:183], v[112:115]
	v_mfma_f32_16x16x32_bf16 v[100:103], v[164:167], v[188:191], v[100:103]
	v_mfma_f32_16x16x32_bf16 v[96:99], v[172:175], v[188:191], v[96:99]
	v_mfma_f32_16x16x32_bf16 v[84:87], v[164:167], v[196:199], v[84:87]
	v_mfma_f32_16x16x32_bf16 v[80:83], v[172:175], v[196:199], v[80:83]
	v_mfma_f32_16x16x32_bf16 v[68:71], v[164:167], v[204:207], v[68:71]
	v_mfma_f32_16x16x32_bf16 v[64:67], v[172:175], v[204:207], v[64:67]
	v_mfma_f32_16x16x32_bf16 v[116:119], v[168:171], v[184:187], v[116:119]
	v_mfma_f32_16x16x32_bf16 v[112:115], v[176:179], v[184:187], v[112:115]
	v_mfma_f32_16x16x32_bf16 v[100:103], v[168:171], v[192:195], v[100:103]
	v_mfma_f32_16x16x32_bf16 v[96:99], v[176:179], v[192:195], v[96:99]
	v_mfma_f32_16x16x32_bf16 v[84:87], v[168:171], v[200:203], v[84:87]
	v_mfma_f32_16x16x32_bf16 v[80:83], v[176:179], v[200:203], v[80:83]
	v_mfma_f32_16x16x32_bf16 v[68:71], v[168:171], v[208:211], v[68:71]
	v_mfma_f32_16x16x32_bf16 v[64:67], v[176:179], v[208:211], v[64:67]
	s_setprio 0
	s_barrier
	s_add_i32 s30, s55, s38
	v_lshl_add_u64 v[212:213], v[212:213], 0, s[12:13]
	s_mov_b32 m0, s30
	ds_read_b128 v[180:183], v149 offset:49152
	ds_read_b128 v[184:187], v149 offset:50176
	ds_read_b128 v[188:191], v149 offset:51200
	ds_read_b128 v[192:195], v149 offset:52224
	ds_read_b128 v[196:199], v149 offset:53248
	ds_read_b128 v[200:203], v149 offset:54272
	ds_read_b128 v[204:207], v149 offset:55296
	ds_read_b128 v[208:211], v149 offset:56320
	global_load_lds_dwordx4 v[212:213], off
	s_add_i32 m0, s30, 0x2000
	s_add_u32 s28, s28, 0x40080
	v_lshl_add_u64 v[212:213], v[214:215], 0, s[12:13]
	s_addc_u32 s29, s29, 0
	s_add_i32 s30, s56, s38
	global_load_lds_dwordx4 v[212:213], off
	v_lshl_add_u64 v[212:213], s[28:29], 0, v[128:129]
	s_mov_b32 m0, s30
	s_nop 0
	global_load_lds_dwordx4 v[212:213], off
	v_lshl_add_u64 v[212:213], s[28:29], 0, v[130:131]
	s_add_i32 m0, s30, 0x2000
	s_nop 0
	global_load_lds_dwordx4 v[212:213], off
	v_lshl_add_u64 v[212:213], v[216:217], 0, s[12:13]
	s_mov_b32 m0, s44
	s_nop 0
	global_load_lds_dwordx4 v[212:213], off
	v_lshl_add_u64 v[212:213], v[218:219], 0, s[12:13]
	s_mov_b32 m0, s45
	s_nop 0
	global_load_lds_dwordx4 v[212:213], off
	s_waitcnt vmcnt(8)
	s_waitcnt lgkmcnt(0)
	s_barrier
	s_setprio 1
	v_mfma_f32_16x16x32_bf16 v[60:63], v[140:143], v[180:183], v[60:63]
	v_mfma_f32_16x16x32_bf16 v[56:59], v[156:159], v[180:183], v[56:59]
	v_mfma_f32_16x16x32_bf16 v[44:47], v[140:143], v[188:191], v[44:47]
	v_mfma_f32_16x16x32_bf16 v[40:43], v[156:159], v[188:191], v[40:43]
	v_mfma_f32_16x16x32_bf16 v[28:31], v[140:143], v[196:199], v[28:31]
	v_mfma_f32_16x16x32_bf16 v[24:27], v[156:159], v[196:199], v[24:27]
	v_mfma_f32_16x16x32_bf16 v[12:15], v[140:143], v[204:207], v[12:15]
	v_mfma_f32_16x16x32_bf16 v[8:11], v[156:159], v[204:207], v[8:11]
	v_mfma_f32_16x16x32_bf16 v[60:63], v[152:155], v[184:187], v[60:63]
	v_mfma_f32_16x16x32_bf16 v[56:59], v[160:163], v[184:187], v[56:59]
	v_mfma_f32_16x16x32_bf16 v[44:47], v[152:155], v[192:195], v[44:47]
	v_mfma_f32_16x16x32_bf16 v[40:43], v[160:163], v[192:195], v[40:43]
	v_mfma_f32_16x16x32_bf16 v[28:31], v[152:155], v[200:203], v[28:31]
	v_mfma_f32_16x16x32_bf16 v[24:27], v[160:163], v[200:203], v[24:27]
	v_mfma_f32_16x16x32_bf16 v[12:15], v[152:155], v[208:211], v[12:15]
	v_mfma_f32_16x16x32_bf16 v[8:11], v[160:163], v[208:211], v[8:11]
	s_setprio 0
	s_setprio 1
	v_mfma_f32_16x16x32_bf16 v[52:55], v[164:167], v[180:183], v[52:55]
	v_mfma_f32_16x16x32_bf16 v[48:51], v[172:175], v[180:183], v[48:51]
	v_mfma_f32_16x16x32_bf16 v[36:39], v[164:167], v[188:191], v[36:39]
	v_mfma_f32_16x16x32_bf16 v[32:35], v[172:175], v[188:191], v[32:35]
	v_mfma_f32_16x16x32_bf16 v[20:23], v[164:167], v[196:199], v[20:23]
	v_mfma_f32_16x16x32_bf16 v[16:19], v[172:175], v[196:199], v[16:19]
	v_mfma_f32_16x16x32_bf16 v[4:7], v[164:167], v[204:207], v[4:7]
	v_mfma_f32_16x16x32_bf16 v[0:3], v[172:175], v[204:207], v[0:3]
	v_mfma_f32_16x16x32_bf16 v[52:55], v[168:171], v[184:187], v[52:55]
	v_mfma_f32_16x16x32_bf16 v[48:51], v[176:179], v[184:187], v[48:51]
	v_mfma_f32_16x16x32_bf16 v[36:39], v[168:171], v[192:195], v[36:39]
	v_mfma_f32_16x16x32_bf16 v[32:35], v[176:179], v[192:195], v[32:35]
	v_mfma_f32_16x16x32_bf16 v[20:23], v[168:171], v[200:203], v[20:23]
	v_mfma_f32_16x16x32_bf16 v[16:19], v[176:179], v[200:203], v[16:19]
	v_mfma_f32_16x16x32_bf16 v[4:7], v[168:171], v[208:211], v[4:7]
	v_mfma_f32_16x16x32_bf16 v[0:3], v[176:179], v[208:211], v[0:3]
	s_setprio 0
	s_barrier
	s_add_i32 s54, s54, 2
	s_add_u32 s26, s26, 0x100
	s_addc_u32 s27, s27, 0
	s_add_u32 s52, s52, 0x100
	s_addc_u32 s53, s53, 0
	s_cmp_gt_u32 s54, 13
	s_cbranch_scc0 .LBB0_1553
	s_and_b64 vcc, exec, s[14:15]
	s_cbranch_vccz .LBB0_1556
	s_barrier

.LBB0_1619:
	ds_read_b128 v[152:155], v143
	ds_read_b128 v[162:165], v143 offset:1024
	ds_read_b128 v[166:169], v143 offset:2048
	ds_read_b128 v[170:173], v143 offset:3072
	ds_read_b128 v[174:177], v158
	ds_read_b128 v[178:181], v158 offset:1024
	ds_read_b128 v[182:185], v158 offset:2048
	ds_read_b128 v[186:189], v158 offset:3072
	s_add_u32 s30, s28, 0xfffc0080
	s_addc_u32 s31, s29, -1
	s_cmp_eq_u32 s55, 12
	s_cselect_b32 s35, s19, s31
	s_cselect_b32 s34, s25, s30
	s_cselect_b32 s31, s17, s54
	s_cselect_b32 s30, s27, s53
	s_waitcnt lgkmcnt(0)
	v_lshl_add_u64 v[156:157], s[28:29], 0, v[144:145]
	s_add_i32 m0, s39, 0xc000
	ds_read_b128 v[190:193], v159
	ds_read_b128 v[194:197], v159 offset:1024
	ds_read_b128 v[198:201], v159 offset:2048
	ds_read_b128 v[202:205], v159 offset:3072
	ds_read_b128 v[206:209], v159 offset:4096
	ds_read_b128 v[210:213], v159 offset:5120
	ds_read_b128 v[214:217], v159 offset:6144
	ds_read_b128 v[218:221], v159 offset:7168
	global_load_lds_dwordx4 v[156:157], off
	v_lshl_add_u64 v[156:157], s[28:29], 0, v[146:147]
	s_add_i32 m0, s39, 0xe000
	s_nop 0
	global_load_lds_dwordx4 v[156:157], off
	s_waitcnt vmcnt(8)
	s_waitcnt lgkmcnt(0)
	s_barrier
	s_setprio 1
	v_mfma_f32_16x16x32_bf16 v[116:119], v[152:155], v[190:193], v[116:119]
	v_mfma_f32_16x16x32_bf16 v[112:115], v[166:169], v[190:193], v[112:115]
	v_mfma_f32_16x16x32_bf16 v[100:103], v[152:155], v[198:201], v[100:103]
	v_mfma_f32_16x16x32_bf16 v[96:99], v[166:169], v[198:201], v[96:99]
	v_mfma_f32_16x16x32_bf16 v[88:91], v[152:155], v[206:209], v[88:91]
	v_mfma_f32_16x16x32_bf16 v[84:87], v[166:169], v[206:209], v[84:87]
	v_mfma_f32_16x16x32_bf16 v[72:75], v[152:155], v[214:217], v[72:75]
	v_mfma_f32_16x16x32_bf16 v[68:71], v[166:169], v[214:217], v[68:71]
	v_mfma_f32_16x16x32_bf16 v[116:119], v[162:165], v[194:197], v[116:119]
	v_mfma_f32_16x16x32_bf16 v[112:115], v[170:173], v[194:197], v[112:115]
	v_mfma_f32_16x16x32_bf16 v[100:103], v[162:165], v[202:205], v[100:103]
	v_mfma_f32_16x16x32_bf16 v[96:99], v[170:173], v[202:205], v[96:99]
	v_mfma_f32_16x16x32_bf16 v[88:91], v[162:165], v[210:213], v[88:91]
	v_mfma_f32_16x16x32_bf16 v[84:87], v[170:173], v[210:213], v[84:87]
	v_mfma_f32_16x16x32_bf16 v[72:75], v[162:165], v[218:221], v[72:75]
	v_mfma_f32_16x16x32_bf16 v[68:71], v[170:173], v[218:221], v[68:71]
	s_setprio 0
	s_setprio 1
	v_mfma_f32_16x16x32_bf16 v[124:127], v[174:177], v[190:193], v[124:127]
	v_mfma_f32_16x16x32_bf16 v[120:123], v[182:185], v[190:193], v[120:123]
	v_mfma_f32_16x16x32_bf16 v[108:111], v[174:177], v[198:201], v[108:111]
	v_mfma_f32_16x16x32_bf16 v[104:107], v[182:185], v[198:201], v[104:107]
	v_mfma_f32_16x16x32_bf16 v[92:95], v[174:177], v[206:209], v[92:95]
	v_mfma_f32_16x16x32_bf16 v[80:83], v[182:185], v[206:209], v[80:83]
	v_mfma_f32_16x16x32_bf16 v[76:79], v[174:177], v[214:217], v[76:79]
	v_mfma_f32_16x16x32_bf16 v[64:67], v[182:185], v[214:217], v[64:67]
	v_mfma_f32_16x16x32_bf16 v[124:127], v[178:181], v[194:197], v[124:127]
	v_mfma_f32_16x16x32_bf16 v[120:123], v[186:189], v[194:197], v[120:123]
	v_mfma_f32_16x16x32_bf16 v[108:111], v[178:181], v[202:205], v[108:111]
	v_mfma_f32_16x16x32_bf16 v[104:107], v[186:189], v[202:205], v[104:107]
	v_mfma_f32_16x16x32_bf16 v[92:95], v[178:181], v[210:213], v[92:95]
	v_mfma_f32_16x16x32_bf16 v[80:83], v[186:189], v[210:213], v[80:83]
	v_mfma_f32_16x16x32_bf16 v[76:79], v[178:181], v[218:221], v[76:79]
	v_mfma_f32_16x16x32_bf16 v[64:67], v[186:189], v[218:221], v[64:67]
	s_setprio 0
	s_barrier
	s_add_i32 s56, s49, s38
	v_lshl_add_u64 v[156:157], s[30:31], 0, v[130:131]
	s_mov_b32 m0, s56
	ds_read_b128 v[190:193], v159 offset:16384
	ds_read_b128 v[194:197], v159 offset:17408
	ds_read_b128 v[198:201], v159 offset:18432
	ds_read_b128 v[202:205], v159 offset:19456
	ds_read_b128 v[206:209], v159 offset:20480
	ds_read_b128 v[210:213], v159 offset:21504
	ds_read_b128 v[214:217], v159 offset:22528
	ds_read_b128 v[218:221], v159 offset:23552
	global_load_lds_dwordx4 v[156:157], off
	s_add_i32 m0, s56, 0x2000
	s_add_u32 s56, s30, 0x40000
	v_lshl_add_u64 v[222:223], s[30:31], 0, v[134:135]
	s_addc_u32 s57, s31, 0
	s_add_i32 s58, s50, s38
	global_load_lds_dwordx4 v[222:223], off
	v_lshl_add_u64 v[224:225], s[56:57], 0, v[130:131]
	s_mov_b32 m0, s58
	v_lshl_add_u64 v[226:227], s[34:35], 0, v[132:133]
	global_load_lds_dwordx4 v[224:225], off
	v_lshl_add_u64 v[224:225], s[56:57], 0, v[134:135]
	s_add_i32 m0, s58, 0x2000
	s_nop 0
	global_load_lds_dwordx4 v[224:225], off
	v_lshl_add_u64 v[224:225], s[34:35], 0, v[128:129]
	s_mov_b32 m0, s39
	s_nop 0
	global_load_lds_dwordx4 v[224:225], off
	s_mov_b32 m0, s40
	s_nop 0
	global_load_lds_dwordx4 v[226:227], off
	s_waitcnt vmcnt(8)
	s_waitcnt lgkmcnt(0)
	s_barrier
	s_setprio 1
	v_mfma_f32_16x16x32_bf16 v[56:59], v[152:155], v[190:193], v[56:59]
	v_mfma_f32_16x16x32_bf16 v[52:55], v[166:169], v[190:193], v[52:55]
	v_mfma_f32_16x16x32_bf16 v[40:43], v[152:155], v[198:201], v[40:43]
	v_mfma_f32_16x16x32_bf16 v[36:39], v[166:169], v[198:201], v[36:39]
	v_mfma_f32_16x16x32_bf16 v[24:27], v[152:155], v[206:209], v[24:27]
	v_mfma_f32_16x16x32_bf16 v[20:23], v[166:169], v[206:209], v[20:23]
	v_mfma_f32_16x16x32_bf16 v[8:11], v[152:155], v[214:217], v[8:11]
	v_mfma_f32_16x16x32_bf16 v[4:7], v[166:169], v[214:217], v[4:7]
	v_mfma_f32_16x16x32_bf16 v[56:59], v[162:165], v[194:197], v[56:59]
	v_mfma_f32_16x16x32_bf16 v[52:55], v[170:173], v[194:197], v[52:55]
	v_mfma_f32_16x16x32_bf16 v[40:43], v[162:165], v[202:205], v[40:43]
	v_mfma_f32_16x16x32_bf16 v[36:39], v[170:173], v[202:205], v[36:39]
	v_mfma_f32_16x16x32_bf16 v[24:27], v[162:165], v[210:213], v[24:27]
	v_mfma_f32_16x16x32_bf16 v[20:23], v[170:173], v[210:213], v[20:23]
	v_mfma_f32_16x16x32_bf16 v[8:11], v[162:165], v[218:221], v[8:11]
	v_mfma_f32_16x16x32_bf16 v[4:7], v[170:173], v[218:221], v[4:7]
	s_setprio 0
	s_setprio 1
	v_mfma_f32_16x16x32_bf16 v[60:63], v[174:177], v[190:193], v[60:63]
	v_mfma_f32_16x16x32_bf16 v[48:51], v[182:185], v[190:193], v[48:51]
	v_mfma_f32_16x16x32_bf16 v[44:47], v[174:177], v[198:201], v[44:47]
	v_mfma_f32_16x16x32_bf16 v[32:35], v[182:185], v[198:201], v[32:35]
	v_mfma_f32_16x16x32_bf16 v[28:31], v[174:177], v[206:209], v[28:31]
	v_mfma_f32_16x16x32_bf16 v[16:19], v[182:185], v[206:209], v[16:19]
	v_mfma_f32_16x16x32_bf16 v[12:15], v[174:177], v[214:217], v[12:15]
	v_mfma_f32_16x16x32_bf16 v[0:3], v[182:185], v[214:217], v[0:3]
	v_mfma_f32_16x16x32_bf16 v[60:63], v[178:181], v[194:197], v[60:63]
	v_mfma_f32_16x16x32_bf16 v[48:51], v[186:189], v[194:197], v[48:51]
	v_mfma_f32_16x16x32_bf16 v[44:47], v[178:181], v[202:205], v[44:47]
	v_mfma_f32_16x16x32_bf16 v[32:35], v[186:189], v[202:205], v[32:35]
	v_mfma_f32_16x16x32_bf16 v[28:31], v[178:181], v[210:213], v[28:31]
	v_mfma_f32_16x16x32_bf16 v[16:19], v[186:189], v[210:213], v[16:19]
	v_mfma_f32_16x16x32_bf16 v[12:15], v[178:181], v[218:221], v[12:15]
	v_mfma_f32_16x16x32_bf16 v[0:3], v[186:189], v[218:221], v[0:3]
	s_setprio 0
	s_barrier
	s_add_i32 s56, 0, 0x18000
	s_add_i32 s57, 0, 0x1c000
	v_add_u32_e32 v170, s56, v141
	v_add_u32_e32 v186, s57, v141
	ds_read_b128 v[152:155], v170
	ds_read_b128 v[162:165], v170 offset:1024
	ds_read_b128 v[166:169], v170 offset:2048
	ds_read_b128 v[170:173], v170 offset:3072
	ds_read_b128 v[174:177], v186
	ds_read_b128 v[178:181], v186 offset:1024
	ds_read_b128 v[182:185], v186 offset:2048
	ds_read_b128 v[186:189], v186 offset:3072
	s_add_u32 s34, s34, 0x40000
	s_addc_u32 s35, s35, 0
	s_mov_b32 m0, s41
	v_lshl_add_u64 v[228:229], s[34:35], 0, v[128:129]
	ds_read_b128 v[190:193], v159 offset:32768
	ds_read_b128 v[194:197], v159 offset:33792
	ds_read_b128 v[198:201], v159 offset:34816
	ds_read_b128 v[202:205], v159 offset:35840
	ds_read_b128 v[206:209], v159 offset:36864
	ds_read_b128 v[210:213], v159 offset:37888
	ds_read_b128 v[214:217], v159 offset:38912
	ds_read_b128 v[218:221], v159 offset:39936
	global_load_lds_dwordx4 v[228:229], off
	v_lshl_add_u64 v[228:229], s[34:35], 0, v[132:133]
	s_mov_b32 m0, s42
	s_nop 0
	global_load_lds_dwordx4 v[228:229], off
	s_waitcnt vmcnt(8)
	s_waitcnt lgkmcnt(0)
	s_barrier
	s_setprio 1
	v_mfma_f32_16x16x32_bf16 v[116:119], v[152:155], v[190:193], v[116:119]
	v_mfma_f32_16x16x32_bf16 v[112:115], v[166:169], v[190:193], v[112:115]
	v_mfma_f32_16x16x32_bf16 v[100:103], v[152:155], v[198:201], v[100:103]
	v_mfma_f32_16x16x32_bf16 v[96:99], v[166:169], v[198:201], v[96:99]
	v_mfma_f32_16x16x32_bf16 v[88:91], v[152:155], v[206:209], v[88:91]
	v_mfma_f32_16x16x32_bf16 v[84:87], v[166:169], v[206:209], v[84:87]
	v_mfma_f32_16x16x32_bf16 v[72:75], v[152:155], v[214:217], v[72:75]
	v_mfma_f32_16x16x32_bf16 v[68:71], v[166:169], v[214:217], v[68:71]
	v_mfma_f32_16x16x32_bf16 v[116:119], v[162:165], v[194:197], v[116:119]
	v_mfma_f32_16x16x32_bf16 v[112:115], v[170:173], v[194:197], v[112:115]
	v_mfma_f32_16x16x32_bf16 v[100:103], v[162:165], v[202:205], v[100:103]
	v_mfma_f32_16x16x32_bf16 v[96:99], v[170:173], v[202:205], v[96:99]
	v_mfma_f32_16x16x32_bf16 v[88:91], v[162:165], v[210:213], v[88:91]
	v_mfma_f32_16x16x32_bf16 v[84:87], v[170:173], v[210:213], v[84:87]
	v_mfma_f32_16x16x32_bf16 v[72:75], v[162:165], v[218:221], v[72:75]
	v_mfma_f32_16x16x32_bf16 v[68:71], v[170:173], v[218:221], v[68:71]
	s_setprio 0
	s_setprio 1
	v_mfma_f32_16x16x32_bf16 v[124:127], v[174:177], v[190:193], v[124:127]
	v_mfma_f32_16x16x32_bf16 v[120:123], v[182:185], v[190:193], v[120:123]
	v_mfma_f32_16x16x32_bf16 v[108:111], v[174:177], v[198:201], v[108:111]
	v_mfma_f32_16x16x32_bf16 v[104:107], v[182:185], v[198:201], v[104:107]
	v_mfma_f32_16x16x32_bf16 v[92:95], v[174:177], v[206:209], v[92:95]
	v_mfma_f32_16x16x32_bf16 v[80:83], v[182:185], v[206:209], v[80:83]
	v_mfma_f32_16x16x32_bf16 v[76:79], v[174:177], v[214:217], v[76:79]
	v_mfma_f32_16x16x32_bf16 v[64:67], v[182:185], v[214:217], v[64:67]
	v_mfma_f32_16x16x32_bf16 v[124:127], v[178:181], v[194:197], v[124:127]
	v_mfma_f32_16x16x32_bf16 v[120:123], v[186:189], v[194:197], v[120:123]
	v_mfma_f32_16x16x32_bf16 v[108:111], v[178:181], v[202:205], v[108:111]
	v_mfma_f32_16x16x32_bf16 v[104:107], v[186:189], v[202:205], v[104:107]
	v_mfma_f32_16x16x32_bf16 v[92:95], v[178:181], v[210:213], v[92:95]
	v_mfma_f32_16x16x32_bf16 v[80:83], v[186:189], v[210:213], v[80:83]
	v_mfma_f32_16x16x32_bf16 v[76:79], v[178:181], v[218:221], v[76:79]
	v_mfma_f32_16x16x32_bf16 v[64:67], v[186:189], v[218:221], v[64:67]
	s_setprio 0
	s_barrier
	s_add_i32 s34, s56, s38
	v_lshl_add_u64 v[156:157], v[156:157], 0, s[10:11]
	s_mov_b32 m0, s34
	ds_read_b128 v[190:193], v159 offset:49152
	ds_read_b128 v[194:197], v159 offset:50176
	ds_read_b128 v[198:201], v159 offset:51200
	ds_read_b128 v[202:205], v159 offset:52224
	ds_read_b128 v[206:209], v159 offset:53248
	ds_read_b128 v[210:213], v159 offset:54272
	ds_read_b128 v[214:217], v159 offset:55296
	ds_read_b128 v[218:221], v159 offset:56320
	global_load_lds_dwordx4 v[156:157], off
	s_add_i32 m0, s34, 0x2000
	s_add_u32 s30, s30, 0x40080
	v_lshl_add_u64 v[156:157], v[222:223], 0, s[10:11]
	s_addc_u32 s31, s31, 0
	s_add_i32 s34, s57, s38
	global_load_lds_dwordx4 v[156:157], off
	v_lshl_add_u64 v[156:157], s[30:31], 0, v[130:131]
	s_mov_b32 m0, s34
	s_nop 0
	global_load_lds_dwordx4 v[156:157], off
	v_lshl_add_u64 v[156:157], s[30:31], 0, v[134:135]
	s_add_i32 m0, s34, 0x2000
	s_nop 0
	global_load_lds_dwordx4 v[156:157], off
	v_lshl_add_u64 v[156:157], v[224:225], 0, s[10:11]
	s_mov_b32 m0, s43
	s_nop 0
	global_load_lds_dwordx4 v[156:157], off
	v_lshl_add_u64 v[156:157], v[226:227], 0, s[10:11]
	s_mov_b32 m0, s44
	s_nop 0
	global_load_lds_dwordx4 v[156:157], off
	s_waitcnt vmcnt(8)
	s_waitcnt lgkmcnt(0)
	s_barrier
	s_setprio 1
	v_mfma_f32_16x16x32_bf16 v[56:59], v[152:155], v[190:193], v[56:59]
	v_mfma_f32_16x16x32_bf16 v[52:55], v[166:169], v[190:193], v[52:55]
	v_mfma_f32_16x16x32_bf16 v[40:43], v[152:155], v[198:201], v[40:43]
	v_mfma_f32_16x16x32_bf16 v[36:39], v[166:169], v[198:201], v[36:39]
	v_mfma_f32_16x16x32_bf16 v[24:27], v[152:155], v[206:209], v[24:27]
	v_mfma_f32_16x16x32_bf16 v[20:23], v[166:169], v[206:209], v[20:23]
	v_mfma_f32_16x16x32_bf16 v[8:11], v[152:155], v[214:217], v[8:11]
	v_mfma_f32_16x16x32_bf16 v[4:7], v[166:169], v[214:217], v[4:7]
	v_mfma_f32_16x16x32_bf16 v[56:59], v[162:165], v[194:197], v[56:59]
	v_mfma_f32_16x16x32_bf16 v[52:55], v[170:173], v[194:197], v[52:55]
	v_mfma_f32_16x16x32_bf16 v[40:43], v[162:165], v[202:205], v[40:43]
	v_mfma_f32_16x16x32_bf16 v[36:39], v[170:173], v[202:205], v[36:39]
	v_mfma_f32_16x16x32_bf16 v[24:27], v[162:165], v[210:213], v[24:27]
	v_mfma_f32_16x16x32_bf16 v[20:23], v[170:173], v[210:213], v[20:23]
	v_mfma_f32_16x16x32_bf16 v[8:11], v[162:165], v[218:221], v[8:11]
	v_mfma_f32_16x16x32_bf16 v[4:7], v[170:173], v[218:221], v[4:7]
	s_setprio 0
	s_setprio 1
	v_mfma_f32_16x16x32_bf16 v[60:63], v[174:177], v[190:193], v[60:63]
	v_mfma_f32_16x16x32_bf16 v[48:51], v[182:185], v[190:193], v[48:51]
	v_mfma_f32_16x16x32_bf16 v[44:47], v[174:177], v[198:201], v[44:47]
	v_mfma_f32_16x16x32_bf16 v[32:35], v[182:185], v[198:201], v[32:35]
	v_mfma_f32_16x16x32_bf16 v[28:31], v[174:177], v[206:209], v[28:31]
	v_mfma_f32_16x16x32_bf16 v[16:19], v[182:185], v[206:209], v[16:19]
	v_mfma_f32_16x16x32_bf16 v[12:15], v[174:177], v[214:217], v[12:15]
	v_mfma_f32_16x16x32_bf16 v[0:3], v[182:185], v[214:217], v[0:3]
	v_mfma_f32_16x16x32_bf16 v[60:63], v[178:181], v[194:197], v[60:63]
	v_mfma_f32_16x16x32_bf16 v[48:51], v[186:189], v[194:197], v[48:51]
	v_mfma_f32_16x16x32_bf16 v[44:47], v[178:181], v[202:205], v[44:47]
	v_mfma_f32_16x16x32_bf16 v[32:35], v[186:189], v[202:205], v[32:35]
	v_mfma_f32_16x16x32_bf16 v[28:31], v[178:181], v[210:213], v[28:31]
	v_mfma_f32_16x16x32_bf16 v[16:19], v[186:189], v[210:213], v[16:19]
	v_mfma_f32_16x16x32_bf16 v[12:15], v[178:181], v[218:221], v[12:15]
	v_mfma_f32_16x16x32_bf16 v[0:3], v[186:189], v[218:221], v[0:3]
	s_setprio 0
	s_barrier
	s_add_i32 s55, s55, 2
	s_add_u32 s28, s28, 0x100
	s_addc_u32 s29, s29, 0
	s_add_u32 s53, s53, 0x100
	s_addc_u32 s54, s54, 0
	s_cmp_gt_u32 s55, 13
	s_cbranch_scc0 .LBB0_1619
	s_and_b64 vcc, exec, s[12:13]
	s_cbranch_vccz .LBB0_1624
	s_barrier
	v_lshl_add_u32 v152, s26, 8, v139
	s_cmp_gt_i32 s24, 21
	s_mov_b64 s[26:27], -1
	s_cbranch_scc1 .LBB0_1625

.LBB0_1705:
	ds_read_b128 v[148:151], v145
	ds_read_b128 v[152:155], v145 offset:1024
	ds_read_b128 v[156:159], v145 offset:2048
	ds_read_b128 v[160:163], v145 offset:3072
	ds_read_b128 v[164:167], v146
	ds_read_b128 v[168:171], v146 offset:1024
	ds_read_b128 v[172:175], v146 offset:2048
	ds_read_b128 v[176:179], v146 offset:3072
	s_add_u32 s26, s24, 0x100
	s_addc_u32 s27, s25, 0
	s_cmp_eq_u32 s58, 40
	s_cselect_b32 s31, s5, s27
	s_cselect_b32 s30, s4, s26
	s_cselect_b32 s29, s23, s57
	s_cselect_b32 s28, s22, s56
	v_lshl_add_u64 v[140:141], s[24:25], 0, v[132:133]
	s_add_i32 m0, s38, 0xc000
	ds_read_b128 v[180:183], v147
	ds_read_b128 v[184:187], v147 offset:1024
	ds_read_b128 v[188:191], v147 offset:2048
	ds_read_b128 v[192:195], v147 offset:3072
	ds_read_b128 v[196:199], v147 offset:4096
	ds_read_b128 v[200:203], v147 offset:5120
	ds_read_b128 v[204:207], v147 offset:6144
	ds_read_b128 v[208:211], v147 offset:7168
	global_load_lds_dwordx4 v[140:141], off
	v_lshl_add_u64 v[140:141], s[24:25], 0, v[134:135]
	s_add_i32 m0, s38, 0xe000
	s_nop 0
	global_load_lds_dwordx4 v[140:141], off
	s_waitcnt vmcnt(8)
	s_waitcnt lgkmcnt(0)
	s_barrier
	s_setprio 1
	v_mfma_f32_16x16x32_bf16 v[124:127], v[148:151], v[180:183], v[124:127]
	v_mfma_f32_16x16x32_bf16 v[120:123], v[156:159], v[180:183], v[120:123]
	v_mfma_f32_16x16x32_bf16 v[116:119], v[148:151], v[188:191], v[116:119]
	v_mfma_f32_16x16x32_bf16 v[112:115], v[156:159], v[188:191], v[112:115]
	v_mfma_f32_16x16x32_bf16 v[92:95], v[148:151], v[196:199], v[92:95]
	v_mfma_f32_16x16x32_bf16 v[88:91], v[156:159], v[196:199], v[88:91]
	v_mfma_f32_16x16x32_bf16 v[84:87], v[148:151], v[204:207], v[84:87]
	v_mfma_f32_16x16x32_bf16 v[80:83], v[156:159], v[204:207], v[80:83]
	v_mfma_f32_16x16x32_bf16 v[124:127], v[152:155], v[184:187], v[124:127]
	v_mfma_f32_16x16x32_bf16 v[120:123], v[160:163], v[184:187], v[120:123]
	v_mfma_f32_16x16x32_bf16 v[116:119], v[152:155], v[192:195], v[116:119]
	v_mfma_f32_16x16x32_bf16 v[112:115], v[160:163], v[192:195], v[112:115]
	v_mfma_f32_16x16x32_bf16 v[92:95], v[152:155], v[200:203], v[92:95]
	v_mfma_f32_16x16x32_bf16 v[88:91], v[160:163], v[200:203], v[88:91]
	v_mfma_f32_16x16x32_bf16 v[84:87], v[152:155], v[208:211], v[84:87]
	v_mfma_f32_16x16x32_bf16 v[80:83], v[160:163], v[208:211], v[80:83]
	s_setprio 0
	s_setprio 1
	v_mfma_f32_16x16x32_bf16 v[108:111], v[164:167], v[180:183], v[108:111]
	v_mfma_f32_16x16x32_bf16 v[104:107], v[172:175], v[180:183], v[104:107]
	v_mfma_f32_16x16x32_bf16 v[100:103], v[164:167], v[188:191], v[100:103]
	v_mfma_f32_16x16x32_bf16 v[96:99], v[172:175], v[188:191], v[96:99]
	v_mfma_f32_16x16x32_bf16 v[76:79], v[164:167], v[196:199], v[76:79]
	v_mfma_f32_16x16x32_bf16 v[72:75], v[172:175], v[196:199], v[72:75]
	v_mfma_f32_16x16x32_bf16 v[68:71], v[164:167], v[204:207], v[68:71]
	v_mfma_f32_16x16x32_bf16 v[64:67], v[172:175], v[204:207], v[64:67]
	v_mfma_f32_16x16x32_bf16 v[108:111], v[168:171], v[184:187], v[108:111]
	v_mfma_f32_16x16x32_bf16 v[104:107], v[176:179], v[184:187], v[104:107]
	v_mfma_f32_16x16x32_bf16 v[100:103], v[168:171], v[192:195], v[100:103]
	v_mfma_f32_16x16x32_bf16 v[96:99], v[176:179], v[192:195], v[96:99]
	v_mfma_f32_16x16x32_bf16 v[76:79], v[168:171], v[200:203], v[76:79]
	v_mfma_f32_16x16x32_bf16 v[72:75], v[176:179], v[200:203], v[72:75]
	v_mfma_f32_16x16x32_bf16 v[68:71], v[168:171], v[208:211], v[68:71]
	v_mfma_f32_16x16x32_bf16 v[64:67], v[176:179], v[208:211], v[64:67]
	s_setprio 0
	s_barrier
	s_add_i32 s24, s46, s37
	v_lshl_add_u64 v[140:141], s[28:29], 0, v[128:129]
	s_mov_b32 m0, s24
	ds_read_b128 v[180:183], v147 offset:16384
	ds_read_b128 v[184:187], v147 offset:17408
	ds_read_b128 v[188:191], v147 offset:18432
	ds_read_b128 v[192:195], v147 offset:19456
	ds_read_b128 v[196:199], v147 offset:20480
	ds_read_b128 v[200:203], v147 offset:21504
	ds_read_b128 v[204:207], v147 offset:22528
	ds_read_b128 v[208:211], v147 offset:23552
	global_load_lds_dwordx4 v[140:141], off
	s_add_i32 m0, s24, 0x2000
	s_add_u32 s24, s28, 0xb0000
	v_lshl_add_u64 v[212:213], s[28:29], 0, v[130:131]
	s_addc_u32 s25, s29, 0
	s_add_i32 s59, s47, s37
	global_load_lds_dwordx4 v[212:213], off
	v_lshl_add_u64 v[214:215], s[24:25], 0, v[128:129]
	s_mov_b32 m0, s59
	v_lshl_add_u64 v[216:217], s[30:31], 0, v[130:131]
	global_load_lds_dwordx4 v[214:215], off
	v_lshl_add_u64 v[214:215], s[24:25], 0, v[130:131]
	s_add_i32 m0, s59, 0x2000
	s_nop 0
	global_load_lds_dwordx4 v[214:215], off
	v_lshl_add_u64 v[214:215], s[30:31], 0, v[128:129]
	s_mov_b32 m0, s38
	s_nop 0
	global_load_lds_dwordx4 v[214:215], off
	s_mov_b32 m0, s39
	s_nop 0
	global_load_lds_dwordx4 v[216:217], off
	s_waitcnt vmcnt(8)
	s_waitcnt lgkmcnt(0)
	s_barrier
	s_setprio 1
	v_mfma_f32_16x16x32_bf16 v[60:63], v[148:151], v[180:183], v[60:63]
	v_mfma_f32_16x16x32_bf16 v[56:59], v[156:159], v[180:183], v[56:59]
	v_mfma_f32_16x16x32_bf16 v[52:55], v[148:151], v[188:191], v[52:55]
	v_mfma_f32_16x16x32_bf16 v[48:51], v[156:159], v[188:191], v[48:51]
	v_mfma_f32_16x16x32_bf16 v[28:31], v[148:151], v[196:199], v[28:31]
	v_mfma_f32_16x16x32_bf16 v[24:27], v[156:159], v[196:199], v[24:27]
	v_mfma_f32_16x16x32_bf16 v[20:23], v[148:151], v[204:207], v[20:23]
	v_mfma_f32_16x16x32_bf16 v[16:19], v[156:159], v[204:207], v[16:19]
	v_mfma_f32_16x16x32_bf16 v[60:63], v[152:155], v[184:187], v[60:63]
	v_mfma_f32_16x16x32_bf16 v[56:59], v[160:163], v[184:187], v[56:59]
	v_mfma_f32_16x16x32_bf16 v[52:55], v[152:155], v[192:195], v[52:55]
	v_mfma_f32_16x16x32_bf16 v[48:51], v[160:163], v[192:195], v[48:51]
	v_mfma_f32_16x16x32_bf16 v[28:31], v[152:155], v[200:203], v[28:31]
	v_mfma_f32_16x16x32_bf16 v[24:27], v[160:163], v[200:203], v[24:27]
	v_mfma_f32_16x16x32_bf16 v[20:23], v[152:155], v[208:211], v[20:23]
	v_mfma_f32_16x16x32_bf16 v[16:19], v[160:163], v[208:211], v[16:19]
	s_setprio 0
	s_setprio 1
	v_mfma_f32_16x16x32_bf16 v[44:47], v[164:167], v[180:183], v[44:47]
	v_mfma_f32_16x16x32_bf16 v[40:43], v[172:175], v[180:183], v[40:43]
	v_mfma_f32_16x16x32_bf16 v[36:39], v[164:167], v[188:191], v[36:39]
	v_mfma_f32_16x16x32_bf16 v[32:35], v[172:175], v[188:191], v[32:35]
	v_mfma_f32_16x16x32_bf16 v[12:15], v[164:167], v[196:199], v[12:15]
	v_mfma_f32_16x16x32_bf16 v[8:11], v[172:175], v[196:199], v[8:11]
	v_mfma_f32_16x16x32_bf16 v[4:7], v[164:167], v[204:207], v[4:7]
	v_mfma_f32_16x16x32_bf16 v[0:3], v[172:175], v[204:207], v[0:3]
	v_mfma_f32_16x16x32_bf16 v[44:47], v[168:171], v[184:187], v[44:47]
	v_mfma_f32_16x16x32_bf16 v[40:43], v[176:179], v[184:187], v[40:43]
	v_mfma_f32_16x16x32_bf16 v[36:39], v[168:171], v[192:195], v[36:39]
	v_mfma_f32_16x16x32_bf16 v[32:35], v[176:179], v[192:195], v[32:35]
	v_mfma_f32_16x16x32_bf16 v[12:15], v[168:171], v[200:203], v[12:15]
	v_mfma_f32_16x16x32_bf16 v[8:11], v[176:179], v[200:203], v[8:11]
	v_mfma_f32_16x16x32_bf16 v[4:7], v[168:171], v[208:211], v[4:7]
	v_mfma_f32_16x16x32_bf16 v[0:3], v[176:179], v[208:211], v[0:3]
	s_setprio 0
	s_barrier
	s_add_i32 s59, 0, 0x18000
	s_add_i32 s60, 0, 0x1c000
	v_add_u32_e32 v160, s59, v143
	v_add_u32_e32 v176, s60, v143
	ds_read_b128 v[148:151], v160
	ds_read_b128 v[152:155], v160 offset:1024
	ds_read_b128 v[156:159], v160 offset:2048
	ds_read_b128 v[160:163], v160 offset:3072
	ds_read_b128 v[164:167], v176
	ds_read_b128 v[168:171], v176 offset:1024
	ds_read_b128 v[172:175], v176 offset:2048
	ds_read_b128 v[176:179], v176 offset:3072
	s_add_u32 s24, s30, 0xb0000
	s_addc_u32 s25, s31, 0
	s_mov_b32 m0, s40
	v_lshl_add_u64 v[218:219], s[24:25], 0, v[128:129]
	ds_read_b128 v[180:183], v147 offset:32768
	ds_read_b128 v[184:187], v147 offset:33792
	ds_read_b128 v[188:191], v147 offset:34816
	ds_read_b128 v[192:195], v147 offset:35840
	ds_read_b128 v[196:199], v147 offset:36864
	ds_read_b128 v[200:203], v147 offset:37888
	ds_read_b128 v[204:207], v147 offset:38912
	ds_read_b128 v[208:211], v147 offset:39936
	global_load_lds_dwordx4 v[218:219], off
	v_lshl_add_u64 v[218:219], s[24:25], 0, v[130:131]
	s_mov_b32 m0, s41
	s_nop 0
	global_load_lds_dwordx4 v[218:219], off
	s_waitcnt vmcnt(8)
	s_waitcnt lgkmcnt(0)
	s_barrier
	s_setprio 1
	v_mfma_f32_16x16x32_bf16 v[124:127], v[148:151], v[180:183], v[124:127]
	v_mfma_f32_16x16x32_bf16 v[120:123], v[156:159], v[180:183], v[120:123]
	v_mfma_f32_16x16x32_bf16 v[116:119], v[148:151], v[188:191], v[116:119]
	v_mfma_f32_16x16x32_bf16 v[112:115], v[156:159], v[188:191], v[112:115]
	v_mfma_f32_16x16x32_bf16 v[92:95], v[148:151], v[196:199], v[92:95]
	v_mfma_f32_16x16x32_bf16 v[88:91], v[156:159], v[196:199], v[88:91]
	v_mfma_f32_16x16x32_bf16 v[84:87], v[148:151], v[204:207], v[84:87]
	v_mfma_f32_16x16x32_bf16 v[80:83], v[156:159], v[204:207], v[80:83]
	v_mfma_f32_16x16x32_bf16 v[124:127], v[152:155], v[184:187], v[124:127]
	v_mfma_f32_16x16x32_bf16 v[120:123], v[160:163], v[184:187], v[120:123]
	v_mfma_f32_16x16x32_bf16 v[116:119], v[152:155], v[192:195], v[116:119]
	v_mfma_f32_16x16x32_bf16 v[112:115], v[160:163], v[192:195], v[112:115]
	v_mfma_f32_16x16x32_bf16 v[92:95], v[152:155], v[200:203], v[92:95]
	v_mfma_f32_16x16x32_bf16 v[88:91], v[160:163], v[200:203], v[88:91]
	v_mfma_f32_16x16x32_bf16 v[84:87], v[152:155], v[208:211], v[84:87]
	v_mfma_f32_16x16x32_bf16 v[80:83], v[160:163], v[208:211], v[80:83]
	s_setprio 0
	s_setprio 1
	v_mfma_f32_16x16x32_bf16 v[108:111], v[164:167], v[180:183], v[108:111]
	v_mfma_f32_16x16x32_bf16 v[104:107], v[172:175], v[180:183], v[104:107]
	v_mfma_f32_16x16x32_bf16 v[100:103], v[164:167], v[188:191], v[100:103]
	v_mfma_f32_16x16x32_bf16 v[96:99], v[172:175], v[188:191], v[96:99]
	v_mfma_f32_16x16x32_bf16 v[76:79], v[164:167], v[196:199], v[76:79]
	v_mfma_f32_16x16x32_bf16 v[72:75], v[172:175], v[196:199], v[72:75]
	v_mfma_f32_16x16x32_bf16 v[68:71], v[164:167], v[204:207], v[68:71]
	v_mfma_f32_16x16x32_bf16 v[64:67], v[172:175], v[204:207], v[64:67]
	v_mfma_f32_16x16x32_bf16 v[108:111], v[168:171], v[184:187], v[108:111]
	v_mfma_f32_16x16x32_bf16 v[104:107], v[176:179], v[184:187], v[104:107]
	v_mfma_f32_16x16x32_bf16 v[100:103], v[168:171], v[192:195], v[100:103]
	v_mfma_f32_16x16x32_bf16 v[96:99], v[176:179], v[192:195], v[96:99]
	v_mfma_f32_16x16x32_bf16 v[76:79], v[168:171], v[200:203], v[76:79]
	v_mfma_f32_16x16x32_bf16 v[72:75], v[176:179], v[200:203], v[72:75]
	v_mfma_f32_16x16x32_bf16 v[68:71], v[168:171], v[208:211], v[68:71]
	v_mfma_f32_16x16x32_bf16 v[64:67], v[176:179], v[208:211], v[64:67]
	s_setprio 0
	s_barrier
	s_add_i32 s24, s59, s37
	v_lshl_add_u64 v[140:141], v[140:141], 0, s[12:13]
	s_mov_b32 m0, s24
	ds_read_b128 v[180:183], v147 offset:49152
	ds_read_b128 v[184:187], v147 offset:50176
	ds_read_b128 v[188:191], v147 offset:51200
	ds_read_b128 v[192:195], v147 offset:52224
	ds_read_b128 v[196:199], v147 offset:53248
	ds_read_b128 v[200:203], v147 offset:54272
	ds_read_b128 v[204:207], v147 offset:55296
	ds_read_b128 v[208:211], v147 offset:56320
	global_load_lds_dwordx4 v[140:141], off
	s_add_i32 m0, s24, 0x2000
	s_add_u32 s24, s28, 0xb0080
	v_lshl_add_u64 v[140:141], v[212:213], 0, s[12:13]
	s_addc_u32 s25, s29, 0
	s_add_i32 s28, s60, s37
	global_load_lds_dwordx4 v[140:141], off
	v_lshl_add_u64 v[140:141], s[24:25], 0, v[128:129]
	s_mov_b32 m0, s28
	s_nop 0
	global_load_lds_dwordx4 v[140:141], off
	v_lshl_add_u64 v[140:141], s[24:25], 0, v[130:131]
	s_add_i32 m0, s28, 0x2000
	s_nop 0
	global_load_lds_dwordx4 v[140:141], off
	v_lshl_add_u64 v[140:141], v[214:215], 0, s[12:13]
	s_mov_b32 m0, s43
	s_nop 0
	global_load_lds_dwordx4 v[140:141], off
	v_lshl_add_u64 v[140:141], v[216:217], 0, s[12:13]
	s_mov_b32 m0, s44
	s_nop 0
	global_load_lds_dwordx4 v[140:141], off
	s_waitcnt vmcnt(8)
	s_waitcnt lgkmcnt(0)
	s_barrier
	s_setprio 1
	v_mfma_f32_16x16x32_bf16 v[60:63], v[148:151], v[180:183], v[60:63]
	v_mfma_f32_16x16x32_bf16 v[56:59], v[156:159], v[180:183], v[56:59]
	v_mfma_f32_16x16x32_bf16 v[52:55], v[148:151], v[188:191], v[52:55]
	v_mfma_f32_16x16x32_bf16 v[48:51], v[156:159], v[188:191], v[48:51]
	v_mfma_f32_16x16x32_bf16 v[28:31], v[148:151], v[196:199], v[28:31]
	v_mfma_f32_16x16x32_bf16 v[24:27], v[156:159], v[196:199], v[24:27]
	v_mfma_f32_16x16x32_bf16 v[20:23], v[148:151], v[204:207], v[20:23]
	v_mfma_f32_16x16x32_bf16 v[16:19], v[156:159], v[204:207], v[16:19]
	v_mfma_f32_16x16x32_bf16 v[60:63], v[152:155], v[184:187], v[60:63]
	v_mfma_f32_16x16x32_bf16 v[56:59], v[160:163], v[184:187], v[56:59]
	v_mfma_f32_16x16x32_bf16 v[52:55], v[152:155], v[192:195], v[52:55]
	v_mfma_f32_16x16x32_bf16 v[48:51], v[160:163], v[192:195], v[48:51]
	v_mfma_f32_16x16x32_bf16 v[28:31], v[152:155], v[200:203], v[28:31]
	v_mfma_f32_16x16x32_bf16 v[24:27], v[160:163], v[200:203], v[24:27]
	v_mfma_f32_16x16x32_bf16 v[20:23], v[152:155], v[208:211], v[20:23]
	v_mfma_f32_16x16x32_bf16 v[16:19], v[160:163], v[208:211], v[16:19]
	s_setprio 0
	s_setprio 1
	v_mfma_f32_16x16x32_bf16 v[44:47], v[164:167], v[180:183], v[44:47]
	v_mfma_f32_16x16x32_bf16 v[40:43], v[172:175], v[180:183], v[40:43]
	v_mfma_f32_16x16x32_bf16 v[36:39], v[164:167], v[188:191], v[36:39]
	v_mfma_f32_16x16x32_bf16 v[32:35], v[172:175], v[188:191], v[32:35]
	v_mfma_f32_16x16x32_bf16 v[12:15], v[164:167], v[196:199], v[12:15]
	v_mfma_f32_16x16x32_bf16 v[8:11], v[172:175], v[196:199], v[8:11]
	v_mfma_f32_16x16x32_bf16 v[4:7], v[164:167], v[204:207], v[4:7]
	v_mfma_f32_16x16x32_bf16 v[0:3], v[172:175], v[204:207], v[0:3]
	v_mfma_f32_16x16x32_bf16 v[44:47], v[168:171], v[184:187], v[44:47]
	v_mfma_f32_16x16x32_bf16 v[40:43], v[176:179], v[184:187], v[40:43]
	v_mfma_f32_16x16x32_bf16 v[36:39], v[168:171], v[192:195], v[36:39]
	v_mfma_f32_16x16x32_bf16 v[32:35], v[176:179], v[192:195], v[32:35]
	v_mfma_f32_16x16x32_bf16 v[12:15], v[168:171], v[200:203], v[12:15]
	v_mfma_f32_16x16x32_bf16 v[8:11], v[176:179], v[200:203], v[8:11]
	v_mfma_f32_16x16x32_bf16 v[4:7], v[168:171], v[208:211], v[4:7]
	v_mfma_f32_16x16x32_bf16 v[0:3], v[176:179], v[208:211], v[0:3]
	s_setprio 0
	s_barrier
	s_add_i32 s58, s58, 2
	s_add_u32 s56, s56, 0x100
	s_addc_u32 s57, s57, 0
	s_cmp_gt_u32 s58, 41
	s_mov_b64 s[24:25], s[26:27]
	s_cbranch_scc0 .LBB0_1705
	s_and_b64 vcc, exec, s[14:15]
	s_cbranch_vccz .LBB0_1708
	s_barrier
